# plus: post-MFMA barrier moved 4 MFMAs early with prioritized tail; DYN_ROWS next-row atomic no longer waited before the row loads are issued
# speedup vs baseline: 1.0020x; 1.0020x over previous
.LBB0_116:
	s_cmp_ge_i32 s3, s38
	s_cselect_b64 s[30:31], -1, 0
	s_cmp_lt_i32 s3, s38
	s_cselect_b64 s[8:9], -1, 0
	s_or_b64 vcc, s[0:1], s[8:9]
	v_cndmask_b32_e32 v104, 0, v104, vcc
	s_nor_b64 s[34:35], vcc, s[4:5]
	s_and_saveexec_b64 s[8:9], s[34:35]
	s_cbranch_execz .LBB0_120
	s_mov_b64 s[36:37], exec
	v_mbcnt_lo_u32_b32 v2, s36, 0
	v_mbcnt_hi_u32_b32 v2, s37, v2
	v_cmp_eq_u32_e32 vcc, 0, v2
	s_and_saveexec_b64 s[34:35], vcc
	s_cbranch_execz .LBB0_119
	s_bcnt1_i32_b64 s25, s[36:37]
	v_mov_b32_e32 v3, s25
	global_atomic_add v223, v1, v3, s[20:21] sc0

.LBB0_120:
	s_or_b64 exec, exec, s[8:9]
	s_ashr_i32 s25, s24, 31
	s_lshl_b64 s[8:9], s[24:25], 14
	v_lshl_add_u64 v[38:39], v[66:67], 0, s[8:9]
	v_add_co_u32_e32 v34, vcc, s42, v38
	global_load_dwordx4 v[62:65], v[38:39], off
	global_load_dwordx4 v[58:61], v[38:39], off offset:1024
	global_load_dwordx4 v[50:53], v[38:39], off offset:2048
	global_load_dwordx4 v[26:29], v[38:39], off offset:3072
	v_addc_co_u32_e32 v35, vcc, 0, v39, vcc
	global_load_dwordx4 v[30:33], v[34:35], off offset:-4096
	v_add_co_u32_e32 v10, vcc, s41, v38
	s_waitcnt vmcnt(4)
	v_readfirstlane_b32 s98, v223
	s_nop 1
	v_mov_b32_e32 v104, s98
	v_mul_f32_e32 v105, v63, v63
	v_addc_co_u32_e32 v11, vcc, 0, v39, vcc
	global_load_dwordx4 v[2:5], v[10:11], off offset:1024
	global_load_dwordx4 v[6:9], v[10:11], off offset:2048
	s_nop 0
	global_load_dwordx4 v[10:13], v[10:11], off offset:3072
	s_nop 0
	global_load_dwordx4 v[14:17], v[34:35], off
	global_load_dwordx4 v[18:21], v[34:35], off offset:1024
	global_load_dwordx4 v[22:25], v[34:35], off offset:2048
	s_nop 0
	global_load_dwordx4 v[34:37], v[34:35], off offset:3072
	v_add_co_u32_e32 v54, vcc, s43, v38
	v_mul_f32_e32 v106, v65, v65
	s_nop 0
	v_addc_co_u32_e32 v55, vcc, 0, v39, vcc
	global_load_dwordx4 v[38:41], v[54:55], off
	global_load_dwordx4 v[42:45], v[54:55], off offset:1024
	global_load_dwordx4 v[46:49], v[54:55], off offset:2048
	s_nop 0
	global_load_dwordx4 v[54:57], v[54:55], off offset:3072
	s_waitcnt vmcnt(14)
	v_mul_f32_e32 v107, v59, v59
	v_mul_f32_e32 v108, v61, v61
	s_waitcnt vmcnt(13)
	v_mul_f32_e32 v109, v51, v51
	v_mul_f32_e32 v110, v53, v53
	v_fmac_f32_e32 v105, v62, v62
	v_fmac_f32_e32 v106, v64, v64
	v_fmac_f32_e32 v107, v58, v58
	v_fmac_f32_e32 v108, v60, v60
	s_waitcnt vmcnt(12)
	v_mul_f32_e32 v111, v27, v27
	v_mul_f32_e32 v112, v29, v29
	v_fmac_f32_e32 v109, v50, v50
	v_fmac_f32_e32 v110, v52, v52
	v_add_f32_e32 v105, v105, v106
	v_add_f32_e32 v106, v107, v108
	v_fmac_f32_e32 v111, v26, v26
	v_fmac_f32_e32 v112, v28, v28
	s_waitcnt vmcnt(11)
	v_mul_f32_e32 v113, v31, v31
	v_mul_f32_e32 v114, v33, v33
	v_add_f32_e32 v107, v109, v110
	v_add_f32_e32 v105, v105, v106
	v_add_f32_e32 v108, v111, v112
	v_fmac_f32_e32 v113, v30, v30
	v_fmac_f32_e32 v114, v32, v32
	v_add_f32_e32 v105, v105, v107
	v_add_f32_e32 v106, v113, v114
	v_add_f32_e32 v105, v105, v108
	v_add_f32_e32 v105, v105, v106
	global_load_dwordx4 v[148:151], v[84:85], off
	global_load_dwordx4 v[152:155], v[86:87], off
	global_load_dwordx4 v[156:159], v[88:89], off
	global_load_dwordx4 v[160:163], v[90:91], off
	global_load_dwordx4 v[164:167], v[92:93], off
	s_waitcnt vmcnt(15)
	v_mul_f32_e32 v115, v3, v3
	v_mul_f32_e32 v116, v5, v5
	s_waitcnt vmcnt(14)
	v_mul_f32_e32 v117, v7, v7
	v_mul_f32_e32 v118, v9, v9
	v_fmac_f32_e32 v115, v2, v2
	v_fmac_f32_e32 v116, v4, v4
	s_waitcnt vmcnt(13)
	v_mul_f32_e32 v119, v11, v11
	v_mul_f32_e32 v120, v13, v13
	v_fmac_f32_e32 v117, v6, v6
	v_fmac_f32_e32 v118, v8, v8
	v_add_f32_e32 v109, v115, v116
	s_waitcnt vmcnt(12)
	v_mul_f32_e32 v121, v15, v15
	v_mul_f32_e32 v122, v17, v17
	v_fmac_f32_e32 v119, v10, v10
	v_fmac_f32_e32 v120, v12, v12
	v_add_f32_e32 v110, v117, v118
	v_add_f32_e32 v105, v105, v109
	s_waitcnt vmcnt(11)
	v_mul_f32_e32 v123, v19, v19
	v_mul_f32_e32 v124, v21, v21
	v_fmac_f32_e32 v121, v14, v14
	v_fmac_f32_e32 v122, v16, v16
	v_add_f32_e32 v111, v119, v120
	v_add_f32_e32 v105, v105, v110
	s_waitcnt vmcnt(10)
	v_mul_f32_e32 v125, v23, v23
	v_mul_f32_e32 v126, v25, v25
	v_fmac_f32_e32 v123, v18, v18
	v_fmac_f32_e32 v124, v20, v20
	v_add_f32_e32 v112, v121, v122
	v_add_f32_e32 v105, v105, v111
	v_fmac_f32_e32 v125, v22, v22
	v_fmac_f32_e32 v126, v24, v24
	v_add_f32_e32 v113, v123, v124
	v_add_f32_e32 v105, v105, v112
	s_waitcnt vmcnt(9)
	v_mul_f32_e32 v106, v35, v35
	v_mul_f32_e32 v107, v37, v37
	v_add_f32_e32 v114, v125, v126
	v_add_f32_e32 v105, v105, v113
	v_fmac_f32_e32 v106, v34, v34
	v_fmac_f32_e32 v107, v36, v36
	v_add_f32_e32 v105, v105, v114
	v_add_f32_e32 v106, v106, v107
	v_add_f32_e32 v105, v105, v106
	s_waitcnt vmcnt(8)
	v_mul_f32_e32 v106, v39, v39
	v_mul_f32_e32 v107, v41, v41
	v_fmac_f32_e32 v106, v38, v38
	v_fmac_f32_e32 v107, v40, v40
	v_add_f32_e32 v106, v106, v107
	v_add_f32_e32 v105, v105, v106
	s_waitcnt vmcnt(7)
	v_mul_f32_e32 v106, v43, v43
	v_mul_f32_e32 v107, v45, v45
	v_fmac_f32_e32 v106, v42, v42
	v_fmac_f32_e32 v107, v44, v44
	v_add_f32_e32 v106, v106, v107
	v_add_f32_e32 v105, v105, v106
	s_waitcnt vmcnt(6)
	v_mul_f32_e32 v106, v47, v47
	v_mul_f32_e32 v107, v49, v49
	v_fmac_f32_e32 v106, v46, v46
	v_fmac_f32_e32 v107, v48, v48
	v_add_f32_e32 v106, v106, v107
	v_add_f32_e32 v105, v105, v106
	s_waitcnt vmcnt(5)
	v_mul_f32_e32 v106, v55, v55
	v_mul_f32_e32 v107, v57, v57
	v_fmac_f32_e32 v106, v54, v54
	v_fmac_f32_e32 v107, v56, v56
	v_add_f32_e32 v110, v106, v107
	v_add_f32_e32 v105, v105, v110
	ds_bpermute_b32 v110, v96, v105
	global_load_dwordx4 v[106:109], v[68:69], off
	s_waitcnt lgkmcnt(0)
	v_add_f32_e32 v105, v105, v110
	ds_bpermute_b32 v114, v97, v105
	global_load_dwordx4 v[110:113], v[68:69], off offset:1024
	s_waitcnt lgkmcnt(0)
	v_add_f32_e32 v105, v105, v114
	ds_bpermute_b32 v118, v98, v105
	global_load_dwordx4 v[114:117], v[68:69], off offset:2048
	s_waitcnt lgkmcnt(0)
	v_add_f32_e32 v105, v105, v118
	ds_bpermute_b32 v118, v99, v105
	s_waitcnt lgkmcnt(0)
	v_add_f32_e32 v105, v105, v118
	ds_bpermute_b32 v122, v100, v105
	global_load_dwordx4 v[118:121], v[68:69], off offset:3072
	s_waitcnt lgkmcnt(0)
	v_add_f32_e32 v105, v105, v122
	global_load_dwordx4 v[122:125], v[72:73], off
	ds_bpermute_b32 v126, v101, v105
	s_waitcnt lgkmcnt(0)
	v_add_f32_e32 v105, v105, v126
	v_fmamk_f32 v105, v105, 0x39800000, v102
	v_mul_f32_e32 v126, 0x4f800000, v105
	v_cmp_gt_f32_e32 vcc, s44, v105
	s_nop 1
	v_cndmask_b32_e32 v105, v105, v126, vcc
	v_sqrt_f32_e32 v130, v105
	global_load_dwordx4 v[126:129], v[74:75], off
	v_add_u32_e32 v131, -1, v130
	v_fma_f32 v132, -v131, v130, v105
	v_add_u32_e32 v135, 1, v130
	v_cmp_ge_f32_e64 s[8:9], 0, v132
	v_fma_f32 v136, -v135, v130, v105
	s_nop 0
	v_cndmask_b32_e64 v134, v130, v131, s[8:9]
	v_cmp_lt_f32_e64 s[8:9], 0, v136
	global_load_dwordx4 v[130:133], v[76:77], off
	s_nop 0
	v_cndmask_b32_e64 v134, v134, v135, s[8:9]
	v_mul_f32_e32 v135, 0x37800000, v134
	v_cndmask_b32_e32 v134, v134, v135, vcc
	v_cmp_class_f32_e32 vcc, v105, v103
	s_nop 1
	v_cndmask_b32_e32 v105, v134, v105, vcc
	v_div_scale_f32 v142, s[8:9], v105, v105, 1.0
	v_rcp_f32_e32 v143, v142
	v_div_scale_f32 v144, vcc, 1.0, v105, 1.0
	global_load_dwordx4 v[134:137], v[78:79], off
	v_fma_f32 v138, -v142, v143, 1.0
	v_fmac_f32_e32 v143, v138, v143
	v_mul_f32_e32 v145, v144, v143
	v_fma_f32 v147, -v142, v145, v144
	v_fmac_f32_e32 v145, v147, v143
	v_fma_f32 v142, -v142, v145, v144
	v_div_fmas_f32 v147, v142, v143, v145
	v_div_fixup_f32 v147, v147, v105, 1.0
	global_load_dwordx4 v[138:141], v[80:81], off
	global_load_dwordx4 v[142:145], v[82:83], off
	s_waitcnt vmcnt(9)
	v_mul_f32_e32 v105, v106, v147
	v_mul_f32_e32 v62, v62, v105
	v_mul_f32_e32 v105, v107, v147
	v_mul_f32_e32 v105, v63, v105
	v_mul_f32_e32 v63, v108, v147
	v_mul_f32_e32 v63, v64, v63
	v_mul_f32_e32 v64, v109, v147
	v_mul_f32_e32 v64, v65, v64
	s_waitcnt vmcnt(8)
	v_mul_f32_e32 v65, v110, v147
	v_mul_f32_e32 v58, v58, v65
	v_mul_f32_e32 v65, v111, v147
	v_mul_f32_e32 v59, v59, v65
	v_mul_f32_e32 v65, v112, v147
	v_mul_f32_e32 v60, v60, v65
	v_mul_f32_e32 v65, v113, v147
	v_mul_f32_e32 v61, v61, v65
	s_waitcnt vmcnt(7)
	v_mul_f32_e32 v65, v114, v147
	v_mul_f32_e32 v50, v50, v65
	v_mul_f32_e32 v65, v115, v147
	v_mul_f32_e32 v51, v51, v65
	v_mul_f32_e32 v65, v116, v147
	v_mul_f32_e32 v52, v52, v65
	v_mul_f32_e32 v65, v117, v147
	v_mul_f32_e32 v53, v53, v65
	s_waitcnt vmcnt(6)
	v_mul_f32_e32 v65, v118, v147
	v_mul_f32_e32 v26, v26, v65
	v_mul_f32_e32 v65, v119, v147
	v_mul_f32_e32 v65, v27, v65
	v_mul_f32_e32 v27, v120, v147
	v_mul_f32_e32 v28, v28, v27
	v_mul_f32_e32 v27, v121, v147
	v_mul_f32_e32 v29, v29, v27
	s_waitcnt vmcnt(5)
	v_mul_f32_e32 v27, v122, v147
	v_mul_f32_e32 v27, v30, v27
	v_mul_f32_e32 v30, v123, v147
	global_load_dwordx4 v[120:123], v[94:95], off
	v_mul_f32_e32 v31, v31, v30
	v_mul_f32_e32 v30, v124, v147
	v_mul_f32_e32 v30, v32, v30
	v_mul_f32_e32 v32, v125, v147
	v_mul_f32_e32 v32, v33, v32
	s_waitcnt vmcnt(5)
	v_mul_f32_e32 v33, v126, v147
	v_mul_f32_e32 v2, v2, v33
	v_mul_f32_e32 v33, v127, v147
	v_mul_f32_e32 v108, v3, v33
	v_mul_f32_e32 v3, v128, v147
	v_mul_f32_e32 v33, v4, v3
	v_mul_f32_e32 v3, v129, v147
	v_mul_f32_e32 v113, v5, v3
	s_waitcnt vmcnt(4)
	v_mul_f32_e32 v4, v131, v147
	v_mul_f32_e32 v109, v7, v4
	v_mul_f32_e32 v4, v132, v147
	v_mul_f32_e32 v3, v130, v147
	v_mul_f32_e32 v106, v8, v4
	v_mul_f32_e32 v4, v133, v147
	v_mul_f32_e32 v3, v6, v3
	v_mul_f32_e32 v114, v9, v4
	v_mul_f32_e32 v8, v147, v149
	v_mul_f32_e32 v9, v147, v153
	s_waitcnt vmcnt(3)
	v_mul_f32_e32 v5, v147, v135
	v_mul_f32_e32 v110, v11, v5
	v_mul_f32_e32 v5, v147, v136
	v_mul_f32_e32 v107, v12, v5
	v_mul_f32_e32 v5, v147, v137
	v_mul_f32_e32 v4, v147, v134
	v_mul_f32_e32 v115, v13, v5
	v_mul_f32_e32 v4, v10, v4
	v_mul_f32_e32 v10, v147, v157
	s_waitcnt vmcnt(2)
	v_mul_f32_e32 v5, v147, v138
	s_waitcnt vmcnt(1)
	v_mul_f32_e32 v7, v147, v143
	v_mul_f32_e32 v6, v147, v139
	v_mul_f32_e32 v112, v19, v7
	v_mul_f32_e32 v7, v147, v144
	v_mul_f32_e32 v5, v14, v5
	v_mul_f32_e32 v111, v15, v6
	v_mul_f32_e32 v6, v147, v140
	v_mul_f32_e32 v14, v20, v7
	v_mul_f32_e32 v7, v147, v145
	v_mul_f32_e32 v13, v16, v6
	v_mul_f32_e32 v6, v147, v141
	v_mul_f32_e32 v117, v21, v7
	v_mul_f32_e32 v7, v147, v148
	v_mul_f32_e32 v21, v23, v8
	v_mul_f32_e32 v23, v39, v10
	v_mul_f32_e32 v10, v147, v158
	v_mul_f32_e32 v116, v17, v6
	v_mul_f32_e32 v7, v22, v7
	v_mul_f32_e32 v22, v35, v9
	v_mul_f32_e32 v9, v147, v154
	v_mul_f32_e32 v17, v40, v10
	v_mul_f32_e32 v10, v147, v159
	v_mul_f32_e32 v16, v36, v9
	v_mul_f32_e32 v36, v41, v10
	v_mul_f32_e32 v10, v147, v160
	v_max_f32_e64 v40, |v62|, |v105|
	v_max_f32_e64 v41, |v63|, |v64|
	v_mul_f32_e32 v10, v42, v10
	v_max3_f32 v40, v40, 0, v41
	v_max_f32_e64 v41, |v58|, |v59|
	v_max_f32_e64 v42, |v60|, |v61|
	v_max3_f32 v40, v40, v41, v42
	v_max_f32_e64 v41, |v50|, |v51|
	v_max_f32_e64 v42, |v52|, |v53|
	v_max3_f32 v40, v40, v41, v42
	v_max_f32_e64 v41, |v26|, |v65|
	v_max_f32_e64 v42, |v28|, |v29|
	v_max3_f32 v40, v40, v41, v42
	v_max_f32_e64 v41, |v27|, |v31|
	v_max_f32_e64 v42, |v30|, |v32|
	v_max3_f32 v40, v40, v41, v42
	v_max_f32_e64 v41, |v2|, |v108|
	v_max_f32_e64 v42, |v33|, |v113|
	v_max3_f32 v40, v40, v41, v42
	v_max_f32_e64 v41, |v3|, |v109|
	v_max_f32_e64 v42, |v106|, |v114|
	v_mul_f32_e32 v6, v147, v142
	v_mul_f32_e32 v8, v147, v150
	v_max3_f32 v40, v40, v41, v42
	v_max_f32_e64 v41, |v4|, |v110|
	v_max_f32_e64 v42, |v107|, |v115|
	v_mul_f32_e32 v6, v18, v6
	v_mul_f32_e32 v15, v24, v8
	v_mul_f32_e32 v8, v147, v151
	v_max3_f32 v40, v40, v41, v42
	v_max_f32_e64 v41, |v5|, |v111|
	v_max_f32_e64 v42, |v13|, |v116|
	v_mul_f32_e32 v118, v25, v8
	v_mul_f32_e32 v8, v147, v152
	v_mul_f32_e32 v9, v147, v155
	v_mul_f32_e32 v11, v147, v161
	v_max3_f32 v40, v40, v41, v42
	v_max_f32_e64 v41, |v6|, |v112|
	v_max_f32_e64 v42, |v14|, |v117|
	v_mul_f32_e32 v8, v34, v8
	v_mul_f32_e32 v35, v37, v9
	v_mul_f32_e32 v9, v147, v156
	v_mul_f32_e32 v24, v43, v11
	v_mul_f32_e32 v11, v147, v162
	v_mul_f32_e32 v12, v147, v165
	v_max3_f32 v40, v40, v41, v42
	v_max_f32_e64 v41, |v7|, |v21|
	v_max_f32_e64 v42, |v15|, |v118|
	v_mul_f32_e32 v9, v38, v9
	v_mul_f32_e32 v18, v44, v11
	v_mul_f32_e32 v11, v147, v163
	v_mul_f32_e32 v25, v47, v12
	v_mul_f32_e32 v12, v147, v166
	v_max3_f32 v40, v40, v41, v42
	v_max_f32_e64 v41, |v8|, |v22|
	v_max_f32_e64 v42, |v16|, |v35|
	v_mul_f32_e32 v37, v45, v11
	v_mul_f32_e32 v11, v147, v164
	v_mul_f32_e32 v19, v48, v12
	v_mul_f32_e32 v12, v147, v167
	s_waitcnt vmcnt(0)
	v_mul_f32_e32 v20, v147, v121
	v_max3_f32 v40, v40, v41, v42
	v_max_f32_e64 v41, |v9|, |v23|
	v_max_f32_e64 v42, |v17|, |v36|
	v_mul_f32_e32 v11, v46, v11
	v_mul_f32_e32 v38, v49, v12
	v_mul_f32_e32 v12, v147, v120
	v_mul_f32_e32 v34, v55, v20
	v_mul_f32_e32 v20, v147, v122
	v_mul_f32_e32 v39, v147, v123
	v_max3_f32 v40, v40, v41, v42
	v_max_f32_e64 v41, |v10|, |v24|
	v_max_f32_e64 v42, |v18|, |v37|
	v_mul_f32_e32 v12, v54, v12
	v_mul_f32_e32 v20, v56, v20
	v_mul_f32_e32 v39, v57, v39
	v_max3_f32 v40, v40, v41, v42
	v_max_f32_e64 v41, |v11|, |v25|
	v_max_f32_e64 v42, |v19|, |v38|
	v_max3_f32 v40, v40, v41, v42
	v_max_f32_e64 v41, |v12|, |v34|
	v_max_f32_e64 v42, |v20|, |v39|
	v_max3_f32 v40, v40, v41, v42
	ds_bpermute_b32 v41, v96, v40
	s_waitcnt lgkmcnt(0)
	v_max_f32_e32 v41, v41, v41
	v_max_f32_e32 v40, v40, v41
	ds_bpermute_b32 v41, v97, v40
	s_waitcnt lgkmcnt(0)
	v_max_f32_e32 v41, v41, v41
	v_max_f32_e32 v40, v40, v41
	ds_bpermute_b32 v41, v98, v40
	s_waitcnt lgkmcnt(0)
	v_max_f32_e32 v41, v41, v41
	v_max_f32_e32 v40, v40, v41
	ds_bpermute_b32 v41, v99, v40
	s_waitcnt lgkmcnt(0)
	v_max_f32_e32 v41, v41, v41
	v_max_f32_e32 v40, v40, v41
	ds_bpermute_b32 v41, v100, v40
	s_waitcnt lgkmcnt(0)
	v_max_f32_e32 v41, v41, v41
	v_max_f32_e32 v40, v40, v41
	ds_bpermute_b32 v41, v101, v40
	s_waitcnt lgkmcnt(0)
	v_max3_f32 v40, v40, v41, s45
	s_and_saveexec_b64 s[8:9], s[6:7]
	s_cbranch_execz .LBB0_122
	s_lshl_b64 s[34:35], s[24:25], 2
	s_add_u32 s34, s26, s34
	v_mul_f32_e32 v41, 0x3c010204, v40
	s_addc_u32 s35, s27, s35
	global_store_dword v1, v41, s[34:35]

.LBB0_203:
	v_add_u32_e32 v162, s69, v147
	v_add_u32_e32 v178, s70, v147
	ds_read_b128 v[148:151], v162
	ds_read_b128 v[152:155], v162 offset:1024
	ds_read_b128 v[158:161], v162 offset:2048
	ds_read_b128 v[162:165], v162 offset:3072
	ds_read_b128 v[166:169], v178
	ds_read_b128 v[170:173], v178 offset:1024
	ds_read_b128 v[174:177], v178 offset:2048
	ds_read_b128 v[178:181], v178 offset:3072
	s_add_u32 s45, s50, 0xfff80080
	s_addc_u32 s47, s51, -1
	s_and_b64 s[52:53], s[52:53], exec
	s_cselect_b32 s55, s19, s47
	s_cselect_b32 s54, s18, s45
	s_cselect_b32 s53, s17, s74
	s_cselect_b32 s52, s16, s73
	v_lshl_add_u64 v[214:215], s[50:51], 0, v[138:139]
	s_add_i32 m0, s49, 0xc000
	ds_read_b128 v[182:185], v157
	ds_read_b128 v[186:189], v157 offset:1024
	ds_read_b128 v[190:193], v157 offset:2048
	ds_read_b128 v[194:197], v157 offset:3072
	ds_read_b128 v[198:201], v157 offset:4096
	ds_read_b128 v[202:205], v157 offset:5120
	ds_read_b128 v[206:209], v157 offset:6144
	ds_read_b128 v[210:213], v157 offset:7168
	global_load_lds_dwordx4 v[214:215], off
	v_lshl_add_u64 v[214:215], s[50:51], 0, v[140:141]
	s_add_i32 m0, s49, 0xe000
	s_nop 0
	global_load_lds_dwordx4 v[214:215], off
	s_waitcnt vmcnt(8)
	s_waitcnt lgkmcnt(0)
	s_barrier
	s_setprio 2
	s_waitcnt lgkmcnt(0)
	v_mfma_i32_16x16x64_i8 v[126:129], v[148:151], v[182:185], v[126:129]
	v_mfma_i32_16x16x64_i8 v[118:121], v[158:161], v[182:185], v[118:121]
	v_mfma_i32_16x16x64_i8 v[110:113], v[148:151], v[190:193], v[110:113]
	v_mfma_i32_16x16x64_i8 v[102:105], v[158:161], v[190:193], v[102:105]
	v_mfma_i32_16x16x64_i8 v[94:97], v[148:151], v[198:201], v[94:97]
	v_mfma_i32_16x16x64_i8 v[86:89], v[158:161], v[198:201], v[86:89]
	v_mfma_i32_16x16x64_i8 v[78:81], v[148:151], v[206:209], v[78:81]
	v_mfma_i32_16x16x64_i8 v[70:73], v[158:161], v[206:209], v[70:73]
	v_mfma_i32_16x16x64_i8 v[126:129], v[152:155], v[186:189], v[126:129]
	v_mfma_i32_16x16x64_i8 v[118:121], v[162:165], v[186:189], v[118:121]
	v_mfma_i32_16x16x64_i8 v[110:113], v[152:155], v[194:197], v[110:113]
	v_mfma_i32_16x16x64_i8 v[102:105], v[162:165], v[194:197], v[102:105]
	v_mfma_i32_16x16x64_i8 v[94:97], v[152:155], v[202:205], v[94:97]
	v_mfma_i32_16x16x64_i8 v[86:89], v[162:165], v[202:205], v[86:89]
	v_mfma_i32_16x16x64_i8 v[78:81], v[152:155], v[210:213], v[78:81]
	v_mfma_i32_16x16x64_i8 v[70:73], v[162:165], v[210:213], v[70:73]
	s_setprio 0
	s_setprio 2
	v_mfma_i32_16x16x64_i8 v[122:125], v[166:169], v[182:185], v[122:125]
	v_mfma_i32_16x16x64_i8 v[114:117], v[174:177], v[182:185], v[114:117]
	v_mfma_i32_16x16x64_i8 v[106:109], v[166:169], v[190:193], v[106:109]
	v_mfma_i32_16x16x64_i8 v[98:101], v[174:177], v[190:193], v[98:101]
	v_mfma_i32_16x16x64_i8 v[90:93], v[166:169], v[198:201], v[90:93]
	v_mfma_i32_16x16x64_i8 v[82:85], v[174:177], v[198:201], v[82:85]
	v_mfma_i32_16x16x64_i8 v[74:77], v[166:169], v[206:209], v[74:77]
	v_mfma_i32_16x16x64_i8 v[66:69], v[174:177], v[206:209], v[66:69]
	v_mfma_i32_16x16x64_i8 v[122:125], v[170:173], v[186:189], v[122:125]
	v_mfma_i32_16x16x64_i8 v[114:117], v[178:181], v[186:189], v[114:117]
	v_mfma_i32_16x16x64_i8 v[106:109], v[170:173], v[194:197], v[106:109]
	v_mfma_i32_16x16x64_i8 v[98:101], v[178:181], v[194:197], v[98:101]
	s_setprio 3
	s_barrier
	v_mfma_i32_16x16x64_i8 v[90:93], v[170:173], v[202:205], v[90:93]
	v_mfma_i32_16x16x64_i8 v[82:85], v[178:181], v[202:205], v[82:85]
	v_mfma_i32_16x16x64_i8 v[74:77], v[170:173], v[210:213], v[74:77]
	v_mfma_i32_16x16x64_i8 v[66:69], v[178:181], v[210:213], v[66:69]
	s_setprio 0
	s_add_i32 s45, s69, s43
	v_lshl_add_u64 v[214:215], s[52:53], 0, v[130:131]
	s_mov_b32 m0, s45
	ds_read_b128 v[182:185], v157 offset:16384
	ds_read_b128 v[186:189], v157 offset:17408
	ds_read_b128 v[190:193], v157 offset:18432
	ds_read_b128 v[194:197], v157 offset:19456
	ds_read_b128 v[198:201], v157 offset:20480
	ds_read_b128 v[202:205], v157 offset:21504
	ds_read_b128 v[206:209], v157 offset:22528
	ds_read_b128 v[210:213], v157 offset:23552
	global_load_lds_dwordx4 v[214:215], off
	s_add_i32 m0, s45, 0x2000
	s_add_u32 s76, s52, 0x80000
	v_lshl_add_u64 v[214:215], s[52:53], 0, v[132:133]
	s_addc_u32 s77, s53, 0
	s_add_i32 s45, s70, s43
	global_load_lds_dwordx4 v[214:215], off
	v_lshl_add_u64 v[214:215], s[76:77], 0, v[130:131]
	s_mov_b32 m0, s45
	v_lshl_add_u64 v[216:217], s[54:55], 0, v[134:135]
	global_load_lds_dwordx4 v[214:215], off
	v_lshl_add_u64 v[214:215], s[76:77], 0, v[132:133]
	s_add_i32 m0, s45, 0x2000
	s_nop 0
	global_load_lds_dwordx4 v[214:215], off
	v_lshl_add_u64 v[214:215], s[54:55], 0, v[136:137]
	s_mov_b32 m0, s49
	s_nop 0
	global_load_lds_dwordx4 v[214:215], off
	s_mov_b32 m0, s58
	s_nop 0
	global_load_lds_dwordx4 v[216:217], off
	s_waitcnt vmcnt(8)
	s_waitcnt lgkmcnt(0)
	s_barrier
	s_setprio 2
	s_waitcnt lgkmcnt(0)
	v_mfma_i32_16x16x64_i8 v[62:65], v[148:151], v[182:185], v[62:65]
	v_mfma_i32_16x16x64_i8 v[54:57], v[158:161], v[182:185], v[54:57]
	v_mfma_i32_16x16x64_i8 v[46:49], v[148:151], v[190:193], v[46:49]
	v_mfma_i32_16x16x64_i8 v[38:41], v[158:161], v[190:193], v[38:41]
	v_mfma_i32_16x16x64_i8 v[30:33], v[148:151], v[198:201], v[30:33]
	v_mfma_i32_16x16x64_i8 v[22:25], v[158:161], v[198:201], v[22:25]
	v_mfma_i32_16x16x64_i8 v[14:17], v[148:151], v[206:209], v[14:17]
	v_mfma_i32_16x16x64_i8 v[6:9], v[158:161], v[206:209], v[6:9]
	v_mfma_i32_16x16x64_i8 v[62:65], v[152:155], v[186:189], v[62:65]
	v_mfma_i32_16x16x64_i8 v[54:57], v[162:165], v[186:189], v[54:57]
	v_mfma_i32_16x16x64_i8 v[46:49], v[152:155], v[194:197], v[46:49]
	v_mfma_i32_16x16x64_i8 v[38:41], v[162:165], v[194:197], v[38:41]
	v_mfma_i32_16x16x64_i8 v[30:33], v[152:155], v[202:205], v[30:33]
	v_mfma_i32_16x16x64_i8 v[22:25], v[162:165], v[202:205], v[22:25]
	v_mfma_i32_16x16x64_i8 v[14:17], v[152:155], v[210:213], v[14:17]
	v_mfma_i32_16x16x64_i8 v[6:9], v[162:165], v[210:213], v[6:9]
	s_setprio 0
	s_setprio 2
	v_mfma_i32_16x16x64_i8 v[58:61], v[166:169], v[182:185], v[58:61]
	v_mfma_i32_16x16x64_i8 v[50:53], v[174:177], v[182:185], v[50:53]
	v_mfma_i32_16x16x64_i8 v[42:45], v[166:169], v[190:193], v[42:45]
	v_mfma_i32_16x16x64_i8 v[34:37], v[174:177], v[190:193], v[34:37]
	v_mfma_i32_16x16x64_i8 v[26:29], v[166:169], v[198:201], v[26:29]
	v_mfma_i32_16x16x64_i8 v[18:21], v[174:177], v[198:201], v[18:21]
	v_mfma_i32_16x16x64_i8 v[10:13], v[166:169], v[206:209], v[10:13]
	v_mfma_i32_16x16x64_i8 v[2:5], v[174:177], v[206:209], v[2:5]
	v_mfma_i32_16x16x64_i8 v[58:61], v[170:173], v[186:189], v[58:61]
	v_mfma_i32_16x16x64_i8 v[50:53], v[178:181], v[186:189], v[50:53]
	v_mfma_i32_16x16x64_i8 v[42:45], v[170:173], v[194:197], v[42:45]
	v_mfma_i32_16x16x64_i8 v[34:37], v[178:181], v[194:197], v[34:37]
	s_setprio 3
	s_barrier
	v_mfma_i32_16x16x64_i8 v[26:29], v[170:173], v[202:205], v[26:29]
	v_mfma_i32_16x16x64_i8 v[18:21], v[178:181], v[202:205], v[18:21]
	v_mfma_i32_16x16x64_i8 v[10:13], v[170:173], v[210:213], v[10:13]
	v_mfma_i32_16x16x64_i8 v[2:5], v[178:181], v[210:213], v[2:5]
	s_setprio 0
	s_add_i32 s45, 0, 0x18000
	s_add_i32 s47, 0, 0x1c000
	v_add_u32_e32 v162, s45, v147
	v_add_u32_e32 v178, s47, v147
	ds_read_b128 v[148:151], v162
	ds_read_b128 v[152:155], v162 offset:1024
	ds_read_b128 v[158:161], v162 offset:2048
	ds_read_b128 v[162:165], v162 offset:3072
	ds_read_b128 v[166:169], v178
	ds_read_b128 v[170:173], v178 offset:1024
	ds_read_b128 v[174:177], v178 offset:2048
	ds_read_b128 v[178:181], v178 offset:3072
	s_add_u32 s54, s54, 0x80000
	s_addc_u32 s55, s55, 0
	s_mov_b32 m0, s59
	v_lshl_add_u64 v[218:219], s[54:55], 0, v[136:137]
	ds_read_b128 v[182:185], v157 offset:32768
	ds_read_b128 v[186:189], v157 offset:33792
	ds_read_b128 v[190:193], v157 offset:34816
	ds_read_b128 v[194:197], v157 offset:35840
	ds_read_b128 v[198:201], v157 offset:36864
	ds_read_b128 v[202:205], v157 offset:37888
	ds_read_b128 v[206:209], v157 offset:38912
	ds_read_b128 v[210:213], v157 offset:39936
	global_load_lds_dwordx4 v[218:219], off
	v_lshl_add_u64 v[218:219], s[54:55], 0, v[134:135]
	s_mov_b32 m0, s60
	s_nop 0
	global_load_lds_dwordx4 v[218:219], off
	s_waitcnt vmcnt(8)
	s_waitcnt lgkmcnt(0)
	s_barrier
	s_setprio 2
	s_waitcnt lgkmcnt(0)
	v_mfma_i32_16x16x64_i8 v[126:129], v[148:151], v[182:185], v[126:129]
	v_mfma_i32_16x16x64_i8 v[118:121], v[158:161], v[182:185], v[118:121]
	v_mfma_i32_16x16x64_i8 v[110:113], v[148:151], v[190:193], v[110:113]
	v_mfma_i32_16x16x64_i8 v[102:105], v[158:161], v[190:193], v[102:105]
	v_mfma_i32_16x16x64_i8 v[94:97], v[148:151], v[198:201], v[94:97]
	v_mfma_i32_16x16x64_i8 v[86:89], v[158:161], v[198:201], v[86:89]
	v_mfma_i32_16x16x64_i8 v[78:81], v[148:151], v[206:209], v[78:81]
	v_mfma_i32_16x16x64_i8 v[70:73], v[158:161], v[206:209], v[70:73]
	v_mfma_i32_16x16x64_i8 v[126:129], v[152:155], v[186:189], v[126:129]
	v_mfma_i32_16x16x64_i8 v[118:121], v[162:165], v[186:189], v[118:121]
	v_mfma_i32_16x16x64_i8 v[110:113], v[152:155], v[194:197], v[110:113]
	v_mfma_i32_16x16x64_i8 v[102:105], v[162:165], v[194:197], v[102:105]
	v_mfma_i32_16x16x64_i8 v[94:97], v[152:155], v[202:205], v[94:97]
	v_mfma_i32_16x16x64_i8 v[86:89], v[162:165], v[202:205], v[86:89]
	v_mfma_i32_16x16x64_i8 v[78:81], v[152:155], v[210:213], v[78:81]
	v_mfma_i32_16x16x64_i8 v[70:73], v[162:165], v[210:213], v[70:73]
	s_setprio 0
	s_setprio 2
	v_mfma_i32_16x16x64_i8 v[122:125], v[166:169], v[182:185], v[122:125]
	v_mfma_i32_16x16x64_i8 v[114:117], v[174:177], v[182:185], v[114:117]
	v_mfma_i32_16x16x64_i8 v[106:109], v[166:169], v[190:193], v[106:109]
	v_mfma_i32_16x16x64_i8 v[98:101], v[174:177], v[190:193], v[98:101]
	v_mfma_i32_16x16x64_i8 v[90:93], v[166:169], v[198:201], v[90:93]
	v_mfma_i32_16x16x64_i8 v[82:85], v[174:177], v[198:201], v[82:85]
	v_mfma_i32_16x16x64_i8 v[74:77], v[166:169], v[206:209], v[74:77]
	v_mfma_i32_16x16x64_i8 v[66:69], v[174:177], v[206:209], v[66:69]
	v_mfma_i32_16x16x64_i8 v[122:125], v[170:173], v[186:189], v[122:125]
	v_mfma_i32_16x16x64_i8 v[114:117], v[178:181], v[186:189], v[114:117]
	v_mfma_i32_16x16x64_i8 v[106:109], v[170:173], v[194:197], v[106:109]
	v_mfma_i32_16x16x64_i8 v[98:101], v[178:181], v[194:197], v[98:101]
	s_setprio 3
	s_barrier
	v_mfma_i32_16x16x64_i8 v[90:93], v[170:173], v[202:205], v[90:93]
	v_mfma_i32_16x16x64_i8 v[82:85], v[178:181], v[202:205], v[82:85]
	v_mfma_i32_16x16x64_i8 v[74:77], v[170:173], v[210:213], v[74:77]
	v_mfma_i32_16x16x64_i8 v[66:69], v[178:181], v[210:213], v[66:69]
	s_setprio 0
	s_add_u32 s54, s52, 0x4000
	s_addc_u32 s55, s53, 0
	s_add_i32 s45, s45, s43
	v_lshl_add_u64 v[218:219], s[54:55], 0, v[130:131]
	s_mov_b32 m0, s45
	ds_read_b128 v[182:185], v157 offset:49152
	ds_read_b128 v[186:189], v157 offset:50176
	ds_read_b128 v[190:193], v157 offset:51200
	ds_read_b128 v[194:197], v157 offset:52224
	ds_read_b128 v[198:201], v157 offset:53248
	ds_read_b128 v[202:205], v157 offset:54272
	ds_read_b128 v[206:209], v157 offset:55296
	ds_read_b128 v[210:213], v157 offset:56320
	global_load_lds_dwordx4 v[218:219], off
	s_add_i32 m0, s45, 0x2000
	s_add_u32 s52, s52, 0x84000
	v_lshl_add_u64 v[218:219], s[54:55], 0, v[132:133]
	s_addc_u32 s53, s53, 0
	s_add_i32 s45, s47, s43
	global_load_lds_dwordx4 v[218:219], off
	v_lshl_add_u64 v[218:219], s[52:53], 0, v[130:131]
	s_mov_b32 m0, s45
	v_lshl_add_u64 v[214:215], v[214:215], 0, s[38:39]
	global_load_lds_dwordx4 v[218:219], off
	v_lshl_add_u64 v[218:219], s[52:53], 0, v[132:133]
	s_add_i32 m0, s45, 0x2000
	s_nop 0
	global_load_lds_dwordx4 v[218:219], off
	s_mov_b32 m0, s64
	s_nop 0
	global_load_lds_dwordx4 v[214:215], off
	v_lshl_add_u64 v[214:215], v[216:217], 0, s[38:39]
	s_mov_b32 m0, s65
	s_nop 0
	global_load_lds_dwordx4 v[214:215], off
	s_waitcnt vmcnt(8)
	s_waitcnt lgkmcnt(0)
	s_barrier
	s_setprio 2
	s_waitcnt lgkmcnt(0)
	v_mfma_i32_16x16x64_i8 v[62:65], v[148:151], v[182:185], v[62:65]
	v_mfma_i32_16x16x64_i8 v[54:57], v[158:161], v[182:185], v[54:57]
	v_mfma_i32_16x16x64_i8 v[46:49], v[148:151], v[190:193], v[46:49]
	v_mfma_i32_16x16x64_i8 v[38:41], v[158:161], v[190:193], v[38:41]
	v_mfma_i32_16x16x64_i8 v[30:33], v[148:151], v[198:201], v[30:33]
	v_mfma_i32_16x16x64_i8 v[22:25], v[158:161], v[198:201], v[22:25]
	v_mfma_i32_16x16x64_i8 v[14:17], v[148:151], v[206:209], v[14:17]
	v_mfma_i32_16x16x64_i8 v[6:9], v[158:161], v[206:209], v[6:9]
	v_mfma_i32_16x16x64_i8 v[62:65], v[152:155], v[186:189], v[62:65]
	v_mfma_i32_16x16x64_i8 v[54:57], v[162:165], v[186:189], v[54:57]
	v_mfma_i32_16x16x64_i8 v[46:49], v[152:155], v[194:197], v[46:49]
	v_mfma_i32_16x16x64_i8 v[38:41], v[162:165], v[194:197], v[38:41]
	v_mfma_i32_16x16x64_i8 v[30:33], v[152:155], v[202:205], v[30:33]
	v_mfma_i32_16x16x64_i8 v[22:25], v[162:165], v[202:205], v[22:25]
	v_mfma_i32_16x16x64_i8 v[14:17], v[152:155], v[210:213], v[14:17]
	v_mfma_i32_16x16x64_i8 v[6:9], v[162:165], v[210:213], v[6:9]
	s_setprio 0
	s_setprio 2
	v_mfma_i32_16x16x64_i8 v[58:61], v[166:169], v[182:185], v[58:61]
	v_mfma_i32_16x16x64_i8 v[50:53], v[174:177], v[182:185], v[50:53]
	v_mfma_i32_16x16x64_i8 v[42:45], v[166:169], v[190:193], v[42:45]
	v_mfma_i32_16x16x64_i8 v[34:37], v[174:177], v[190:193], v[34:37]
	v_mfma_i32_16x16x64_i8 v[26:29], v[166:169], v[198:201], v[26:29]
	v_mfma_i32_16x16x64_i8 v[18:21], v[174:177], v[198:201], v[18:21]
	v_mfma_i32_16x16x64_i8 v[10:13], v[166:169], v[206:209], v[10:13]
	v_mfma_i32_16x16x64_i8 v[2:5], v[174:177], v[206:209], v[2:5]
	v_mfma_i32_16x16x64_i8 v[58:61], v[170:173], v[186:189], v[58:61]
	v_mfma_i32_16x16x64_i8 v[50:53], v[178:181], v[186:189], v[50:53]
	v_mfma_i32_16x16x64_i8 v[42:45], v[170:173], v[194:197], v[42:45]
	v_mfma_i32_16x16x64_i8 v[34:37], v[178:181], v[194:197], v[34:37]
	s_setprio 3
	s_barrier
	v_mfma_i32_16x16x64_i8 v[26:29], v[170:173], v[202:205], v[26:29]
	v_mfma_i32_16x16x64_i8 v[18:21], v[178:181], v[202:205], v[18:21]
	v_mfma_i32_16x16x64_i8 v[10:13], v[170:173], v[210:213], v[10:13]
	v_mfma_i32_16x16x64_i8 v[2:5], v[178:181], v[210:213], v[2:5]
	s_setprio 0
	s_add_i32 s75, s75, 2
	s_add_u32 s73, s73, 0x8000
	s_addc_u32 s74, s74, 0
	s_add_u32 s50, s50, 0x100
	s_addc_u32 s51, s51, 0
	s_cmp_gt_u32 s75, 29
	s_cbranch_scc1 .LBB0_209

.LBB0_222:
	v_mov_b32_e32 v8, 0
	s_and_saveexec_b64 s[16:17], vcc
	s_cbranch_execz .LBB0_226
	s_mov_b64 s[20:21], exec
	v_mbcnt_lo_u32_b32 v8, s20, 0
	v_mbcnt_hi_u32_b32 v8, s21, v8
	v_cmp_eq_u32_e64 s[6:7], 0, v8
	s_and_saveexec_b64 s[18:19], s[6:7]
	s_cbranch_execz .LBB0_225
	s_bcnt1_i32_b64 s6, s[20:21]
	v_mov_b32_e32 v9, s6
	global_atomic_add v223, v3, v9, s[10:11] sc0

.LBB0_226:
	s_or_b64 exec, exec, s[16:17]
	s_ashr_i32 s6, s63, 31
	s_lshr_b32 s6, s6, 25
	s_add_i32 s6, s63, s6
	s_ashr_i32 s6, s6, 7
	s_waitcnt lgkmcnt(0)
	v_lshl_add_u32 v10, s6, 6, v6
	s_lshl_b32 s7, s6, 12
	s_lshl_b32 s16, s63, 5
	v_ashrrev_i32_e32 v11, 31, v10
	s_sub_i32 s16, s16, s7
	v_lshlrev_b64 v[10:11], 14, v[10:11]
	v_lshl_add_u64 v[10:11], s[0:1], 0, v[10:11]
	s_ashr_i32 s17, s16, 31
	v_lshl_add_u64 v[10:11], s[16:17], 2, v[10:11]
	v_lshl_add_u64 v[10:11], v[10:11], 0, v[2:3]
	v_add_co_u32_e64 v12, s[6:7], s24, v10
	s_nop 1
	v_addc_co_u32_e64 v13, s[6:7], 0, v11, s[6:7]
	v_add_co_u32_e64 v14, s[6:7], s25, v10
	s_nop 1
	v_addc_co_u32_e64 v15, s[6:7], 0, v11, s[6:7]
	v_add_co_u32_e64 v16, s[6:7], s30, v10
	s_nop 1
	v_addc_co_u32_e64 v17, s[6:7], 0, v11, s[6:7]
	v_add_co_u32_e64 v18, s[6:7], s31, v10
	s_nop 1
	v_addc_co_u32_e64 v19, s[6:7], 0, v11, s[6:7]
	v_add_co_u32_e64 v20, s[6:7], s34, v10
	s_nop 1
	v_addc_co_u32_e64 v21, s[6:7], 0, v11, s[6:7]
	v_add_co_u32_e64 v22, s[6:7], s35, v10
	s_nop 1
	v_addc_co_u32_e64 v23, s[6:7], 0, v11, s[6:7]
	v_add_co_u32_e64 v24, s[6:7], s38, v10
	s_nop 1
	v_addc_co_u32_e64 v25, s[6:7], 0, v11, s[6:7]
	global_load_dword v9, v[10:11], off nt
	global_load_dword v28, v[12:13], off nt
	global_load_dword v29, v[14:15], off nt
	global_load_dword v30, v[16:17], off nt
	global_load_dword v31, v[18:19], off nt
	global_load_dword v32, v[20:21], off nt
	global_load_dword v33, v[22:23], off nt
	global_load_dword v34, v[24:25], off nt
	v_add_co_u32_e64 v12, s[6:7], s39, v10
	s_nop 1
	v_addc_co_u32_e64 v13, s[6:7], 0, v11, s[6:7]
	v_add_co_u32_e64 v14, s[6:7], s40, v10
	s_nop 1
	v_addc_co_u32_e64 v15, s[6:7], 0, v11, s[6:7]
	v_add_co_u32_e64 v16, s[6:7], s41, v10
	s_nop 1
	v_addc_co_u32_e64 v17, s[6:7], 0, v11, s[6:7]
	v_add_co_u32_e64 v18, s[6:7], s42, v10
	s_nop 1
	v_addc_co_u32_e64 v19, s[6:7], 0, v11, s[6:7]
	v_add_co_u32_e64 v20, s[6:7], s43, v10
	s_nop 1
	v_addc_co_u32_e64 v21, s[6:7], 0, v11, s[6:7]
	v_add_co_u32_e64 v22, s[6:7], s44, v10
	s_nop 1
	v_addc_co_u32_e64 v23, s[6:7], 0, v11, s[6:7]
	v_add_co_u32_e64 v24, s[6:7], s45, v10
	s_nop 1
	v_addc_co_u32_e64 v25, s[6:7], 0, v11, s[6:7]
	v_add_co_u32_e64 v26, s[6:7], s46, v10
	s_nop 1
	v_addc_co_u32_e64 v27, s[6:7], 0, v11, s[6:7]
	global_load_dword v35, v[12:13], off nt
	global_load_dword v36, v[14:15], off nt
	global_load_dword v37, v[16:17], off nt
	global_load_dword v38, v[18:19], off nt
	global_load_dword v39, v[20:21], off nt
	global_load_dword v40, v[22:23], off nt
	global_load_dword v41, v[24:25], off nt
	global_load_dword v42, v[26:27], off nt
	v_add_co_u32_e64 v12, s[6:7], s47, v10
	s_nop 1
	v_addc_co_u32_e64 v13, s[6:7], 0, v11, s[6:7]
	v_add_co_u32_e64 v14, s[6:7], s48, v10
	s_nop 1
	v_addc_co_u32_e64 v15, s[6:7], 0, v11, s[6:7]
	v_add_co_u32_e64 v16, s[6:7], s49, v10
	s_nop 1
	v_addc_co_u32_e64 v17, s[6:7], 0, v11, s[6:7]
	v_add_co_u32_e64 v18, s[6:7], s50, v10
	s_nop 1
	v_addc_co_u32_e64 v19, s[6:7], 0, v11, s[6:7]
	v_add_co_u32_e64 v20, s[6:7], s51, v10
	s_nop 1
	v_addc_co_u32_e64 v21, s[6:7], 0, v11, s[6:7]
	v_add_co_u32_e64 v22, s[6:7], s52, v10
	s_nop 1
	v_addc_co_u32_e64 v23, s[6:7], 0, v11, s[6:7]
	v_add_co_u32_e64 v24, s[6:7], s53, v10
	s_nop 1
	v_addc_co_u32_e64 v25, s[6:7], 0, v11, s[6:7]
	v_add_co_u32_e64 v26, s[6:7], s54, v10
	s_nop 1
	v_addc_co_u32_e64 v27, s[6:7], 0, v11, s[6:7]
	global_load_dword v43, v[12:13], off nt
	global_load_dword v44, v[14:15], off nt
	global_load_dword v45, v[16:17], off nt
	global_load_dword v46, v[18:19], off nt
	global_load_dword v47, v[20:21], off nt
	global_load_dword v48, v[22:23], off nt
	global_load_dword v49, v[24:25], off nt
	s_nop 0
	global_load_dword v26, v[26:27], off nt
	v_add_co_u32_e64 v12, s[6:7], s55, v10
	s_waitcnt vmcnt(14)
	v_readfirstlane_b32 s98, v223
	s_nop 1
	v_mov_b32_e32 v8, s98
	v_sub_f32_e32 v27, v35, v36
	v_addc_co_u32_e64 v13, s[6:7], 0, v11, s[6:7]
	v_add_co_u32_e64 v14, s[6:7], s56, v10
	s_nop 1
	v_addc_co_u32_e64 v15, s[6:7], 0, v11, s[6:7]
	v_add_co_u32_e64 v16, s[6:7], s57, v10
	s_nop 1
	v_addc_co_u32_e64 v17, s[6:7], 0, v11, s[6:7]
	v_add_co_u32_e64 v18, s[6:7], s58, v10
	s_nop 1
	v_addc_co_u32_e64 v19, s[6:7], 0, v11, s[6:7]
	v_add_co_u32_e64 v20, s[6:7], s59, v10
	s_nop 1
	v_addc_co_u32_e64 v21, s[6:7], 0, v11, s[6:7]
	v_add_co_u32_e64 v22, s[6:7], s60, v10
	s_nop 1
	v_addc_co_u32_e64 v23, s[6:7], 0, v11, s[6:7]
	v_add_co_u32_e64 v24, s[6:7], s61, v10
	s_nop 1
	v_addc_co_u32_e64 v25, s[6:7], 0, v11, s[6:7]
	v_add_co_u32_e64 v10, s[6:7], s62, v10
	s_nop 1
	v_addc_co_u32_e64 v11, s[6:7], 0, v11, s[6:7]
	global_load_dword v12, v[12:13], off nt
	s_nop 0
	global_load_dword v13, v[14:15], off nt
	s_nop 0
	global_load_dword v14, v[16:17], off nt
	global_load_dword v15, v[18:19], off nt
	s_nop 0
	global_load_dword v16, v[20:21], off nt
	global_load_dword v17, v[22:23], off nt
	global_load_dword v18, v[24:25], off nt
	s_nop 0
	global_load_dword v10, v[10:11], off nt
	v_add_f32_e32 v11, v9, v28
	v_sub_f32_e32 v9, v9, v28
	v_add_f32_e32 v19, v29, v30
	v_sub_f32_e32 v20, v29, v30
	v_add_f32_e32 v21, v31, v32
	v_sub_f32_e32 v22, v31, v32
	v_add_f32_e32 v23, v33, v34
	v_sub_f32_e32 v24, v33, v34
	v_add_f32_e32 v25, v35, v36
	s_waitcnt vmcnt(20)
	v_add_f32_e32 v28, v37, v38
	v_sub_f32_e32 v29, v37, v38
	s_waitcnt vmcnt(18)
	v_add_f32_e32 v30, v39, v40
	v_sub_f32_e32 v31, v39, v40
	s_waitcnt vmcnt(16)
	v_add_f32_e32 v32, v41, v42
	v_sub_f32_e32 v33, v41, v42
	s_waitcnt vmcnt(14)
	v_add_f32_e32 v34, v43, v44
	v_sub_f32_e32 v35, v43, v44
	s_waitcnt vmcnt(12)
	v_add_f32_e32 v36, v45, v46
	v_sub_f32_e32 v37, v45, v46
	s_waitcnt vmcnt(10)
	v_add_f32_e32 v38, v47, v48
	v_sub_f32_e32 v39, v47, v48
	s_waitcnt vmcnt(8)
	v_add_f32_e32 v40, v49, v26
	v_sub_f32_e32 v26, v49, v26
	s_waitcnt vmcnt(6)
	v_add_f32_e32 v41, v12, v13
	v_sub_f32_e32 v12, v12, v13
	s_waitcnt vmcnt(4)
	v_add_f32_e32 v13, v14, v15
	v_sub_f32_e32 v14, v14, v15
	s_waitcnt vmcnt(2)
	v_add_f32_e32 v15, v16, v17
	v_sub_f32_e32 v16, v16, v17
	s_waitcnt vmcnt(0)
	v_add_f32_e32 v17, v18, v10
	v_sub_f32_e32 v10, v18, v10
	v_add_f32_e32 v18, v11, v19
	v_sub_f32_e32 v11, v11, v19
	v_add_f32_e32 v19, v9, v20
	v_sub_f32_e32 v9, v9, v20
	v_add_f32_e32 v20, v21, v23
	v_sub_f32_e32 v21, v21, v23
	v_add_f32_e32 v23, v22, v24
	v_sub_f32_e32 v22, v22, v24
	v_add_f32_e32 v24, v25, v28
	v_sub_f32_e32 v25, v25, v28
	v_add_f32_e32 v28, v27, v29
	v_sub_f32_e32 v27, v27, v29
	v_add_f32_e32 v29, v30, v32
	v_sub_f32_e32 v30, v30, v32
	v_add_f32_e32 v32, v31, v33
	v_sub_f32_e32 v31, v31, v33
	v_add_f32_e32 v33, v34, v36
	v_sub_f32_e32 v34, v34, v36
	v_add_f32_e32 v36, v35, v37
	v_sub_f32_e32 v35, v35, v37
	v_add_f32_e32 v37, v38, v40
	v_sub_f32_e32 v38, v38, v40
	v_add_f32_e32 v40, v39, v26
	v_sub_f32_e32 v26, v39, v26
	v_add_f32_e32 v39, v41, v13
	v_sub_f32_e32 v13, v41, v13
	v_add_f32_e32 v41, v12, v14
	v_sub_f32_e32 v12, v12, v14
	v_add_f32_e32 v14, v15, v17
	v_sub_f32_e32 v15, v15, v17
	v_add_f32_e32 v17, v16, v10
	v_sub_f32_e32 v10, v16, v10
	v_add_f32_e32 v16, v18, v20
	v_sub_f32_e32 v18, v18, v20
	v_add_f32_e32 v20, v19, v23
	v_sub_f32_e32 v19, v19, v23
	v_add_f32_e32 v23, v11, v21
	v_sub_f32_e32 v11, v11, v21
	v_add_f32_e32 v21, v9, v22
	v_sub_f32_e32 v9, v9, v22
	v_add_f32_e32 v22, v24, v29
	v_sub_f32_e32 v24, v24, v29
	v_add_f32_e32 v29, v28, v32
	v_sub_f32_e32 v28, v28, v32
	v_add_f32_e32 v32, v25, v30
	v_sub_f32_e32 v25, v25, v30
	v_add_f32_e32 v30, v27, v31
	v_sub_f32_e32 v27, v27, v31
	v_add_f32_e32 v31, v33, v37
	v_sub_f32_e32 v33, v33, v37
	v_add_f32_e32 v37, v36, v40
	v_sub_f32_e32 v36, v36, v40
	v_add_f32_e32 v40, v34, v38
	v_sub_f32_e32 v34, v34, v38
	v_add_f32_e32 v38, v35, v26
	v_sub_f32_e32 v26, v35, v26
	v_add_f32_e32 v35, v39, v14
	v_sub_f32_e32 v14, v39, v14
	v_add_f32_e32 v39, v41, v17
	v_sub_f32_e32 v17, v41, v17
	v_add_f32_e32 v41, v13, v15
	v_sub_f32_e32 v13, v13, v15
	v_add_f32_e32 v15, v12, v10
	v_sub_f32_e32 v10, v12, v10
	v_add_f32_e32 v12, v16, v22
	v_sub_f32_e32 v16, v16, v22
	v_add_f32_e32 v22, v20, v29
	v_sub_f32_e32 v20, v20, v29
	v_add_f32_e32 v29, v23, v32
	v_sub_f32_e32 v23, v23, v32
	v_add_f32_e32 v32, v21, v30
	v_sub_f32_e32 v21, v21, v30
	v_add_f32_e32 v30, v18, v24
	v_sub_f32_e32 v18, v18, v24
	v_add_f32_e32 v24, v19, v28
	v_sub_f32_e32 v19, v19, v28
	v_add_f32_e32 v28, v11, v25
	v_sub_f32_e32 v11, v11, v25
	v_add_f32_e32 v25, v9, v27
	v_sub_f32_e32 v9, v9, v27
	v_add_f32_e32 v27, v31, v35
	v_sub_f32_e32 v31, v31, v35
	v_add_f32_e32 v35, v37, v39
	v_sub_f32_e32 v37, v37, v39
	v_add_f32_e32 v39, v40, v41
	v_sub_f32_e32 v40, v40, v41
	v_add_f32_e32 v41, v38, v15
	v_sub_f32_e32 v15, v38, v15
	v_add_f32_e32 v38, v33, v14
	v_sub_f32_e32 v14, v33, v14
	v_add_f32_e32 v33, v36, v17
	v_sub_f32_e32 v17, v36, v17
	v_add_f32_e32 v36, v34, v13
	v_sub_f32_e32 v13, v34, v13
	v_add_f32_e32 v34, v26, v10
	v_sub_f32_e32 v10, v26, v10
	v_add_f32_e32 v26, v12, v27
	v_sub_f32_e32 v12, v12, v27
	v_add_f32_e32 v27, v22, v35
	ds_bpermute_b32 v43, v7, v27
	v_sub_f32_e32 v22, v22, v35
	v_add_f32_e32 v35, v29, v39
	v_sub_f32_e32 v29, v29, v39
	v_add_f32_e32 v39, v32, v41
	v_sub_f32_e32 v32, v32, v41
	v_add_f32_e32 v41, v30, v38
	s_waitcnt lgkmcnt(0)
	v_fmac_f32_e32 v43, v27, v1
	ds_bpermute_b32 v27, v7, v41
	v_sub_f32_e32 v30, v30, v38
	v_add_f32_e32 v38, v24, v33
	v_sub_f32_e32 v24, v24, v33
	v_add_f32_e32 v33, v28, v36
	v_sub_f32_e32 v28, v28, v36
	v_add_f32_e32 v36, v25, v34
	v_sub_f32_e32 v25, v25, v34
	v_add_f32_e32 v34, v16, v31
	v_sub_f32_e32 v16, v16, v31
	v_add_f32_e32 v31, v20, v37
	v_sub_f32_e32 v20, v20, v37
	v_add_f32_e32 v37, v23, v40
	v_sub_f32_e32 v23, v23, v40
	v_add_f32_e32 v40, v21, v15
	s_waitcnt lgkmcnt(0)
	v_fmac_f32_e32 v27, v41, v1
	ds_bpermute_b32 v41, v7, v40
	ds_bpermute_b32 v42, v7, v26
	v_sub_f32_e32 v15, v21, v15
	v_add_f32_e32 v21, v18, v14
	v_sub_f32_e32 v14, v18, v14
	s_waitcnt lgkmcnt(1)
	v_fmac_f32_e32 v41, v40, v1
	ds_bpermute_b32 v40, v7, v12
	s_waitcnt lgkmcnt(1)
	v_fmac_f32_e32 v42, v26, v1
	ds_bpermute_b32 v26, v7, v39
	v_add_f32_e32 v18, v19, v17
	v_sub_f32_e32 v17, v19, v17
	v_add_f32_e32 v19, v11, v13
	v_sub_f32_e32 v11, v11, v13
	v_add_f32_e32 v13, v9, v10
	v_sub_f32_e32 v9, v9, v10
	ds_bpermute_b32 v10, v7, v35
	ds_bpermute_b32 v45, v7, v33
	ds_bpermute_b32 v44, v7, v38
	s_waitcnt lgkmcnt(4)
	v_fmac_f32_e32 v40, v12, v1
	ds_bpermute_b32 v12, v7, v22
	s_waitcnt lgkmcnt(4)
	v_fmac_f32_e32 v26, v39, v1
	ds_bpermute_b32 v39, v7, v37
	s_waitcnt lgkmcnt(4)
	v_fmac_f32_e32 v10, v35, v1
	s_waitcnt lgkmcnt(3)
	v_fmac_f32_e32 v45, v33, v1
	ds_bpermute_b32 v33, v7, v36
	ds_bpermute_b32 v35, v7, v34
	s_waitcnt lgkmcnt(4)
	v_fmac_f32_e32 v44, v38, v1
	ds_bpermute_b32 v38, v7, v31
	s_waitcnt lgkmcnt(4)
	v_fmac_f32_e32 v12, v22, v1
	ds_bpermute_b32 v22, v7, v28
	s_waitcnt lgkmcnt(4)
	v_fmac_f32_e32 v39, v37, v1
	ds_bpermute_b32 v37, v7, v13
	s_waitcnt lgkmcnt(4)
	v_fmac_f32_e32 v33, v36, v1
	s_waitcnt lgkmcnt(3)
	v_fmac_f32_e32 v35, v34, v1
	ds_bpermute_b32 v34, v7, v18
	ds_bpermute_b32 v36, v7, v19
	s_waitcnt lgkmcnt(4)
	v_fmac_f32_e32 v38, v31, v1
	ds_bpermute_b32 v31, v7, v21
	s_waitcnt lgkmcnt(4)
	v_fmac_f32_e32 v22, v28, v1
	ds_bpermute_b32 v28, v7, v9
	s_waitcnt lgkmcnt(4)
	v_fmac_f32_e32 v37, v13, v1
	ds_bpermute_b32 v13, v7, v29
	s_waitcnt lgkmcnt(4)
	v_fmac_f32_e32 v34, v18, v1
	s_waitcnt lgkmcnt(3)
	v_fmac_f32_e32 v36, v19, v1
	ds_bpermute_b32 v18, v7, v32
	ds_bpermute_b32 v19, v7, v30
	s_waitcnt lgkmcnt(4)
	v_fmac_f32_e32 v31, v21, v1
	ds_bpermute_b32 v21, v7, v24
	s_waitcnt lgkmcnt(4)
	v_fmac_f32_e32 v28, v9, v1
	v_max3_f32 v9, |v42|, 0, |v43|
	v_max3_f32 v9, v9, |v10|, |v26|
	s_waitcnt lgkmcnt(3)
	v_fmac_f32_e32 v13, v29, v1
	ds_bpermute_b32 v29, v7, v16
	v_max3_f32 v9, v9, |v27|, |v44|
	s_waitcnt lgkmcnt(3)
	v_fmac_f32_e32 v18, v32, v1
	s_waitcnt lgkmcnt(2)
	v_fmac_f32_e32 v19, v30, v1
	ds_bpermute_b32 v30, v7, v20
	ds_bpermute_b32 v32, v7, v23
	v_max3_f32 v9, v9, |v45|, |v33|
	s_waitcnt lgkmcnt(3)
	v_fmac_f32_e32 v21, v24, v1
	ds_bpermute_b32 v24, v7, v25
	v_max3_f32 v9, v9, |v35|, |v38|
	v_max3_f32 v9, v9, |v39|, |v41|
	v_max3_f32 v9, v9, |v31|, |v34|
	s_waitcnt lgkmcnt(3)
	v_fmac_f32_e32 v29, v16, v1
	ds_bpermute_b32 v16, v7, v15
	v_max3_f32 v9, v9, |v36|, |v37|
	s_waitcnt lgkmcnt(3)
	v_fmac_f32_e32 v30, v20, v1
	s_waitcnt lgkmcnt(2)
	v_fmac_f32_e32 v32, v23, v1
	ds_bpermute_b32 v20, v7, v14
	ds_bpermute_b32 v23, v7, v17
	v_max3_f32 v9, v9, |v40|, |v12|
	s_waitcnt lgkmcnt(3)
	v_fmac_f32_e32 v24, v25, v1
	ds_bpermute_b32 v25, v7, v11
	v_max3_f32 v9, v9, |v13|, |v18|
	v_max3_f32 v9, v9, |v19|, |v21|
	v_max3_f32 v9, v9, |v22|, |v24|
	s_waitcnt lgkmcnt(3)
	v_fmac_f32_e32 v16, v15, v1
	v_max3_f32 v9, v9, |v29|, |v30|
	s_waitcnt lgkmcnt(2)
	v_fmac_f32_e32 v20, v14, v1
	s_waitcnt lgkmcnt(1)
	v_fmac_f32_e32 v23, v17, v1
	v_max3_f32 v9, v9, |v32|, |v16|
	s_waitcnt lgkmcnt(0)
	v_fmac_f32_e32 v25, v11, v1
	v_max3_f32 v9, v9, |v20|, |v23|
	v_max3_f32 v9, v9, |v25|, |v28|
	ds_bpermute_b32 v10, v7, v9
	s_and_saveexec_b64 s[6:7], s[4:5]
	s_cbranch_execz .LBB0_221
	s_waitcnt lgkmcnt(0)
	v_max_f32_e32 v10, v10, v10
	v_max_f32_e32 v9, v9, v9
	v_lshl_add_u64 v[12:13], s[16:17], 2, v[4:5]
	v_max_f32_e32 v9, v9, v10
	global_atomic_umax v[12:13], v9, off
	s_branch .LBB0_221

.LBB0_322:
	s_cmp_ge_i32 s46, s47
	s_cselect_b64 s[40:41], -1, 0
	s_cmp_lt_i32 s46, s47
	s_cselect_b64 s[0:1], -1, 0
	s_or_b64 vcc, s[18:19], s[0:1]
	v_cndmask_b32_e32 v100, 0, v100, vcc
	s_nor_b64 s[42:43], vcc, s[4:5]
	s_and_saveexec_b64 s[0:1], s[42:43]
	s_cbranch_execz .LBB0_326
	s_mov_b64 s[44:45], exec
	v_mbcnt_lo_u32_b32 v2, s44, 0
	v_mbcnt_hi_u32_b32 v2, s45, v2
	v_cmp_eq_u32_e32 vcc, 0, v2
	s_and_saveexec_b64 s[42:43], vcc
	s_cbranch_execz .LBB0_325
	s_bcnt1_i32_b64 s39, s[44:45]
	v_mov_b32_e32 v3, s39
	global_atomic_add v223, v1, v3, s[24:25] sc0
.LBB0_325:
	s_or_b64 exec, exec, s[42:43]
.LBB0_326:
	s_or_b64 exec, exec, s[0:1]
	s_mul_hi_i32 s43, s38, 0x2b00
	s_mul_i32 s42, s38, 0x2b00
	v_lshl_add_u64 v[94:95], s[42:43], 1, v[90:91]
	v_add_co_u32_e32 v2, vcc, 0x1000, v94
	global_load_dwordx4 v[86:89], v[94:95], off
	global_load_dwordx4 v[82:85], v[94:95], off offset:1024
	global_load_dwordx4 v[78:81], v[94:95], off offset:2048
	global_load_dwordx4 v[74:77], v[94:95], off offset:3072
	v_addc_co_u32_e32 v3, vcc, 0, v95, vcc
	global_load_dwordx4 v[70:73], v[2:3], off
	global_load_dwordx4 v[66:69], v[2:3], off offset:1024
	global_load_dwordx4 v[62:65], v[2:3], off offset:2048
	global_load_dwordx4 v[58:61], v[2:3], off offset:3072
	v_add_co_u32_e32 v2, vcc, 0x2000, v94
	v_mov_b32_e32 v4, 0
	s_nop 0
	v_addc_co_u32_e32 v3, vcc, 0, v95, vcc
	global_load_dwordx4 v[54:57], v[2:3], off
	global_load_dwordx4 v[50:53], v[2:3], off offset:1024
	global_load_dwordx4 v[46:49], v[2:3], off offset:2048
	global_load_dwordx4 v[42:45], v[2:3], off offset:3072
	v_add_co_u32_e32 v2, vcc, 0x3000, v94
	v_mov_b32_e32 v5, 0
	s_nop 0
	v_addc_co_u32_e32 v3, vcc, 0, v95, vcc
	global_load_dwordx4 v[38:41], v[2:3], off
	global_load_dwordx4 v[34:37], v[2:3], off offset:1024
	global_load_dwordx4 v[30:33], v[2:3], off offset:2048
	global_load_dwordx4 v[26:29], v[2:3], off offset:3072
	v_add_co_u32_e32 v2, vcc, 0x4000, v94
	s_nop 1
	v_addc_co_u32_e32 v3, vcc, 0, v95, vcc
	global_load_dwordx4 v[22:25], v[2:3], off
	global_load_dwordx4 v[18:21], v[2:3], off offset:1024
	global_load_dwordx4 v[14:17], v[2:3], off offset:2048
	global_load_dwordx4 v[10:13], v[2:3], off offset:3072
	v_add_co_u32_e32 v2, vcc, 0x5000, v94
	s_nop 1
	v_addc_co_u32_e32 v3, vcc, 0, v95, vcc
	global_load_dwordx4 v[6:9], v[2:3], off
	v_mov_b32_e32 v2, 0
	v_mov_b32_e32 v3, 0
	s_and_saveexec_b64 s[0:1], s[6:7]
	s_cbranch_execz .LBB0_328
	v_add_co_u32_e32 v2, vcc, 0x5000, v94
	s_nop 1
	v_addc_co_u32_e32 v3, vcc, 0, v95, vcc
	global_load_dwordx4 v[2:5], v[2:3], off offset:1024
.LBB0_328:
	s_or_b64 exec, exec, s[0:1]
	s_waitcnt vmcnt(20)
	v_readfirstlane_b32 s98, v223
	s_nop 1
	v_mov_b32_e32 v100, s98
	v_lshlrev_b32_e32 v94, 16, v86
	v_and_b32_e32 v86, 0xffff0000, v86
	v_lshlrev_b32_e32 v95, 16, v87
	v_and_b32_e32 v87, 0xffff0000, v87
	v_lshlrev_b32_e32 v101, 16, v88
	v_and_b32_e32 v88, 0xffff0000, v88
	v_lshlrev_b32_e32 v102, 16, v89
	v_and_b32_e32 v89, 0xffff0000, v89
	v_add_f32_e32 v103, v94, v86
	v_sub_f32_e32 v86, v94, v86
	v_add_f32_e32 v94, v95, v87
	v_sub_f32_e32 v87, v95, v87
	v_add_f32_e32 v95, v101, v88
	v_sub_f32_e32 v88, v101, v88
	v_add_f32_e32 v101, v102, v89
	v_sub_f32_e32 v89, v102, v89
	v_add_f32_e32 v102, v103, v94
	v_sub_f32_e32 v94, v103, v94
	v_add_f32_e32 v103, v86, v87
	v_sub_f32_e32 v86, v86, v87
	v_add_f32_e32 v87, v95, v101
	v_sub_f32_e32 v95, v95, v101
	v_add_f32_e32 v101, v88, v89
	v_sub_f32_e32 v88, v88, v89
	v_add_f32_e32 v89, v102, v87
	v_sub_f32_e32 v87, v102, v87
	v_add_f32_e32 v102, v103, v101
	v_sub_f32_e32 v101, v103, v101
	v_add_f32_e32 v103, v94, v95
	v_sub_f32_e32 v94, v94, v95
	v_add_f32_e32 v95, v86, v88
	v_sub_f32_e32 v86, v86, v88
	v_mov_b32_dpp v88, v89 quad_perm:[1,0,3,2] row_mask:0xf bank_mask:0xf bound_ctrl:1
	v_fmac_f32_e32 v88, v89, v96
	v_mov_b32_dpp v89, v102 quad_perm:[1,0,3,2] row_mask:0xf bank_mask:0xf bound_ctrl:1
	v_fmac_f32_e32 v89, v102, v96
	v_mov_b32_dpp v102, v103 quad_perm:[1,0,3,2] row_mask:0xf bank_mask:0xf bound_ctrl:1
	v_fmac_f32_e32 v102, v103, v96
	v_mov_b32_dpp v103, v95 quad_perm:[1,0,3,2] row_mask:0xf bank_mask:0xf bound_ctrl:1
	v_fmac_f32_e32 v103, v95, v96
	v_mov_b32_dpp v95, v87 quad_perm:[1,0,3,2] row_mask:0xf bank_mask:0xf bound_ctrl:1
	v_fmac_f32_e32 v95, v87, v96
	v_mov_b32_dpp v87, v101 quad_perm:[1,0,3,2] row_mask:0xf bank_mask:0xf bound_ctrl:1
	v_fmac_f32_e32 v87, v101, v96
	v_mov_b32_dpp v101, v94 quad_perm:[1,0,3,2] row_mask:0xf bank_mask:0xf bound_ctrl:1
	v_fmac_f32_e32 v101, v94, v96
	v_mov_b32_dpp v94, v86 quad_perm:[1,0,3,2] row_mask:0xf bank_mask:0xf bound_ctrl:1
	v_fmac_f32_e32 v94, v86, v96
	v_mov_b32_dpp v86, v88 quad_perm:[2,3,0,1] row_mask:0xf bank_mask:0xf bound_ctrl:1
	v_fmac_f32_e32 v86, v88, v97
	v_mov_b32_dpp v88, v89 quad_perm:[2,3,0,1] row_mask:0xf bank_mask:0xf bound_ctrl:1
	v_fmac_f32_e32 v88, v89, v97
	v_mov_b32_dpp v89, v102 quad_perm:[2,3,0,1] row_mask:0xf bank_mask:0xf bound_ctrl:1
	v_fmac_f32_e32 v89, v102, v97
	v_mov_b32_dpp v102, v103 quad_perm:[2,3,0,1] row_mask:0xf bank_mask:0xf bound_ctrl:1
	v_fmac_f32_e32 v102, v103, v97
	v_mov_b32_dpp v103, v95 quad_perm:[2,3,0,1] row_mask:0xf bank_mask:0xf bound_ctrl:1
	v_fmac_f32_e32 v103, v95, v97
	v_mov_b32_dpp v95, v87 quad_perm:[2,3,0,1] row_mask:0xf bank_mask:0xf bound_ctrl:1
	v_mov_b32_dpp v106, v94 quad_perm:[2,3,0,1] row_mask:0xf bank_mask:0xf bound_ctrl:1
	v_fmac_f32_e32 v95, v87, v97
	v_fmac_f32_e32 v106, v94, v97
	ds_swizzle_b32 v94, v102 offset:swizzle(SWAP,4)
	ds_swizzle_b32 v107, v103 offset:swizzle(SWAP,4)
	ds_swizzle_b32 v108, v95 offset:swizzle(SWAP,4)
	ds_swizzle_b32 v110, v106 offset:swizzle(SWAP,4)
	v_mov_b32_dpp v87, v101 quad_perm:[2,3,0,1] row_mask:0xf bank_mask:0xf bound_ctrl:1
	s_waitcnt lgkmcnt(3)
	v_fmac_f32_e32 v94, v102, v98
	s_waitcnt lgkmcnt(2)
	v_fmac_f32_e32 v107, v103, v98
	s_waitcnt lgkmcnt(1)
	v_fmac_f32_e32 v108, v95, v98
	s_waitcnt lgkmcnt(0)
	v_fmac_f32_e32 v110, v106, v98
	s_waitcnt vmcnt(19)
	v_lshlrev_b32_e32 v95, 16, v82
	v_and_b32_e32 v82, 0xffff0000, v82
	v_lshlrev_b32_e32 v102, 16, v83
	v_and_b32_e32 v83, 0xffff0000, v83
	v_lshlrev_b32_e32 v103, 16, v84
	v_and_b32_e32 v84, 0xffff0000, v84
	v_lshlrev_b32_e32 v106, 16, v85
	v_and_b32_e32 v85, 0xffff0000, v85
	v_add_f32_e32 v111, v95, v82
	v_sub_f32_e32 v82, v95, v82
	v_add_f32_e32 v95, v102, v83
	v_sub_f32_e32 v83, v102, v83
	v_add_f32_e32 v102, v103, v84
	v_sub_f32_e32 v84, v103, v84
	v_add_f32_e32 v103, v106, v85
	v_sub_f32_e32 v85, v106, v85
	v_add_f32_e32 v106, v111, v95
	v_sub_f32_e32 v95, v111, v95
	v_add_f32_e32 v111, v82, v83
	v_sub_f32_e32 v82, v82, v83
	v_add_f32_e32 v83, v102, v103
	v_sub_f32_e32 v102, v102, v103
	v_add_f32_e32 v103, v84, v85
	v_sub_f32_e32 v84, v84, v85
	v_add_f32_e32 v85, v106, v83
	v_sub_f32_e32 v83, v106, v83
	v_add_f32_e32 v106, v111, v103
	v_sub_f32_e32 v103, v111, v103
	v_add_f32_e32 v111, v95, v102
	v_sub_f32_e32 v95, v95, v102
	v_add_f32_e32 v102, v82, v84
	v_sub_f32_e32 v82, v82, v84
	v_mov_b32_dpp v84, v85 quad_perm:[1,0,3,2] row_mask:0xf bank_mask:0xf bound_ctrl:1
	v_fmac_f32_e32 v84, v85, v96
	v_mov_b32_dpp v85, v106 quad_perm:[1,0,3,2] row_mask:0xf bank_mask:0xf bound_ctrl:1
	v_fmac_f32_e32 v85, v106, v96
	v_mov_b32_dpp v106, v111 quad_perm:[1,0,3,2] row_mask:0xf bank_mask:0xf bound_ctrl:1
	v_fmac_f32_e32 v106, v111, v96
	v_mov_b32_dpp v111, v102 quad_perm:[1,0,3,2] row_mask:0xf bank_mask:0xf bound_ctrl:1
	v_fmac_f32_e32 v111, v102, v96
	v_mov_b32_dpp v102, v83 quad_perm:[1,0,3,2] row_mask:0xf bank_mask:0xf bound_ctrl:1
	v_fmac_f32_e32 v102, v83, v96
	v_mov_b32_dpp v83, v103 quad_perm:[1,0,3,2] row_mask:0xf bank_mask:0xf bound_ctrl:1
	v_fmac_f32_e32 v83, v103, v96
	v_mov_b32_dpp v103, v95 quad_perm:[1,0,3,2] row_mask:0xf bank_mask:0xf bound_ctrl:1
	v_fmac_f32_e32 v103, v95, v96
	v_mov_b32_dpp v95, v82 quad_perm:[1,0,3,2] row_mask:0xf bank_mask:0xf bound_ctrl:1
	v_fmac_f32_e32 v95, v82, v96
	v_mov_b32_dpp v82, v84 quad_perm:[2,3,0,1] row_mask:0xf bank_mask:0xf bound_ctrl:1
	v_fmac_f32_e32 v82, v84, v97
	v_mov_b32_dpp v84, v85 quad_perm:[2,3,0,1] row_mask:0xf bank_mask:0xf bound_ctrl:1
	v_fmac_f32_e32 v84, v85, v97
	v_mov_b32_dpp v85, v106 quad_perm:[2,3,0,1] row_mask:0xf bank_mask:0xf bound_ctrl:1
	v_fmac_f32_e32 v85, v106, v97
	v_mov_b32_dpp v106, v111 quad_perm:[2,3,0,1] row_mask:0xf bank_mask:0xf bound_ctrl:1
	v_fmac_f32_e32 v106, v111, v97
	v_mov_b32_dpp v111, v102 quad_perm:[2,3,0,1] row_mask:0xf bank_mask:0xf bound_ctrl:1
	v_fmac_f32_e32 v111, v102, v97
	v_mov_b32_dpp v102, v83 quad_perm:[2,3,0,1] row_mask:0xf bank_mask:0xf bound_ctrl:1
	v_mov_b32_dpp v114, v95 quad_perm:[2,3,0,1] row_mask:0xf bank_mask:0xf bound_ctrl:1
	v_fmac_f32_e32 v102, v83, v97
	v_fmac_f32_e32 v114, v95, v97
	ds_swizzle_b32 v95, v106 offset:swizzle(SWAP,4)
	ds_swizzle_b32 v115, v111 offset:swizzle(SWAP,4)
	ds_swizzle_b32 v116, v102 offset:swizzle(SWAP,4)
	ds_swizzle_b32 v118, v114 offset:swizzle(SWAP,4)
	v_fmac_f32_e32 v87, v101, v97
	s_waitcnt lgkmcnt(3)
	v_fmac_f32_e32 v95, v106, v98
	s_waitcnt lgkmcnt(2)
	v_fmac_f32_e32 v115, v111, v98
	s_waitcnt lgkmcnt(1)
	v_fmac_f32_e32 v116, v102, v98
	s_waitcnt lgkmcnt(0)
	v_fmac_f32_e32 v118, v114, v98
	s_waitcnt vmcnt(18)
	v_lshlrev_b32_e32 v102, 16, v78
	v_and_b32_e32 v78, 0xffff0000, v78
	v_lshlrev_b32_e32 v106, 16, v79
	v_and_b32_e32 v79, 0xffff0000, v79
	v_lshlrev_b32_e32 v111, 16, v80
	v_and_b32_e32 v80, 0xffff0000, v80
	v_lshlrev_b32_e32 v114, 16, v81
	v_and_b32_e32 v81, 0xffff0000, v81
	v_add_f32_e32 v119, v102, v78
	v_sub_f32_e32 v78, v102, v78
	v_add_f32_e32 v102, v106, v79
	v_sub_f32_e32 v79, v106, v79
	v_add_f32_e32 v106, v111, v80
	v_sub_f32_e32 v80, v111, v80
	v_add_f32_e32 v111, v114, v81
	v_sub_f32_e32 v81, v114, v81
	v_add_f32_e32 v114, v119, v102
	v_sub_f32_e32 v102, v119, v102
	v_add_f32_e32 v119, v78, v79
	v_sub_f32_e32 v78, v78, v79
	v_add_f32_e32 v79, v106, v111
	v_sub_f32_e32 v106, v106, v111
	v_add_f32_e32 v111, v80, v81
	v_sub_f32_e32 v80, v80, v81
	v_add_f32_e32 v81, v114, v79
	v_sub_f32_e32 v79, v114, v79
	v_add_f32_e32 v114, v119, v111
	v_sub_f32_e32 v111, v119, v111
	v_add_f32_e32 v119, v102, v106
	v_sub_f32_e32 v102, v102, v106
	v_add_f32_e32 v106, v78, v80
	v_sub_f32_e32 v78, v78, v80
	v_mov_b32_dpp v80, v81 quad_perm:[1,0,3,2] row_mask:0xf bank_mask:0xf bound_ctrl:1
	v_fmac_f32_e32 v80, v81, v96
	v_mov_b32_dpp v81, v114 quad_perm:[1,0,3,2] row_mask:0xf bank_mask:0xf bound_ctrl:1
	v_fmac_f32_e32 v81, v114, v96
	v_mov_b32_dpp v114, v119 quad_perm:[1,0,3,2] row_mask:0xf bank_mask:0xf bound_ctrl:1
	v_fmac_f32_e32 v114, v119, v96
	v_mov_b32_dpp v119, v106 quad_perm:[1,0,3,2] row_mask:0xf bank_mask:0xf bound_ctrl:1
	v_fmac_f32_e32 v119, v106, v96
	v_mov_b32_dpp v106, v79 quad_perm:[1,0,3,2] row_mask:0xf bank_mask:0xf bound_ctrl:1
	v_fmac_f32_e32 v106, v79, v96
	v_mov_b32_dpp v79, v111 quad_perm:[1,0,3,2] row_mask:0xf bank_mask:0xf bound_ctrl:1
	v_fmac_f32_e32 v79, v111, v96
	v_mov_b32_dpp v111, v102 quad_perm:[1,0,3,2] row_mask:0xf bank_mask:0xf bound_ctrl:1
	v_fmac_f32_e32 v111, v102, v96
	v_mov_b32_dpp v102, v78 quad_perm:[1,0,3,2] row_mask:0xf bank_mask:0xf bound_ctrl:1
	v_fmac_f32_e32 v102, v78, v96
	v_mov_b32_dpp v78, v80 quad_perm:[2,3,0,1] row_mask:0xf bank_mask:0xf bound_ctrl:1
	v_fmac_f32_e32 v78, v80, v97
	v_mov_b32_dpp v80, v81 quad_perm:[2,3,0,1] row_mask:0xf bank_mask:0xf bound_ctrl:1
	ds_swizzle_b32 v101, v86 offset:swizzle(SWAP,4)
	ds_swizzle_b32 v104, v88 offset:swizzle(SWAP,4)
	ds_swizzle_b32 v105, v89 offset:swizzle(SWAP,4)
	v_fmac_f32_e32 v80, v81, v97
	v_mov_b32_dpp v81, v114 quad_perm:[2,3,0,1] row_mask:0xf bank_mask:0xf bound_ctrl:1
	ds_swizzle_b32 v109, v87 offset:swizzle(SWAP,4)
	v_mov_b32_dpp v83, v103 quad_perm:[2,3,0,1] row_mask:0xf bank_mask:0xf bound_ctrl:1
	v_fmac_f32_e32 v81, v114, v97
	v_mov_b32_dpp v114, v119 quad_perm:[2,3,0,1] row_mask:0xf bank_mask:0xf bound_ctrl:1
	v_fmac_f32_e32 v83, v103, v97
	ds_swizzle_b32 v103, v82 offset:swizzle(SWAP,4)
	ds_swizzle_b32 v112, v84 offset:swizzle(SWAP,4)
	v_fmac_f32_e32 v114, v119, v97
	v_mov_b32_dpp v119, v106 quad_perm:[2,3,0,1] row_mask:0xf bank_mask:0xf bound_ctrl:1
	ds_swizzle_b32 v117, v83 offset:swizzle(SWAP,4)
	v_fmac_f32_e32 v119, v106, v97
	v_mov_b32_dpp v106, v79 quad_perm:[2,3,0,1] row_mask:0xf bank_mask:0xf bound_ctrl:1
	ds_swizzle_b32 v113, v85 offset:swizzle(SWAP,4)
	v_fmac_f32_e32 v106, v79, v97
	v_mov_b32_dpp v79, v111 quad_perm:[2,3,0,1] row_mask:0xf bank_mask:0xf bound_ctrl:1
	v_mov_b32_dpp v122, v102 quad_perm:[2,3,0,1] row_mask:0xf bank_mask:0xf bound_ctrl:1
	s_waitcnt lgkmcnt(7)
	v_fmac_f32_e32 v101, v86, v98
	s_waitcnt lgkmcnt(6)
	v_fmac_f32_e32 v104, v88, v98
	s_waitcnt lgkmcnt(5)
	v_fmac_f32_e32 v105, v89, v98
	v_fmac_f32_e32 v79, v111, v97
	ds_swizzle_b32 v111, v78 offset:swizzle(SWAP,4)
	ds_swizzle_b32 v120, v80 offset:swizzle(SWAP,4)
	ds_swizzle_b32 v121, v81 offset:swizzle(SWAP,4)
	v_fmac_f32_e32 v122, v102, v97
	ds_swizzle_b32 v102, v114 offset:swizzle(SWAP,4)
	s_waitcnt lgkmcnt(8)
	v_fmac_f32_e32 v109, v87, v98
	v_cvt_pk_bf16_f32 v88, v101, v104
	v_cvt_pk_bf16_f32 v89, v105, v94
	v_max_f32_e64 v101, |v101|, |v104|
	v_max_f32_e64 v94, |v105|, |v94|
	s_waitcnt lgkmcnt(7)
	v_fmac_f32_e32 v103, v82, v98
	s_waitcnt lgkmcnt(6)
	v_fmac_f32_e32 v112, v84, v98
	v_max3_f32 v94, v101, 0, v94
	v_max_f32_e64 v101, |v109|, |v110|
	v_cvt_pk_bf16_f32 v86, v107, v108
	v_cvt_pk_bf16_f32 v87, v109, v110
	s_waitcnt lgkmcnt(5)
	v_fmac_f32_e32 v117, v83, v98
	v_cvt_pk_bf16_f32 v84, v103, v112
	v_max3_f32 v101, |v107|, |v108|, v101
	v_max_f32_e64 v103, |v103|, |v112|
	s_waitcnt lgkmcnt(4)
	v_fmac_f32_e32 v113, v85, v98
	v_max3_f32 v94, v94, v101, v103
	v_max_f32_e64 v101, |v117|, |v118|
	v_cvt_pk_bf16_f32 v85, v113, v95
	s_waitcnt lgkmcnt(3)
	v_fmac_f32_e32 v111, v78, v98
	s_waitcnt lgkmcnt(2)
	v_fmac_f32_e32 v120, v80, v98
	s_waitcnt lgkmcnt(1)
	v_fmac_f32_e32 v121, v81, v98
	s_waitcnt lgkmcnt(0)
	v_fmac_f32_e32 v102, v114, v98
	v_max_f32_e64 v95, |v113|, |v95|
	v_max3_f32 v101, |v115|, |v116|, v101
	v_max3_f32 v94, v94, v95, v101
	v_max_f32_e64 v95, |v111|, |v120|
	v_max_f32_e64 v101, |v121|, |v102|
	v_cvt_pk_bf16_f32 v82, v115, v116
	v_cvt_pk_bf16_f32 v83, v117, v118
	v_cvt_pk_bf16_f32 v80, v111, v120
	v_cvt_pk_bf16_f32 v81, v121, v102
	v_max3_f32 v94, v94, v95, v101
	s_waitcnt vmcnt(17)
	v_lshlrev_b32_e32 v101, 16, v74
	v_and_b32_e32 v74, 0xffff0000, v74
	v_lshlrev_b32_e32 v102, 16, v75
	v_and_b32_e32 v75, 0xffff0000, v75
	v_lshlrev_b32_e32 v103, 16, v76
	v_and_b32_e32 v76, 0xffff0000, v76
	v_lshlrev_b32_e32 v104, 16, v77
	v_and_b32_e32 v77, 0xffff0000, v77
	v_add_f32_e32 v105, v101, v74
	v_sub_f32_e32 v74, v101, v74
	v_add_f32_e32 v101, v102, v75
	v_sub_f32_e32 v75, v102, v75
	v_add_f32_e32 v102, v103, v76
	v_sub_f32_e32 v76, v103, v76
	v_add_f32_e32 v103, v104, v77
	v_sub_f32_e32 v77, v104, v77
	v_add_f32_e32 v104, v105, v101
	v_sub_f32_e32 v101, v105, v101
	v_add_f32_e32 v105, v74, v75
	v_sub_f32_e32 v74, v74, v75
	v_add_f32_e32 v75, v102, v103
	v_sub_f32_e32 v102, v102, v103
	v_add_f32_e32 v103, v76, v77
	v_sub_f32_e32 v76, v76, v77
	v_add_f32_e32 v77, v104, v75
	v_sub_f32_e32 v75, v104, v75
	v_add_f32_e32 v104, v105, v103
	v_sub_f32_e32 v103, v105, v103
	v_add_f32_e32 v105, v101, v102
	v_sub_f32_e32 v101, v101, v102
	v_add_f32_e32 v102, v74, v76
	v_sub_f32_e32 v74, v74, v76
	v_mov_b32_dpp v76, v77 quad_perm:[1,0,3,2] row_mask:0xf bank_mask:0xf bound_ctrl:1
	v_fmac_f32_e32 v76, v77, v96
	v_mov_b32_dpp v77, v104 quad_perm:[1,0,3,2] row_mask:0xf bank_mask:0xf bound_ctrl:1
	v_fmac_f32_e32 v77, v104, v96
	v_mov_b32_dpp v104, v105 quad_perm:[1,0,3,2] row_mask:0xf bank_mask:0xf bound_ctrl:1
	v_fmac_f32_e32 v104, v105, v96
	v_mov_b32_dpp v105, v102 quad_perm:[1,0,3,2] row_mask:0xf bank_mask:0xf bound_ctrl:1
	v_fmac_f32_e32 v105, v102, v96
	v_mov_b32_dpp v102, v75 quad_perm:[1,0,3,2] row_mask:0xf bank_mask:0xf bound_ctrl:1
	v_fmac_f32_e32 v102, v75, v96
	v_mov_b32_dpp v75, v103 quad_perm:[1,0,3,2] row_mask:0xf bank_mask:0xf bound_ctrl:1
	v_fmac_f32_e32 v75, v103, v96
	v_mov_b32_dpp v103, v101 quad_perm:[1,0,3,2] row_mask:0xf bank_mask:0xf bound_ctrl:1
	v_fmac_f32_e32 v103, v101, v96
	v_mov_b32_dpp v101, v74 quad_perm:[1,0,3,2] row_mask:0xf bank_mask:0xf bound_ctrl:1
	v_fmac_f32_e32 v101, v74, v96
	v_mov_b32_dpp v74, v76 quad_perm:[2,3,0,1] row_mask:0xf bank_mask:0xf bound_ctrl:1
	v_fmac_f32_e32 v74, v76, v97
	v_mov_b32_dpp v76, v77 quad_perm:[2,3,0,1] row_mask:0xf bank_mask:0xf bound_ctrl:1
	ds_swizzle_b32 v124, v106 offset:swizzle(SWAP,4)
	v_fmac_f32_e32 v76, v77, v97
	v_mov_b32_dpp v77, v104 quad_perm:[2,3,0,1] row_mask:0xf bank_mask:0xf bound_ctrl:1
	v_fmac_f32_e32 v77, v104, v97
	v_mov_b32_dpp v104, v105 quad_perm:[2,3,0,1] row_mask:0xf bank_mask:0xf bound_ctrl:1
	v_fmac_f32_e32 v104, v105, v97
	v_mov_b32_dpp v105, v102 quad_perm:[2,3,0,1] row_mask:0xf bank_mask:0xf bound_ctrl:1
	v_fmac_f32_e32 v105, v102, v97
	v_mov_b32_dpp v102, v75 quad_perm:[2,3,0,1] row_mask:0xf bank_mask:0xf bound_ctrl:1
	ds_swizzle_b32 v125, v79 offset:swizzle(SWAP,4)
	ds_swizzle_b32 v126, v122 offset:swizzle(SWAP,4)
	v_fmac_f32_e32 v102, v75, v97
	v_mov_b32_dpp v75, v103 quad_perm:[2,3,0,1] row_mask:0xf bank_mask:0xf bound_ctrl:1
	v_mov_b32_dpp v108, v101 quad_perm:[2,3,0,1] row_mask:0xf bank_mask:0xf bound_ctrl:1
	ds_swizzle_b32 v123, v119 offset:swizzle(SWAP,4)
	s_waitcnt lgkmcnt(3)
	v_fmac_f32_e32 v124, v106, v98
	v_fmac_f32_e32 v75, v103, v97
	ds_swizzle_b32 v103, v74 offset:swizzle(SWAP,4)
	ds_swizzle_b32 v106, v76 offset:swizzle(SWAP,4)
	v_fmac_f32_e32 v108, v101, v97
	ds_swizzle_b32 v107, v77 offset:swizzle(SWAP,4)
	ds_swizzle_b32 v101, v104 offset:swizzle(SWAP,4)
	ds_swizzle_b32 v110, v102 offset:swizzle(SWAP,4)
	ds_swizzle_b32 v111, v75 offset:swizzle(SWAP,4)
	ds_swizzle_b32 v112, v108 offset:swizzle(SWAP,4)
	ds_swizzle_b32 v109, v105 offset:swizzle(SWAP,4)
	s_waitcnt lgkmcnt(10)
	v_fmac_f32_e32 v125, v79, v98
	s_waitcnt lgkmcnt(9)
	v_fmac_f32_e32 v126, v122, v98
	s_waitcnt lgkmcnt(8)
	v_fmac_f32_e32 v123, v119, v98
	v_max_f32_e64 v95, |v125|, |v126|
	s_waitcnt lgkmcnt(7)
	v_fmac_f32_e32 v103, v74, v98
	s_waitcnt lgkmcnt(6)
	v_fmac_f32_e32 v106, v76, v98
	v_max3_f32 v95, |v123|, |v124|, v95
	s_waitcnt lgkmcnt(5)
	v_fmac_f32_e32 v107, v77, v98
	s_waitcnt lgkmcnt(4)
	v_fmac_f32_e32 v101, v104, v98
	s_waitcnt lgkmcnt(3)
	v_fmac_f32_e32 v110, v102, v98
	s_waitcnt lgkmcnt(2)
	v_fmac_f32_e32 v111, v75, v98
	s_waitcnt lgkmcnt(1)
	v_fmac_f32_e32 v112, v108, v98
	v_max_f32_e64 v102, |v103|, |v106|
	v_cvt_pk_bf16_f32 v78, v123, v124
	v_cvt_pk_bf16_f32 v79, v125, v126
	s_waitcnt lgkmcnt(0)
	v_fmac_f32_e32 v109, v105, v98
	v_cvt_pk_bf16_f32 v76, v103, v106
	v_cvt_pk_bf16_f32 v77, v107, v101
	v_max3_f32 v94, v94, v95, v102
	v_max_f32_e64 v95, |v107|, |v101|
	v_max_f32_e64 v101, |v111|, |v112|
	v_max3_f32 v101, |v109|, |v110|, v101
	v_max3_f32 v94, v94, v95, v101
	v_cvt_pk_bf16_f32 v74, v109, v110
	v_cvt_pk_bf16_f32 v75, v111, v112
	s_waitcnt vmcnt(16)
	v_lshlrev_b32_e32 v95, 16, v70
	v_and_b32_e32 v70, 0xffff0000, v70
	v_lshlrev_b32_e32 v101, 16, v71
	v_and_b32_e32 v71, 0xffff0000, v71
	v_lshlrev_b32_e32 v102, 16, v72
	v_and_b32_e32 v72, 0xffff0000, v72
	v_lshlrev_b32_e32 v103, 16, v73
	v_and_b32_e32 v73, 0xffff0000, v73
	v_add_f32_e32 v104, v95, v70
	v_sub_f32_e32 v70, v95, v70
	v_add_f32_e32 v95, v101, v71
	v_sub_f32_e32 v71, v101, v71
	v_add_f32_e32 v101, v102, v72
	v_sub_f32_e32 v72, v102, v72
	v_add_f32_e32 v102, v103, v73
	v_sub_f32_e32 v73, v103, v73
	v_add_f32_e32 v103, v104, v95
	v_sub_f32_e32 v95, v104, v95
	v_add_f32_e32 v104, v70, v71
	v_sub_f32_e32 v70, v70, v71
	v_add_f32_e32 v71, v101, v102
	v_sub_f32_e32 v101, v101, v102
	v_add_f32_e32 v102, v72, v73
	v_sub_f32_e32 v72, v72, v73
	v_add_f32_e32 v73, v103, v71
	v_sub_f32_e32 v71, v103, v71
	v_add_f32_e32 v103, v104, v102
	v_sub_f32_e32 v102, v104, v102
	v_add_f32_e32 v104, v95, v101
	v_sub_f32_e32 v95, v95, v101
	v_add_f32_e32 v101, v70, v72
	v_sub_f32_e32 v70, v70, v72
	v_mov_b32_dpp v72, v73 quad_perm:[1,0,3,2] row_mask:0xf bank_mask:0xf bound_ctrl:1
	v_fmac_f32_e32 v72, v73, v96
	v_mov_b32_dpp v73, v103 quad_perm:[1,0,3,2] row_mask:0xf bank_mask:0xf bound_ctrl:1
	v_fmac_f32_e32 v73, v103, v96
	v_mov_b32_dpp v103, v104 quad_perm:[1,0,3,2] row_mask:0xf bank_mask:0xf bound_ctrl:1
	v_fmac_f32_e32 v103, v104, v96
	v_mov_b32_dpp v104, v101 quad_perm:[1,0,3,2] row_mask:0xf bank_mask:0xf bound_ctrl:1
	v_fmac_f32_e32 v104, v101, v96
	v_mov_b32_dpp v101, v71 quad_perm:[1,0,3,2] row_mask:0xf bank_mask:0xf bound_ctrl:1
	v_fmac_f32_e32 v101, v71, v96
	v_mov_b32_dpp v71, v102 quad_perm:[1,0,3,2] row_mask:0xf bank_mask:0xf bound_ctrl:1
	v_fmac_f32_e32 v71, v102, v96
	v_mov_b32_dpp v102, v95 quad_perm:[1,0,3,2] row_mask:0xf bank_mask:0xf bound_ctrl:1
	v_fmac_f32_e32 v102, v95, v96
	v_mov_b32_dpp v95, v70 quad_perm:[1,0,3,2] row_mask:0xf bank_mask:0xf bound_ctrl:1
	v_fmac_f32_e32 v95, v70, v96
	v_mov_b32_dpp v70, v72 quad_perm:[2,3,0,1] row_mask:0xf bank_mask:0xf bound_ctrl:1
	v_fmac_f32_e32 v70, v72, v97
	v_mov_b32_dpp v72, v73 quad_perm:[2,3,0,1] row_mask:0xf bank_mask:0xf bound_ctrl:1
	v_fmac_f32_e32 v72, v73, v97
	v_mov_b32_dpp v73, v103 quad_perm:[2,3,0,1] row_mask:0xf bank_mask:0xf bound_ctrl:1
	v_fmac_f32_e32 v73, v103, v97
	v_mov_b32_dpp v103, v104 quad_perm:[2,3,0,1] row_mask:0xf bank_mask:0xf bound_ctrl:1
	v_fmac_f32_e32 v103, v104, v97
	v_mov_b32_dpp v104, v101 quad_perm:[2,3,0,1] row_mask:0xf bank_mask:0xf bound_ctrl:1
	v_fmac_f32_e32 v104, v101, v97
	v_mov_b32_dpp v101, v71 quad_perm:[2,3,0,1] row_mask:0xf bank_mask:0xf bound_ctrl:1
	v_mov_b32_dpp v107, v95 quad_perm:[2,3,0,1] row_mask:0xf bank_mask:0xf bound_ctrl:1
	v_fmac_f32_e32 v101, v71, v97
	v_fmac_f32_e32 v107, v95, v97
	ds_swizzle_b32 v95, v103 offset:swizzle(SWAP,4)
	ds_swizzle_b32 v108, v104 offset:swizzle(SWAP,4)
	ds_swizzle_b32 v109, v101 offset:swizzle(SWAP,4)
	ds_swizzle_b32 v111, v107 offset:swizzle(SWAP,4)
	v_mov_b32_dpp v71, v102 quad_perm:[2,3,0,1] row_mask:0xf bank_mask:0xf bound_ctrl:1
	s_waitcnt lgkmcnt(3)
	v_fmac_f32_e32 v95, v103, v98
	s_waitcnt lgkmcnt(2)
	v_fmac_f32_e32 v108, v104, v98
	s_waitcnt lgkmcnt(1)
	v_fmac_f32_e32 v109, v101, v98
	s_waitcnt lgkmcnt(0)
	v_fmac_f32_e32 v111, v107, v98
	s_waitcnt vmcnt(15)
	v_lshlrev_b32_e32 v101, 16, v66
	v_and_b32_e32 v66, 0xffff0000, v66
	v_lshlrev_b32_e32 v103, 16, v67
	v_and_b32_e32 v67, 0xffff0000, v67
	v_lshlrev_b32_e32 v104, 16, v68
	v_and_b32_e32 v68, 0xffff0000, v68
	v_lshlrev_b32_e32 v107, 16, v69
	v_and_b32_e32 v69, 0xffff0000, v69
	v_add_f32_e32 v112, v101, v66
	v_sub_f32_e32 v66, v101, v66
	v_add_f32_e32 v101, v103, v67
	v_sub_f32_e32 v67, v103, v67
	v_add_f32_e32 v103, v104, v68
	v_sub_f32_e32 v68, v104, v68
	v_add_f32_e32 v104, v107, v69
	v_sub_f32_e32 v69, v107, v69
	v_add_f32_e32 v107, v112, v101
	v_sub_f32_e32 v101, v112, v101
	v_add_f32_e32 v112, v66, v67
	v_sub_f32_e32 v66, v66, v67
	v_add_f32_e32 v67, v103, v104
	v_sub_f32_e32 v103, v103, v104
	v_add_f32_e32 v104, v68, v69
	v_sub_f32_e32 v68, v68, v69
	v_add_f32_e32 v69, v107, v67
	v_sub_f32_e32 v67, v107, v67
	v_add_f32_e32 v107, v112, v104
	v_sub_f32_e32 v104, v112, v104
	v_add_f32_e32 v112, v101, v103
	v_sub_f32_e32 v101, v101, v103
	v_add_f32_e32 v103, v66, v68
	v_sub_f32_e32 v66, v66, v68
	v_mov_b32_dpp v68, v69 quad_perm:[1,0,3,2] row_mask:0xf bank_mask:0xf bound_ctrl:1
	v_fmac_f32_e32 v68, v69, v96
	v_mov_b32_dpp v69, v107 quad_perm:[1,0,3,2] row_mask:0xf bank_mask:0xf bound_ctrl:1
	v_fmac_f32_e32 v69, v107, v96
	v_mov_b32_dpp v107, v112 quad_perm:[1,0,3,2] row_mask:0xf bank_mask:0xf bound_ctrl:1
	v_fmac_f32_e32 v107, v112, v96
	v_mov_b32_dpp v112, v103 quad_perm:[1,0,3,2] row_mask:0xf bank_mask:0xf bound_ctrl:1
	v_fmac_f32_e32 v112, v103, v96
	v_mov_b32_dpp v103, v67 quad_perm:[1,0,3,2] row_mask:0xf bank_mask:0xf bound_ctrl:1
	v_fmac_f32_e32 v103, v67, v96
	v_mov_b32_dpp v67, v104 quad_perm:[1,0,3,2] row_mask:0xf bank_mask:0xf bound_ctrl:1
	v_fmac_f32_e32 v67, v104, v96
	v_mov_b32_dpp v104, v101 quad_perm:[1,0,3,2] row_mask:0xf bank_mask:0xf bound_ctrl:1
	v_fmac_f32_e32 v104, v101, v96
	v_mov_b32_dpp v101, v66 quad_perm:[1,0,3,2] row_mask:0xf bank_mask:0xf bound_ctrl:1
	v_fmac_f32_e32 v101, v66, v96
	v_mov_b32_dpp v66, v68 quad_perm:[2,3,0,1] row_mask:0xf bank_mask:0xf bound_ctrl:1
	v_fmac_f32_e32 v66, v68, v97
	v_mov_b32_dpp v68, v69 quad_perm:[2,3,0,1] row_mask:0xf bank_mask:0xf bound_ctrl:1
	v_fmac_f32_e32 v68, v69, v97
	v_mov_b32_dpp v69, v107 quad_perm:[2,3,0,1] row_mask:0xf bank_mask:0xf bound_ctrl:1
	v_fmac_f32_e32 v69, v107, v97
	v_mov_b32_dpp v107, v112 quad_perm:[2,3,0,1] row_mask:0xf bank_mask:0xf bound_ctrl:1
	v_fmac_f32_e32 v107, v112, v97
	v_mov_b32_dpp v112, v103 quad_perm:[2,3,0,1] row_mask:0xf bank_mask:0xf bound_ctrl:1
	v_fmac_f32_e32 v112, v103, v97
	v_mov_b32_dpp v103, v67 quad_perm:[2,3,0,1] row_mask:0xf bank_mask:0xf bound_ctrl:1
	v_mov_b32_dpp v115, v101 quad_perm:[2,3,0,1] row_mask:0xf bank_mask:0xf bound_ctrl:1
	v_fmac_f32_e32 v103, v67, v97
	v_fmac_f32_e32 v115, v101, v97
	ds_swizzle_b32 v101, v107 offset:swizzle(SWAP,4)
	ds_swizzle_b32 v116, v112 offset:swizzle(SWAP,4)
	ds_swizzle_b32 v117, v103 offset:swizzle(SWAP,4)
	ds_swizzle_b32 v119, v115 offset:swizzle(SWAP,4)
	v_fmac_f32_e32 v71, v102, v97
	s_waitcnt lgkmcnt(3)
	v_fmac_f32_e32 v101, v107, v98
	s_waitcnt lgkmcnt(2)
	v_fmac_f32_e32 v116, v112, v98
	s_waitcnt lgkmcnt(1)
	v_fmac_f32_e32 v117, v103, v98
	s_waitcnt lgkmcnt(0)
	v_fmac_f32_e32 v119, v115, v98
	s_waitcnt vmcnt(14)
	v_lshlrev_b32_e32 v103, 16, v62
	v_and_b32_e32 v62, 0xffff0000, v62
	v_lshlrev_b32_e32 v107, 16, v63
	v_and_b32_e32 v63, 0xffff0000, v63
	v_lshlrev_b32_e32 v112, 16, v64
	v_and_b32_e32 v64, 0xffff0000, v64
	v_lshlrev_b32_e32 v115, 16, v65
	v_and_b32_e32 v65, 0xffff0000, v65
	v_add_f32_e32 v120, v103, v62
	v_sub_f32_e32 v62, v103, v62
	v_add_f32_e32 v103, v107, v63
	v_sub_f32_e32 v63, v107, v63
	v_add_f32_e32 v107, v112, v64
	v_sub_f32_e32 v64, v112, v64
	v_add_f32_e32 v112, v115, v65
	v_sub_f32_e32 v65, v115, v65
	v_add_f32_e32 v115, v120, v103
	v_sub_f32_e32 v103, v120, v103
	v_add_f32_e32 v120, v62, v63
	v_sub_f32_e32 v62, v62, v63
	v_add_f32_e32 v63, v107, v112
	v_sub_f32_e32 v107, v107, v112
	v_add_f32_e32 v112, v64, v65
	v_sub_f32_e32 v64, v64, v65
	v_add_f32_e32 v65, v115, v63
	v_sub_f32_e32 v63, v115, v63
	v_add_f32_e32 v115, v120, v112
	v_sub_f32_e32 v112, v120, v112
	v_add_f32_e32 v120, v103, v107
	v_sub_f32_e32 v103, v103, v107
	v_add_f32_e32 v107, v62, v64
	v_sub_f32_e32 v62, v62, v64
	v_mov_b32_dpp v64, v65 quad_perm:[1,0,3,2] row_mask:0xf bank_mask:0xf bound_ctrl:1
	v_fmac_f32_e32 v64, v65, v96
	v_mov_b32_dpp v65, v115 quad_perm:[1,0,3,2] row_mask:0xf bank_mask:0xf bound_ctrl:1
	v_fmac_f32_e32 v65, v115, v96
	v_mov_b32_dpp v115, v120 quad_perm:[1,0,3,2] row_mask:0xf bank_mask:0xf bound_ctrl:1
	v_fmac_f32_e32 v115, v120, v96
	v_mov_b32_dpp v120, v107 quad_perm:[1,0,3,2] row_mask:0xf bank_mask:0xf bound_ctrl:1
	v_fmac_f32_e32 v120, v107, v96
	v_mov_b32_dpp v107, v63 quad_perm:[1,0,3,2] row_mask:0xf bank_mask:0xf bound_ctrl:1
	v_fmac_f32_e32 v107, v63, v96
	v_mov_b32_dpp v63, v112 quad_perm:[1,0,3,2] row_mask:0xf bank_mask:0xf bound_ctrl:1
	v_fmac_f32_e32 v63, v112, v96
	v_mov_b32_dpp v112, v103 quad_perm:[1,0,3,2] row_mask:0xf bank_mask:0xf bound_ctrl:1
	v_fmac_f32_e32 v112, v103, v96
	v_mov_b32_dpp v103, v62 quad_perm:[1,0,3,2] row_mask:0xf bank_mask:0xf bound_ctrl:1
	v_fmac_f32_e32 v103, v62, v96
	v_mov_b32_dpp v62, v64 quad_perm:[2,3,0,1] row_mask:0xf bank_mask:0xf bound_ctrl:1
	v_fmac_f32_e32 v62, v64, v97
	v_mov_b32_dpp v64, v65 quad_perm:[2,3,0,1] row_mask:0xf bank_mask:0xf bound_ctrl:1
	ds_swizzle_b32 v102, v70 offset:swizzle(SWAP,4)
	ds_swizzle_b32 v105, v72 offset:swizzle(SWAP,4)
	ds_swizzle_b32 v106, v73 offset:swizzle(SWAP,4)
	v_fmac_f32_e32 v64, v65, v97
	v_mov_b32_dpp v65, v115 quad_perm:[2,3,0,1] row_mask:0xf bank_mask:0xf bound_ctrl:1
	ds_swizzle_b32 v110, v71 offset:swizzle(SWAP,4)
	v_mov_b32_dpp v67, v104 quad_perm:[2,3,0,1] row_mask:0xf bank_mask:0xf bound_ctrl:1
	v_fmac_f32_e32 v65, v115, v97
	v_mov_b32_dpp v115, v120 quad_perm:[2,3,0,1] row_mask:0xf bank_mask:0xf bound_ctrl:1
	v_fmac_f32_e32 v67, v104, v97
	ds_swizzle_b32 v104, v66 offset:swizzle(SWAP,4)
	ds_swizzle_b32 v113, v68 offset:swizzle(SWAP,4)
	v_fmac_f32_e32 v115, v120, v97
	v_mov_b32_dpp v120, v107 quad_perm:[2,3,0,1] row_mask:0xf bank_mask:0xf bound_ctrl:1
	ds_swizzle_b32 v114, v69 offset:swizzle(SWAP,4)
	ds_swizzle_b32 v118, v67 offset:swizzle(SWAP,4)
	v_fmac_f32_e32 v120, v107, v97
	v_mov_b32_dpp v107, v63 quad_perm:[2,3,0,1] row_mask:0xf bank_mask:0xf bound_ctrl:1
	v_fmac_f32_e32 v107, v63, v97
	v_mov_b32_dpp v63, v112 quad_perm:[2,3,0,1] row_mask:0xf bank_mask:0xf bound_ctrl:1
	v_mov_b32_dpp v123, v103 quad_perm:[2,3,0,1] row_mask:0xf bank_mask:0xf bound_ctrl:1
	s_waitcnt lgkmcnt(7)
	v_fmac_f32_e32 v102, v70, v98
	s_waitcnt lgkmcnt(6)
	v_fmac_f32_e32 v105, v72, v98
	s_waitcnt lgkmcnt(5)
	v_fmac_f32_e32 v106, v73, v98
	v_fmac_f32_e32 v63, v112, v97
	ds_swizzle_b32 v112, v62 offset:swizzle(SWAP,4)
	ds_swizzle_b32 v121, v64 offset:swizzle(SWAP,4)
	ds_swizzle_b32 v122, v65 offset:swizzle(SWAP,4)
	v_fmac_f32_e32 v123, v103, v97
	ds_swizzle_b32 v103, v115 offset:swizzle(SWAP,4)
	s_waitcnt lgkmcnt(8)
	v_fmac_f32_e32 v110, v71, v98
	v_cvt_pk_bf16_f32 v72, v102, v105
	v_cvt_pk_bf16_f32 v73, v106, v95
	v_max_f32_e64 v102, |v102|, |v105|
	v_max_f32_e64 v95, |v106|, |v95|
	s_waitcnt lgkmcnt(7)
	v_fmac_f32_e32 v104, v66, v98
	s_waitcnt lgkmcnt(6)
	v_fmac_f32_e32 v113, v68, v98
	v_max3_f32 v94, v94, v102, v95
	v_max_f32_e64 v95, |v110|, |v111|
	s_waitcnt lgkmcnt(5)
	v_fmac_f32_e32 v114, v69, v98
	s_waitcnt lgkmcnt(4)
	v_fmac_f32_e32 v118, v67, v98
	v_max3_f32 v95, |v108|, |v109|, v95
	v_max_f32_e64 v102, |v104|, |v113|
	v_cvt_pk_bf16_f32 v70, v108, v109
	v_cvt_pk_bf16_f32 v71, v110, v111
	v_cvt_pk_bf16_f32 v68, v104, v113
	v_cvt_pk_bf16_f32 v69, v114, v101
	v_max3_f32 v94, v94, v95, v102
	v_max_f32_e64 v95, |v114|, |v101|
	v_max_f32_e64 v101, |v118|, |v119|
	s_waitcnt lgkmcnt(3)
	v_fmac_f32_e32 v112, v62, v98
	s_waitcnt lgkmcnt(2)
	v_fmac_f32_e32 v121, v64, v98
	s_waitcnt lgkmcnt(1)
	v_fmac_f32_e32 v122, v65, v98
	s_waitcnt lgkmcnt(0)
	v_fmac_f32_e32 v103, v115, v98
	v_max3_f32 v101, |v116|, |v117|, v101
	v_max3_f32 v94, v94, v95, v101
	v_max_f32_e64 v95, |v112|, |v121|
	v_max_f32_e64 v101, |v122|, |v103|
	v_cvt_pk_bf16_f32 v66, v116, v117
	v_cvt_pk_bf16_f32 v67, v118, v119
	v_cvt_pk_bf16_f32 v64, v112, v121
	v_cvt_pk_bf16_f32 v65, v122, v103
	v_max3_f32 v94, v94, v95, v101
	s_waitcnt vmcnt(13)
	v_lshlrev_b32_e32 v101, 16, v58
	v_and_b32_e32 v58, 0xffff0000, v58
	v_lshlrev_b32_e32 v102, 16, v59
	v_and_b32_e32 v59, 0xffff0000, v59
	v_lshlrev_b32_e32 v103, 16, v60
	v_and_b32_e32 v60, 0xffff0000, v60
	v_lshlrev_b32_e32 v104, 16, v61
	v_and_b32_e32 v61, 0xffff0000, v61
	v_add_f32_e32 v105, v101, v58
	v_sub_f32_e32 v58, v101, v58
	v_add_f32_e32 v101, v102, v59
	v_sub_f32_e32 v59, v102, v59
	v_add_f32_e32 v102, v103, v60
	v_sub_f32_e32 v60, v103, v60
	v_add_f32_e32 v103, v104, v61
	v_sub_f32_e32 v61, v104, v61
	v_add_f32_e32 v104, v105, v101
	v_sub_f32_e32 v101, v105, v101
	v_add_f32_e32 v105, v58, v59
	v_sub_f32_e32 v58, v58, v59
	v_add_f32_e32 v59, v102, v103
	v_sub_f32_e32 v102, v102, v103
	v_add_f32_e32 v103, v60, v61
	v_sub_f32_e32 v60, v60, v61
	v_add_f32_e32 v61, v104, v59
	v_sub_f32_e32 v59, v104, v59
	v_add_f32_e32 v104, v105, v103
	v_sub_f32_e32 v103, v105, v103
	v_add_f32_e32 v105, v101, v102
	v_sub_f32_e32 v101, v101, v102
	v_add_f32_e32 v102, v58, v60
	v_sub_f32_e32 v58, v58, v60
	v_mov_b32_dpp v60, v61 quad_perm:[1,0,3,2] row_mask:0xf bank_mask:0xf bound_ctrl:1
	v_fmac_f32_e32 v60, v61, v96
	v_mov_b32_dpp v61, v104 quad_perm:[1,0,3,2] row_mask:0xf bank_mask:0xf bound_ctrl:1
	v_fmac_f32_e32 v61, v104, v96
	v_mov_b32_dpp v104, v105 quad_perm:[1,0,3,2] row_mask:0xf bank_mask:0xf bound_ctrl:1
	v_fmac_f32_e32 v104, v105, v96
	v_mov_b32_dpp v105, v102 quad_perm:[1,0,3,2] row_mask:0xf bank_mask:0xf bound_ctrl:1
	v_fmac_f32_e32 v105, v102, v96
	v_mov_b32_dpp v102, v59 quad_perm:[1,0,3,2] row_mask:0xf bank_mask:0xf bound_ctrl:1
	v_fmac_f32_e32 v102, v59, v96
	v_mov_b32_dpp v59, v103 quad_perm:[1,0,3,2] row_mask:0xf bank_mask:0xf bound_ctrl:1
	v_fmac_f32_e32 v59, v103, v96
	v_mov_b32_dpp v103, v101 quad_perm:[1,0,3,2] row_mask:0xf bank_mask:0xf bound_ctrl:1
	v_fmac_f32_e32 v103, v101, v96
	v_mov_b32_dpp v101, v58 quad_perm:[1,0,3,2] row_mask:0xf bank_mask:0xf bound_ctrl:1
	v_fmac_f32_e32 v101, v58, v96
	v_mov_b32_dpp v58, v60 quad_perm:[2,3,0,1] row_mask:0xf bank_mask:0xf bound_ctrl:1
	v_fmac_f32_e32 v58, v60, v97
	v_mov_b32_dpp v60, v61 quad_perm:[2,3,0,1] row_mask:0xf bank_mask:0xf bound_ctrl:1
	v_fmac_f32_e32 v60, v61, v97
	v_mov_b32_dpp v61, v104 quad_perm:[2,3,0,1] row_mask:0xf bank_mask:0xf bound_ctrl:1
	ds_swizzle_b32 v125, v107 offset:swizzle(SWAP,4)
	v_fmac_f32_e32 v61, v104, v97
	v_mov_b32_dpp v104, v105 quad_perm:[2,3,0,1] row_mask:0xf bank_mask:0xf bound_ctrl:1
	v_fmac_f32_e32 v104, v105, v97
	v_mov_b32_dpp v105, v102 quad_perm:[2,3,0,1] row_mask:0xf bank_mask:0xf bound_ctrl:1
	v_fmac_f32_e32 v105, v102, v97
	v_mov_b32_dpp v102, v59 quad_perm:[2,3,0,1] row_mask:0xf bank_mask:0xf bound_ctrl:1
	ds_swizzle_b32 v126, v63 offset:swizzle(SWAP,4)
	ds_swizzle_b32 v127, v123 offset:swizzle(SWAP,4)
	v_fmac_f32_e32 v102, v59, v97
	v_mov_b32_dpp v59, v103 quad_perm:[2,3,0,1] row_mask:0xf bank_mask:0xf bound_ctrl:1
	v_mov_b32_dpp v108, v101 quad_perm:[2,3,0,1] row_mask:0xf bank_mask:0xf bound_ctrl:1
	ds_swizzle_b32 v124, v120 offset:swizzle(SWAP,4)
	v_fmac_f32_e32 v59, v103, v97
	ds_swizzle_b32 v103, v58 offset:swizzle(SWAP,4)
	ds_swizzle_b32 v106, v60 offset:swizzle(SWAP,4)
	v_fmac_f32_e32 v108, v101, v97
	s_waitcnt lgkmcnt(5)
	v_fmac_f32_e32 v125, v107, v98
	ds_swizzle_b32 v107, v61 offset:swizzle(SWAP,4)
	ds_swizzle_b32 v101, v104 offset:swizzle(SWAP,4)
	ds_swizzle_b32 v110, v102 offset:swizzle(SWAP,4)
	ds_swizzle_b32 v111, v59 offset:swizzle(SWAP,4)
	ds_swizzle_b32 v112, v108 offset:swizzle(SWAP,4)
	ds_swizzle_b32 v109, v105 offset:swizzle(SWAP,4)
	s_waitcnt lgkmcnt(10)
	v_fmac_f32_e32 v126, v63, v98
	s_waitcnt lgkmcnt(9)
	v_fmac_f32_e32 v127, v123, v98
	s_waitcnt lgkmcnt(8)
	v_fmac_f32_e32 v124, v120, v98
	v_max_f32_e64 v95, |v126|, |v127|
	s_waitcnt lgkmcnt(7)
	v_fmac_f32_e32 v103, v58, v98
	s_waitcnt lgkmcnt(6)
	v_fmac_f32_e32 v106, v60, v98
	v_max3_f32 v95, |v124|, |v125|, v95
	s_waitcnt lgkmcnt(5)
	v_fmac_f32_e32 v107, v61, v98
	s_waitcnt lgkmcnt(4)
	v_fmac_f32_e32 v101, v104, v98
	s_waitcnt lgkmcnt(3)
	v_fmac_f32_e32 v110, v102, v98
	s_waitcnt lgkmcnt(2)
	v_fmac_f32_e32 v111, v59, v98
	s_waitcnt lgkmcnt(1)
	v_fmac_f32_e32 v112, v108, v98
	v_max_f32_e64 v102, |v103|, |v106|
	v_cvt_pk_bf16_f32 v62, v124, v125
	v_cvt_pk_bf16_f32 v63, v126, v127
	s_waitcnt lgkmcnt(0)
	v_fmac_f32_e32 v109, v105, v98
	v_cvt_pk_bf16_f32 v60, v103, v106
	v_cvt_pk_bf16_f32 v61, v107, v101
	v_max3_f32 v94, v94, v95, v102
	v_max_f32_e64 v95, |v107|, |v101|
	v_max_f32_e64 v101, |v111|, |v112|
	v_max3_f32 v101, |v109|, |v110|, v101
	v_max3_f32 v94, v94, v95, v101
	v_cvt_pk_bf16_f32 v58, v109, v110
	v_cvt_pk_bf16_f32 v59, v111, v112
	s_waitcnt vmcnt(12)
	v_lshlrev_b32_e32 v95, 16, v54
	v_and_b32_e32 v54, 0xffff0000, v54
	v_lshlrev_b32_e32 v101, 16, v55
	v_and_b32_e32 v55, 0xffff0000, v55
	v_lshlrev_b32_e32 v102, 16, v56
	v_and_b32_e32 v56, 0xffff0000, v56
	v_lshlrev_b32_e32 v103, 16, v57
	v_and_b32_e32 v57, 0xffff0000, v57
	v_add_f32_e32 v104, v95, v54
	v_sub_f32_e32 v54, v95, v54
	v_add_f32_e32 v95, v101, v55
	v_sub_f32_e32 v55, v101, v55
	v_add_f32_e32 v101, v102, v56
	v_sub_f32_e32 v56, v102, v56
	v_add_f32_e32 v102, v103, v57
	v_sub_f32_e32 v57, v103, v57
	v_add_f32_e32 v103, v104, v95
	v_sub_f32_e32 v95, v104, v95
	v_add_f32_e32 v104, v54, v55
	v_sub_f32_e32 v54, v54, v55
	v_add_f32_e32 v55, v101, v102
	v_sub_f32_e32 v101, v101, v102
	v_add_f32_e32 v102, v56, v57
	v_sub_f32_e32 v56, v56, v57
	v_add_f32_e32 v57, v103, v55
	v_sub_f32_e32 v55, v103, v55
	v_add_f32_e32 v103, v104, v102
	v_sub_f32_e32 v102, v104, v102
	v_add_f32_e32 v104, v95, v101
	v_sub_f32_e32 v95, v95, v101
	v_add_f32_e32 v101, v54, v56
	v_sub_f32_e32 v54, v54, v56
	v_mov_b32_dpp v56, v57 quad_perm:[1,0,3,2] row_mask:0xf bank_mask:0xf bound_ctrl:1
	v_fmac_f32_e32 v56, v57, v96
	v_mov_b32_dpp v57, v103 quad_perm:[1,0,3,2] row_mask:0xf bank_mask:0xf bound_ctrl:1
	v_fmac_f32_e32 v57, v103, v96
	v_mov_b32_dpp v103, v104 quad_perm:[1,0,3,2] row_mask:0xf bank_mask:0xf bound_ctrl:1
	v_fmac_f32_e32 v103, v104, v96
	v_mov_b32_dpp v104, v101 quad_perm:[1,0,3,2] row_mask:0xf bank_mask:0xf bound_ctrl:1
	v_fmac_f32_e32 v104, v101, v96
	v_mov_b32_dpp v101, v55 quad_perm:[1,0,3,2] row_mask:0xf bank_mask:0xf bound_ctrl:1
	v_fmac_f32_e32 v101, v55, v96
	v_mov_b32_dpp v55, v102 quad_perm:[1,0,3,2] row_mask:0xf bank_mask:0xf bound_ctrl:1
	v_fmac_f32_e32 v55, v102, v96
	v_mov_b32_dpp v102, v95 quad_perm:[1,0,3,2] row_mask:0xf bank_mask:0xf bound_ctrl:1
	v_fmac_f32_e32 v102, v95, v96
	v_mov_b32_dpp v95, v54 quad_perm:[1,0,3,2] row_mask:0xf bank_mask:0xf bound_ctrl:1
	v_fmac_f32_e32 v95, v54, v96
	v_mov_b32_dpp v54, v56 quad_perm:[2,3,0,1] row_mask:0xf bank_mask:0xf bound_ctrl:1
	v_fmac_f32_e32 v54, v56, v97
	v_mov_b32_dpp v56, v57 quad_perm:[2,3,0,1] row_mask:0xf bank_mask:0xf bound_ctrl:1
	v_fmac_f32_e32 v56, v57, v97
	v_mov_b32_dpp v57, v103 quad_perm:[2,3,0,1] row_mask:0xf bank_mask:0xf bound_ctrl:1
	v_fmac_f32_e32 v57, v103, v97
	v_mov_b32_dpp v103, v104 quad_perm:[2,3,0,1] row_mask:0xf bank_mask:0xf bound_ctrl:1
	v_fmac_f32_e32 v103, v104, v97
	v_mov_b32_dpp v104, v101 quad_perm:[2,3,0,1] row_mask:0xf bank_mask:0xf bound_ctrl:1
	v_fmac_f32_e32 v104, v101, v97
	v_mov_b32_dpp v101, v55 quad_perm:[2,3,0,1] row_mask:0xf bank_mask:0xf bound_ctrl:1
	v_mov_b32_dpp v107, v95 quad_perm:[2,3,0,1] row_mask:0xf bank_mask:0xf bound_ctrl:1
	v_fmac_f32_e32 v101, v55, v97
	v_fmac_f32_e32 v107, v95, v97
	ds_swizzle_b32 v95, v103 offset:swizzle(SWAP,4)
	ds_swizzle_b32 v108, v104 offset:swizzle(SWAP,4)
	ds_swizzle_b32 v109, v101 offset:swizzle(SWAP,4)
	ds_swizzle_b32 v111, v107 offset:swizzle(SWAP,4)
	v_mov_b32_dpp v55, v102 quad_perm:[2,3,0,1] row_mask:0xf bank_mask:0xf bound_ctrl:1
	s_waitcnt lgkmcnt(3)
	v_fmac_f32_e32 v95, v103, v98
	s_waitcnt lgkmcnt(2)
	v_fmac_f32_e32 v108, v104, v98
	s_waitcnt lgkmcnt(1)
	v_fmac_f32_e32 v109, v101, v98
	s_waitcnt lgkmcnt(0)
	v_fmac_f32_e32 v111, v107, v98
	s_waitcnt vmcnt(11)
	v_lshlrev_b32_e32 v101, 16, v50
	v_and_b32_e32 v50, 0xffff0000, v50
	v_lshlrev_b32_e32 v103, 16, v51
	v_and_b32_e32 v51, 0xffff0000, v51
	v_lshlrev_b32_e32 v104, 16, v52
	v_and_b32_e32 v52, 0xffff0000, v52
	v_lshlrev_b32_e32 v107, 16, v53
	v_and_b32_e32 v53, 0xffff0000, v53
	v_add_f32_e32 v112, v101, v50
	v_sub_f32_e32 v50, v101, v50
	v_add_f32_e32 v101, v103, v51
	v_sub_f32_e32 v51, v103, v51
	v_add_f32_e32 v103, v104, v52
	v_sub_f32_e32 v52, v104, v52
	v_add_f32_e32 v104, v107, v53
	v_sub_f32_e32 v53, v107, v53
	v_add_f32_e32 v107, v112, v101
	v_sub_f32_e32 v101, v112, v101
	v_add_f32_e32 v112, v50, v51
	v_sub_f32_e32 v50, v50, v51
	v_add_f32_e32 v51, v103, v104
	v_sub_f32_e32 v103, v103, v104
	v_add_f32_e32 v104, v52, v53
	v_sub_f32_e32 v52, v52, v53
	v_add_f32_e32 v53, v107, v51
	v_sub_f32_e32 v51, v107, v51
	v_add_f32_e32 v107, v112, v104
	v_sub_f32_e32 v104, v112, v104
	v_add_f32_e32 v112, v101, v103
	v_sub_f32_e32 v101, v101, v103
	v_add_f32_e32 v103, v50, v52
	v_sub_f32_e32 v50, v50, v52
	v_mov_b32_dpp v52, v53 quad_perm:[1,0,3,2] row_mask:0xf bank_mask:0xf bound_ctrl:1
	v_fmac_f32_e32 v52, v53, v96
	v_mov_b32_dpp v53, v107 quad_perm:[1,0,3,2] row_mask:0xf bank_mask:0xf bound_ctrl:1
	v_fmac_f32_e32 v53, v107, v96
	v_mov_b32_dpp v107, v112 quad_perm:[1,0,3,2] row_mask:0xf bank_mask:0xf bound_ctrl:1
	v_fmac_f32_e32 v107, v112, v96
	v_mov_b32_dpp v112, v103 quad_perm:[1,0,3,2] row_mask:0xf bank_mask:0xf bound_ctrl:1
	v_fmac_f32_e32 v112, v103, v96
	v_mov_b32_dpp v103, v51 quad_perm:[1,0,3,2] row_mask:0xf bank_mask:0xf bound_ctrl:1
	v_fmac_f32_e32 v103, v51, v96
	v_mov_b32_dpp v51, v104 quad_perm:[1,0,3,2] row_mask:0xf bank_mask:0xf bound_ctrl:1
	v_fmac_f32_e32 v51, v104, v96
	v_mov_b32_dpp v104, v101 quad_perm:[1,0,3,2] row_mask:0xf bank_mask:0xf bound_ctrl:1
	v_fmac_f32_e32 v104, v101, v96
	v_mov_b32_dpp v101, v50 quad_perm:[1,0,3,2] row_mask:0xf bank_mask:0xf bound_ctrl:1
	v_fmac_f32_e32 v101, v50, v96
	v_mov_b32_dpp v50, v52 quad_perm:[2,3,0,1] row_mask:0xf bank_mask:0xf bound_ctrl:1
	v_fmac_f32_e32 v50, v52, v97
	v_mov_b32_dpp v52, v53 quad_perm:[2,3,0,1] row_mask:0xf bank_mask:0xf bound_ctrl:1
	v_fmac_f32_e32 v52, v53, v97
	v_mov_b32_dpp v53, v107 quad_perm:[2,3,0,1] row_mask:0xf bank_mask:0xf bound_ctrl:1
	v_fmac_f32_e32 v53, v107, v97
	v_mov_b32_dpp v107, v112 quad_perm:[2,3,0,1] row_mask:0xf bank_mask:0xf bound_ctrl:1
	v_fmac_f32_e32 v107, v112, v97
	v_mov_b32_dpp v112, v103 quad_perm:[2,3,0,1] row_mask:0xf bank_mask:0xf bound_ctrl:1
	v_fmac_f32_e32 v112, v103, v97
	v_mov_b32_dpp v103, v51 quad_perm:[2,3,0,1] row_mask:0xf bank_mask:0xf bound_ctrl:1
	v_mov_b32_dpp v115, v101 quad_perm:[2,3,0,1] row_mask:0xf bank_mask:0xf bound_ctrl:1
	v_fmac_f32_e32 v103, v51, v97
	v_fmac_f32_e32 v115, v101, v97
	ds_swizzle_b32 v101, v107 offset:swizzle(SWAP,4)
	ds_swizzle_b32 v116, v112 offset:swizzle(SWAP,4)
	ds_swizzle_b32 v117, v103 offset:swizzle(SWAP,4)
	ds_swizzle_b32 v119, v115 offset:swizzle(SWAP,4)
	v_fmac_f32_e32 v55, v102, v97
	s_waitcnt lgkmcnt(3)
	v_fmac_f32_e32 v101, v107, v98
	s_waitcnt lgkmcnt(2)
	v_fmac_f32_e32 v116, v112, v98
	s_waitcnt lgkmcnt(1)
	v_fmac_f32_e32 v117, v103, v98
	s_waitcnt lgkmcnt(0)
	v_fmac_f32_e32 v119, v115, v98
	s_waitcnt vmcnt(10)
	v_lshlrev_b32_e32 v103, 16, v46
	v_and_b32_e32 v46, 0xffff0000, v46
	v_lshlrev_b32_e32 v107, 16, v47
	v_and_b32_e32 v47, 0xffff0000, v47
	v_lshlrev_b32_e32 v112, 16, v48
	v_and_b32_e32 v48, 0xffff0000, v48
	v_lshlrev_b32_e32 v115, 16, v49
	v_and_b32_e32 v49, 0xffff0000, v49
	v_add_f32_e32 v120, v103, v46
	v_sub_f32_e32 v46, v103, v46
	v_add_f32_e32 v103, v107, v47
	v_sub_f32_e32 v47, v107, v47
	v_add_f32_e32 v107, v112, v48
	v_sub_f32_e32 v48, v112, v48
	v_add_f32_e32 v112, v115, v49
	v_sub_f32_e32 v49, v115, v49
	v_add_f32_e32 v115, v120, v103
	v_sub_f32_e32 v103, v120, v103
	v_add_f32_e32 v120, v46, v47
	v_sub_f32_e32 v46, v46, v47
	v_add_f32_e32 v47, v107, v112
	v_sub_f32_e32 v107, v107, v112
	v_add_f32_e32 v112, v48, v49
	v_sub_f32_e32 v48, v48, v49
	v_add_f32_e32 v49, v115, v47
	v_sub_f32_e32 v47, v115, v47
	v_add_f32_e32 v115, v120, v112
	v_sub_f32_e32 v112, v120, v112
	v_add_f32_e32 v120, v103, v107
	v_sub_f32_e32 v103, v103, v107
	v_add_f32_e32 v107, v46, v48
	v_sub_f32_e32 v46, v46, v48
	v_mov_b32_dpp v48, v49 quad_perm:[1,0,3,2] row_mask:0xf bank_mask:0xf bound_ctrl:1
	v_fmac_f32_e32 v48, v49, v96
	v_mov_b32_dpp v49, v115 quad_perm:[1,0,3,2] row_mask:0xf bank_mask:0xf bound_ctrl:1
	v_fmac_f32_e32 v49, v115, v96
	v_mov_b32_dpp v115, v120 quad_perm:[1,0,3,2] row_mask:0xf bank_mask:0xf bound_ctrl:1
	v_fmac_f32_e32 v115, v120, v96
	v_mov_b32_dpp v120, v107 quad_perm:[1,0,3,2] row_mask:0xf bank_mask:0xf bound_ctrl:1
	v_fmac_f32_e32 v120, v107, v96
	v_mov_b32_dpp v107, v47 quad_perm:[1,0,3,2] row_mask:0xf bank_mask:0xf bound_ctrl:1
	v_fmac_f32_e32 v107, v47, v96
	v_mov_b32_dpp v47, v112 quad_perm:[1,0,3,2] row_mask:0xf bank_mask:0xf bound_ctrl:1
	v_fmac_f32_e32 v47, v112, v96
	v_mov_b32_dpp v112, v103 quad_perm:[1,0,3,2] row_mask:0xf bank_mask:0xf bound_ctrl:1
	v_fmac_f32_e32 v112, v103, v96
	v_mov_b32_dpp v103, v46 quad_perm:[1,0,3,2] row_mask:0xf bank_mask:0xf bound_ctrl:1
	v_fmac_f32_e32 v103, v46, v96
	v_mov_b32_dpp v46, v48 quad_perm:[2,3,0,1] row_mask:0xf bank_mask:0xf bound_ctrl:1
	v_fmac_f32_e32 v46, v48, v97
	v_mov_b32_dpp v48, v49 quad_perm:[2,3,0,1] row_mask:0xf bank_mask:0xf bound_ctrl:1
	ds_swizzle_b32 v102, v54 offset:swizzle(SWAP,4)
	ds_swizzle_b32 v105, v56 offset:swizzle(SWAP,4)
	ds_swizzle_b32 v106, v57 offset:swizzle(SWAP,4)
	v_fmac_f32_e32 v48, v49, v97
	v_mov_b32_dpp v49, v115 quad_perm:[2,3,0,1] row_mask:0xf bank_mask:0xf bound_ctrl:1
	ds_swizzle_b32 v110, v55 offset:swizzle(SWAP,4)
	v_mov_b32_dpp v51, v104 quad_perm:[2,3,0,1] row_mask:0xf bank_mask:0xf bound_ctrl:1
	v_fmac_f32_e32 v49, v115, v97
	v_mov_b32_dpp v115, v120 quad_perm:[2,3,0,1] row_mask:0xf bank_mask:0xf bound_ctrl:1
	v_fmac_f32_e32 v51, v104, v97
	ds_swizzle_b32 v104, v50 offset:swizzle(SWAP,4)
	ds_swizzle_b32 v113, v52 offset:swizzle(SWAP,4)
	v_fmac_f32_e32 v115, v120, v97
	v_mov_b32_dpp v120, v107 quad_perm:[2,3,0,1] row_mask:0xf bank_mask:0xf bound_ctrl:1
	ds_swizzle_b32 v114, v53 offset:swizzle(SWAP,4)
	ds_swizzle_b32 v118, v51 offset:swizzle(SWAP,4)
	v_fmac_f32_e32 v120, v107, v97
	v_mov_b32_dpp v107, v47 quad_perm:[2,3,0,1] row_mask:0xf bank_mask:0xf bound_ctrl:1
	v_fmac_f32_e32 v107, v47, v97
	v_mov_b32_dpp v47, v112 quad_perm:[2,3,0,1] row_mask:0xf bank_mask:0xf bound_ctrl:1
	v_mov_b32_dpp v123, v103 quad_perm:[2,3,0,1] row_mask:0xf bank_mask:0xf bound_ctrl:1
	s_waitcnt lgkmcnt(7)
	v_fmac_f32_e32 v102, v54, v98
	s_waitcnt lgkmcnt(6)
	v_fmac_f32_e32 v105, v56, v98
	s_waitcnt lgkmcnt(5)
	v_fmac_f32_e32 v106, v57, v98
	v_fmac_f32_e32 v47, v112, v97
	ds_swizzle_b32 v112, v46 offset:swizzle(SWAP,4)
	ds_swizzle_b32 v121, v48 offset:swizzle(SWAP,4)
	ds_swizzle_b32 v122, v49 offset:swizzle(SWAP,4)
	v_fmac_f32_e32 v123, v103, v97
	ds_swizzle_b32 v103, v115 offset:swizzle(SWAP,4)
	s_waitcnt lgkmcnt(8)
	v_fmac_f32_e32 v110, v55, v98
	v_cvt_pk_bf16_f32 v56, v102, v105
	v_cvt_pk_bf16_f32 v57, v106, v95
	v_max_f32_e64 v102, |v102|, |v105|
	v_max_f32_e64 v95, |v106|, |v95|
	s_waitcnt lgkmcnt(7)
	v_fmac_f32_e32 v104, v50, v98
	s_waitcnt lgkmcnt(6)
	v_fmac_f32_e32 v113, v52, v98
	v_max3_f32 v94, v94, v102, v95
	v_max_f32_e64 v95, |v110|, |v111|
	s_waitcnt lgkmcnt(5)
	v_fmac_f32_e32 v114, v53, v98
	s_waitcnt lgkmcnt(4)
	v_fmac_f32_e32 v118, v51, v98
	v_max3_f32 v95, |v108|, |v109|, v95
	v_max_f32_e64 v102, |v104|, |v113|
	v_cvt_pk_bf16_f32 v54, v108, v109
	v_cvt_pk_bf16_f32 v55, v110, v111
	v_cvt_pk_bf16_f32 v52, v104, v113
	v_cvt_pk_bf16_f32 v53, v114, v101
	v_max3_f32 v94, v94, v95, v102
	v_max_f32_e64 v95, |v114|, |v101|
	v_max_f32_e64 v101, |v118|, |v119|
	s_waitcnt lgkmcnt(3)
	v_fmac_f32_e32 v112, v46, v98
	s_waitcnt lgkmcnt(2)
	v_fmac_f32_e32 v121, v48, v98
	s_waitcnt lgkmcnt(1)
	v_fmac_f32_e32 v122, v49, v98
	s_waitcnt lgkmcnt(0)
	v_fmac_f32_e32 v103, v115, v98
	v_max3_f32 v101, |v116|, |v117|, v101
	v_max3_f32 v94, v94, v95, v101
	v_max_f32_e64 v95, |v112|, |v121|
	v_max_f32_e64 v101, |v122|, |v103|
	v_cvt_pk_bf16_f32 v50, v116, v117
	v_cvt_pk_bf16_f32 v51, v118, v119
	v_cvt_pk_bf16_f32 v48, v112, v121
	v_cvt_pk_bf16_f32 v49, v122, v103
	v_max3_f32 v94, v94, v95, v101
	s_waitcnt vmcnt(9)
	v_lshlrev_b32_e32 v101, 16, v42
	v_and_b32_e32 v42, 0xffff0000, v42
	v_lshlrev_b32_e32 v102, 16, v43
	v_and_b32_e32 v43, 0xffff0000, v43
	v_lshlrev_b32_e32 v103, 16, v44
	v_and_b32_e32 v44, 0xffff0000, v44
	v_lshlrev_b32_e32 v104, 16, v45
	v_and_b32_e32 v45, 0xffff0000, v45
	v_add_f32_e32 v105, v101, v42
	v_sub_f32_e32 v42, v101, v42
	v_add_f32_e32 v101, v102, v43
	v_sub_f32_e32 v43, v102, v43
	v_add_f32_e32 v102, v103, v44
	v_sub_f32_e32 v44, v103, v44
	v_add_f32_e32 v103, v104, v45
	v_sub_f32_e32 v45, v104, v45
	v_add_f32_e32 v104, v105, v101
	v_sub_f32_e32 v101, v105, v101
	v_add_f32_e32 v105, v42, v43
	v_sub_f32_e32 v42, v42, v43
	v_add_f32_e32 v43, v102, v103
	v_sub_f32_e32 v102, v102, v103
	v_add_f32_e32 v103, v44, v45
	v_sub_f32_e32 v44, v44, v45
	v_add_f32_e32 v45, v104, v43
	v_sub_f32_e32 v43, v104, v43
	v_add_f32_e32 v104, v105, v103
	v_sub_f32_e32 v103, v105, v103
	v_add_f32_e32 v105, v101, v102
	v_sub_f32_e32 v101, v101, v102
	v_add_f32_e32 v102, v42, v44
	v_sub_f32_e32 v42, v42, v44
	v_mov_b32_dpp v44, v45 quad_perm:[1,0,3,2] row_mask:0xf bank_mask:0xf bound_ctrl:1
	v_fmac_f32_e32 v44, v45, v96
	v_mov_b32_dpp v45, v104 quad_perm:[1,0,3,2] row_mask:0xf bank_mask:0xf bound_ctrl:1
	v_fmac_f32_e32 v45, v104, v96
	v_mov_b32_dpp v104, v105 quad_perm:[1,0,3,2] row_mask:0xf bank_mask:0xf bound_ctrl:1
	v_fmac_f32_e32 v104, v105, v96
	v_mov_b32_dpp v105, v102 quad_perm:[1,0,3,2] row_mask:0xf bank_mask:0xf bound_ctrl:1
	v_fmac_f32_e32 v105, v102, v96
	v_mov_b32_dpp v102, v43 quad_perm:[1,0,3,2] row_mask:0xf bank_mask:0xf bound_ctrl:1
	v_fmac_f32_e32 v102, v43, v96
	v_mov_b32_dpp v43, v103 quad_perm:[1,0,3,2] row_mask:0xf bank_mask:0xf bound_ctrl:1
	v_fmac_f32_e32 v43, v103, v96
	v_mov_b32_dpp v103, v101 quad_perm:[1,0,3,2] row_mask:0xf bank_mask:0xf bound_ctrl:1
	v_fmac_f32_e32 v103, v101, v96
	v_mov_b32_dpp v101, v42 quad_perm:[1,0,3,2] row_mask:0xf bank_mask:0xf bound_ctrl:1
	v_fmac_f32_e32 v101, v42, v96
	v_mov_b32_dpp v42, v44 quad_perm:[2,3,0,1] row_mask:0xf bank_mask:0xf bound_ctrl:1
	v_fmac_f32_e32 v42, v44, v97
	v_mov_b32_dpp v44, v45 quad_perm:[2,3,0,1] row_mask:0xf bank_mask:0xf bound_ctrl:1
	v_fmac_f32_e32 v44, v45, v97
	v_mov_b32_dpp v45, v104 quad_perm:[2,3,0,1] row_mask:0xf bank_mask:0xf bound_ctrl:1
	ds_swizzle_b32 v125, v107 offset:swizzle(SWAP,4)
	v_fmac_f32_e32 v45, v104, v97
	v_mov_b32_dpp v104, v105 quad_perm:[2,3,0,1] row_mask:0xf bank_mask:0xf bound_ctrl:1
	v_fmac_f32_e32 v104, v105, v97
	v_mov_b32_dpp v105, v102 quad_perm:[2,3,0,1] row_mask:0xf bank_mask:0xf bound_ctrl:1
	v_fmac_f32_e32 v105, v102, v97
	v_mov_b32_dpp v102, v43 quad_perm:[2,3,0,1] row_mask:0xf bank_mask:0xf bound_ctrl:1
	ds_swizzle_b32 v126, v47 offset:swizzle(SWAP,4)
	ds_swizzle_b32 v127, v123 offset:swizzle(SWAP,4)
	v_fmac_f32_e32 v102, v43, v97
	v_mov_b32_dpp v43, v103 quad_perm:[2,3,0,1] row_mask:0xf bank_mask:0xf bound_ctrl:1
	v_mov_b32_dpp v108, v101 quad_perm:[2,3,0,1] row_mask:0xf bank_mask:0xf bound_ctrl:1
	ds_swizzle_b32 v124, v120 offset:swizzle(SWAP,4)
	v_fmac_f32_e32 v43, v103, v97
	ds_swizzle_b32 v103, v42 offset:swizzle(SWAP,4)
	ds_swizzle_b32 v106, v44 offset:swizzle(SWAP,4)
	v_fmac_f32_e32 v108, v101, v97
	s_waitcnt lgkmcnt(5)
	v_fmac_f32_e32 v125, v107, v98
	ds_swizzle_b32 v107, v45 offset:swizzle(SWAP,4)
	ds_swizzle_b32 v101, v104 offset:swizzle(SWAP,4)
	ds_swizzle_b32 v110, v102 offset:swizzle(SWAP,4)
	ds_swizzle_b32 v111, v43 offset:swizzle(SWAP,4)
	ds_swizzle_b32 v112, v108 offset:swizzle(SWAP,4)
	ds_swizzle_b32 v109, v105 offset:swizzle(SWAP,4)
	s_waitcnt lgkmcnt(10)
	v_fmac_f32_e32 v126, v47, v98
	s_waitcnt lgkmcnt(9)
	v_fmac_f32_e32 v127, v123, v98
	s_waitcnt lgkmcnt(8)
	v_fmac_f32_e32 v124, v120, v98
	v_max_f32_e64 v95, |v126|, |v127|
	s_waitcnt lgkmcnt(7)
	v_fmac_f32_e32 v103, v42, v98
	s_waitcnt lgkmcnt(6)
	v_fmac_f32_e32 v106, v44, v98
	v_max3_f32 v95, |v124|, |v125|, v95
	s_waitcnt lgkmcnt(5)
	v_fmac_f32_e32 v107, v45, v98
	s_waitcnt lgkmcnt(4)
	v_fmac_f32_e32 v101, v104, v98
	s_waitcnt lgkmcnt(3)
	v_fmac_f32_e32 v110, v102, v98
	s_waitcnt lgkmcnt(2)
	v_fmac_f32_e32 v111, v43, v98
	s_waitcnt lgkmcnt(1)
	v_fmac_f32_e32 v112, v108, v98
	v_max_f32_e64 v102, |v103|, |v106|
	v_cvt_pk_bf16_f32 v46, v124, v125
	v_cvt_pk_bf16_f32 v47, v126, v127
	s_waitcnt lgkmcnt(0)
	v_fmac_f32_e32 v109, v105, v98
	v_cvt_pk_bf16_f32 v44, v103, v106
	v_cvt_pk_bf16_f32 v45, v107, v101
	v_max3_f32 v94, v94, v95, v102
	v_max_f32_e64 v95, |v107|, |v101|
	v_max_f32_e64 v101, |v111|, |v112|
	v_max3_f32 v101, |v109|, |v110|, v101
	v_max3_f32 v94, v94, v95, v101
	v_cvt_pk_bf16_f32 v42, v109, v110
	v_cvt_pk_bf16_f32 v43, v111, v112
	s_waitcnt vmcnt(8)
	v_lshlrev_b32_e32 v95, 16, v38
	v_and_b32_e32 v38, 0xffff0000, v38
	v_lshlrev_b32_e32 v101, 16, v39
	v_and_b32_e32 v39, 0xffff0000, v39
	v_lshlrev_b32_e32 v102, 16, v40
	v_and_b32_e32 v40, 0xffff0000, v40
	v_lshlrev_b32_e32 v103, 16, v41
	v_and_b32_e32 v41, 0xffff0000, v41
	v_add_f32_e32 v104, v95, v38
	v_sub_f32_e32 v38, v95, v38
	v_add_f32_e32 v95, v101, v39
	v_sub_f32_e32 v39, v101, v39
	v_add_f32_e32 v101, v102, v40
	v_sub_f32_e32 v40, v102, v40
	v_add_f32_e32 v102, v103, v41
	v_sub_f32_e32 v41, v103, v41
	v_add_f32_e32 v103, v104, v95
	v_sub_f32_e32 v95, v104, v95
	v_add_f32_e32 v104, v38, v39
	v_sub_f32_e32 v38, v38, v39
	v_add_f32_e32 v39, v101, v102
	v_sub_f32_e32 v101, v101, v102
	v_add_f32_e32 v102, v40, v41
	v_sub_f32_e32 v40, v40, v41
	v_add_f32_e32 v41, v103, v39
	v_sub_f32_e32 v39, v103, v39
	v_add_f32_e32 v103, v104, v102
	v_sub_f32_e32 v102, v104, v102
	v_add_f32_e32 v104, v95, v101
	v_sub_f32_e32 v95, v95, v101
	v_add_f32_e32 v101, v38, v40
	v_sub_f32_e32 v38, v38, v40
	v_mov_b32_dpp v40, v41 quad_perm:[1,0,3,2] row_mask:0xf bank_mask:0xf bound_ctrl:1
	v_fmac_f32_e32 v40, v41, v96
	v_mov_b32_dpp v41, v103 quad_perm:[1,0,3,2] row_mask:0xf bank_mask:0xf bound_ctrl:1
	v_fmac_f32_e32 v41, v103, v96
	v_mov_b32_dpp v103, v104 quad_perm:[1,0,3,2] row_mask:0xf bank_mask:0xf bound_ctrl:1
	v_fmac_f32_e32 v103, v104, v96
	v_mov_b32_dpp v104, v101 quad_perm:[1,0,3,2] row_mask:0xf bank_mask:0xf bound_ctrl:1
	v_fmac_f32_e32 v104, v101, v96
	v_mov_b32_dpp v101, v39 quad_perm:[1,0,3,2] row_mask:0xf bank_mask:0xf bound_ctrl:1
	v_fmac_f32_e32 v101, v39, v96
	v_mov_b32_dpp v39, v102 quad_perm:[1,0,3,2] row_mask:0xf bank_mask:0xf bound_ctrl:1
	v_fmac_f32_e32 v39, v102, v96
	v_mov_b32_dpp v102, v95 quad_perm:[1,0,3,2] row_mask:0xf bank_mask:0xf bound_ctrl:1
	v_fmac_f32_e32 v102, v95, v96
	v_mov_b32_dpp v95, v38 quad_perm:[1,0,3,2] row_mask:0xf bank_mask:0xf bound_ctrl:1
	v_fmac_f32_e32 v95, v38, v96
	v_mov_b32_dpp v38, v40 quad_perm:[2,3,0,1] row_mask:0xf bank_mask:0xf bound_ctrl:1
	v_fmac_f32_e32 v38, v40, v97
	v_mov_b32_dpp v40, v41 quad_perm:[2,3,0,1] row_mask:0xf bank_mask:0xf bound_ctrl:1
	v_fmac_f32_e32 v40, v41, v97
	v_mov_b32_dpp v41, v103 quad_perm:[2,3,0,1] row_mask:0xf bank_mask:0xf bound_ctrl:1
	v_fmac_f32_e32 v41, v103, v97
	v_mov_b32_dpp v103, v104 quad_perm:[2,3,0,1] row_mask:0xf bank_mask:0xf bound_ctrl:1
	v_fmac_f32_e32 v103, v104, v97
	v_mov_b32_dpp v104, v101 quad_perm:[2,3,0,1] row_mask:0xf bank_mask:0xf bound_ctrl:1
	v_fmac_f32_e32 v104, v101, v97
	v_mov_b32_dpp v101, v39 quad_perm:[2,3,0,1] row_mask:0xf bank_mask:0xf bound_ctrl:1
	v_mov_b32_dpp v107, v95 quad_perm:[2,3,0,1] row_mask:0xf bank_mask:0xf bound_ctrl:1
	v_fmac_f32_e32 v101, v39, v97
	v_fmac_f32_e32 v107, v95, v97
	ds_swizzle_b32 v95, v103 offset:swizzle(SWAP,4)
	ds_swizzle_b32 v108, v104 offset:swizzle(SWAP,4)
	ds_swizzle_b32 v109, v101 offset:swizzle(SWAP,4)
	ds_swizzle_b32 v111, v107 offset:swizzle(SWAP,4)
	v_mov_b32_dpp v39, v102 quad_perm:[2,3,0,1] row_mask:0xf bank_mask:0xf bound_ctrl:1
	s_waitcnt lgkmcnt(3)
	v_fmac_f32_e32 v95, v103, v98
	s_waitcnt lgkmcnt(2)
	v_fmac_f32_e32 v108, v104, v98
	s_waitcnt lgkmcnt(1)
	v_fmac_f32_e32 v109, v101, v98
	s_waitcnt lgkmcnt(0)
	v_fmac_f32_e32 v111, v107, v98
	s_waitcnt vmcnt(7)
	v_lshlrev_b32_e32 v101, 16, v34
	v_and_b32_e32 v34, 0xffff0000, v34
	v_lshlrev_b32_e32 v103, 16, v35
	v_and_b32_e32 v35, 0xffff0000, v35
	v_lshlrev_b32_e32 v104, 16, v36
	v_and_b32_e32 v36, 0xffff0000, v36
	v_lshlrev_b32_e32 v107, 16, v37
	v_and_b32_e32 v37, 0xffff0000, v37
	v_add_f32_e32 v112, v101, v34
	v_sub_f32_e32 v34, v101, v34
	v_add_f32_e32 v101, v103, v35
	v_sub_f32_e32 v35, v103, v35
	v_add_f32_e32 v103, v104, v36
	v_sub_f32_e32 v36, v104, v36
	v_add_f32_e32 v104, v107, v37
	v_sub_f32_e32 v37, v107, v37
	v_add_f32_e32 v107, v112, v101
	v_sub_f32_e32 v101, v112, v101
	v_add_f32_e32 v112, v34, v35
	v_sub_f32_e32 v34, v34, v35
	v_add_f32_e32 v35, v103, v104
	v_sub_f32_e32 v103, v103, v104
	v_add_f32_e32 v104, v36, v37
	v_sub_f32_e32 v36, v36, v37
	v_add_f32_e32 v37, v107, v35
	v_sub_f32_e32 v35, v107, v35
	v_add_f32_e32 v107, v112, v104
	v_sub_f32_e32 v104, v112, v104
	v_add_f32_e32 v112, v101, v103
	v_sub_f32_e32 v101, v101, v103
	v_add_f32_e32 v103, v34, v36
	v_sub_f32_e32 v34, v34, v36
	v_mov_b32_dpp v36, v37 quad_perm:[1,0,3,2] row_mask:0xf bank_mask:0xf bound_ctrl:1
	v_fmac_f32_e32 v36, v37, v96
	v_mov_b32_dpp v37, v107 quad_perm:[1,0,3,2] row_mask:0xf bank_mask:0xf bound_ctrl:1
	v_fmac_f32_e32 v37, v107, v96
	v_mov_b32_dpp v107, v112 quad_perm:[1,0,3,2] row_mask:0xf bank_mask:0xf bound_ctrl:1
	v_fmac_f32_e32 v107, v112, v96
	v_mov_b32_dpp v112, v103 quad_perm:[1,0,3,2] row_mask:0xf bank_mask:0xf bound_ctrl:1
	v_fmac_f32_e32 v112, v103, v96
	v_mov_b32_dpp v103, v35 quad_perm:[1,0,3,2] row_mask:0xf bank_mask:0xf bound_ctrl:1
	v_fmac_f32_e32 v103, v35, v96
	v_mov_b32_dpp v35, v104 quad_perm:[1,0,3,2] row_mask:0xf bank_mask:0xf bound_ctrl:1
	v_fmac_f32_e32 v35, v104, v96
	v_mov_b32_dpp v104, v101 quad_perm:[1,0,3,2] row_mask:0xf bank_mask:0xf bound_ctrl:1
	v_fmac_f32_e32 v104, v101, v96
	v_mov_b32_dpp v101, v34 quad_perm:[1,0,3,2] row_mask:0xf bank_mask:0xf bound_ctrl:1
	v_fmac_f32_e32 v101, v34, v96
	v_mov_b32_dpp v34, v36 quad_perm:[2,3,0,1] row_mask:0xf bank_mask:0xf bound_ctrl:1
	v_fmac_f32_e32 v34, v36, v97
	v_mov_b32_dpp v36, v37 quad_perm:[2,3,0,1] row_mask:0xf bank_mask:0xf bound_ctrl:1
	v_fmac_f32_e32 v36, v37, v97
	v_mov_b32_dpp v37, v107 quad_perm:[2,3,0,1] row_mask:0xf bank_mask:0xf bound_ctrl:1
	v_fmac_f32_e32 v37, v107, v97
	v_mov_b32_dpp v107, v112 quad_perm:[2,3,0,1] row_mask:0xf bank_mask:0xf bound_ctrl:1
	v_fmac_f32_e32 v107, v112, v97
	v_mov_b32_dpp v112, v103 quad_perm:[2,3,0,1] row_mask:0xf bank_mask:0xf bound_ctrl:1
	v_fmac_f32_e32 v112, v103, v97
	v_mov_b32_dpp v103, v35 quad_perm:[2,3,0,1] row_mask:0xf bank_mask:0xf bound_ctrl:1
	v_mov_b32_dpp v115, v101 quad_perm:[2,3,0,1] row_mask:0xf bank_mask:0xf bound_ctrl:1
	v_fmac_f32_e32 v103, v35, v97
	v_fmac_f32_e32 v115, v101, v97
	ds_swizzle_b32 v101, v107 offset:swizzle(SWAP,4)
	ds_swizzle_b32 v116, v112 offset:swizzle(SWAP,4)
	ds_swizzle_b32 v117, v103 offset:swizzle(SWAP,4)
	ds_swizzle_b32 v119, v115 offset:swizzle(SWAP,4)
	v_fmac_f32_e32 v39, v102, v97
	s_waitcnt lgkmcnt(3)
	v_fmac_f32_e32 v101, v107, v98
	s_waitcnt lgkmcnt(2)
	v_fmac_f32_e32 v116, v112, v98
	s_waitcnt lgkmcnt(1)
	v_fmac_f32_e32 v117, v103, v98
	s_waitcnt lgkmcnt(0)
	v_fmac_f32_e32 v119, v115, v98
	s_waitcnt vmcnt(6)
	v_lshlrev_b32_e32 v103, 16, v30
	v_and_b32_e32 v30, 0xffff0000, v30
	v_lshlrev_b32_e32 v107, 16, v31
	v_and_b32_e32 v31, 0xffff0000, v31
	v_lshlrev_b32_e32 v112, 16, v32
	v_and_b32_e32 v32, 0xffff0000, v32
	v_lshlrev_b32_e32 v115, 16, v33
	v_and_b32_e32 v33, 0xffff0000, v33
	v_add_f32_e32 v120, v103, v30
	v_sub_f32_e32 v30, v103, v30
	v_add_f32_e32 v103, v107, v31
	v_sub_f32_e32 v31, v107, v31
	v_add_f32_e32 v107, v112, v32
	v_sub_f32_e32 v32, v112, v32
	v_add_f32_e32 v112, v115, v33
	v_sub_f32_e32 v33, v115, v33
	v_add_f32_e32 v115, v120, v103
	v_sub_f32_e32 v103, v120, v103
	v_add_f32_e32 v120, v30, v31
	v_sub_f32_e32 v30, v30, v31
	v_add_f32_e32 v31, v107, v112
	v_sub_f32_e32 v107, v107, v112
	v_add_f32_e32 v112, v32, v33
	v_sub_f32_e32 v32, v32, v33
	v_add_f32_e32 v33, v115, v31
	v_sub_f32_e32 v31, v115, v31
	v_add_f32_e32 v115, v120, v112
	v_sub_f32_e32 v112, v120, v112
	v_add_f32_e32 v120, v103, v107
	v_sub_f32_e32 v103, v103, v107
	v_add_f32_e32 v107, v30, v32
	v_sub_f32_e32 v30, v30, v32
	v_mov_b32_dpp v32, v33 quad_perm:[1,0,3,2] row_mask:0xf bank_mask:0xf bound_ctrl:1
	v_fmac_f32_e32 v32, v33, v96
	v_mov_b32_dpp v33, v115 quad_perm:[1,0,3,2] row_mask:0xf bank_mask:0xf bound_ctrl:1
	v_fmac_f32_e32 v33, v115, v96
	v_mov_b32_dpp v115, v120 quad_perm:[1,0,3,2] row_mask:0xf bank_mask:0xf bound_ctrl:1
	v_fmac_f32_e32 v115, v120, v96
	v_mov_b32_dpp v120, v107 quad_perm:[1,0,3,2] row_mask:0xf bank_mask:0xf bound_ctrl:1
	v_fmac_f32_e32 v120, v107, v96
	v_mov_b32_dpp v107, v31 quad_perm:[1,0,3,2] row_mask:0xf bank_mask:0xf bound_ctrl:1
	v_fmac_f32_e32 v107, v31, v96
	v_mov_b32_dpp v31, v112 quad_perm:[1,0,3,2] row_mask:0xf bank_mask:0xf bound_ctrl:1
	v_fmac_f32_e32 v31, v112, v96
	v_mov_b32_dpp v112, v103 quad_perm:[1,0,3,2] row_mask:0xf bank_mask:0xf bound_ctrl:1
	v_fmac_f32_e32 v112, v103, v96
	v_mov_b32_dpp v103, v30 quad_perm:[1,0,3,2] row_mask:0xf bank_mask:0xf bound_ctrl:1
	v_fmac_f32_e32 v103, v30, v96
	v_mov_b32_dpp v30, v32 quad_perm:[2,3,0,1] row_mask:0xf bank_mask:0xf bound_ctrl:1
	v_fmac_f32_e32 v30, v32, v97
	v_mov_b32_dpp v32, v33 quad_perm:[2,3,0,1] row_mask:0xf bank_mask:0xf bound_ctrl:1
	ds_swizzle_b32 v102, v38 offset:swizzle(SWAP,4)
	ds_swizzle_b32 v105, v40 offset:swizzle(SWAP,4)
	ds_swizzle_b32 v106, v41 offset:swizzle(SWAP,4)
	v_fmac_f32_e32 v32, v33, v97
	v_mov_b32_dpp v33, v115 quad_perm:[2,3,0,1] row_mask:0xf bank_mask:0xf bound_ctrl:1
	ds_swizzle_b32 v110, v39 offset:swizzle(SWAP,4)
	v_mov_b32_dpp v35, v104 quad_perm:[2,3,0,1] row_mask:0xf bank_mask:0xf bound_ctrl:1
	v_fmac_f32_e32 v33, v115, v97
	v_mov_b32_dpp v115, v120 quad_perm:[2,3,0,1] row_mask:0xf bank_mask:0xf bound_ctrl:1
	v_fmac_f32_e32 v35, v104, v97
	ds_swizzle_b32 v104, v34 offset:swizzle(SWAP,4)
	ds_swizzle_b32 v113, v36 offset:swizzle(SWAP,4)
	v_fmac_f32_e32 v115, v120, v97
	v_mov_b32_dpp v120, v107 quad_perm:[2,3,0,1] row_mask:0xf bank_mask:0xf bound_ctrl:1
	ds_swizzle_b32 v114, v37 offset:swizzle(SWAP,4)
	ds_swizzle_b32 v118, v35 offset:swizzle(SWAP,4)
	v_fmac_f32_e32 v120, v107, v97
	v_mov_b32_dpp v107, v31 quad_perm:[2,3,0,1] row_mask:0xf bank_mask:0xf bound_ctrl:1
	v_fmac_f32_e32 v107, v31, v97
	v_mov_b32_dpp v31, v112 quad_perm:[2,3,0,1] row_mask:0xf bank_mask:0xf bound_ctrl:1
	v_mov_b32_dpp v123, v103 quad_perm:[2,3,0,1] row_mask:0xf bank_mask:0xf bound_ctrl:1
	s_waitcnt lgkmcnt(7)
	v_fmac_f32_e32 v102, v38, v98
	s_waitcnt lgkmcnt(6)
	v_fmac_f32_e32 v105, v40, v98
	s_waitcnt lgkmcnt(5)
	v_fmac_f32_e32 v106, v41, v98
	v_fmac_f32_e32 v31, v112, v97
	ds_swizzle_b32 v112, v30 offset:swizzle(SWAP,4)
	ds_swizzle_b32 v121, v32 offset:swizzle(SWAP,4)
	ds_swizzle_b32 v122, v33 offset:swizzle(SWAP,4)
	v_fmac_f32_e32 v123, v103, v97
	ds_swizzle_b32 v103, v115 offset:swizzle(SWAP,4)
	s_waitcnt lgkmcnt(8)
	v_fmac_f32_e32 v110, v39, v98
	v_cvt_pk_bf16_f32 v40, v102, v105
	v_cvt_pk_bf16_f32 v41, v106, v95
	v_max_f32_e64 v102, |v102|, |v105|
	v_max_f32_e64 v95, |v106|, |v95|
	s_waitcnt lgkmcnt(7)
	v_fmac_f32_e32 v104, v34, v98
	s_waitcnt lgkmcnt(6)
	v_fmac_f32_e32 v113, v36, v98
	v_max3_f32 v94, v94, v102, v95
	v_max_f32_e64 v95, |v110|, |v111|
	s_waitcnt lgkmcnt(5)
	v_fmac_f32_e32 v114, v37, v98
	s_waitcnt lgkmcnt(4)
	v_fmac_f32_e32 v118, v35, v98
	v_max3_f32 v95, |v108|, |v109|, v95
	v_max_f32_e64 v102, |v104|, |v113|
	v_cvt_pk_bf16_f32 v38, v108, v109
	v_cvt_pk_bf16_f32 v39, v110, v111
	v_cvt_pk_bf16_f32 v36, v104, v113
	v_cvt_pk_bf16_f32 v37, v114, v101
	v_max3_f32 v94, v94, v95, v102
	v_max_f32_e64 v95, |v114|, |v101|
	v_max_f32_e64 v101, |v118|, |v119|
	s_waitcnt lgkmcnt(3)
	v_fmac_f32_e32 v112, v30, v98
	s_waitcnt lgkmcnt(2)
	v_fmac_f32_e32 v121, v32, v98
	s_waitcnt lgkmcnt(1)
	v_fmac_f32_e32 v122, v33, v98
	s_waitcnt lgkmcnt(0)
	v_fmac_f32_e32 v103, v115, v98
	v_max3_f32 v101, |v116|, |v117|, v101
	v_max3_f32 v94, v94, v95, v101
	v_max_f32_e64 v95, |v112|, |v121|
	v_max_f32_e64 v101, |v122|, |v103|
	v_cvt_pk_bf16_f32 v34, v116, v117
	v_cvt_pk_bf16_f32 v35, v118, v119
	v_cvt_pk_bf16_f32 v32, v112, v121
	v_cvt_pk_bf16_f32 v33, v122, v103
	v_max3_f32 v94, v94, v95, v101
	s_waitcnt vmcnt(5)
	v_lshlrev_b32_e32 v101, 16, v26
	v_and_b32_e32 v26, 0xffff0000, v26
	v_lshlrev_b32_e32 v102, 16, v27
	v_and_b32_e32 v27, 0xffff0000, v27
	v_lshlrev_b32_e32 v103, 16, v28
	v_and_b32_e32 v28, 0xffff0000, v28
	v_lshlrev_b32_e32 v104, 16, v29
	v_and_b32_e32 v29, 0xffff0000, v29
	v_add_f32_e32 v105, v101, v26
	v_sub_f32_e32 v26, v101, v26
	v_add_f32_e32 v101, v102, v27
	v_sub_f32_e32 v27, v102, v27
	v_add_f32_e32 v102, v103, v28
	v_sub_f32_e32 v28, v103, v28
	v_add_f32_e32 v103, v104, v29
	v_sub_f32_e32 v29, v104, v29
	v_add_f32_e32 v104, v105, v101
	v_sub_f32_e32 v101, v105, v101
	v_add_f32_e32 v105, v26, v27
	v_sub_f32_e32 v26, v26, v27
	v_add_f32_e32 v27, v102, v103
	v_sub_f32_e32 v102, v102, v103
	v_add_f32_e32 v103, v28, v29
	v_sub_f32_e32 v28, v28, v29
	v_add_f32_e32 v29, v104, v27
	v_sub_f32_e32 v27, v104, v27
	v_add_f32_e32 v104, v105, v103
	v_sub_f32_e32 v103, v105, v103
	v_add_f32_e32 v105, v101, v102
	v_sub_f32_e32 v101, v101, v102
	v_add_f32_e32 v102, v26, v28
	v_sub_f32_e32 v26, v26, v28
	v_mov_b32_dpp v28, v29 quad_perm:[1,0,3,2] row_mask:0xf bank_mask:0xf bound_ctrl:1
	v_fmac_f32_e32 v28, v29, v96
	v_mov_b32_dpp v29, v104 quad_perm:[1,0,3,2] row_mask:0xf bank_mask:0xf bound_ctrl:1
	v_fmac_f32_e32 v29, v104, v96
	v_mov_b32_dpp v104, v105 quad_perm:[1,0,3,2] row_mask:0xf bank_mask:0xf bound_ctrl:1
	v_fmac_f32_e32 v104, v105, v96
	v_mov_b32_dpp v105, v102 quad_perm:[1,0,3,2] row_mask:0xf bank_mask:0xf bound_ctrl:1
	v_fmac_f32_e32 v105, v102, v96
	v_mov_b32_dpp v102, v27 quad_perm:[1,0,3,2] row_mask:0xf bank_mask:0xf bound_ctrl:1
	v_fmac_f32_e32 v102, v27, v96
	v_mov_b32_dpp v27, v103 quad_perm:[1,0,3,2] row_mask:0xf bank_mask:0xf bound_ctrl:1
	v_fmac_f32_e32 v27, v103, v96
	v_mov_b32_dpp v103, v101 quad_perm:[1,0,3,2] row_mask:0xf bank_mask:0xf bound_ctrl:1
	v_fmac_f32_e32 v103, v101, v96
	v_mov_b32_dpp v101, v26 quad_perm:[1,0,3,2] row_mask:0xf bank_mask:0xf bound_ctrl:1
	v_fmac_f32_e32 v101, v26, v96
	v_mov_b32_dpp v26, v28 quad_perm:[2,3,0,1] row_mask:0xf bank_mask:0xf bound_ctrl:1
	v_fmac_f32_e32 v26, v28, v97
	v_mov_b32_dpp v28, v29 quad_perm:[2,3,0,1] row_mask:0xf bank_mask:0xf bound_ctrl:1
	v_fmac_f32_e32 v28, v29, v97
	v_mov_b32_dpp v29, v104 quad_perm:[2,3,0,1] row_mask:0xf bank_mask:0xf bound_ctrl:1
	ds_swizzle_b32 v125, v107 offset:swizzle(SWAP,4)
	v_fmac_f32_e32 v29, v104, v97
	v_mov_b32_dpp v104, v105 quad_perm:[2,3,0,1] row_mask:0xf bank_mask:0xf bound_ctrl:1
	v_fmac_f32_e32 v104, v105, v97
	v_mov_b32_dpp v105, v102 quad_perm:[2,3,0,1] row_mask:0xf bank_mask:0xf bound_ctrl:1
	v_fmac_f32_e32 v105, v102, v97
	v_mov_b32_dpp v102, v27 quad_perm:[2,3,0,1] row_mask:0xf bank_mask:0xf bound_ctrl:1
	ds_swizzle_b32 v126, v31 offset:swizzle(SWAP,4)
	ds_swizzle_b32 v127, v123 offset:swizzle(SWAP,4)
	v_fmac_f32_e32 v102, v27, v97
	v_mov_b32_dpp v27, v103 quad_perm:[2,3,0,1] row_mask:0xf bank_mask:0xf bound_ctrl:1
	v_mov_b32_dpp v108, v101 quad_perm:[2,3,0,1] row_mask:0xf bank_mask:0xf bound_ctrl:1
	ds_swizzle_b32 v124, v120 offset:swizzle(SWAP,4)
	v_fmac_f32_e32 v27, v103, v97
	ds_swizzle_b32 v103, v26 offset:swizzle(SWAP,4)
	ds_swizzle_b32 v106, v28 offset:swizzle(SWAP,4)
	v_fmac_f32_e32 v108, v101, v97
	s_waitcnt lgkmcnt(5)
	v_fmac_f32_e32 v125, v107, v98
	ds_swizzle_b32 v107, v29 offset:swizzle(SWAP,4)
	ds_swizzle_b32 v101, v104 offset:swizzle(SWAP,4)
	ds_swizzle_b32 v110, v102 offset:swizzle(SWAP,4)
	ds_swizzle_b32 v111, v27 offset:swizzle(SWAP,4)
	ds_swizzle_b32 v112, v108 offset:swizzle(SWAP,4)
	ds_swizzle_b32 v109, v105 offset:swizzle(SWAP,4)
	s_waitcnt lgkmcnt(10)
	v_fmac_f32_e32 v126, v31, v98
	s_waitcnt lgkmcnt(9)
	v_fmac_f32_e32 v127, v123, v98
	s_waitcnt lgkmcnt(8)
	v_fmac_f32_e32 v124, v120, v98
	v_max_f32_e64 v95, |v126|, |v127|
	s_waitcnt lgkmcnt(7)
	v_fmac_f32_e32 v103, v26, v98
	s_waitcnt lgkmcnt(6)
	v_fmac_f32_e32 v106, v28, v98
	v_max3_f32 v95, |v124|, |v125|, v95
	s_waitcnt lgkmcnt(5)
	v_fmac_f32_e32 v107, v29, v98
	s_waitcnt lgkmcnt(4)
	v_fmac_f32_e32 v101, v104, v98
	s_waitcnt lgkmcnt(3)
	v_fmac_f32_e32 v110, v102, v98
	s_waitcnt lgkmcnt(2)
	v_fmac_f32_e32 v111, v27, v98
	s_waitcnt lgkmcnt(1)
	v_fmac_f32_e32 v112, v108, v98
	v_max_f32_e64 v102, |v103|, |v106|
	v_cvt_pk_bf16_f32 v30, v124, v125
	v_cvt_pk_bf16_f32 v31, v126, v127
	s_waitcnt lgkmcnt(0)
	v_fmac_f32_e32 v109, v105, v98
	v_cvt_pk_bf16_f32 v28, v103, v106
	v_cvt_pk_bf16_f32 v29, v107, v101
	v_max3_f32 v94, v94, v95, v102
	v_max_f32_e64 v95, |v107|, |v101|
	v_max_f32_e64 v101, |v111|, |v112|
	v_max3_f32 v101, |v109|, |v110|, v101
	v_max3_f32 v94, v94, v95, v101
	v_cvt_pk_bf16_f32 v26, v109, v110
	v_cvt_pk_bf16_f32 v27, v111, v112
	s_waitcnt vmcnt(4)
	v_lshlrev_b32_e32 v95, 16, v22
	v_and_b32_e32 v22, 0xffff0000, v22
	v_lshlrev_b32_e32 v101, 16, v23
	v_and_b32_e32 v23, 0xffff0000, v23
	v_lshlrev_b32_e32 v102, 16, v24
	v_and_b32_e32 v24, 0xffff0000, v24
	v_lshlrev_b32_e32 v103, 16, v25
	v_and_b32_e32 v25, 0xffff0000, v25
	v_add_f32_e32 v104, v95, v22
	v_sub_f32_e32 v22, v95, v22
	v_add_f32_e32 v95, v101, v23
	v_sub_f32_e32 v23, v101, v23
	v_add_f32_e32 v101, v102, v24
	v_sub_f32_e32 v24, v102, v24
	v_add_f32_e32 v102, v103, v25
	v_sub_f32_e32 v25, v103, v25
	v_add_f32_e32 v103, v104, v95
	v_sub_f32_e32 v95, v104, v95
	v_add_f32_e32 v104, v22, v23
	v_sub_f32_e32 v22, v22, v23
	v_add_f32_e32 v23, v101, v102
	v_sub_f32_e32 v101, v101, v102
	v_add_f32_e32 v102, v24, v25
	v_sub_f32_e32 v24, v24, v25
	v_add_f32_e32 v25, v103, v23
	v_sub_f32_e32 v23, v103, v23
	v_add_f32_e32 v103, v104, v102
	v_sub_f32_e32 v102, v104, v102
	v_add_f32_e32 v104, v95, v101
	v_sub_f32_e32 v95, v95, v101
	v_add_f32_e32 v101, v22, v24
	v_sub_f32_e32 v22, v22, v24
	v_mov_b32_dpp v24, v25 quad_perm:[1,0,3,2] row_mask:0xf bank_mask:0xf bound_ctrl:1
	v_fmac_f32_e32 v24, v25, v96
	v_mov_b32_dpp v25, v103 quad_perm:[1,0,3,2] row_mask:0xf bank_mask:0xf bound_ctrl:1
	v_fmac_f32_e32 v25, v103, v96
	v_mov_b32_dpp v103, v104 quad_perm:[1,0,3,2] row_mask:0xf bank_mask:0xf bound_ctrl:1
	v_fmac_f32_e32 v103, v104, v96
	v_mov_b32_dpp v104, v101 quad_perm:[1,0,3,2] row_mask:0xf bank_mask:0xf bound_ctrl:1
	v_fmac_f32_e32 v104, v101, v96
	v_mov_b32_dpp v101, v23 quad_perm:[1,0,3,2] row_mask:0xf bank_mask:0xf bound_ctrl:1
	v_fmac_f32_e32 v101, v23, v96
	v_mov_b32_dpp v23, v102 quad_perm:[1,0,3,2] row_mask:0xf bank_mask:0xf bound_ctrl:1
	v_fmac_f32_e32 v23, v102, v96
	v_mov_b32_dpp v102, v95 quad_perm:[1,0,3,2] row_mask:0xf bank_mask:0xf bound_ctrl:1
	v_fmac_f32_e32 v102, v95, v96
	v_mov_b32_dpp v95, v22 quad_perm:[1,0,3,2] row_mask:0xf bank_mask:0xf bound_ctrl:1
	v_fmac_f32_e32 v95, v22, v96
	v_mov_b32_dpp v22, v24 quad_perm:[2,3,0,1] row_mask:0xf bank_mask:0xf bound_ctrl:1
	v_fmac_f32_e32 v22, v24, v97
	v_mov_b32_dpp v24, v25 quad_perm:[2,3,0,1] row_mask:0xf bank_mask:0xf bound_ctrl:1
	v_fmac_f32_e32 v24, v25, v97
	v_mov_b32_dpp v25, v103 quad_perm:[2,3,0,1] row_mask:0xf bank_mask:0xf bound_ctrl:1
	v_fmac_f32_e32 v25, v103, v97
	v_mov_b32_dpp v103, v104 quad_perm:[2,3,0,1] row_mask:0xf bank_mask:0xf bound_ctrl:1
	v_fmac_f32_e32 v103, v104, v97
	v_mov_b32_dpp v104, v101 quad_perm:[2,3,0,1] row_mask:0xf bank_mask:0xf bound_ctrl:1
	v_fmac_f32_e32 v104, v101, v97
	v_mov_b32_dpp v101, v23 quad_perm:[2,3,0,1] row_mask:0xf bank_mask:0xf bound_ctrl:1
	v_mov_b32_dpp v107, v95 quad_perm:[2,3,0,1] row_mask:0xf bank_mask:0xf bound_ctrl:1
	v_fmac_f32_e32 v101, v23, v97
	v_fmac_f32_e32 v107, v95, v97
	ds_swizzle_b32 v95, v103 offset:swizzle(SWAP,4)
	ds_swizzle_b32 v108, v104 offset:swizzle(SWAP,4)
	ds_swizzle_b32 v109, v101 offset:swizzle(SWAP,4)
	ds_swizzle_b32 v111, v107 offset:swizzle(SWAP,4)
	v_mov_b32_dpp v23, v102 quad_perm:[2,3,0,1] row_mask:0xf bank_mask:0xf bound_ctrl:1
	s_waitcnt lgkmcnt(3)
	v_fmac_f32_e32 v95, v103, v98
	s_waitcnt lgkmcnt(2)
	v_fmac_f32_e32 v108, v104, v98
	s_waitcnt lgkmcnt(1)
	v_fmac_f32_e32 v109, v101, v98
	s_waitcnt lgkmcnt(0)
	v_fmac_f32_e32 v111, v107, v98
	s_waitcnt vmcnt(3)
	v_lshlrev_b32_e32 v101, 16, v18
	v_and_b32_e32 v18, 0xffff0000, v18
	v_lshlrev_b32_e32 v103, 16, v19
	v_and_b32_e32 v19, 0xffff0000, v19
	v_lshlrev_b32_e32 v104, 16, v20
	v_and_b32_e32 v20, 0xffff0000, v20
	v_lshlrev_b32_e32 v107, 16, v21
	v_and_b32_e32 v21, 0xffff0000, v21
	v_add_f32_e32 v112, v101, v18
	v_sub_f32_e32 v18, v101, v18
	v_add_f32_e32 v101, v103, v19
	v_sub_f32_e32 v19, v103, v19
	v_add_f32_e32 v103, v104, v20
	v_sub_f32_e32 v20, v104, v20
	v_add_f32_e32 v104, v107, v21
	v_sub_f32_e32 v21, v107, v21
	v_add_f32_e32 v107, v112, v101
	v_sub_f32_e32 v101, v112, v101
	v_add_f32_e32 v112, v18, v19
	v_sub_f32_e32 v18, v18, v19
	v_add_f32_e32 v19, v103, v104
	v_sub_f32_e32 v103, v103, v104
	v_add_f32_e32 v104, v20, v21
	v_sub_f32_e32 v20, v20, v21
	v_add_f32_e32 v21, v107, v19
	v_sub_f32_e32 v19, v107, v19
	v_add_f32_e32 v107, v112, v104
	v_sub_f32_e32 v104, v112, v104
	v_add_f32_e32 v112, v101, v103
	v_sub_f32_e32 v101, v101, v103
	v_add_f32_e32 v103, v18, v20
	v_sub_f32_e32 v18, v18, v20
	v_mov_b32_dpp v20, v21 quad_perm:[1,0,3,2] row_mask:0xf bank_mask:0xf bound_ctrl:1
	v_fmac_f32_e32 v20, v21, v96
	v_mov_b32_dpp v21, v107 quad_perm:[1,0,3,2] row_mask:0xf bank_mask:0xf bound_ctrl:1
	v_fmac_f32_e32 v21, v107, v96
	v_mov_b32_dpp v107, v112 quad_perm:[1,0,3,2] row_mask:0xf bank_mask:0xf bound_ctrl:1
	v_fmac_f32_e32 v107, v112, v96
	v_mov_b32_dpp v112, v103 quad_perm:[1,0,3,2] row_mask:0xf bank_mask:0xf bound_ctrl:1
	v_fmac_f32_e32 v112, v103, v96
	v_mov_b32_dpp v103, v19 quad_perm:[1,0,3,2] row_mask:0xf bank_mask:0xf bound_ctrl:1
	v_fmac_f32_e32 v103, v19, v96
	v_mov_b32_dpp v19, v104 quad_perm:[1,0,3,2] row_mask:0xf bank_mask:0xf bound_ctrl:1
	v_fmac_f32_e32 v19, v104, v96
	v_mov_b32_dpp v104, v101 quad_perm:[1,0,3,2] row_mask:0xf bank_mask:0xf bound_ctrl:1
	v_fmac_f32_e32 v104, v101, v96
	v_mov_b32_dpp v101, v18 quad_perm:[1,0,3,2] row_mask:0xf bank_mask:0xf bound_ctrl:1
	v_fmac_f32_e32 v101, v18, v96
	v_mov_b32_dpp v18, v20 quad_perm:[2,3,0,1] row_mask:0xf bank_mask:0xf bound_ctrl:1
	v_fmac_f32_e32 v18, v20, v97
	v_mov_b32_dpp v20, v21 quad_perm:[2,3,0,1] row_mask:0xf bank_mask:0xf bound_ctrl:1
	v_fmac_f32_e32 v20, v21, v97
	v_mov_b32_dpp v21, v107 quad_perm:[2,3,0,1] row_mask:0xf bank_mask:0xf bound_ctrl:1
	v_fmac_f32_e32 v21, v107, v97
	v_mov_b32_dpp v107, v112 quad_perm:[2,3,0,1] row_mask:0xf bank_mask:0xf bound_ctrl:1
	v_fmac_f32_e32 v107, v112, v97
	v_mov_b32_dpp v112, v103 quad_perm:[2,3,0,1] row_mask:0xf bank_mask:0xf bound_ctrl:1
	v_fmac_f32_e32 v112, v103, v97
	v_mov_b32_dpp v103, v19 quad_perm:[2,3,0,1] row_mask:0xf bank_mask:0xf bound_ctrl:1
	v_mov_b32_dpp v115, v101 quad_perm:[2,3,0,1] row_mask:0xf bank_mask:0xf bound_ctrl:1
	v_fmac_f32_e32 v103, v19, v97
	v_fmac_f32_e32 v115, v101, v97
	ds_swizzle_b32 v101, v107 offset:swizzle(SWAP,4)
	ds_swizzle_b32 v116, v112 offset:swizzle(SWAP,4)
	ds_swizzle_b32 v117, v103 offset:swizzle(SWAP,4)
	ds_swizzle_b32 v119, v115 offset:swizzle(SWAP,4)
	v_fmac_f32_e32 v23, v102, v97
	s_waitcnt lgkmcnt(3)
	v_fmac_f32_e32 v101, v107, v98
	s_waitcnt lgkmcnt(2)
	v_fmac_f32_e32 v116, v112, v98
	s_waitcnt lgkmcnt(1)
	v_fmac_f32_e32 v117, v103, v98
	s_waitcnt lgkmcnt(0)
	v_fmac_f32_e32 v119, v115, v98
	s_waitcnt vmcnt(2)
	v_lshlrev_b32_e32 v103, 16, v14
	v_and_b32_e32 v14, 0xffff0000, v14
	v_lshlrev_b32_e32 v107, 16, v15
	v_and_b32_e32 v15, 0xffff0000, v15
	v_lshlrev_b32_e32 v112, 16, v16
	v_and_b32_e32 v16, 0xffff0000, v16
	v_lshlrev_b32_e32 v115, 16, v17
	v_and_b32_e32 v17, 0xffff0000, v17
	v_add_f32_e32 v120, v103, v14
	v_sub_f32_e32 v14, v103, v14
	v_add_f32_e32 v103, v107, v15
	v_sub_f32_e32 v15, v107, v15
	v_add_f32_e32 v107, v112, v16
	v_sub_f32_e32 v16, v112, v16
	v_add_f32_e32 v112, v115, v17
	v_sub_f32_e32 v17, v115, v17
	v_add_f32_e32 v115, v120, v103
	v_sub_f32_e32 v103, v120, v103
	v_add_f32_e32 v120, v14, v15
	v_sub_f32_e32 v14, v14, v15
	v_add_f32_e32 v15, v107, v112
	v_sub_f32_e32 v107, v107, v112
	v_add_f32_e32 v112, v16, v17
	v_sub_f32_e32 v16, v16, v17
	v_add_f32_e32 v17, v115, v15
	v_sub_f32_e32 v15, v115, v15
	v_add_f32_e32 v115, v120, v112
	v_sub_f32_e32 v112, v120, v112
	v_add_f32_e32 v120, v103, v107
	v_sub_f32_e32 v103, v103, v107
	v_add_f32_e32 v107, v14, v16
	v_sub_f32_e32 v14, v14, v16
	v_mov_b32_dpp v16, v17 quad_perm:[1,0,3,2] row_mask:0xf bank_mask:0xf bound_ctrl:1
	v_fmac_f32_e32 v16, v17, v96
	v_mov_b32_dpp v17, v115 quad_perm:[1,0,3,2] row_mask:0xf bank_mask:0xf bound_ctrl:1
	v_fmac_f32_e32 v17, v115, v96
	v_mov_b32_dpp v115, v120 quad_perm:[1,0,3,2] row_mask:0xf bank_mask:0xf bound_ctrl:1
	v_fmac_f32_e32 v115, v120, v96
	v_mov_b32_dpp v120, v107 quad_perm:[1,0,3,2] row_mask:0xf bank_mask:0xf bound_ctrl:1
	v_fmac_f32_e32 v120, v107, v96
	v_mov_b32_dpp v107, v15 quad_perm:[1,0,3,2] row_mask:0xf bank_mask:0xf bound_ctrl:1
	v_fmac_f32_e32 v107, v15, v96
	v_mov_b32_dpp v15, v112 quad_perm:[1,0,3,2] row_mask:0xf bank_mask:0xf bound_ctrl:1
	v_fmac_f32_e32 v15, v112, v96
	v_mov_b32_dpp v112, v103 quad_perm:[1,0,3,2] row_mask:0xf bank_mask:0xf bound_ctrl:1
	v_fmac_f32_e32 v112, v103, v96
	v_mov_b32_dpp v103, v14 quad_perm:[1,0,3,2] row_mask:0xf bank_mask:0xf bound_ctrl:1
	v_fmac_f32_e32 v103, v14, v96
	v_mov_b32_dpp v14, v16 quad_perm:[2,3,0,1] row_mask:0xf bank_mask:0xf bound_ctrl:1
	v_fmac_f32_e32 v14, v16, v97
	v_mov_b32_dpp v16, v17 quad_perm:[2,3,0,1] row_mask:0xf bank_mask:0xf bound_ctrl:1
	ds_swizzle_b32 v102, v22 offset:swizzle(SWAP,4)
	ds_swizzle_b32 v105, v24 offset:swizzle(SWAP,4)
	ds_swizzle_b32 v106, v25 offset:swizzle(SWAP,4)
	v_fmac_f32_e32 v16, v17, v97
	v_mov_b32_dpp v17, v115 quad_perm:[2,3,0,1] row_mask:0xf bank_mask:0xf bound_ctrl:1
	ds_swizzle_b32 v110, v23 offset:swizzle(SWAP,4)
	v_mov_b32_dpp v19, v104 quad_perm:[2,3,0,1] row_mask:0xf bank_mask:0xf bound_ctrl:1
	v_fmac_f32_e32 v17, v115, v97
	v_mov_b32_dpp v115, v120 quad_perm:[2,3,0,1] row_mask:0xf bank_mask:0xf bound_ctrl:1
	v_fmac_f32_e32 v19, v104, v97
	ds_swizzle_b32 v104, v18 offset:swizzle(SWAP,4)
	ds_swizzle_b32 v113, v20 offset:swizzle(SWAP,4)
	v_fmac_f32_e32 v115, v120, v97
	v_mov_b32_dpp v120, v107 quad_perm:[2,3,0,1] row_mask:0xf bank_mask:0xf bound_ctrl:1
	ds_swizzle_b32 v114, v21 offset:swizzle(SWAP,4)
	ds_swizzle_b32 v118, v19 offset:swizzle(SWAP,4)
	v_fmac_f32_e32 v120, v107, v97
	v_mov_b32_dpp v107, v15 quad_perm:[2,3,0,1] row_mask:0xf bank_mask:0xf bound_ctrl:1
	v_fmac_f32_e32 v107, v15, v97
	v_mov_b32_dpp v15, v112 quad_perm:[2,3,0,1] row_mask:0xf bank_mask:0xf bound_ctrl:1
	v_mov_b32_dpp v123, v103 quad_perm:[2,3,0,1] row_mask:0xf bank_mask:0xf bound_ctrl:1
	s_waitcnt lgkmcnt(7)
	v_fmac_f32_e32 v102, v22, v98
	s_waitcnt lgkmcnt(6)
	v_fmac_f32_e32 v105, v24, v98
	s_waitcnt lgkmcnt(5)
	v_fmac_f32_e32 v106, v25, v98
	v_fmac_f32_e32 v15, v112, v97
	ds_swizzle_b32 v112, v14 offset:swizzle(SWAP,4)
	ds_swizzle_b32 v121, v16 offset:swizzle(SWAP,4)
	ds_swizzle_b32 v122, v17 offset:swizzle(SWAP,4)
	v_fmac_f32_e32 v123, v103, v97
	ds_swizzle_b32 v103, v115 offset:swizzle(SWAP,4)
	s_waitcnt lgkmcnt(8)
	v_fmac_f32_e32 v110, v23, v98
	v_cvt_pk_bf16_f32 v24, v102, v105
	v_cvt_pk_bf16_f32 v25, v106, v95
	v_max_f32_e64 v102, |v102|, |v105|
	v_max_f32_e64 v95, |v106|, |v95|
	s_waitcnt lgkmcnt(7)
	v_fmac_f32_e32 v104, v18, v98
	s_waitcnt lgkmcnt(6)
	v_fmac_f32_e32 v113, v20, v98
	v_max3_f32 v94, v94, v102, v95
	v_max_f32_e64 v95, |v110|, |v111|
	s_waitcnt lgkmcnt(5)
	v_fmac_f32_e32 v114, v21, v98
	s_waitcnt lgkmcnt(4)
	v_fmac_f32_e32 v118, v19, v98
	v_max3_f32 v95, |v108|, |v109|, v95
	v_max_f32_e64 v102, |v104|, |v113|
	v_cvt_pk_bf16_f32 v22, v108, v109
	v_cvt_pk_bf16_f32 v23, v110, v111
	v_cvt_pk_bf16_f32 v20, v104, v113
	v_cvt_pk_bf16_f32 v21, v114, v101
	v_max3_f32 v94, v94, v95, v102
	v_max_f32_e64 v95, |v114|, |v101|
	v_max_f32_e64 v101, |v118|, |v119|
	s_waitcnt lgkmcnt(3)
	v_fmac_f32_e32 v112, v14, v98
	s_waitcnt lgkmcnt(2)
	v_fmac_f32_e32 v121, v16, v98
	s_waitcnt lgkmcnt(1)
	v_fmac_f32_e32 v122, v17, v98
	s_waitcnt lgkmcnt(0)
	v_fmac_f32_e32 v103, v115, v98
	v_max3_f32 v101, |v116|, |v117|, v101
	v_max3_f32 v94, v94, v95, v101
	v_max_f32_e64 v95, |v112|, |v121|
	v_max_f32_e64 v101, |v122|, |v103|
	v_cvt_pk_bf16_f32 v18, v116, v117
	v_cvt_pk_bf16_f32 v19, v118, v119
	v_cvt_pk_bf16_f32 v16, v112, v121
	v_cvt_pk_bf16_f32 v17, v122, v103
	v_max3_f32 v94, v94, v95, v101
	s_waitcnt vmcnt(1)
	v_lshlrev_b32_e32 v101, 16, v10
	v_and_b32_e32 v10, 0xffff0000, v10
	v_lshlrev_b32_e32 v102, 16, v11
	v_and_b32_e32 v11, 0xffff0000, v11
	v_lshlrev_b32_e32 v103, 16, v12
	v_and_b32_e32 v12, 0xffff0000, v12
	v_lshlrev_b32_e32 v104, 16, v13
	v_and_b32_e32 v13, 0xffff0000, v13
	v_add_f32_e32 v105, v101, v10
	v_sub_f32_e32 v10, v101, v10
	v_add_f32_e32 v101, v102, v11
	v_sub_f32_e32 v11, v102, v11
	v_add_f32_e32 v102, v103, v12
	v_sub_f32_e32 v12, v103, v12
	v_add_f32_e32 v103, v104, v13
	v_sub_f32_e32 v13, v104, v13
	v_add_f32_e32 v104, v105, v101
	v_sub_f32_e32 v101, v105, v101
	v_add_f32_e32 v105, v10, v11
	v_sub_f32_e32 v10, v10, v11
	v_add_f32_e32 v11, v102, v103
	v_sub_f32_e32 v102, v102, v103
	v_add_f32_e32 v103, v12, v13
	v_sub_f32_e32 v12, v12, v13
	v_add_f32_e32 v13, v104, v11
	v_sub_f32_e32 v11, v104, v11
	v_add_f32_e32 v104, v105, v103
	v_sub_f32_e32 v103, v105, v103
	v_add_f32_e32 v105, v101, v102
	v_sub_f32_e32 v101, v101, v102
	v_add_f32_e32 v102, v10, v12
	v_sub_f32_e32 v10, v10, v12
	v_mov_b32_dpp v12, v13 quad_perm:[1,0,3,2] row_mask:0xf bank_mask:0xf bound_ctrl:1
	v_fmac_f32_e32 v12, v13, v96
	v_mov_b32_dpp v13, v104 quad_perm:[1,0,3,2] row_mask:0xf bank_mask:0xf bound_ctrl:1
	v_fmac_f32_e32 v13, v104, v96
	v_mov_b32_dpp v104, v105 quad_perm:[1,0,3,2] row_mask:0xf bank_mask:0xf bound_ctrl:1
	v_fmac_f32_e32 v104, v105, v96
	v_mov_b32_dpp v105, v102 quad_perm:[1,0,3,2] row_mask:0xf bank_mask:0xf bound_ctrl:1
	v_fmac_f32_e32 v105, v102, v96
	v_mov_b32_dpp v102, v11 quad_perm:[1,0,3,2] row_mask:0xf bank_mask:0xf bound_ctrl:1
	v_fmac_f32_e32 v102, v11, v96
	v_mov_b32_dpp v11, v103 quad_perm:[1,0,3,2] row_mask:0xf bank_mask:0xf bound_ctrl:1
	v_fmac_f32_e32 v11, v103, v96
	v_mov_b32_dpp v103, v101 quad_perm:[1,0,3,2] row_mask:0xf bank_mask:0xf bound_ctrl:1
	v_fmac_f32_e32 v103, v101, v96
	v_mov_b32_dpp v101, v10 quad_perm:[1,0,3,2] row_mask:0xf bank_mask:0xf bound_ctrl:1
	v_fmac_f32_e32 v101, v10, v96
	v_mov_b32_dpp v10, v12 quad_perm:[2,3,0,1] row_mask:0xf bank_mask:0xf bound_ctrl:1
	v_fmac_f32_e32 v10, v12, v97
	v_mov_b32_dpp v12, v13 quad_perm:[2,3,0,1] row_mask:0xf bank_mask:0xf bound_ctrl:1
	v_fmac_f32_e32 v12, v13, v97
	v_mov_b32_dpp v13, v104 quad_perm:[2,3,0,1] row_mask:0xf bank_mask:0xf bound_ctrl:1
	ds_swizzle_b32 v125, v107 offset:swizzle(SWAP,4)
	v_fmac_f32_e32 v13, v104, v97
	v_mov_b32_dpp v104, v105 quad_perm:[2,3,0,1] row_mask:0xf bank_mask:0xf bound_ctrl:1
	v_fmac_f32_e32 v104, v105, v97
	v_mov_b32_dpp v105, v102 quad_perm:[2,3,0,1] row_mask:0xf bank_mask:0xf bound_ctrl:1
	v_fmac_f32_e32 v105, v102, v97
	v_mov_b32_dpp v102, v11 quad_perm:[2,3,0,1] row_mask:0xf bank_mask:0xf bound_ctrl:1
	ds_swizzle_b32 v126, v15 offset:swizzle(SWAP,4)
	ds_swizzle_b32 v127, v123 offset:swizzle(SWAP,4)
	v_fmac_f32_e32 v102, v11, v97
	v_mov_b32_dpp v11, v103 quad_perm:[2,3,0,1] row_mask:0xf bank_mask:0xf bound_ctrl:1
	v_mov_b32_dpp v108, v101 quad_perm:[2,3,0,1] row_mask:0xf bank_mask:0xf bound_ctrl:1
	ds_swizzle_b32 v124, v120 offset:swizzle(SWAP,4)
	v_fmac_f32_e32 v11, v103, v97
	ds_swizzle_b32 v103, v10 offset:swizzle(SWAP,4)
	ds_swizzle_b32 v106, v12 offset:swizzle(SWAP,4)
	v_fmac_f32_e32 v108, v101, v97
	s_waitcnt lgkmcnt(5)
	v_fmac_f32_e32 v125, v107, v98
	ds_swizzle_b32 v107, v13 offset:swizzle(SWAP,4)
	ds_swizzle_b32 v101, v104 offset:swizzle(SWAP,4)
	ds_swizzle_b32 v110, v102 offset:swizzle(SWAP,4)
	ds_swizzle_b32 v111, v11 offset:swizzle(SWAP,4)
	ds_swizzle_b32 v112, v108 offset:swizzle(SWAP,4)
	ds_swizzle_b32 v109, v105 offset:swizzle(SWAP,4)
	s_waitcnt lgkmcnt(10)
	v_fmac_f32_e32 v126, v15, v98
	s_waitcnt lgkmcnt(9)
	v_fmac_f32_e32 v127, v123, v98
	s_waitcnt lgkmcnt(8)
	v_fmac_f32_e32 v124, v120, v98
	v_max_f32_e64 v95, |v126|, |v127|
	s_waitcnt lgkmcnt(7)
	v_fmac_f32_e32 v103, v10, v98
	s_waitcnt lgkmcnt(6)
	v_fmac_f32_e32 v106, v12, v98
	v_max3_f32 v95, |v124|, |v125|, v95
	s_waitcnt lgkmcnt(5)
	v_fmac_f32_e32 v107, v13, v98
	s_waitcnt lgkmcnt(4)
	v_fmac_f32_e32 v101, v104, v98
	s_waitcnt lgkmcnt(3)
	v_fmac_f32_e32 v110, v102, v98
	s_waitcnt lgkmcnt(2)
	v_fmac_f32_e32 v111, v11, v98
	s_waitcnt lgkmcnt(1)
	v_fmac_f32_e32 v112, v108, v98
	v_max_f32_e64 v102, |v103|, |v106|
	v_cvt_pk_bf16_f32 v14, v124, v125
	v_cvt_pk_bf16_f32 v15, v126, v127
	s_waitcnt lgkmcnt(0)
	v_fmac_f32_e32 v109, v105, v98
	v_cvt_pk_bf16_f32 v12, v103, v106
	v_cvt_pk_bf16_f32 v13, v107, v101
	v_max3_f32 v94, v94, v95, v102
	v_max_f32_e64 v95, |v107|, |v101|
	v_max_f32_e64 v101, |v111|, |v112|
	v_max3_f32 v101, |v109|, |v110|, v101
	v_max3_f32 v94, v94, v95, v101
	v_cvt_pk_bf16_f32 v10, v109, v110
	v_cvt_pk_bf16_f32 v11, v111, v112
	s_waitcnt vmcnt(0)
	v_lshlrev_b32_e32 v95, 16, v6
	v_and_b32_e32 v6, 0xffff0000, v6
	v_lshlrev_b32_e32 v101, 16, v7
	v_and_b32_e32 v7, 0xffff0000, v7
	v_lshlrev_b32_e32 v102, 16, v8
	v_and_b32_e32 v8, 0xffff0000, v8
	v_lshlrev_b32_e32 v103, 16, v9
	v_and_b32_e32 v9, 0xffff0000, v9
	v_add_f32_e32 v104, v95, v6
	v_sub_f32_e32 v6, v95, v6
	v_add_f32_e32 v95, v101, v7
	v_sub_f32_e32 v7, v101, v7
	v_add_f32_e32 v101, v102, v8
	v_sub_f32_e32 v8, v102, v8
	v_add_f32_e32 v102, v103, v9
	v_sub_f32_e32 v9, v103, v9
	v_add_f32_e32 v103, v104, v95
	v_sub_f32_e32 v95, v104, v95
	v_add_f32_e32 v104, v6, v7
	v_sub_f32_e32 v6, v6, v7
	v_add_f32_e32 v7, v101, v102
	v_sub_f32_e32 v101, v101, v102
	v_add_f32_e32 v102, v8, v9
	v_sub_f32_e32 v8, v8, v9
	v_add_f32_e32 v9, v103, v7
	v_sub_f32_e32 v7, v103, v7
	v_add_f32_e32 v103, v104, v102
	v_sub_f32_e32 v102, v104, v102
	v_add_f32_e32 v104, v95, v101
	v_sub_f32_e32 v95, v95, v101
	v_add_f32_e32 v101, v6, v8
	v_sub_f32_e32 v6, v6, v8
	v_mov_b32_dpp v8, v9 quad_perm:[1,0,3,2] row_mask:0xf bank_mask:0xf bound_ctrl:1
	v_fmac_f32_e32 v8, v9, v96
	v_mov_b32_dpp v9, v103 quad_perm:[1,0,3,2] row_mask:0xf bank_mask:0xf bound_ctrl:1
	v_fmac_f32_e32 v9, v103, v96
	v_mov_b32_dpp v103, v104 quad_perm:[1,0,3,2] row_mask:0xf bank_mask:0xf bound_ctrl:1
	v_fmac_f32_e32 v103, v104, v96
	v_mov_b32_dpp v104, v101 quad_perm:[1,0,3,2] row_mask:0xf bank_mask:0xf bound_ctrl:1
	v_fmac_f32_e32 v104, v101, v96
	v_mov_b32_dpp v101, v7 quad_perm:[1,0,3,2] row_mask:0xf bank_mask:0xf bound_ctrl:1
	v_fmac_f32_e32 v101, v7, v96
	v_mov_b32_dpp v7, v102 quad_perm:[1,0,3,2] row_mask:0xf bank_mask:0xf bound_ctrl:1
	v_fmac_f32_e32 v7, v102, v96
	v_mov_b32_dpp v102, v95 quad_perm:[1,0,3,2] row_mask:0xf bank_mask:0xf bound_ctrl:1
	v_fmac_f32_e32 v102, v95, v96
	v_mov_b32_dpp v95, v6 quad_perm:[1,0,3,2] row_mask:0xf bank_mask:0xf bound_ctrl:1
	v_fmac_f32_e32 v95, v6, v96
	v_mov_b32_dpp v6, v8 quad_perm:[2,3,0,1] row_mask:0xf bank_mask:0xf bound_ctrl:1
	v_fmac_f32_e32 v6, v8, v97
	v_mov_b32_dpp v8, v9 quad_perm:[2,3,0,1] row_mask:0xf bank_mask:0xf bound_ctrl:1
	v_fmac_f32_e32 v8, v9, v97
	v_mov_b32_dpp v9, v103 quad_perm:[2,3,0,1] row_mask:0xf bank_mask:0xf bound_ctrl:1
	v_fmac_f32_e32 v9, v103, v97
	v_mov_b32_dpp v103, v104 quad_perm:[2,3,0,1] row_mask:0xf bank_mask:0xf bound_ctrl:1
	v_fmac_f32_e32 v103, v104, v97
	v_mov_b32_dpp v104, v101 quad_perm:[2,3,0,1] row_mask:0xf bank_mask:0xf bound_ctrl:1
	v_fmac_f32_e32 v104, v101, v97
	v_mov_b32_dpp v101, v7 quad_perm:[2,3,0,1] row_mask:0xf bank_mask:0xf bound_ctrl:1
	v_fmac_f32_e32 v101, v7, v97
	v_mov_b32_dpp v7, v102 quad_perm:[2,3,0,1] row_mask:0xf bank_mask:0xf bound_ctrl:1
	v_fmac_f32_e32 v7, v102, v97
	ds_swizzle_b32 v102, v6 offset:swizzle(SWAP,4)
	ds_swizzle_b32 v105, v8 offset:swizzle(SWAP,4)
	ds_swizzle_b32 v106, v9 offset:swizzle(SWAP,4)
	v_mov_b32_dpp v107, v95 quad_perm:[2,3,0,1] row_mask:0xf bank_mask:0xf bound_ctrl:1
	v_fmac_f32_e32 v107, v95, v97
	s_waitcnt lgkmcnt(2)
	v_fmac_f32_e32 v102, v6, v98
	s_waitcnt lgkmcnt(1)
	v_fmac_f32_e32 v105, v8, v98
	s_waitcnt lgkmcnt(0)
	v_fmac_f32_e32 v106, v9, v98
	ds_swizzle_b32 v6, v103 offset:swizzle(SWAP,4)
	ds_swizzle_b32 v8, v104 offset:swizzle(SWAP,4)
	ds_swizzle_b32 v9, v101 offset:swizzle(SWAP,4)
	ds_swizzle_b32 v95, v7 offset:swizzle(SWAP,4)
	ds_swizzle_b32 v108, v107 offset:swizzle(SWAP,4)
	s_waitcnt lgkmcnt(4)
	v_fmac_f32_e32 v6, v103, v98
	s_waitcnt lgkmcnt(3)
	v_fmac_f32_e32 v8, v104, v98
	s_waitcnt lgkmcnt(2)
	v_fmac_f32_e32 v9, v101, v98
	s_waitcnt lgkmcnt(1)
	v_fmac_f32_e32 v95, v7, v98
	v_lshlrev_b32_e32 v7, 16, v2
	v_and_b32_e32 v2, 0xffff0000, v2
	v_lshlrev_b32_e32 v101, 16, v3
	v_and_b32_e32 v3, 0xffff0000, v3
	v_lshlrev_b32_e32 v103, 16, v4
	v_and_b32_e32 v4, 0xffff0000, v4
	v_lshlrev_b32_e32 v104, 16, v5
	v_and_b32_e32 v5, 0xffff0000, v5
	s_waitcnt lgkmcnt(0)
	v_fmac_f32_e32 v108, v107, v98
	v_add_f32_e32 v107, v7, v2
	v_sub_f32_e32 v2, v7, v2
	v_add_f32_e32 v7, v101, v3
	v_sub_f32_e32 v3, v101, v3
	v_add_f32_e32 v101, v103, v4
	v_sub_f32_e32 v4, v103, v4
	v_add_f32_e32 v103, v104, v5
	v_sub_f32_e32 v5, v104, v5
	v_add_f32_e32 v104, v107, v7
	v_sub_f32_e32 v7, v107, v7
	v_add_f32_e32 v107, v2, v3
	v_sub_f32_e32 v2, v2, v3
	v_add_f32_e32 v3, v101, v103
	v_sub_f32_e32 v101, v101, v103
	v_add_f32_e32 v103, v4, v5
	v_sub_f32_e32 v4, v4, v5
	v_add_f32_e32 v5, v104, v3
	v_sub_f32_e32 v3, v104, v3
	v_add_f32_e32 v104, v107, v103
	v_sub_f32_e32 v103, v107, v103
	v_add_f32_e32 v107, v7, v101
	v_sub_f32_e32 v7, v7, v101
	v_add_f32_e32 v101, v2, v4
	v_sub_f32_e32 v2, v2, v4
	v_mov_b32_dpp v4, v5 quad_perm:[1,0,3,2] row_mask:0xf bank_mask:0xf bound_ctrl:1
	v_fmac_f32_e32 v4, v5, v96
	v_mov_b32_dpp v5, v104 quad_perm:[1,0,3,2] row_mask:0xf bank_mask:0xf bound_ctrl:1
	v_fmac_f32_e32 v5, v104, v96
	v_mov_b32_dpp v104, v107 quad_perm:[1,0,3,2] row_mask:0xf bank_mask:0xf bound_ctrl:1
	v_fmac_f32_e32 v104, v107, v96
	v_mov_b32_dpp v107, v101 quad_perm:[1,0,3,2] row_mask:0xf bank_mask:0xf bound_ctrl:1
	v_fmac_f32_e32 v107, v101, v96
	v_mov_b32_dpp v101, v3 quad_perm:[1,0,3,2] row_mask:0xf bank_mask:0xf bound_ctrl:1
	v_fmac_f32_e32 v101, v3, v96
	v_mov_b32_dpp v3, v103 quad_perm:[1,0,3,2] row_mask:0xf bank_mask:0xf bound_ctrl:1
	v_fmac_f32_e32 v3, v103, v96
	v_mov_b32_dpp v103, v7 quad_perm:[1,0,3,2] row_mask:0xf bank_mask:0xf bound_ctrl:1
	v_fmac_f32_e32 v103, v7, v96
	v_mov_b32_dpp v7, v2 quad_perm:[1,0,3,2] row_mask:0xf bank_mask:0xf bound_ctrl:1
	v_fmac_f32_e32 v7, v2, v96
	v_mov_b32_dpp v2, v4 quad_perm:[2,3,0,1] row_mask:0xf bank_mask:0xf bound_ctrl:1
	v_fmac_f32_e32 v2, v4, v97
	v_mov_b32_dpp v4, v5 quad_perm:[2,3,0,1] row_mask:0xf bank_mask:0xf bound_ctrl:1
	v_fmac_f32_e32 v4, v5, v97
	v_mov_b32_dpp v5, v104 quad_perm:[2,3,0,1] row_mask:0xf bank_mask:0xf bound_ctrl:1
	v_fmac_f32_e32 v5, v104, v97
	v_mov_b32_dpp v104, v107 quad_perm:[2,3,0,1] row_mask:0xf bank_mask:0xf bound_ctrl:1
	ds_swizzle_b32 v111, v5 offset:swizzle(SWAP,4)
	v_fmac_f32_e32 v104, v107, v97
	v_mov_b32_dpp v107, v101 quad_perm:[2,3,0,1] row_mask:0xf bank_mask:0xf bound_ctrl:1
	v_fmac_f32_e32 v107, v101, v97
	v_mov_b32_dpp v101, v3 quad_perm:[2,3,0,1] row_mask:0xf bank_mask:0xf bound_ctrl:1
	v_fmac_f32_e32 v101, v3, v97
	v_mov_b32_dpp v3, v103 quad_perm:[2,3,0,1] row_mask:0xf bank_mask:0xf bound_ctrl:1
	ds_swizzle_b32 v109, v2 offset:swizzle(SWAP,4)
	ds_swizzle_b32 v110, v4 offset:swizzle(SWAP,4)
	v_fmac_f32_e32 v3, v103, v97
	v_mov_b32_dpp v103, v7 quad_perm:[2,3,0,1] row_mask:0xf bank_mask:0xf bound_ctrl:1
	v_fmac_f32_e32 v103, v7, v97
	s_waitcnt lgkmcnt(2)
	v_fmac_f32_e32 v111, v5, v98
	ds_swizzle_b32 v5, v101 offset:swizzle(SWAP,4)
	ds_swizzle_b32 v7, v3 offset:swizzle(SWAP,4)
	ds_swizzle_b32 v112, v103 offset:swizzle(SWAP,4)
	s_waitcnt lgkmcnt(4)
	v_fmac_f32_e32 v109, v2, v98
	s_waitcnt lgkmcnt(3)
	v_fmac_f32_e32 v110, v4, v98
	ds_swizzle_b32 v2, v104 offset:swizzle(SWAP,4)
	ds_swizzle_b32 v4, v107 offset:swizzle(SWAP,4)
	s_waitcnt lgkmcnt(4)
	v_fmac_f32_e32 v5, v101, v98
	s_waitcnt lgkmcnt(3)
	v_fmac_f32_e32 v7, v3, v98
	v_max_f32_e64 v3, |v102|, |v105|
	v_max_f32_e64 v101, |v106|, |v6|
	v_max3_f32 v3, v94, v3, v101
	v_max_f32_e64 v94, |v95|, |v108|
	s_waitcnt lgkmcnt(2)
	v_fmac_f32_e32 v112, v103, v98
	v_max3_f32 v94, |v8|, |v9|, v94
	v_max_f32_e64 v101, |v109|, |v110|
	s_waitcnt lgkmcnt(1)
	v_fmac_f32_e32 v2, v104, v98
	s_waitcnt lgkmcnt(0)
	v_fmac_f32_e32 v4, v107, v98
	v_max3_f32 v3, v3, v94, v101
	v_max_f32_e64 v101, |v7|, |v112|
	v_max_f32_e64 v94, |v111|, |v2|
	v_max3_f32 v101, |v4|, |v5|, v101
	v_max3_f32 v3, v3, v94, v101
	v_and_b32_e32 v94, 64, v99
	v_add_u32_e32 v104, 64, v94
	v_xor_b32_e32 v94, 1, v99
	v_cmp_lt_i32_e32 vcc, v94, v104
	v_cvt_pk_bf16_f32 v101, v102, v105
	v_cvt_pk_bf16_f32 v103, v106, v6
	s_nop 1
	v_cndmask_b32_e32 v94, v99, v94, vcc
	v_lshlrev_b32_e32 v94, 2, v94
	ds_bpermute_b32 v94, v94, v3
	s_waitcnt lgkmcnt(0)
	v_max_f32_e32 v94, v94, v94
	v_max_f32_e32 v3, v3, v94
	v_xor_b32_e32 v94, 2, v99
	v_cmp_lt_i32_e32 vcc, v94, v104
	s_nop 1
	v_cndmask_b32_e32 v94, v99, v94, vcc
	v_lshlrev_b32_e32 v94, 2, v94
	ds_bpermute_b32 v94, v94, v3
	s_waitcnt lgkmcnt(0)
	v_max_f32_e32 v94, v94, v94
	v_max_f32_e32 v3, v3, v94
	v_xor_b32_e32 v94, 4, v99
	v_cmp_lt_i32_e32 vcc, v94, v104
	s_nop 1
	v_cndmask_b32_e32 v94, v99, v94, vcc
	v_lshlrev_b32_e32 v94, 2, v94
	ds_bpermute_b32 v94, v94, v3
	s_waitcnt lgkmcnt(0)
	v_max_f32_e32 v94, v94, v94
	v_max_f32_e32 v3, v3, v94
	v_xor_b32_e32 v94, 8, v99
	v_cmp_lt_i32_e32 vcc, v94, v104
	s_nop 1
	v_cndmask_b32_e32 v94, v99, v94, vcc
	v_lshlrev_b32_e32 v94, 2, v94
	ds_bpermute_b32 v94, v94, v3
	s_waitcnt lgkmcnt(0)
	v_max_f32_e32 v94, v94, v94
	v_max_f32_e32 v3, v3, v94
	v_xor_b32_e32 v94, 16, v99
	v_cmp_lt_i32_e32 vcc, v94, v104
	s_nop 1
	v_cndmask_b32_e32 v94, v99, v94, vcc
	v_lshlrev_b32_e32 v94, 2, v94
	ds_bpermute_b32 v107, v94, v3
	v_cvt_pk_bf16_f32 v94, v8, v9
	v_cvt_pk_bf16_f32 v95, v95, v108
	v_cvt_pk_bf16_f32 v8, v109, v110
	v_cvt_pk_bf16_f32 v9, v111, v2
	s_waitcnt lgkmcnt(0)
	v_max_f32_e32 v6, v107, v107
	v_max_f32_e32 v3, v3, v6
	v_xor_b32_e32 v6, 32, v99
	v_cmp_lt_i32_e32 vcc, v6, v104
	s_nop 1
	v_cndmask_b32_e32 v6, v99, v6, vcc
	v_lshlrev_b32_e32 v6, 2, v6
	ds_bpermute_b32 v102, v6, v3
	v_cvt_pk_bf16_f32 v6, v4, v5
	v_cvt_pk_bf16_f32 v7, v7, v112
	s_waitcnt lgkmcnt(0)
	v_max3_f32 v2, v3, v102, s52
	s_and_saveexec_b64 s[0:1], s[8:9]
	s_cbranch_execz .LBB0_330
	s_ashr_i32 s39, s38, 31
	s_lshl_b64 s[44:45], s[38:39], 2
	s_add_u32 s44, s34, s44
	v_mul_f32_e32 v3, 0x3a810204, v2
	s_addc_u32 s45, s35, s45
	global_store_dword v1, v3, s[44:45]

.LBB0_409:
	ds_read_b128 v[148:151], v157
	ds_read_b128 v[152:155], v157 offset:1024
	ds_read_b128 v[160:163], v157 offset:2048
	ds_read_b128 v[164:167], v157 offset:3072
	ds_read_b128 v[168:171], v158
	ds_read_b128 v[172:175], v158 offset:1024
	ds_read_b128 v[176:179], v158 offset:2048
	ds_read_b128 v[180:183], v158 offset:3072
	s_add_u32 s48, s0, 0x100
	s_addc_u32 s49, s1, 0
	s_cmpk_eq_i32 s77, 0x52
	s_cselect_b32 s53, s7, s49
	s_cselect_b32 s52, s6, s48
	s_cselect_b32 s51, s47, s76
	s_cselect_b32 s50, s46, s75
	v_lshl_add_u64 v[216:217], s[0:1], 0, v[138:139]
	s_add_i32 m0, s55, 0xc000
	ds_read_b128 v[184:187], v159
	ds_read_b128 v[188:191], v159 offset:1024
	ds_read_b128 v[192:195], v159 offset:2048
	ds_read_b128 v[196:199], v159 offset:3072
	ds_read_b128 v[200:203], v159 offset:4096
	ds_read_b128 v[204:207], v159 offset:5120
	ds_read_b128 v[208:211], v159 offset:6144
	ds_read_b128 v[212:215], v159 offset:7168
	global_load_lds_dwordx4 v[216:217], off
	v_lshl_add_u64 v[216:217], s[0:1], 0, v[140:141]
	s_add_i32 m0, s55, 0xe000
	s_nop 0
	global_load_lds_dwordx4 v[216:217], off
	s_waitcnt vmcnt(8)
	s_waitcnt lgkmcnt(0)
	s_barrier
	s_setprio 2
	s_waitcnt lgkmcnt(0)
	v_mfma_i32_16x16x64_i8 v[126:129], v[148:151], v[184:187], v[126:129]
	v_mfma_i32_16x16x64_i8 v[122:125], v[160:163], v[184:187], v[122:125]
	v_mfma_i32_16x16x64_i8 v[118:121], v[148:151], v[192:195], v[118:121]
	v_mfma_i32_16x16x64_i8 v[114:117], v[160:163], v[192:195], v[114:117]
	v_mfma_i32_16x16x64_i8 v[110:113], v[148:151], v[200:203], v[110:113]
	v_mfma_i32_16x16x64_i8 v[106:109], v[160:163], v[200:203], v[106:109]
	v_mfma_i32_16x16x64_i8 v[102:105], v[148:151], v[208:211], v[102:105]
	v_mfma_i32_16x16x64_i8 v[98:101], v[160:163], v[208:211], v[98:101]
	v_mfma_i32_16x16x64_i8 v[126:129], v[152:155], v[188:191], v[126:129]
	v_mfma_i32_16x16x64_i8 v[122:125], v[164:167], v[188:191], v[122:125]
	v_mfma_i32_16x16x64_i8 v[118:121], v[152:155], v[196:199], v[118:121]
	v_mfma_i32_16x16x64_i8 v[114:117], v[164:167], v[196:199], v[114:117]
	v_mfma_i32_16x16x64_i8 v[110:113], v[152:155], v[204:207], v[110:113]
	v_mfma_i32_16x16x64_i8 v[106:109], v[164:167], v[204:207], v[106:109]
	v_mfma_i32_16x16x64_i8 v[102:105], v[152:155], v[212:215], v[102:105]
	v_mfma_i32_16x16x64_i8 v[98:101], v[164:167], v[212:215], v[98:101]
	s_setprio 0
	s_setprio 2
	v_mfma_i32_16x16x64_i8 v[62:65], v[168:171], v[184:187], v[62:65]
	v_mfma_i32_16x16x64_i8 v[58:61], v[176:179], v[184:187], v[58:61]
	v_mfma_i32_16x16x64_i8 v[54:57], v[168:171], v[192:195], v[54:57]
	v_mfma_i32_16x16x64_i8 v[50:53], v[176:179], v[192:195], v[50:53]
	v_mfma_i32_16x16x64_i8 v[46:49], v[168:171], v[200:203], v[46:49]
	v_mfma_i32_16x16x64_i8 v[42:45], v[176:179], v[200:203], v[42:45]
	v_mfma_i32_16x16x64_i8 v[38:41], v[168:171], v[208:211], v[38:41]
	v_mfma_i32_16x16x64_i8 v[34:37], v[176:179], v[208:211], v[34:37]
	v_mfma_i32_16x16x64_i8 v[62:65], v[172:175], v[188:191], v[62:65]
	v_mfma_i32_16x16x64_i8 v[58:61], v[180:183], v[188:191], v[58:61]
	v_mfma_i32_16x16x64_i8 v[54:57], v[172:175], v[196:199], v[54:57]
	v_mfma_i32_16x16x64_i8 v[50:53], v[180:183], v[196:199], v[50:53]
	s_setprio 3
	s_barrier
	v_mfma_i32_16x16x64_i8 v[46:49], v[172:175], v[204:207], v[46:49]
	v_mfma_i32_16x16x64_i8 v[42:45], v[180:183], v[204:207], v[42:45]
	v_mfma_i32_16x16x64_i8 v[38:41], v[172:175], v[212:215], v[38:41]
	v_mfma_i32_16x16x64_i8 v[34:37], v[180:183], v[212:215], v[34:37]
	s_setprio 0
	s_add_i32 s0, s63, s54
	v_lshl_add_u64 v[216:217], s[50:51], 0, v[130:131]
	s_mov_b32 m0, s0
	ds_read_b128 v[184:187], v159 offset:16384
	ds_read_b128 v[188:191], v159 offset:17408
	ds_read_b128 v[192:195], v159 offset:18432
	ds_read_b128 v[196:199], v159 offset:19456
	ds_read_b128 v[200:203], v159 offset:20480
	ds_read_b128 v[204:207], v159 offset:21504
	ds_read_b128 v[208:211], v159 offset:22528
	ds_read_b128 v[212:215], v159 offset:23552
	global_load_lds_dwordx4 v[216:217], off
	s_add_i32 m0, s0, 0x2000
	s_add_u32 s0, s50, 0x158000
	v_lshl_add_u64 v[216:217], s[50:51], 0, v[134:135]
	s_addc_u32 s1, s51, 0
	s_add_i32 s78, s64, s54
	global_load_lds_dwordx4 v[216:217], off
	v_lshl_add_u64 v[216:217], s[0:1], 0, v[130:131]
	s_mov_b32 m0, s78
	v_lshl_add_u64 v[218:219], s[52:53], 0, v[136:137]
	global_load_lds_dwordx4 v[216:217], off
	v_lshl_add_u64 v[216:217], s[0:1], 0, v[134:135]
	s_add_i32 m0, s78, 0x2000
	s_nop 0
	global_load_lds_dwordx4 v[216:217], off
	v_lshl_add_u64 v[216:217], s[52:53], 0, v[132:133]
	s_mov_b32 m0, s55
	s_nop 0
	global_load_lds_dwordx4 v[216:217], off
	s_mov_b32 m0, s56
	s_nop 0
	global_load_lds_dwordx4 v[218:219], off
	s_waitcnt vmcnt(8)
	s_waitcnt lgkmcnt(0)
	s_barrier
	s_setprio 2
	s_waitcnt lgkmcnt(0)
	v_mfma_i32_16x16x64_i8 v[94:97], v[148:151], v[184:187], v[94:97]
	v_mfma_i32_16x16x64_i8 v[90:93], v[160:163], v[184:187], v[90:93]
	v_mfma_i32_16x16x64_i8 v[86:89], v[148:151], v[192:195], v[86:89]
	v_mfma_i32_16x16x64_i8 v[82:85], v[160:163], v[192:195], v[82:85]
	v_mfma_i32_16x16x64_i8 v[78:81], v[148:151], v[200:203], v[78:81]
	v_mfma_i32_16x16x64_i8 v[74:77], v[160:163], v[200:203], v[74:77]
	v_mfma_i32_16x16x64_i8 v[70:73], v[148:151], v[208:211], v[70:73]
	v_mfma_i32_16x16x64_i8 v[66:69], v[160:163], v[208:211], v[66:69]
	v_mfma_i32_16x16x64_i8 v[94:97], v[152:155], v[188:191], v[94:97]
	v_mfma_i32_16x16x64_i8 v[90:93], v[164:167], v[188:191], v[90:93]
	v_mfma_i32_16x16x64_i8 v[86:89], v[152:155], v[196:199], v[86:89]
	v_mfma_i32_16x16x64_i8 v[82:85], v[164:167], v[196:199], v[82:85]
	v_mfma_i32_16x16x64_i8 v[78:81], v[152:155], v[204:207], v[78:81]
	v_mfma_i32_16x16x64_i8 v[74:77], v[164:167], v[204:207], v[74:77]
	v_mfma_i32_16x16x64_i8 v[70:73], v[152:155], v[212:215], v[70:73]
	v_mfma_i32_16x16x64_i8 v[66:69], v[164:167], v[212:215], v[66:69]
	s_setprio 0
	s_setprio 2
	v_mfma_i32_16x16x64_i8 v[30:33], v[168:171], v[184:187], v[30:33]
	v_mfma_i32_16x16x64_i8 v[26:29], v[176:179], v[184:187], v[26:29]
	v_mfma_i32_16x16x64_i8 v[22:25], v[168:171], v[192:195], v[22:25]
	v_mfma_i32_16x16x64_i8 v[18:21], v[176:179], v[192:195], v[18:21]
	v_mfma_i32_16x16x64_i8 v[14:17], v[168:171], v[200:203], v[14:17]
	v_mfma_i32_16x16x64_i8 v[10:13], v[176:179], v[200:203], v[10:13]
	v_mfma_i32_16x16x64_i8 v[6:9], v[168:171], v[208:211], v[6:9]
	v_mfma_i32_16x16x64_i8 v[2:5], v[176:179], v[208:211], v[2:5]
	v_mfma_i32_16x16x64_i8 v[30:33], v[172:175], v[188:191], v[30:33]
	v_mfma_i32_16x16x64_i8 v[26:29], v[180:183], v[188:191], v[26:29]
	v_mfma_i32_16x16x64_i8 v[22:25], v[172:175], v[196:199], v[22:25]
	v_mfma_i32_16x16x64_i8 v[18:21], v[180:183], v[196:199], v[18:21]
	s_setprio 3
	s_barrier
	v_mfma_i32_16x16x64_i8 v[14:17], v[172:175], v[204:207], v[14:17]
	v_mfma_i32_16x16x64_i8 v[10:13], v[180:183], v[204:207], v[10:13]
	v_mfma_i32_16x16x64_i8 v[6:9], v[172:175], v[212:215], v[6:9]
	v_mfma_i32_16x16x64_i8 v[2:5], v[180:183], v[212:215], v[2:5]
	s_setprio 0
	s_add_i32 s78, 0, 0x18000
	s_add_i32 s79, 0, 0x1c000
	v_add_u32_e32 v164, s78, v147
	v_add_u32_e32 v180, s79, v147
	ds_read_b128 v[148:151], v164
	ds_read_b128 v[152:155], v164 offset:1024
	ds_read_b128 v[160:163], v164 offset:2048
	ds_read_b128 v[164:167], v164 offset:3072
	ds_read_b128 v[168:171], v180
	ds_read_b128 v[172:175], v180 offset:1024
	ds_read_b128 v[176:179], v180 offset:2048
	ds_read_b128 v[180:183], v180 offset:3072
	s_add_u32 s0, s52, 0x158000
	s_addc_u32 s1, s53, 0
	s_mov_b32 m0, s57
	v_lshl_add_u64 v[220:221], s[0:1], 0, v[132:133]
	ds_read_b128 v[184:187], v159 offset:32768
	ds_read_b128 v[188:191], v159 offset:33792
	ds_read_b128 v[192:195], v159 offset:34816
	ds_read_b128 v[196:199], v159 offset:35840
	ds_read_b128 v[200:203], v159 offset:36864
	ds_read_b128 v[204:207], v159 offset:37888
	ds_read_b128 v[208:211], v159 offset:38912
	ds_read_b128 v[212:215], v159 offset:39936
	global_load_lds_dwordx4 v[220:221], off
	v_lshl_add_u64 v[220:221], s[0:1], 0, v[136:137]
	s_mov_b32 m0, s58
	s_nop 0
	global_load_lds_dwordx4 v[220:221], off
	s_waitcnt vmcnt(8)
	s_waitcnt lgkmcnt(0)
	s_barrier
	s_setprio 2
	s_waitcnt lgkmcnt(0)
	v_mfma_i32_16x16x64_i8 v[126:129], v[148:151], v[184:187], v[126:129]
	v_mfma_i32_16x16x64_i8 v[122:125], v[160:163], v[184:187], v[122:125]
	v_mfma_i32_16x16x64_i8 v[118:121], v[148:151], v[192:195], v[118:121]
	v_mfma_i32_16x16x64_i8 v[114:117], v[160:163], v[192:195], v[114:117]
	v_mfma_i32_16x16x64_i8 v[110:113], v[148:151], v[200:203], v[110:113]
	v_mfma_i32_16x16x64_i8 v[106:109], v[160:163], v[200:203], v[106:109]
	v_mfma_i32_16x16x64_i8 v[102:105], v[148:151], v[208:211], v[102:105]
	v_mfma_i32_16x16x64_i8 v[98:101], v[160:163], v[208:211], v[98:101]
	v_mfma_i32_16x16x64_i8 v[126:129], v[152:155], v[188:191], v[126:129]
	v_mfma_i32_16x16x64_i8 v[122:125], v[164:167], v[188:191], v[122:125]
	v_mfma_i32_16x16x64_i8 v[118:121], v[152:155], v[196:199], v[118:121]
	v_mfma_i32_16x16x64_i8 v[114:117], v[164:167], v[196:199], v[114:117]
	v_mfma_i32_16x16x64_i8 v[110:113], v[152:155], v[204:207], v[110:113]
	v_mfma_i32_16x16x64_i8 v[106:109], v[164:167], v[204:207], v[106:109]
	v_mfma_i32_16x16x64_i8 v[102:105], v[152:155], v[212:215], v[102:105]
	v_mfma_i32_16x16x64_i8 v[98:101], v[164:167], v[212:215], v[98:101]
	s_setprio 0
	s_setprio 2
	v_mfma_i32_16x16x64_i8 v[62:65], v[168:171], v[184:187], v[62:65]
	v_mfma_i32_16x16x64_i8 v[58:61], v[176:179], v[184:187], v[58:61]
	v_mfma_i32_16x16x64_i8 v[54:57], v[168:171], v[192:195], v[54:57]
	v_mfma_i32_16x16x64_i8 v[50:53], v[176:179], v[192:195], v[50:53]
	v_mfma_i32_16x16x64_i8 v[46:49], v[168:171], v[200:203], v[46:49]
	v_mfma_i32_16x16x64_i8 v[42:45], v[176:179], v[200:203], v[42:45]
	v_mfma_i32_16x16x64_i8 v[38:41], v[168:171], v[208:211], v[38:41]
	v_mfma_i32_16x16x64_i8 v[34:37], v[176:179], v[208:211], v[34:37]
	v_mfma_i32_16x16x64_i8 v[62:65], v[172:175], v[188:191], v[62:65]
	v_mfma_i32_16x16x64_i8 v[58:61], v[180:183], v[188:191], v[58:61]
	v_mfma_i32_16x16x64_i8 v[54:57], v[172:175], v[196:199], v[54:57]
	v_mfma_i32_16x16x64_i8 v[50:53], v[180:183], v[196:199], v[50:53]
	s_setprio 3
	s_barrier
	v_mfma_i32_16x16x64_i8 v[46:49], v[172:175], v[204:207], v[46:49]
	v_mfma_i32_16x16x64_i8 v[42:45], v[180:183], v[204:207], v[42:45]
	v_mfma_i32_16x16x64_i8 v[38:41], v[172:175], v[212:215], v[38:41]
	v_mfma_i32_16x16x64_i8 v[34:37], v[180:183], v[212:215], v[34:37]
	s_setprio 0
	s_add_u32 s0, s50, 0x4000
	s_addc_u32 s1, s51, 0
	s_add_i32 s52, s78, s54
	v_lshl_add_u64 v[220:221], s[0:1], 0, v[130:131]
	s_mov_b32 m0, s52
	ds_read_b128 v[184:187], v159 offset:49152
	ds_read_b128 v[188:191], v159 offset:50176
	ds_read_b128 v[192:195], v159 offset:51200
	ds_read_b128 v[196:199], v159 offset:52224
	ds_read_b128 v[200:203], v159 offset:53248
	ds_read_b128 v[204:207], v159 offset:54272
	ds_read_b128 v[208:211], v159 offset:55296
	ds_read_b128 v[212:215], v159 offset:56320
	global_load_lds_dwordx4 v[220:221], off
	s_add_i32 m0, s52, 0x2000
	v_lshl_add_u64 v[220:221], s[0:1], 0, v[134:135]
	s_add_u32 s0, s50, 0x15c000
	s_addc_u32 s1, s51, 0
	s_add_i32 s50, s79, s54
	global_load_lds_dwordx4 v[220:221], off
	v_lshl_add_u64 v[220:221], s[0:1], 0, v[130:131]
	s_mov_b32 m0, s50
	v_lshl_add_u64 v[216:217], v[216:217], 0, s[18:19]
	global_load_lds_dwordx4 v[220:221], off
	v_lshl_add_u64 v[220:221], s[0:1], 0, v[134:135]
	s_add_i32 m0, s50, 0x2000
	s_nop 0
	global_load_lds_dwordx4 v[220:221], off
	s_mov_b32 m0, s60
	s_nop 0
	global_load_lds_dwordx4 v[216:217], off
	v_lshl_add_u64 v[216:217], v[218:219], 0, s[18:19]
	s_mov_b32 m0, s61
	s_nop 0
	global_load_lds_dwordx4 v[216:217], off
	s_waitcnt vmcnt(8)
	s_waitcnt lgkmcnt(0)
	s_barrier
	s_setprio 2
	s_waitcnt lgkmcnt(0)
	v_mfma_i32_16x16x64_i8 v[94:97], v[148:151], v[184:187], v[94:97]
	v_mfma_i32_16x16x64_i8 v[90:93], v[160:163], v[184:187], v[90:93]
	v_mfma_i32_16x16x64_i8 v[86:89], v[148:151], v[192:195], v[86:89]
	v_mfma_i32_16x16x64_i8 v[82:85], v[160:163], v[192:195], v[82:85]
	v_mfma_i32_16x16x64_i8 v[78:81], v[148:151], v[200:203], v[78:81]
	v_mfma_i32_16x16x64_i8 v[74:77], v[160:163], v[200:203], v[74:77]
	v_mfma_i32_16x16x64_i8 v[70:73], v[148:151], v[208:211], v[70:73]
	v_mfma_i32_16x16x64_i8 v[66:69], v[160:163], v[208:211], v[66:69]
	v_mfma_i32_16x16x64_i8 v[94:97], v[152:155], v[188:191], v[94:97]
	v_mfma_i32_16x16x64_i8 v[90:93], v[164:167], v[188:191], v[90:93]
	v_mfma_i32_16x16x64_i8 v[86:89], v[152:155], v[196:199], v[86:89]
	v_mfma_i32_16x16x64_i8 v[82:85], v[164:167], v[196:199], v[82:85]
	v_mfma_i32_16x16x64_i8 v[78:81], v[152:155], v[204:207], v[78:81]
	v_mfma_i32_16x16x64_i8 v[74:77], v[164:167], v[204:207], v[74:77]
	v_mfma_i32_16x16x64_i8 v[70:73], v[152:155], v[212:215], v[70:73]
	v_mfma_i32_16x16x64_i8 v[66:69], v[164:167], v[212:215], v[66:69]
	s_setprio 0
	s_setprio 2
	v_mfma_i32_16x16x64_i8 v[30:33], v[168:171], v[184:187], v[30:33]
	v_mfma_i32_16x16x64_i8 v[26:29], v[176:179], v[184:187], v[26:29]
	v_mfma_i32_16x16x64_i8 v[22:25], v[168:171], v[192:195], v[22:25]
	v_mfma_i32_16x16x64_i8 v[18:21], v[176:179], v[192:195], v[18:21]
	v_mfma_i32_16x16x64_i8 v[14:17], v[168:171], v[200:203], v[14:17]
	v_mfma_i32_16x16x64_i8 v[10:13], v[176:179], v[200:203], v[10:13]
	v_mfma_i32_16x16x64_i8 v[6:9], v[168:171], v[208:211], v[6:9]
	v_mfma_i32_16x16x64_i8 v[2:5], v[176:179], v[208:211], v[2:5]
	v_mfma_i32_16x16x64_i8 v[30:33], v[172:175], v[188:191], v[30:33]
	v_mfma_i32_16x16x64_i8 v[26:29], v[180:183], v[188:191], v[26:29]
	v_mfma_i32_16x16x64_i8 v[22:25], v[172:175], v[196:199], v[22:25]
	v_mfma_i32_16x16x64_i8 v[18:21], v[180:183], v[196:199], v[18:21]
	s_setprio 3
	s_barrier
	v_mfma_i32_16x16x64_i8 v[14:17], v[172:175], v[204:207], v[14:17]
	v_mfma_i32_16x16x64_i8 v[10:13], v[180:183], v[204:207], v[10:13]
	v_mfma_i32_16x16x64_i8 v[6:9], v[172:175], v[212:215], v[6:9]
	v_mfma_i32_16x16x64_i8 v[2:5], v[180:183], v[212:215], v[2:5]
	s_setprio 0
	s_add_i32 s77, s77, 2
	s_add_u32 s75, s75, 0x8000
	s_addc_u32 s76, s76, 0
	s_cmpk_gt_u32 s77, 0x53
	s_mov_b64 s[0:1], s[48:49]
	s_cbranch_scc0 .LBB0_409
	s_and_b64 vcc, exec, s[20:21]
	s_cbranch_vccz .LBB0_412
	s_barrier

.LBB0_477:
	s_cmp_ge_i32 s3, s44
	s_cselect_b64 s[40:41], -1, 0
	s_cmp_lt_i32 s3, s44
	s_cselect_b64 s[0:1], -1, 0
	s_or_b64 vcc, s[18:19], s[0:1]
	v_cndmask_b32_e32 v83, 0, v83, vcc
	s_nor_b64 s[8:9], s[4:5], vcc
	s_and_saveexec_b64 s[0:1], s[8:9]
	s_cbranch_execz .LBB0_481
	s_mov_b64 s[42:43], exec
	v_mbcnt_lo_u32_b32 v2, s42, 0
	v_mbcnt_hi_u32_b32 v2, s43, v2
	v_cmp_eq_u32_e32 vcc, 0, v2
	s_and_saveexec_b64 s[8:9], vcc
	s_cbranch_execz .LBB0_480
	s_bcnt1_i32_b64 s39, s[42:43]
	v_mov_b32_e32 v3, s39
	global_atomic_add v223, v67, v3, s[24:25] sc0

.LBB0_481:
	s_or_b64 exec, exec, s[0:1]
	s_ashr_i32 s39, s38, 31
	s_lshl_b64 s[0:1], s[38:39], 13
	v_lshl_add_u64 v[8:9], v[68:69], 0, s[0:1]
	global_load_dwordx2 v[10:11], v[8:9], off
	global_load_dwordx2 v[12:13], v[8:9], off offset:512
	global_load_dwordx2 v[14:15], v[8:9], off offset:1024
	global_load_dwordx2 v[16:17], v[8:9], off offset:1536
	global_load_dwordx2 v[18:19], v[8:9], off offset:2048
	global_load_dwordx2 v[20:21], v[8:9], off offset:2560
	global_load_dwordx2 v[22:23], v[8:9], off offset:3072
	global_load_dwordx2 v[24:25], v[8:9], off offset:3584
	s_lshl_b64 s[8:9], s[38:39], 14
	v_add_co_u32_e32 v8, vcc, 0x1000, v8
	v_lshl_add_u64 v[6:7], v[70:71], 0, s[8:9]
	s_nop 0
	v_addc_co_u32_e32 v9, vcc, 0, v9, vcc
	global_load_dwordx4 v[2:5], v[6:7], off
	global_load_dwordx2 v[26:27], v[8:9], off
	global_load_dwordx2 v[28:29], v[8:9], off offset:512
	global_load_dwordx2 v[30:31], v[8:9], off offset:1024
	global_load_dwordx2 v[32:33], v[8:9], off offset:1536
	global_load_dwordx2 v[34:35], v[8:9], off offset:2048
	global_load_dwordx2 v[36:37], v[8:9], off offset:2560
	global_load_dwordx2 v[38:39], v[8:9], off offset:3072
	s_nop 0
	global_load_dwordx2 v[8:9], v[8:9], off offset:3584
	s_nop 0
	global_load_dwordx4 v[62:65], v[6:7], off offset:1024
	global_load_dwordx4 v[54:57], v[6:7], off offset:2048
	global_load_dwordx4 v[50:53], v[6:7], off offset:3072
	s_waitcnt vmcnt(19)
	v_readfirstlane_b32 s98, v223
	s_nop 1
	v_mov_b32_e32 v83, s98
	v_and_b32_e32 v89, 0xffff0000, v10
	v_and_b32_e32 v91, 0xffff0000, v11
	s_waitcnt vmcnt(18)
	v_and_b32_e32 v95, 0xffff0000, v12
	v_and_b32_e32 v97, 0xffff0000, v13
	v_lshlrev_b32_e32 v88, 16, v10
	v_lshlrev_b32_e32 v90, 16, v11
	v_lshlrev_b32_e32 v94, 16, v12
	v_lshlrev_b32_e32 v96, 16, v13
	s_waitcnt vmcnt(17)
	v_and_b32_e32 v99, 0xffff0000, v14
	v_and_b32_e32 v101, 0xffff0000, v15
	v_mul_f32_e32 v10, v89, v89
	v_mul_f32_e32 v11, v91, v91
	v_mul_f32_e32 v12, v95, v95
	v_mul_f32_e32 v13, v97, v97
	v_lshlrev_b32_e32 v98, 16, v14
	v_lshlrev_b32_e32 v100, 16, v15
	s_waitcnt vmcnt(16)
	v_and_b32_e32 v103, 0xffff0000, v16
	v_and_b32_e32 v105, 0xffff0000, v17
	v_mul_f32_e32 v14, v99, v99
	v_mul_f32_e32 v15, v101, v101
	v_fmac_f32_e32 v10, v88, v88
	v_fmac_f32_e32 v11, v90, v90
	v_fmac_f32_e32 v12, v94, v94
	v_fmac_f32_e32 v13, v96, v96
	v_lshlrev_b32_e32 v102, 16, v16
	v_lshlrev_b32_e32 v104, 16, v17
	s_waitcnt vmcnt(15)
	v_and_b32_e32 v107, 0xffff0000, v18
	v_and_b32_e32 v109, 0xffff0000, v19
	v_mul_f32_e32 v16, v103, v103
	v_mul_f32_e32 v17, v105, v105
	v_fmac_f32_e32 v14, v98, v98
	v_fmac_f32_e32 v15, v100, v100
	v_add_f32_e32 v10, v10, v11
	v_add_f32_e32 v11, v12, v13
	v_lshlrev_b32_e32 v106, 16, v18
	v_lshlrev_b32_e32 v108, 16, v19
	s_waitcnt vmcnt(14)
	v_and_b32_e32 v111, 0xffff0000, v20
	v_and_b32_e32 v113, 0xffff0000, v21
	v_mul_f32_e32 v18, v107, v107
	v_mul_f32_e32 v19, v109, v109
	v_fmac_f32_e32 v16, v102, v102
	v_fmac_f32_e32 v17, v104, v104
	v_add_f32_e32 v12, v14, v15
	v_add_f32_e32 v10, v10, v11
	v_lshlrev_b32_e32 v110, 16, v20
	v_lshlrev_b32_e32 v112, 16, v21
	s_waitcnt vmcnt(13)
	v_and_b32_e32 v115, 0xffff0000, v22
	v_and_b32_e32 v117, 0xffff0000, v23
	v_mul_f32_e32 v20, v111, v111
	v_mul_f32_e32 v21, v113, v113
	v_fmac_f32_e32 v18, v106, v106
	v_fmac_f32_e32 v19, v108, v108
	v_add_f32_e32 v13, v16, v17
	v_add_f32_e32 v10, v10, v12
	v_lshlrev_b32_e32 v114, 16, v22
	v_lshlrev_b32_e32 v116, 16, v23
	v_mul_f32_e32 v22, v115, v115
	v_fmac_f32_e32 v20, v110, v110
	v_fmac_f32_e32 v21, v112, v112
	v_add_f32_e32 v14, v18, v19
	v_add_f32_e32 v10, v10, v13
	v_mul_f32_e32 v11, v117, v117
	v_fmac_f32_e32 v22, v114, v114
	v_add_f32_e32 v15, v20, v21
	v_add_f32_e32 v10, v10, v14
	v_fmac_f32_e32 v11, v116, v116
	v_add_f32_e32 v10, v10, v15
	v_add_f32_e32 v11, v22, v11
	s_waitcnt vmcnt(12)
	v_and_b32_e32 v119, 0xffff0000, v24
	v_and_b32_e32 v121, 0xffff0000, v25
	v_add_f32_e32 v10, v10, v11
	v_lshlrev_b32_e32 v118, 16, v24
	v_lshlrev_b32_e32 v120, 16, v25
	v_mul_f32_e32 v11, v119, v119
	v_mul_f32_e32 v12, v121, v121
	v_fmac_f32_e32 v11, v118, v118
	v_fmac_f32_e32 v12, v120, v120
	v_add_f32_e32 v11, v11, v12
	s_waitcnt vmcnt(10)
	v_and_b32_e32 v123, 0xffff0000, v26
	v_and_b32_e32 v125, 0xffff0000, v27
	v_add_f32_e32 v10, v10, v11
	v_lshlrev_b32_e32 v122, 16, v26
	v_lshlrev_b32_e32 v124, 16, v27
	v_mul_f32_e32 v11, v123, v123
	v_mul_f32_e32 v12, v125, v125
	v_fmac_f32_e32 v11, v122, v122
	v_fmac_f32_e32 v12, v124, v124
	v_add_f32_e32 v11, v11, v12
	s_waitcnt vmcnt(9)
	v_and_b32_e32 v127, 0xffff0000, v28
	v_and_b32_e32 v129, 0xffff0000, v29
	v_add_f32_e32 v10, v10, v11
	v_lshlrev_b32_e32 v126, 16, v28
	v_lshlrev_b32_e32 v128, 16, v29
	v_mul_f32_e32 v11, v127, v127
	v_mul_f32_e32 v12, v129, v129
	v_fmac_f32_e32 v11, v126, v126
	v_fmac_f32_e32 v12, v128, v128
	v_add_f32_e32 v11, v11, v12
	s_waitcnt vmcnt(8)
	v_and_b32_e32 v131, 0xffff0000, v30
	v_and_b32_e32 v133, 0xffff0000, v31
	v_add_f32_e32 v10, v10, v11
	v_lshlrev_b32_e32 v130, 16, v30
	v_lshlrev_b32_e32 v132, 16, v31
	v_mul_f32_e32 v11, v131, v131
	v_mul_f32_e32 v12, v133, v133
	v_fmac_f32_e32 v11, v130, v130
	v_fmac_f32_e32 v12, v132, v132
	v_add_f32_e32 v11, v11, v12
	s_waitcnt vmcnt(7)
	v_and_b32_e32 v135, 0xffff0000, v32
	v_and_b32_e32 v137, 0xffff0000, v33
	v_add_f32_e32 v10, v10, v11
	v_lshlrev_b32_e32 v134, 16, v32
	v_lshlrev_b32_e32 v136, 16, v33
	v_mul_f32_e32 v11, v135, v135
	v_mul_f32_e32 v12, v137, v137
	v_fmac_f32_e32 v11, v134, v134
	v_fmac_f32_e32 v12, v136, v136
	v_add_f32_e32 v11, v11, v12
	s_waitcnt vmcnt(6)
	v_and_b32_e32 v139, 0xffff0000, v34
	v_and_b32_e32 v141, 0xffff0000, v35
	v_add_f32_e32 v10, v10, v11
	v_lshlrev_b32_e32 v138, 16, v34
	v_lshlrev_b32_e32 v140, 16, v35
	v_mul_f32_e32 v11, v139, v139
	v_mul_f32_e32 v12, v141, v141
	v_fmac_f32_e32 v11, v138, v138
	v_fmac_f32_e32 v12, v140, v140
	v_add_f32_e32 v11, v11, v12
	s_waitcnt vmcnt(5)
	v_and_b32_e32 v143, 0xffff0000, v36
	v_and_b32_e32 v145, 0xffff0000, v37
	v_add_f32_e32 v10, v10, v11
	v_lshlrev_b32_e32 v142, 16, v36
	v_lshlrev_b32_e32 v144, 16, v37
	v_mul_f32_e32 v11, v143, v143
	v_mul_f32_e32 v12, v145, v145
	v_fmac_f32_e32 v11, v142, v142
	v_fmac_f32_e32 v12, v144, v144
	v_add_f32_e32 v11, v11, v12
	s_waitcnt vmcnt(4)
	v_and_b32_e32 v148, 0xffff0000, v38
	v_and_b32_e32 v150, 0xffff0000, v39
	v_add_f32_e32 v10, v10, v11
	v_lshlrev_b32_e32 v147, 16, v38
	v_lshlrev_b32_e32 v149, 16, v39
	v_mul_f32_e32 v11, v148, v148
	v_mul_f32_e32 v12, v150, v150
	s_waitcnt vmcnt(3)
	v_and_b32_e32 v152, 0xffff0000, v8
	v_and_b32_e32 v154, 0xffff0000, v9
	v_fmac_f32_e32 v11, v147, v147
	v_fmac_f32_e32 v12, v149, v149
	v_lshlrev_b32_e32 v151, 16, v8
	v_lshlrev_b32_e32 v153, 16, v9
	v_mul_f32_e32 v8, v152, v152
	v_mul_f32_e32 v9, v154, v154
	v_add_f32_e32 v11, v11, v12
	v_fmac_f32_e32 v8, v151, v151
	v_fmac_f32_e32 v9, v153, v153
	v_add_f32_e32 v10, v10, v11
	v_add_f32_e32 v8, v8, v9
	v_add_f32_e32 v8, v10, v8
	ds_bpermute_b32 v9, v1, v8
	s_waitcnt lgkmcnt(0)
	v_add_f32_e32 v8, v8, v9
	ds_bpermute_b32 v9, v76, v8
	s_waitcnt lgkmcnt(0)
	v_add_f32_e32 v10, v8, v9
	ds_bpermute_b32 v11, v77, v10
	v_add_co_u32_e32 v8, vcc, s47, v6
	s_waitcnt lgkmcnt(0)
	v_add_f32_e32 v10, v10, v11
	ds_bpermute_b32 v11, v78, v10
	v_addc_co_u32_e32 v9, vcc, 0, v7, vcc
	v_add_co_u32_e32 v58, vcc, s48, v6
	s_waitcnt lgkmcnt(0)
	v_add_f32_e32 v10, v10, v11
	ds_bpermute_b32 v11, v79, v10
	v_addc_co_u32_e32 v59, vcc, 0, v7, vcc
	v_add_co_u32_e32 v6, vcc, s49, v6
	s_waitcnt lgkmcnt(0)
	v_add_f32_e32 v10, v10, v11
	ds_bpermute_b32 v11, v80, v10
	global_load_dwordx4 v[46:49], v[8:9], off offset:1024
	global_load_dwordx4 v[38:41], v[8:9], off offset:2048
	global_load_dwordx4 v[34:37], v[58:59], off
	global_load_dwordx4 v[30:33], v[58:59], off offset:1024
	global_load_dwordx4 v[26:29], v[58:59], off offset:2048
	global_load_dwordx4 v[22:25], v[58:59], off offset:3072
	v_addc_co_u32_e32 v7, vcc, 0, v7, vcc
	global_load_dwordx4 v[42:45], v[8:9], off offset:3072
	global_load_dwordx4 v[18:21], v[6:7], off
	s_waitcnt lgkmcnt(0)
	v_add_f32_e32 v8, v10, v11
	v_fmamk_f32 v8, v8, 0x39800000, v66
	v_mul_f32_e32 v9, 0x4f800000, v8
	v_cmp_gt_f32_e32 vcc, s50, v8
	s_nop 1
	v_cndmask_b32_e32 v84, v8, v9, vcc
	global_load_dwordx4 v[14:17], v[6:7], off offset:1024
	global_load_dwordx4 v[10:13], v[6:7], off offset:2048
	s_nop 0
	global_load_dwordx4 v[58:61], v[58:59], off offset:-4096
	s_nop 0
	global_load_dwordx4 v[6:9], v[6:7], off offset:3072
	v_sqrt_f32_e32 v85, v84
	s_nop 0
	v_add_u32_e32 v86, -1, v85
	v_fma_f32 v87, -v86, v85, v84
	v_cmp_ge_f32_e64 s[8:9], 0, v87
	v_add_u32_e32 v87, 1, v85
	s_nop 0
	v_cndmask_b32_e64 v86, v85, v86, s[8:9]
	v_fma_f32 v85, -v87, v85, v84
	v_cmp_lt_f32_e64 s[8:9], 0, v85
	s_nop 1
	v_cndmask_b32_e64 v85, v86, v87, s[8:9]
	v_mul_f32_e32 v86, 0x37800000, v85
	v_cndmask_b32_e32 v85, v85, v86, vcc
	v_cmp_class_f32_e32 vcc, v84, v82
	s_nop 1
	v_cndmask_b32_e32 v92, v85, v84, vcc
	v_div_scale_f32 v84, s[8:9], v92, v92, 0.5
	v_rcp_f32_e32 v93, v84
	s_nop 0
	v_fma_f32 v85, -v84, v93, 1.0
	v_fmac_f32_e32 v93, v85, v93
	v_div_scale_f32 v85, vcc, 0.5, v92, 0.5
	v_mul_f32_e32 v155, v85, v93
	v_fma_f32 v86, -v84, v155, v85
	v_fmac_f32_e32 v155, v86, v93
	v_fma_f32 v156, -v84, v155, v85
	ds_read_b128 v[84:87], v81
	v_div_fmas_f32 v93, v156, v93, v155
	v_div_fixup_f32 v155, v93, v92, 0.5
	v_mul_f32_e32 v88, v155, v88
	v_lshl_add_u64 v[92:93], v[72:73], 0, s[0:1]
	s_waitcnt lgkmcnt(0)
	v_fma_f32 v2, v84, v88, v2
	v_mul_f32_e32 v84, v155, v89
	v_fma_f32 v3, v85, v84, v3
	v_mul_f32_e32 v84, v155, v90
	v_fma_f32 v4, v86, v84, v4
	v_mul_f32_e32 v84, v155, v91
	v_fmac_f32_e32 v5, v87, v84
	v_cvt_pk_bf16_f32 v88, v2, v3
	v_cvt_pk_bf16_f32 v89, v4, v5
	ds_read_b128 v[84:87], v81 offset:1024
	global_store_dwordx2 v[92:93], v[88:89], off
	v_mul_f32_e32 v88, v155, v94
	s_waitcnt vmcnt(15) lgkmcnt(0)
	v_fma_f32 v84, v84, v88, v62
	v_mul_f32_e32 v62, v155, v95
	v_fma_f32 v63, v85, v62, v63
	v_mul_f32_e32 v62, v155, v96
	v_fma_f32 v62, v86, v62, v64
	v_mul_f32_e32 v64, v155, v97
	v_fmac_f32_e32 v65, v87, v64
	v_cvt_pk_bf16_f32 v90, v84, v63
	v_cvt_pk_bf16_f32 v91, v62, v65
	ds_read_b128 v[86:89], v81 offset:2048
	v_mul_f32_e32 v64, v155, v98
	global_store_dwordx2 v[92:93], v[90:91], off offset:512
	s_waitcnt vmcnt(15) lgkmcnt(0)
	v_fma_f32 v54, v64, v86, v54
	v_mul_f32_e32 v64, v155, v99
	v_fma_f32 v55, v64, v87, v55
	v_mul_f32_e32 v64, v155, v100
	v_fma_f32 v56, v64, v88, v56
	v_mul_f32_e32 v64, v155, v101
	v_fmac_f32_e32 v57, v64, v89
	v_cvt_pk_bf16_f32 v90, v54, v55
	v_cvt_pk_bf16_f32 v91, v56, v57
	ds_read_b128 v[86:89], v81 offset:3072
	v_mul_f32_e32 v64, v155, v102
	global_store_dwordx2 v[92:93], v[90:91], off offset:1024
	s_waitcnt vmcnt(15) lgkmcnt(0)
	v_fma_f32 v64, v64, v86, v50
	v_mul_f32_e32 v50, v155, v103
	v_fma_f32 v85, v50, v87, v51
	v_mul_f32_e32 v50, v155, v104
	v_fma_f32 v86, v50, v88, v52
	v_mul_f32_e32 v50, v155, v105
	v_fmac_f32_e32 v53, v50, v89
	v_cvt_pk_bf16_f32 v50, v64, v85
	v_cvt_pk_bf16_f32 v51, v86, v53
	global_store_dwordx2 v[92:93], v[50:51], off offset:1536
	ds_read_b128 v[88:91], v81 offset:4096
	v_mul_f32_e32 v50, v155, v106
	v_mul_f32_e32 v51, v155, v107
	v_mul_f32_e32 v52, v155, v108
	s_waitcnt vmcnt(5) lgkmcnt(0)
	v_fma_f32 v50, v50, v88, v58
	v_mul_f32_e32 v58, v155, v109
	v_fma_f32 v51, v51, v89, v59
	v_fma_f32 v52, v52, v90, v60
	v_fmac_f32_e32 v61, v58, v91
	v_cvt_pk_bf16_f32 v58, v50, v51
	v_cvt_pk_bf16_f32 v59, v52, v61
	ds_read_b128 v[88:91], v81 offset:5120
	global_store_dwordx2 v[92:93], v[58:59], off offset:2048
	v_mul_f32_e32 v58, v155, v110
	s_waitcnt lgkmcnt(0)
	v_fma_f32 v58, v58, v88, v46
	v_mul_f32_e32 v46, v155, v111
	v_fma_f32 v47, v46, v89, v47
	v_mul_f32_e32 v46, v155, v112
	v_fma_f32 v46, v46, v90, v48
	v_mul_f32_e32 v48, v155, v113
	v_fmac_f32_e32 v49, v48, v91
	v_cvt_pk_bf16_f32 v94, v58, v47
	v_cvt_pk_bf16_f32 v95, v46, v49
	ds_read_b128 v[88:91], v81 offset:6144
	v_mul_f32_e32 v48, v155, v114
	global_store_dwordx2 v[92:93], v[94:95], off offset:2560
	s_waitcnt lgkmcnt(0)
	v_fma_f32 v38, v48, v88, v38
	v_mul_f32_e32 v48, v155, v115
	v_fma_f32 v39, v48, v89, v39
	v_mul_f32_e32 v48, v155, v116
	v_fma_f32 v40, v48, v90, v40
	v_mul_f32_e32 v48, v155, v117
	v_fmac_f32_e32 v41, v48, v91
	v_cvt_pk_bf16_f32 v94, v38, v39
	v_cvt_pk_bf16_f32 v95, v40, v41
	ds_read_b128 v[88:91], v81 offset:7168
	v_mul_f32_e32 v48, v155, v118
	global_store_dwordx2 v[92:93], v[94:95], off offset:3072
	s_waitcnt lgkmcnt(0)
	v_fma_f32 v42, v48, v88, v42
	v_mul_f32_e32 v48, v155, v119
	v_fma_f32 v43, v48, v89, v43
	v_mul_f32_e32 v48, v155, v120
	v_fma_f32 v44, v48, v90, v44
	v_mul_f32_e32 v48, v155, v121
	v_fmac_f32_e32 v45, v48, v91
	v_cvt_pk_bf16_f32 v88, v42, v43
	v_cvt_pk_bf16_f32 v89, v44, v45
	global_store_dwordx2 v[92:93], v[88:89], off offset:3584
	ds_read_b128 v[88:91], v81 offset:8192
	v_mul_f32_e32 v48, v155, v122
	v_mul_f32_e32 v59, v155, v123
	v_mul_f32_e32 v60, v155, v124
	v_add_co_u32_e32 v92, vcc, s47, v92
	s_waitcnt lgkmcnt(0)
	v_fma_f32 v34, v48, v88, v34
	v_mul_f32_e32 v48, v155, v125
	v_fma_f32 v35, v59, v89, v35
	v_fma_f32 v36, v60, v90, v36
	v_fmac_f32_e32 v37, v48, v91
	v_cvt_pk_bf16_f32 v94, v34, v35
	v_cvt_pk_bf16_f32 v95, v36, v37
	ds_read_b128 v[88:91], v81 offset:9216
	v_mul_f32_e32 v48, v155, v126
	v_addc_co_u32_e32 v93, vcc, 0, v93, vcc
	global_store_dwordx2 v[92:93], v[94:95], off
	s_waitcnt lgkmcnt(0)
	v_fma_f32 v48, v48, v88, v30
	v_mul_f32_e32 v30, v155, v127
	v_fma_f32 v31, v30, v89, v31
	v_mul_f32_e32 v30, v155, v128
	v_fma_f32 v30, v30, v90, v32
	v_mul_f32_e32 v32, v155, v129
	v_fmac_f32_e32 v33, v32, v91
	v_cvt_pk_bf16_f32 v94, v48, v31
	v_cvt_pk_bf16_f32 v95, v30, v33
	ds_read_b128 v[88:91], v81 offset:10240
	v_mul_f32_e32 v32, v155, v130
	global_store_dwordx2 v[92:93], v[94:95], off offset:512
	s_waitcnt lgkmcnt(0)
	v_fma_f32 v26, v32, v88, v26
	v_mul_f32_e32 v32, v155, v131
	v_fma_f32 v27, v32, v89, v27
	v_mul_f32_e32 v32, v155, v132
	v_fma_f32 v28, v32, v90, v28
	v_mul_f32_e32 v32, v155, v133
	v_fmac_f32_e32 v29, v32, v91
	v_cvt_pk_bf16_f32 v94, v26, v27
	v_cvt_pk_bf16_f32 v95, v28, v29
	ds_read_b128 v[88:91], v81 offset:11264
	v_mul_f32_e32 v32, v155, v134
	global_store_dwordx2 v[92:93], v[94:95], off offset:1024
	s_waitcnt lgkmcnt(0)
	v_fma_f32 v22, v32, v88, v22
	v_mul_f32_e32 v32, v155, v135
	v_fma_f32 v23, v32, v89, v23
	v_mul_f32_e32 v32, v155, v136
	v_fma_f32 v24, v32, v90, v24
	v_mul_f32_e32 v32, v155, v137
	v_fmac_f32_e32 v25, v32, v91
	v_cvt_pk_bf16_f32 v88, v22, v23
	v_cvt_pk_bf16_f32 v89, v24, v25
	global_store_dwordx2 v[92:93], v[88:89], off offset:1536
	ds_read_b128 v[88:91], v81 offset:12288
	v_mul_f32_e32 v32, v155, v138
	v_mul_f32_e32 v59, v155, v139
	v_mul_f32_e32 v60, v155, v140
	s_waitcnt lgkmcnt(0)
	v_fma_f32 v18, v32, v88, v18
	v_mul_f32_e32 v32, v155, v141
	v_fma_f32 v19, v59, v89, v19
	v_fma_f32 v20, v60, v90, v20
	v_fmac_f32_e32 v21, v32, v91
	v_cvt_pk_bf16_f32 v94, v18, v19
	v_cvt_pk_bf16_f32 v95, v20, v21
	ds_read_b128 v[88:91], v81 offset:13312
	v_mul_f32_e32 v32, v155, v142
	global_store_dwordx2 v[92:93], v[94:95], off offset:2048
	s_waitcnt lgkmcnt(0)
	v_fma_f32 v32, v32, v88, v14
	v_mul_f32_e32 v14, v155, v143
	v_fma_f32 v15, v14, v89, v15
	v_mul_f32_e32 v14, v155, v144
	v_fma_f32 v14, v14, v90, v16
	v_mul_f32_e32 v16, v155, v145
	v_fmac_f32_e32 v17, v16, v91
	v_cvt_pk_bf16_f32 v94, v32, v15
	v_cvt_pk_bf16_f32 v95, v14, v17
	ds_read_b128 v[88:91], v81 offset:14336
	v_mul_f32_e32 v16, v155, v147
	global_store_dwordx2 v[92:93], v[94:95], off offset:2560
	s_waitcnt lgkmcnt(0)
	v_fma_f32 v10, v16, v88, v10
	v_mul_f32_e32 v16, v155, v148
	v_fma_f32 v11, v16, v89, v11
	v_mul_f32_e32 v16, v155, v149
	v_fma_f32 v12, v16, v90, v12
	v_mul_f32_e32 v16, v155, v150
	v_fmac_f32_e32 v13, v16, v91
	v_cvt_pk_bf16_f32 v94, v10, v11
	v_cvt_pk_bf16_f32 v95, v12, v13
	ds_read_b128 v[88:91], v81 offset:15360
	v_mul_f32_e32 v16, v155, v151
	global_store_dwordx2 v[92:93], v[94:95], off offset:3072
	s_waitcnt vmcnt(15) lgkmcnt(0)
	v_fma_f32 v6, v16, v88, v6
	v_mul_f32_e32 v16, v155, v152
	v_fma_f32 v7, v16, v89, v7
	v_mul_f32_e32 v16, v155, v153
	v_fma_f32 v8, v16, v90, v8
	v_mul_f32_e32 v16, v155, v154
	v_fmac_f32_e32 v9, v16, v91
	v_cvt_pk_bf16_f32 v88, v6, v7
	v_cvt_pk_bf16_f32 v89, v8, v9
	global_store_dwordx2 v[92:93], v[88:89], off offset:3584
	v_mul_f32_e32 v16, v3, v3
	v_mul_f32_e32 v59, v5, v5
	v_fmac_f32_e32 v16, v2, v2
	v_fmac_f32_e32 v59, v4, v4
	v_add_f32_e32 v16, v16, v59
	v_mul_f32_e32 v59, v63, v63
	v_mul_f32_e32 v60, v65, v65
	v_fmac_f32_e32 v59, v84, v84
	v_fmac_f32_e32 v60, v62, v62
	v_add_f32_e32 v59, v59, v60
	v_add_f32_e32 v16, v16, v59
	v_mul_f32_e32 v59, v55, v55
	v_mul_f32_e32 v60, v57, v57
	v_fmac_f32_e32 v59, v54, v54
	v_fmac_f32_e32 v60, v56, v56
	v_add_f32_e32 v59, v59, v60
	v_add_f32_e32 v16, v16, v59
	v_mul_f32_e32 v59, v85, v85
	v_mul_f32_e32 v60, v53, v53
	v_fmac_f32_e32 v59, v64, v64
	v_fmac_f32_e32 v60, v86, v86
	v_add_f32_e32 v59, v59, v60
	v_add_f32_e32 v16, v16, v59
	v_mul_f32_e32 v59, v51, v51
	v_mul_f32_e32 v60, v61, v61
	v_fmac_f32_e32 v59, v50, v50
	v_fmac_f32_e32 v60, v52, v52
	v_add_f32_e32 v59, v59, v60
	v_add_f32_e32 v16, v16, v59
	v_mul_f32_e32 v59, v47, v47
	v_mul_f32_e32 v60, v49, v49
	v_fmac_f32_e32 v59, v58, v58
	v_fmac_f32_e32 v60, v46, v46
	v_add_f32_e32 v59, v59, v60
	v_add_f32_e32 v16, v16, v59
	v_mul_f32_e32 v59, v39, v39
	v_mul_f32_e32 v60, v41, v41
	v_fmac_f32_e32 v59, v38, v38
	v_fmac_f32_e32 v60, v40, v40
	v_add_f32_e32 v59, v59, v60
	v_add_f32_e32 v16, v16, v59
	v_mul_f32_e32 v59, v43, v43
	v_mul_f32_e32 v60, v45, v45
	v_fmac_f32_e32 v59, v42, v42
	v_fmac_f32_e32 v60, v44, v44
	v_add_f32_e32 v59, v59, v60
	v_add_f32_e32 v16, v16, v59
	v_mul_f32_e32 v59, v35, v35
	v_mul_f32_e32 v60, v37, v37
	v_fmac_f32_e32 v59, v34, v34
	v_fmac_f32_e32 v60, v36, v36
	v_add_f32_e32 v59, v59, v60
	v_add_f32_e32 v16, v16, v59
	v_mul_f32_e32 v59, v31, v31
	v_mul_f32_e32 v60, v33, v33
	v_fmac_f32_e32 v59, v48, v48
	v_fmac_f32_e32 v60, v30, v30
	v_add_f32_e32 v59, v59, v60
	v_add_f32_e32 v16, v16, v59
	v_mul_f32_e32 v59, v27, v27
	v_mul_f32_e32 v60, v29, v29
	v_fmac_f32_e32 v59, v26, v26
	v_fmac_f32_e32 v60, v28, v28
	v_add_f32_e32 v59, v59, v60
	v_add_f32_e32 v16, v16, v59
	v_mul_f32_e32 v59, v23, v23
	v_mul_f32_e32 v60, v25, v25
	v_fmac_f32_e32 v59, v22, v22
	v_fmac_f32_e32 v60, v24, v24
	v_add_f32_e32 v59, v59, v60
	v_add_f32_e32 v16, v16, v59
	v_mul_f32_e32 v59, v19, v19
	v_mul_f32_e32 v60, v21, v21
	v_fmac_f32_e32 v59, v18, v18
	v_fmac_f32_e32 v60, v20, v20
	v_add_f32_e32 v59, v59, v60
	v_add_f32_e32 v16, v16, v59
	v_mul_f32_e32 v59, v15, v15
	v_mul_f32_e32 v60, v17, v17
	v_fmac_f32_e32 v59, v32, v32
	v_fmac_f32_e32 v60, v14, v14
	v_add_f32_e32 v59, v59, v60
	v_add_f32_e32 v16, v16, v59
	v_mul_f32_e32 v59, v11, v11
	v_mul_f32_e32 v60, v13, v13
	v_fmac_f32_e32 v59, v10, v10
	v_fmac_f32_e32 v60, v12, v12
	v_add_f32_e32 v59, v59, v60
	v_add_f32_e32 v16, v16, v59
	v_mul_f32_e32 v59, v7, v7
	v_mul_f32_e32 v60, v9, v9
	v_fmac_f32_e32 v59, v6, v6
	v_fmac_f32_e32 v60, v8, v8
	v_add_f32_e32 v59, v59, v60
	v_add_f32_e32 v16, v16, v59
	ds_bpermute_b32 v59, v1, v16
	s_waitcnt lgkmcnt(0)
	v_add_f32_e32 v16, v16, v59
	ds_bpermute_b32 v59, v76, v16
	s_waitcnt lgkmcnt(0)
	v_add_f32_e32 v16, v16, v59
	ds_bpermute_b32 v59, v77, v16
	s_waitcnt lgkmcnt(0)
	v_add_f32_e32 v16, v16, v59
	ds_bpermute_b32 v59, v78, v16
	s_waitcnt lgkmcnt(0)
	v_add_f32_e32 v16, v16, v59
	ds_bpermute_b32 v59, v79, v16
	s_waitcnt lgkmcnt(0)
	v_add_f32_e32 v16, v16, v59
	ds_bpermute_b32 v59, v80, v16
	s_waitcnt lgkmcnt(0)
	v_add_f32_e32 v16, v16, v59
	v_fmamk_f32 v16, v16, 0x39800000, v66
	v_mul_f32_e32 v59, 0x4f800000, v16
	v_cmp_gt_f32_e32 vcc, s50, v16
	s_nop 1
	v_cndmask_b32_e32 v16, v16, v59, vcc
	v_sqrt_f32_e32 v59, v16
	s_nop 0
	v_add_u32_e32 v60, -1, v59
	v_fma_f32 v87, -v60, v59, v16
	v_cmp_ge_f32_e64 s[8:9], 0, v87
	v_add_u32_e32 v87, 1, v59
	s_nop 0
	v_cndmask_b32_e64 v60, v59, v60, s[8:9]
	v_fma_f32 v59, -v87, v59, v16
	v_cmp_lt_f32_e64 s[8:9], 0, v59
	s_nop 1
	v_cndmask_b32_e64 v59, v60, v87, s[8:9]
	v_mul_f32_e32 v60, 0x37800000, v59
	v_cndmask_b32_e32 v59, v59, v60, vcc
	v_cmp_class_f32_e32 vcc, v16, v82
	s_nop 1
	v_cndmask_b32_e32 v16, v59, v16, vcc
	v_div_scale_f32 v59, s[0:1], v16, v16, 1.0
	v_rcp_f32_e32 v60, v59
	s_nop 0
	v_fma_f32 v87, -v59, v60, 1.0
	v_fmac_f32_e32 v60, v87, v60
	v_div_scale_f32 v87, vcc, 1.0, v16, 1.0
	v_mul_f32_e32 v88, v87, v60
	v_fma_f32 v89, -v59, v88, v87
	v_fmac_f32_e32 v88, v89, v60
	v_fma_f32 v59, -v59, v88, v87
	v_div_fmas_f32 v59, v59, v60, v88
	v_div_fixup_f32 v87, v59, v16, 1.0
	s_and_saveexec_b64 s[0:1], s[6:7]
	s_cbranch_execz .LBB0_483
	s_lshl_b64 s[8:9], s[38:39], 2
	s_add_u32 s8, s10, s8
	s_addc_u32 s9, s11, s9
	global_store_dword v67, v87, s[8:9]

.LBB0_558:
	ds_read_b128 v[148:151], v163
	ds_read_b128 v[152:155], v163 offset:1024
	ds_read_b128 v[156:159], v163 offset:2048
	ds_read_b128 v[166:169], v163 offset:3072
	ds_read_b128 v[170:173], v164
	ds_read_b128 v[174:177], v164 offset:1024
	ds_read_b128 v[178:181], v164 offset:2048
	ds_read_b128 v[182:185], v164 offset:3072
	s_add_u32 s48, s0, 0x100
	s_addc_u32 s49, s1, 0
	s_cmp_eq_u32 s67, 28
	s_cselect_b32 s53, s7, s49
	s_cselect_b32 s52, s6, s48
	s_cselect_b32 s51, s45, s43
	s_cselect_b32 s50, s44, s41
	v_lshl_add_u64 v[160:161], s[0:1], 0, v[138:139]
	s_add_i32 m0, s47, 0xc000
	ds_read_b128 v[186:189], v165
	ds_read_b128 v[190:193], v165 offset:1024
	ds_read_b128 v[194:197], v165 offset:2048
	ds_read_b128 v[198:201], v165 offset:3072
	ds_read_b128 v[202:205], v165 offset:4096
	ds_read_b128 v[206:209], v165 offset:5120
	ds_read_b128 v[210:213], v165 offset:6144
	ds_read_b128 v[214:217], v165 offset:7168
	global_load_lds_dwordx4 v[160:161], off
	v_lshl_add_u64 v[160:161], s[0:1], 0, v[140:141]
	s_add_i32 m0, s47, 0xe000
	s_nop 0
	global_load_lds_dwordx4 v[160:161], off
	s_waitcnt vmcnt(8)
	s_waitcnt lgkmcnt(0)
	s_barrier
	s_setprio 2
	s_waitcnt lgkmcnt(0)
	v_mfma_i32_16x16x64_i8 v[126:129], v[148:151], v[186:189], v[126:129]
	v_mfma_i32_16x16x64_i8 v[122:125], v[156:159], v[186:189], v[122:125]
	v_mfma_i32_16x16x64_i8 v[118:121], v[148:151], v[194:197], v[118:121]
	v_mfma_i32_16x16x64_i8 v[114:117], v[156:159], v[194:197], v[114:117]
	v_mfma_i32_16x16x64_i8 v[110:113], v[148:151], v[202:205], v[110:113]
	v_mfma_i32_16x16x64_i8 v[106:109], v[156:159], v[202:205], v[106:109]
	v_mfma_i32_16x16x64_i8 v[102:105], v[148:151], v[210:213], v[102:105]
	v_mfma_i32_16x16x64_i8 v[98:101], v[156:159], v[210:213], v[98:101]
	v_mfma_i32_16x16x64_i8 v[126:129], v[152:155], v[190:193], v[126:129]
	v_mfma_i32_16x16x64_i8 v[122:125], v[166:169], v[190:193], v[122:125]
	v_mfma_i32_16x16x64_i8 v[118:121], v[152:155], v[198:201], v[118:121]
	v_mfma_i32_16x16x64_i8 v[114:117], v[166:169], v[198:201], v[114:117]
	v_mfma_i32_16x16x64_i8 v[110:113], v[152:155], v[206:209], v[110:113]
	v_mfma_i32_16x16x64_i8 v[106:109], v[166:169], v[206:209], v[106:109]
	v_mfma_i32_16x16x64_i8 v[102:105], v[152:155], v[214:217], v[102:105]
	v_mfma_i32_16x16x64_i8 v[98:101], v[166:169], v[214:217], v[98:101]
	s_setprio 0
	s_setprio 2
	v_mfma_i32_16x16x64_i8 v[66:69], v[170:173], v[186:189], v[66:69]
	v_mfma_i32_16x16x64_i8 v[58:61], v[178:181], v[186:189], v[58:61]
	v_mfma_i32_16x16x64_i8 v[54:57], v[170:173], v[194:197], v[54:57]
	v_mfma_i32_16x16x64_i8 v[50:53], v[178:181], v[194:197], v[50:53]
	v_mfma_i32_16x16x64_i8 v[46:49], v[170:173], v[202:205], v[46:49]
	v_mfma_i32_16x16x64_i8 v[42:45], v[178:181], v[202:205], v[42:45]
	v_mfma_i32_16x16x64_i8 v[38:41], v[170:173], v[210:213], v[38:41]
	v_mfma_i32_16x16x64_i8 v[34:37], v[178:181], v[210:213], v[34:37]
	v_mfma_i32_16x16x64_i8 v[66:69], v[174:177], v[190:193], v[66:69]
	v_mfma_i32_16x16x64_i8 v[58:61], v[182:185], v[190:193], v[58:61]
	v_mfma_i32_16x16x64_i8 v[54:57], v[174:177], v[198:201], v[54:57]
	v_mfma_i32_16x16x64_i8 v[50:53], v[182:185], v[198:201], v[50:53]
	s_setprio 3
	s_barrier
	v_mfma_i32_16x16x64_i8 v[46:49], v[174:177], v[206:209], v[46:49]
	v_mfma_i32_16x16x64_i8 v[42:45], v[182:185], v[206:209], v[42:45]
	v_mfma_i32_16x16x64_i8 v[38:41], v[174:177], v[214:217], v[38:41]
	v_mfma_i32_16x16x64_i8 v[34:37], v[182:185], v[214:217], v[34:37]
	s_setprio 0
	s_add_i32 s0, s62, s3
	v_lshl_add_u64 v[160:161], s[50:51], 0, v[130:131]
	s_mov_b32 m0, s0
	ds_read_b128 v[186:189], v165 offset:16384
	ds_read_b128 v[190:193], v165 offset:17408
	ds_read_b128 v[194:197], v165 offset:18432
	ds_read_b128 v[198:201], v165 offset:19456
	ds_read_b128 v[202:205], v165 offset:20480
	ds_read_b128 v[206:209], v165 offset:21504
	ds_read_b128 v[210:213], v165 offset:22528
	ds_read_b128 v[214:217], v165 offset:23552
	global_load_lds_dwordx4 v[160:161], off
	s_add_i32 m0, s0, 0x2000
	s_add_u32 s0, s50, 0x80000
	v_lshl_add_u64 v[160:161], s[50:51], 0, v[132:133]
	s_addc_u32 s1, s51, 0
	s_add_i32 s68, s63, s3
	global_load_lds_dwordx4 v[160:161], off
	v_lshl_add_u64 v[160:161], s[0:1], 0, v[130:131]
	s_mov_b32 m0, s68
	v_lshl_add_u64 v[218:219], s[52:53], 0, v[134:135]
	global_load_lds_dwordx4 v[160:161], off
	v_lshl_add_u64 v[160:161], s[0:1], 0, v[132:133]
	s_add_i32 m0, s68, 0x2000
	s_nop 0
	global_load_lds_dwordx4 v[160:161], off
	v_lshl_add_u64 v[160:161], s[52:53], 0, v[136:137]
	s_mov_b32 m0, s47
	s_nop 0
	global_load_lds_dwordx4 v[160:161], off
	s_mov_b32 m0, s55
	s_nop 0
	global_load_lds_dwordx4 v[218:219], off
	s_waitcnt vmcnt(8)
	s_waitcnt lgkmcnt(0)
	s_barrier
	s_setprio 2
	s_waitcnt lgkmcnt(0)
	v_mfma_i32_16x16x64_i8 v[94:97], v[148:151], v[186:189], v[94:97]
	v_mfma_i32_16x16x64_i8 v[90:93], v[156:159], v[186:189], v[90:93]
	v_mfma_i32_16x16x64_i8 v[86:89], v[148:151], v[194:197], v[86:89]
	v_mfma_i32_16x16x64_i8 v[82:85], v[156:159], v[194:197], v[82:85]
	v_mfma_i32_16x16x64_i8 v[78:81], v[148:151], v[202:205], v[78:81]
	v_mfma_i32_16x16x64_i8 v[74:77], v[156:159], v[202:205], v[74:77]
	v_mfma_i32_16x16x64_i8 v[70:73], v[148:151], v[210:213], v[70:73]
	v_mfma_i32_16x16x64_i8 v[62:65], v[156:159], v[210:213], v[62:65]
	v_mfma_i32_16x16x64_i8 v[94:97], v[152:155], v[190:193], v[94:97]
	v_mfma_i32_16x16x64_i8 v[90:93], v[166:169], v[190:193], v[90:93]
	v_mfma_i32_16x16x64_i8 v[86:89], v[152:155], v[198:201], v[86:89]
	v_mfma_i32_16x16x64_i8 v[82:85], v[166:169], v[198:201], v[82:85]
	v_mfma_i32_16x16x64_i8 v[78:81], v[152:155], v[206:209], v[78:81]
	v_mfma_i32_16x16x64_i8 v[74:77], v[166:169], v[206:209], v[74:77]
	v_mfma_i32_16x16x64_i8 v[70:73], v[152:155], v[214:217], v[70:73]
	v_mfma_i32_16x16x64_i8 v[62:65], v[166:169], v[214:217], v[62:65]
	s_setprio 0
	s_setprio 2
	v_mfma_i32_16x16x64_i8 v[30:33], v[170:173], v[186:189], v[30:33]
	v_mfma_i32_16x16x64_i8 v[26:29], v[178:181], v[186:189], v[26:29]
	v_mfma_i32_16x16x64_i8 v[22:25], v[170:173], v[194:197], v[22:25]
	v_mfma_i32_16x16x64_i8 v[18:21], v[178:181], v[194:197], v[18:21]
	v_mfma_i32_16x16x64_i8 v[14:17], v[170:173], v[202:205], v[14:17]
	v_mfma_i32_16x16x64_i8 v[10:13], v[178:181], v[202:205], v[10:13]
	v_mfma_i32_16x16x64_i8 v[6:9], v[170:173], v[210:213], v[6:9]
	v_mfma_i32_16x16x64_i8 v[2:5], v[178:181], v[210:213], v[2:5]
	v_mfma_i32_16x16x64_i8 v[30:33], v[174:177], v[190:193], v[30:33]
	v_mfma_i32_16x16x64_i8 v[26:29], v[182:185], v[190:193], v[26:29]
	v_mfma_i32_16x16x64_i8 v[22:25], v[174:177], v[198:201], v[22:25]
	v_mfma_i32_16x16x64_i8 v[18:21], v[182:185], v[198:201], v[18:21]
	s_setprio 3
	s_barrier
	v_mfma_i32_16x16x64_i8 v[14:17], v[174:177], v[206:209], v[14:17]
	v_mfma_i32_16x16x64_i8 v[10:13], v[182:185], v[206:209], v[10:13]
	v_mfma_i32_16x16x64_i8 v[6:9], v[174:177], v[214:217], v[6:9]
	v_mfma_i32_16x16x64_i8 v[2:5], v[182:185], v[214:217], v[2:5]
	s_setprio 0
	s_add_i32 s68, 0, 0x18000
	s_add_i32 s69, 0, 0x1c000
	v_add_u32_e32 v166, s68, v147
	v_add_u32_e32 v182, s69, v147
	ds_read_b128 v[148:151], v166
	ds_read_b128 v[152:155], v166 offset:1024
	ds_read_b128 v[156:159], v166 offset:2048
	ds_read_b128 v[166:169], v166 offset:3072
	ds_read_b128 v[170:173], v182
	ds_read_b128 v[174:177], v182 offset:1024
	ds_read_b128 v[178:181], v182 offset:2048
	ds_read_b128 v[182:185], v182 offset:3072
	s_add_u32 s0, s52, 0x80000
	s_addc_u32 s1, s53, 0
	s_mov_b32 m0, s56
	v_lshl_add_u64 v[220:221], s[0:1], 0, v[136:137]
	ds_read_b128 v[186:189], v165 offset:32768
	ds_read_b128 v[190:193], v165 offset:33792
	ds_read_b128 v[194:197], v165 offset:34816
	ds_read_b128 v[198:201], v165 offset:35840
	ds_read_b128 v[202:205], v165 offset:36864
	ds_read_b128 v[206:209], v165 offset:37888
	ds_read_b128 v[210:213], v165 offset:38912
	ds_read_b128 v[214:217], v165 offset:39936
	global_load_lds_dwordx4 v[220:221], off
	v_lshl_add_u64 v[220:221], s[0:1], 0, v[134:135]
	s_mov_b32 m0, s57
	s_nop 0
	global_load_lds_dwordx4 v[220:221], off
	s_waitcnt vmcnt(8)
	s_waitcnt lgkmcnt(0)
	s_barrier
	s_setprio 2
	s_waitcnt lgkmcnt(0)
	v_mfma_i32_16x16x64_i8 v[126:129], v[148:151], v[186:189], v[126:129]
	v_mfma_i32_16x16x64_i8 v[122:125], v[156:159], v[186:189], v[122:125]
	v_mfma_i32_16x16x64_i8 v[118:121], v[148:151], v[194:197], v[118:121]
	v_mfma_i32_16x16x64_i8 v[114:117], v[156:159], v[194:197], v[114:117]
	v_mfma_i32_16x16x64_i8 v[110:113], v[148:151], v[202:205], v[110:113]
	v_mfma_i32_16x16x64_i8 v[106:109], v[156:159], v[202:205], v[106:109]
	v_mfma_i32_16x16x64_i8 v[102:105], v[148:151], v[210:213], v[102:105]
	v_mfma_i32_16x16x64_i8 v[98:101], v[156:159], v[210:213], v[98:101]
	v_mfma_i32_16x16x64_i8 v[126:129], v[152:155], v[190:193], v[126:129]
	v_mfma_i32_16x16x64_i8 v[122:125], v[166:169], v[190:193], v[122:125]
	v_mfma_i32_16x16x64_i8 v[118:121], v[152:155], v[198:201], v[118:121]
	v_mfma_i32_16x16x64_i8 v[114:117], v[166:169], v[198:201], v[114:117]
	v_mfma_i32_16x16x64_i8 v[110:113], v[152:155], v[206:209], v[110:113]
	v_mfma_i32_16x16x64_i8 v[106:109], v[166:169], v[206:209], v[106:109]
	v_mfma_i32_16x16x64_i8 v[102:105], v[152:155], v[214:217], v[102:105]
	v_mfma_i32_16x16x64_i8 v[98:101], v[166:169], v[214:217], v[98:101]
	s_setprio 0
	s_setprio 2
	v_mfma_i32_16x16x64_i8 v[66:69], v[170:173], v[186:189], v[66:69]
	v_mfma_i32_16x16x64_i8 v[58:61], v[178:181], v[186:189], v[58:61]
	v_mfma_i32_16x16x64_i8 v[54:57], v[170:173], v[194:197], v[54:57]
	v_mfma_i32_16x16x64_i8 v[50:53], v[178:181], v[194:197], v[50:53]
	v_mfma_i32_16x16x64_i8 v[46:49], v[170:173], v[202:205], v[46:49]
	v_mfma_i32_16x16x64_i8 v[42:45], v[178:181], v[202:205], v[42:45]
	v_mfma_i32_16x16x64_i8 v[38:41], v[170:173], v[210:213], v[38:41]
	v_mfma_i32_16x16x64_i8 v[34:37], v[178:181], v[210:213], v[34:37]
	v_mfma_i32_16x16x64_i8 v[66:69], v[174:177], v[190:193], v[66:69]
	v_mfma_i32_16x16x64_i8 v[58:61], v[182:185], v[190:193], v[58:61]
	v_mfma_i32_16x16x64_i8 v[54:57], v[174:177], v[198:201], v[54:57]
	v_mfma_i32_16x16x64_i8 v[50:53], v[182:185], v[198:201], v[50:53]
	s_setprio 3
	s_barrier
	v_mfma_i32_16x16x64_i8 v[46:49], v[174:177], v[206:209], v[46:49]
	v_mfma_i32_16x16x64_i8 v[42:45], v[182:185], v[206:209], v[42:45]
	v_mfma_i32_16x16x64_i8 v[38:41], v[174:177], v[214:217], v[38:41]
	v_mfma_i32_16x16x64_i8 v[34:37], v[182:185], v[214:217], v[34:37]
	s_setprio 0
	s_add_u32 s0, s50, 0x4000
	s_addc_u32 s1, s51, 0
	s_add_i32 s52, s68, s3
	v_lshl_add_u64 v[220:221], s[0:1], 0, v[130:131]
	s_mov_b32 m0, s52
	ds_read_b128 v[186:189], v165 offset:49152
	ds_read_b128 v[190:193], v165 offset:50176
	ds_read_b128 v[194:197], v165 offset:51200
	ds_read_b128 v[198:201], v165 offset:52224
	ds_read_b128 v[202:205], v165 offset:53248
	ds_read_b128 v[206:209], v165 offset:54272
	ds_read_b128 v[210:213], v165 offset:55296
	ds_read_b128 v[214:217], v165 offset:56320
	global_load_lds_dwordx4 v[220:221], off
	s_add_i32 m0, s52, 0x2000
	v_lshl_add_u64 v[220:221], s[0:1], 0, v[132:133]
	s_add_u32 s0, s50, 0x84000
	s_addc_u32 s1, s51, 0
	s_add_i32 s50, s69, s3
	global_load_lds_dwordx4 v[220:221], off
	v_lshl_add_u64 v[220:221], s[0:1], 0, v[130:131]
	s_mov_b32 m0, s50
	v_lshl_add_u64 v[160:161], v[160:161], 0, s[20:21]
	global_load_lds_dwordx4 v[220:221], off
	v_lshl_add_u64 v[220:221], s[0:1], 0, v[132:133]
	s_add_i32 m0, s50, 0x2000
	s_nop 0
	global_load_lds_dwordx4 v[220:221], off
	s_mov_b32 m0, s59
	s_nop 0
	global_load_lds_dwordx4 v[160:161], off
	v_lshl_add_u64 v[160:161], v[218:219], 0, s[20:21]
	s_mov_b32 m0, s60
	s_nop 0
	global_load_lds_dwordx4 v[160:161], off
	s_waitcnt vmcnt(8)
	s_waitcnt lgkmcnt(0)
	s_barrier
	s_setprio 2
	s_waitcnt lgkmcnt(0)
	v_mfma_i32_16x16x64_i8 v[94:97], v[148:151], v[186:189], v[94:97]
	v_mfma_i32_16x16x64_i8 v[90:93], v[156:159], v[186:189], v[90:93]
	v_mfma_i32_16x16x64_i8 v[86:89], v[148:151], v[194:197], v[86:89]
	v_mfma_i32_16x16x64_i8 v[82:85], v[156:159], v[194:197], v[82:85]
	v_mfma_i32_16x16x64_i8 v[78:81], v[148:151], v[202:205], v[78:81]
	v_mfma_i32_16x16x64_i8 v[74:77], v[156:159], v[202:205], v[74:77]
	v_mfma_i32_16x16x64_i8 v[70:73], v[148:151], v[210:213], v[70:73]
	v_mfma_i32_16x16x64_i8 v[62:65], v[156:159], v[210:213], v[62:65]
	v_mfma_i32_16x16x64_i8 v[94:97], v[152:155], v[190:193], v[94:97]
	v_mfma_i32_16x16x64_i8 v[90:93], v[166:169], v[190:193], v[90:93]
	v_mfma_i32_16x16x64_i8 v[86:89], v[152:155], v[198:201], v[86:89]
	v_mfma_i32_16x16x64_i8 v[82:85], v[166:169], v[198:201], v[82:85]
	v_mfma_i32_16x16x64_i8 v[78:81], v[152:155], v[206:209], v[78:81]
	v_mfma_i32_16x16x64_i8 v[74:77], v[166:169], v[206:209], v[74:77]
	v_mfma_i32_16x16x64_i8 v[70:73], v[152:155], v[214:217], v[70:73]
	v_mfma_i32_16x16x64_i8 v[62:65], v[166:169], v[214:217], v[62:65]
	s_setprio 0
	s_setprio 2
	v_mfma_i32_16x16x64_i8 v[30:33], v[170:173], v[186:189], v[30:33]
	v_mfma_i32_16x16x64_i8 v[26:29], v[178:181], v[186:189], v[26:29]
	v_mfma_i32_16x16x64_i8 v[22:25], v[170:173], v[194:197], v[22:25]
	v_mfma_i32_16x16x64_i8 v[18:21], v[178:181], v[194:197], v[18:21]
	v_mfma_i32_16x16x64_i8 v[14:17], v[170:173], v[202:205], v[14:17]
	v_mfma_i32_16x16x64_i8 v[10:13], v[178:181], v[202:205], v[10:13]
	v_mfma_i32_16x16x64_i8 v[6:9], v[170:173], v[210:213], v[6:9]
	v_mfma_i32_16x16x64_i8 v[2:5], v[178:181], v[210:213], v[2:5]
	v_mfma_i32_16x16x64_i8 v[30:33], v[174:177], v[190:193], v[30:33]
	v_mfma_i32_16x16x64_i8 v[26:29], v[182:185], v[190:193], v[26:29]
	v_mfma_i32_16x16x64_i8 v[22:25], v[174:177], v[198:201], v[22:25]
	v_mfma_i32_16x16x64_i8 v[18:21], v[182:185], v[198:201], v[18:21]
	s_setprio 3
	s_barrier
	v_mfma_i32_16x16x64_i8 v[14:17], v[174:177], v[206:209], v[14:17]
	v_mfma_i32_16x16x64_i8 v[10:13], v[182:185], v[206:209], v[10:13]
	v_mfma_i32_16x16x64_i8 v[6:9], v[174:177], v[214:217], v[6:9]
	v_mfma_i32_16x16x64_i8 v[2:5], v[182:185], v[214:217], v[2:5]
	s_setprio 0
	s_add_i32 s67, s67, 2
	s_add_u32 s41, s41, 0x8000
	s_addc_u32 s43, s43, 0
	s_cmp_gt_u32 s67, 29
	s_mov_b64 s[0:1], s[48:49]
	s_cbranch_scc0 .LBB0_558
	s_and_b64 vcc, exec, s[24:25]
	s_cbranch_vccz .LBB0_561
	s_barrier

.LBB0_584:
	ds_read_b128 v[148:151], v157
	ds_read_b128 v[152:155], v157 offset:1024
	ds_read_b128 v[160:163], v157 offset:2048
	ds_read_b128 v[164:167], v157 offset:3072
	ds_read_b128 v[168:171], v158
	ds_read_b128 v[172:175], v158 offset:1024
	ds_read_b128 v[176:179], v158 offset:2048
	ds_read_b128 v[180:183], v158 offset:3072
	s_add_u32 s46, s0, 0xfff00080
	s_addc_u32 s47, s1, -1
	s_cmp_eq_u32 s64, 60
	s_cselect_b32 s49, s7, s47
	s_cselect_b32 s48, s6, s46
	s_cselect_b32 s47, s43, s41
	s_cselect_b32 s46, s42, s39
	v_lshl_add_u64 v[216:217], s[0:1], 0, v[138:139]
	s_add_i32 m0, s45, 0xc000
	ds_read_b128 v[184:187], v159
	ds_read_b128 v[188:191], v159 offset:1024
	ds_read_b128 v[192:195], v159 offset:2048
	ds_read_b128 v[196:199], v159 offset:3072
	ds_read_b128 v[200:203], v159 offset:4096
	ds_read_b128 v[204:207], v159 offset:5120
	ds_read_b128 v[208:211], v159 offset:6144
	ds_read_b128 v[212:215], v159 offset:7168
	global_load_lds_dwordx4 v[216:217], off
	v_lshl_add_u64 v[216:217], s[0:1], 0, v[140:141]
	s_add_i32 m0, s45, 0xe000
	s_nop 0
	global_load_lds_dwordx4 v[216:217], off
	s_waitcnt vmcnt(8)
	s_waitcnt lgkmcnt(0)
	s_barrier
	s_setprio 2
	s_waitcnt lgkmcnt(0)
	v_mfma_f32_16x16x32_bf16 v[126:129], v[148:151], v[184:187], v[126:129]
	v_mfma_f32_16x16x32_bf16 v[122:125], v[160:163], v[184:187], v[122:125]
	v_mfma_f32_16x16x32_bf16 v[110:113], v[148:151], v[192:195], v[110:113]
	v_mfma_f32_16x16x32_bf16 v[106:109], v[160:163], v[192:195], v[106:109]
	v_mfma_f32_16x16x32_bf16 v[94:97], v[148:151], v[200:203], v[94:97]
	v_mfma_f32_16x16x32_bf16 v[90:93], v[160:163], v[200:203], v[90:93]
	v_mfma_f32_16x16x32_bf16 v[86:89], v[148:151], v[208:211], v[86:89]
	v_mfma_f32_16x16x32_bf16 v[78:81], v[160:163], v[208:211], v[78:81]
	v_mfma_f32_16x16x32_bf16 v[126:129], v[152:155], v[188:191], v[126:129]
	v_mfma_f32_16x16x32_bf16 v[122:125], v[164:167], v[188:191], v[122:125]
	v_mfma_f32_16x16x32_bf16 v[110:113], v[152:155], v[196:199], v[110:113]
	v_mfma_f32_16x16x32_bf16 v[106:109], v[164:167], v[196:199], v[106:109]
	v_mfma_f32_16x16x32_bf16 v[94:97], v[152:155], v[204:207], v[94:97]
	v_mfma_f32_16x16x32_bf16 v[90:93], v[164:167], v[204:207], v[90:93]
	v_mfma_f32_16x16x32_bf16 v[86:89], v[152:155], v[212:215], v[86:89]
	v_mfma_f32_16x16x32_bf16 v[78:81], v[164:167], v[212:215], v[78:81]
	s_setprio 0
	s_setprio 2
	v_mfma_f32_16x16x32_bf16 v[118:121], v[168:171], v[184:187], v[118:121]
	v_mfma_f32_16x16x32_bf16 v[114:117], v[176:179], v[184:187], v[114:117]
	v_mfma_f32_16x16x32_bf16 v[102:105], v[168:171], v[192:195], v[102:105]
	v_mfma_f32_16x16x32_bf16 v[98:101], v[176:179], v[192:195], v[98:101]
	v_mfma_f32_16x16x32_bf16 v[82:85], v[168:171], v[200:203], v[82:85]
	v_mfma_f32_16x16x32_bf16 v[74:77], v[176:179], v[200:203], v[74:77]
	v_mfma_f32_16x16x32_bf16 v[70:73], v[168:171], v[208:211], v[70:73]
	v_mfma_f32_16x16x32_bf16 v[66:69], v[176:179], v[208:211], v[66:69]
	v_mfma_f32_16x16x32_bf16 v[118:121], v[172:175], v[188:191], v[118:121]
	v_mfma_f32_16x16x32_bf16 v[114:117], v[180:183], v[188:191], v[114:117]
	v_mfma_f32_16x16x32_bf16 v[102:105], v[172:175], v[196:199], v[102:105]
	v_mfma_f32_16x16x32_bf16 v[98:101], v[180:183], v[196:199], v[98:101]
	s_setprio 3
	s_barrier
	v_mfma_f32_16x16x32_bf16 v[82:85], v[172:175], v[204:207], v[82:85]
	v_mfma_f32_16x16x32_bf16 v[74:77], v[180:183], v[204:207], v[74:77]
	v_mfma_f32_16x16x32_bf16 v[70:73], v[172:175], v[212:215], v[70:73]
	v_mfma_f32_16x16x32_bf16 v[66:69], v[180:183], v[212:215], v[66:69]
	s_setprio 0
	s_add_i32 s65, s60, s52
	v_lshl_add_u64 v[216:217], s[46:47], 0, v[130:131]
	s_mov_b32 m0, s65
	ds_read_b128 v[184:187], v159 offset:16384
	ds_read_b128 v[188:191], v159 offset:17408
	ds_read_b128 v[192:195], v159 offset:18432
	ds_read_b128 v[196:199], v159 offset:19456
	ds_read_b128 v[200:203], v159 offset:20480
	ds_read_b128 v[204:207], v159 offset:21504
	ds_read_b128 v[208:211], v159 offset:22528
	ds_read_b128 v[212:215], v159 offset:23552
	global_load_lds_dwordx4 v[216:217], off
	s_add_i32 m0, s65, 0x2000
	s_add_u32 s68, s46, 0x100000
	v_lshl_add_u64 v[216:217], s[46:47], 0, v[134:135]
	s_addc_u32 s69, s47, 0
	s_add_i32 s65, s61, s52
	global_load_lds_dwordx4 v[216:217], off
	v_lshl_add_u64 v[216:217], s[68:69], 0, v[130:131]
	s_mov_b32 m0, s65
	v_lshl_add_u64 v[218:219], s[48:49], 0, v[136:137]
	global_load_lds_dwordx4 v[216:217], off
	v_lshl_add_u64 v[216:217], s[68:69], 0, v[134:135]
	s_add_i32 m0, s65, 0x2000
	s_nop 0
	global_load_lds_dwordx4 v[216:217], off
	v_lshl_add_u64 v[216:217], s[48:49], 0, v[132:133]
	s_mov_b32 m0, s45
	s_nop 0
	global_load_lds_dwordx4 v[216:217], off
	s_mov_b32 m0, s53
	s_nop 0
	global_load_lds_dwordx4 v[218:219], off
	s_waitcnt vmcnt(8)
	s_waitcnt lgkmcnt(0)
	s_barrier
	s_setprio 2
	s_waitcnt lgkmcnt(0)
	v_mfma_f32_16x16x32_bf16 v[62:65], v[148:151], v[184:187], v[62:65]
	v_mfma_f32_16x16x32_bf16 v[58:61], v[160:163], v[184:187], v[58:61]
	v_mfma_f32_16x16x32_bf16 v[46:49], v[148:151], v[192:195], v[46:49]
	v_mfma_f32_16x16x32_bf16 v[42:45], v[160:163], v[192:195], v[42:45]
	v_mfma_f32_16x16x32_bf16 v[30:33], v[148:151], v[200:203], v[30:33]
	v_mfma_f32_16x16x32_bf16 v[26:29], v[160:163], v[200:203], v[26:29]
	v_mfma_f32_16x16x32_bf16 v[14:17], v[148:151], v[208:211], v[14:17]
	v_mfma_f32_16x16x32_bf16 v[10:13], v[160:163], v[208:211], v[10:13]
	v_mfma_f32_16x16x32_bf16 v[62:65], v[152:155], v[188:191], v[62:65]
	v_mfma_f32_16x16x32_bf16 v[58:61], v[164:167], v[188:191], v[58:61]
	v_mfma_f32_16x16x32_bf16 v[46:49], v[152:155], v[196:199], v[46:49]
	v_mfma_f32_16x16x32_bf16 v[42:45], v[164:167], v[196:199], v[42:45]
	v_mfma_f32_16x16x32_bf16 v[30:33], v[152:155], v[204:207], v[30:33]
	v_mfma_f32_16x16x32_bf16 v[26:29], v[164:167], v[204:207], v[26:29]
	v_mfma_f32_16x16x32_bf16 v[14:17], v[152:155], v[212:215], v[14:17]
	v_mfma_f32_16x16x32_bf16 v[10:13], v[164:167], v[212:215], v[10:13]
	s_setprio 0
	s_setprio 2
	v_mfma_f32_16x16x32_bf16 v[54:57], v[168:171], v[184:187], v[54:57]
	v_mfma_f32_16x16x32_bf16 v[50:53], v[176:179], v[184:187], v[50:53]
	v_mfma_f32_16x16x32_bf16 v[38:41], v[168:171], v[192:195], v[38:41]
	v_mfma_f32_16x16x32_bf16 v[34:37], v[176:179], v[192:195], v[34:37]
	v_mfma_f32_16x16x32_bf16 v[22:25], v[168:171], v[200:203], v[22:25]
	v_mfma_f32_16x16x32_bf16 v[18:21], v[176:179], v[200:203], v[18:21]
	v_mfma_f32_16x16x32_bf16 v[6:9], v[168:171], v[208:211], v[6:9]
	v_mfma_f32_16x16x32_bf16 v[2:5], v[176:179], v[208:211], v[2:5]
	v_mfma_f32_16x16x32_bf16 v[54:57], v[172:175], v[188:191], v[54:57]
	v_mfma_f32_16x16x32_bf16 v[50:53], v[180:183], v[188:191], v[50:53]
	v_mfma_f32_16x16x32_bf16 v[38:41], v[172:175], v[196:199], v[38:41]
	v_mfma_f32_16x16x32_bf16 v[34:37], v[180:183], v[196:199], v[34:37]
	s_setprio 3
	s_barrier
	v_mfma_f32_16x16x32_bf16 v[22:25], v[172:175], v[204:207], v[22:25]
	v_mfma_f32_16x16x32_bf16 v[18:21], v[180:183], v[204:207], v[18:21]
	v_mfma_f32_16x16x32_bf16 v[6:9], v[172:175], v[212:215], v[6:9]
	v_mfma_f32_16x16x32_bf16 v[2:5], v[180:183], v[212:215], v[2:5]
	s_setprio 0
	s_add_i32 s65, 0, 0x18000
	s_add_i32 s67, 0, 0x1c000
	v_add_u32_e32 v164, s65, v147
	v_add_u32_e32 v180, s67, v147
	ds_read_b128 v[148:151], v164
	ds_read_b128 v[152:155], v164 offset:1024
	ds_read_b128 v[160:163], v164 offset:2048
	ds_read_b128 v[164:167], v164 offset:3072
	ds_read_b128 v[168:171], v180
	ds_read_b128 v[172:175], v180 offset:1024
	ds_read_b128 v[176:179], v180 offset:2048
	ds_read_b128 v[180:183], v180 offset:3072
	s_add_u32 s48, s48, 0x100000
	s_addc_u32 s49, s49, 0
	s_mov_b32 m0, s54
	v_lshl_add_u64 v[220:221], s[48:49], 0, v[132:133]
	ds_read_b128 v[184:187], v159 offset:32768
	ds_read_b128 v[188:191], v159 offset:33792
	ds_read_b128 v[192:195], v159 offset:34816
	ds_read_b128 v[196:199], v159 offset:35840
	ds_read_b128 v[200:203], v159 offset:36864
	ds_read_b128 v[204:207], v159 offset:37888
	ds_read_b128 v[208:211], v159 offset:38912
	ds_read_b128 v[212:215], v159 offset:39936
	global_load_lds_dwordx4 v[220:221], off
	v_lshl_add_u64 v[220:221], s[48:49], 0, v[136:137]
	s_mov_b32 m0, s55
	s_nop 0
	global_load_lds_dwordx4 v[220:221], off
	s_waitcnt vmcnt(8)
	s_waitcnt lgkmcnt(0)
	s_barrier
	s_setprio 2
	s_waitcnt lgkmcnt(0)
	v_mfma_f32_16x16x32_bf16 v[126:129], v[148:151], v[184:187], v[126:129]
	v_mfma_f32_16x16x32_bf16 v[122:125], v[160:163], v[184:187], v[122:125]
	v_mfma_f32_16x16x32_bf16 v[110:113], v[148:151], v[192:195], v[110:113]
	v_mfma_f32_16x16x32_bf16 v[106:109], v[160:163], v[192:195], v[106:109]
	v_mfma_f32_16x16x32_bf16 v[94:97], v[148:151], v[200:203], v[94:97]
	v_mfma_f32_16x16x32_bf16 v[90:93], v[160:163], v[200:203], v[90:93]
	v_mfma_f32_16x16x32_bf16 v[86:89], v[148:151], v[208:211], v[86:89]
	v_mfma_f32_16x16x32_bf16 v[78:81], v[160:163], v[208:211], v[78:81]
	v_mfma_f32_16x16x32_bf16 v[126:129], v[152:155], v[188:191], v[126:129]
	v_mfma_f32_16x16x32_bf16 v[122:125], v[164:167], v[188:191], v[122:125]
	v_mfma_f32_16x16x32_bf16 v[110:113], v[152:155], v[196:199], v[110:113]
	v_mfma_f32_16x16x32_bf16 v[106:109], v[164:167], v[196:199], v[106:109]
	v_mfma_f32_16x16x32_bf16 v[94:97], v[152:155], v[204:207], v[94:97]
	v_mfma_f32_16x16x32_bf16 v[90:93], v[164:167], v[204:207], v[90:93]
	v_mfma_f32_16x16x32_bf16 v[86:89], v[152:155], v[212:215], v[86:89]
	v_mfma_f32_16x16x32_bf16 v[78:81], v[164:167], v[212:215], v[78:81]
	s_setprio 0
	s_setprio 2
	v_mfma_f32_16x16x32_bf16 v[118:121], v[168:171], v[184:187], v[118:121]
	v_mfma_f32_16x16x32_bf16 v[114:117], v[176:179], v[184:187], v[114:117]
	v_mfma_f32_16x16x32_bf16 v[102:105], v[168:171], v[192:195], v[102:105]
	v_mfma_f32_16x16x32_bf16 v[98:101], v[176:179], v[192:195], v[98:101]
	v_mfma_f32_16x16x32_bf16 v[82:85], v[168:171], v[200:203], v[82:85]
	v_mfma_f32_16x16x32_bf16 v[74:77], v[176:179], v[200:203], v[74:77]
	v_mfma_f32_16x16x32_bf16 v[70:73], v[168:171], v[208:211], v[70:73]
	v_mfma_f32_16x16x32_bf16 v[66:69], v[176:179], v[208:211], v[66:69]
	v_mfma_f32_16x16x32_bf16 v[118:121], v[172:175], v[188:191], v[118:121]
	v_mfma_f32_16x16x32_bf16 v[114:117], v[180:183], v[188:191], v[114:117]
	v_mfma_f32_16x16x32_bf16 v[102:105], v[172:175], v[196:199], v[102:105]
	v_mfma_f32_16x16x32_bf16 v[98:101], v[180:183], v[196:199], v[98:101]
	s_setprio 3
	s_barrier
	v_mfma_f32_16x16x32_bf16 v[82:85], v[172:175], v[204:207], v[82:85]
	v_mfma_f32_16x16x32_bf16 v[74:77], v[180:183], v[204:207], v[74:77]
	v_mfma_f32_16x16x32_bf16 v[70:73], v[172:175], v[212:215], v[70:73]
	v_mfma_f32_16x16x32_bf16 v[66:69], v[180:183], v[212:215], v[66:69]
	s_setprio 0
	s_add_u32 s48, s46, 0x4000
	s_addc_u32 s49, s47, 0
	s_add_i32 s65, s65, s52
	v_lshl_add_u64 v[220:221], s[48:49], 0, v[130:131]
	s_mov_b32 m0, s65
	ds_read_b128 v[184:187], v159 offset:49152
	ds_read_b128 v[188:191], v159 offset:50176
	ds_read_b128 v[192:195], v159 offset:51200
	ds_read_b128 v[196:199], v159 offset:52224
	ds_read_b128 v[200:203], v159 offset:53248
	ds_read_b128 v[204:207], v159 offset:54272
	ds_read_b128 v[208:211], v159 offset:55296
	ds_read_b128 v[212:215], v159 offset:56320
	global_load_lds_dwordx4 v[220:221], off
	s_add_i32 m0, s65, 0x2000
	s_add_u32 s46, s46, 0x104000
	v_lshl_add_u64 v[220:221], s[48:49], 0, v[134:135]
	s_addc_u32 s47, s47, 0
	s_add_i32 s48, s67, s52
	global_load_lds_dwordx4 v[220:221], off
	v_lshl_add_u64 v[220:221], s[46:47], 0, v[130:131]
	s_mov_b32 m0, s48
	v_lshl_add_u64 v[216:217], v[216:217], 0, s[20:21]
	global_load_lds_dwordx4 v[220:221], off
	v_lshl_add_u64 v[220:221], s[46:47], 0, v[134:135]
	s_add_i32 m0, s48, 0x2000
	s_nop 0
	global_load_lds_dwordx4 v[220:221], off
	s_mov_b32 m0, s57
	s_nop 0
	global_load_lds_dwordx4 v[216:217], off
	v_lshl_add_u64 v[216:217], v[218:219], 0, s[20:21]
	s_mov_b32 m0, s58
	s_nop 0
	global_load_lds_dwordx4 v[216:217], off
	s_waitcnt vmcnt(8)
	s_waitcnt lgkmcnt(0)
	s_barrier
	s_setprio 2
	s_waitcnt lgkmcnt(0)
	v_mfma_f32_16x16x32_bf16 v[62:65], v[148:151], v[184:187], v[62:65]
	v_mfma_f32_16x16x32_bf16 v[58:61], v[160:163], v[184:187], v[58:61]
	v_mfma_f32_16x16x32_bf16 v[46:49], v[148:151], v[192:195], v[46:49]
	v_mfma_f32_16x16x32_bf16 v[42:45], v[160:163], v[192:195], v[42:45]
	v_mfma_f32_16x16x32_bf16 v[30:33], v[148:151], v[200:203], v[30:33]
	v_mfma_f32_16x16x32_bf16 v[26:29], v[160:163], v[200:203], v[26:29]
	v_mfma_f32_16x16x32_bf16 v[14:17], v[148:151], v[208:211], v[14:17]
	v_mfma_f32_16x16x32_bf16 v[10:13], v[160:163], v[208:211], v[10:13]
	v_mfma_f32_16x16x32_bf16 v[62:65], v[152:155], v[188:191], v[62:65]
	v_mfma_f32_16x16x32_bf16 v[58:61], v[164:167], v[188:191], v[58:61]
	v_mfma_f32_16x16x32_bf16 v[46:49], v[152:155], v[196:199], v[46:49]
	v_mfma_f32_16x16x32_bf16 v[42:45], v[164:167], v[196:199], v[42:45]
	v_mfma_f32_16x16x32_bf16 v[30:33], v[152:155], v[204:207], v[30:33]
	v_mfma_f32_16x16x32_bf16 v[26:29], v[164:167], v[204:207], v[26:29]
	v_mfma_f32_16x16x32_bf16 v[14:17], v[152:155], v[212:215], v[14:17]
	v_mfma_f32_16x16x32_bf16 v[10:13], v[164:167], v[212:215], v[10:13]
	s_setprio 0
	s_setprio 2
	v_mfma_f32_16x16x32_bf16 v[54:57], v[168:171], v[184:187], v[54:57]
	v_mfma_f32_16x16x32_bf16 v[50:53], v[176:179], v[184:187], v[50:53]
	v_mfma_f32_16x16x32_bf16 v[38:41], v[168:171], v[192:195], v[38:41]
	v_mfma_f32_16x16x32_bf16 v[34:37], v[176:179], v[192:195], v[34:37]
	v_mfma_f32_16x16x32_bf16 v[22:25], v[168:171], v[200:203], v[22:25]
	v_mfma_f32_16x16x32_bf16 v[18:21], v[176:179], v[200:203], v[18:21]
	v_mfma_f32_16x16x32_bf16 v[6:9], v[168:171], v[208:211], v[6:9]
	v_mfma_f32_16x16x32_bf16 v[2:5], v[176:179], v[208:211], v[2:5]
	v_mfma_f32_16x16x32_bf16 v[54:57], v[172:175], v[188:191], v[54:57]
	v_mfma_f32_16x16x32_bf16 v[50:53], v[180:183], v[188:191], v[50:53]
	v_mfma_f32_16x16x32_bf16 v[38:41], v[172:175], v[196:199], v[38:41]
	v_mfma_f32_16x16x32_bf16 v[34:37], v[180:183], v[196:199], v[34:37]
	s_setprio 3
	s_barrier
	v_mfma_f32_16x16x32_bf16 v[22:25], v[172:175], v[204:207], v[22:25]
	v_mfma_f32_16x16x32_bf16 v[18:21], v[180:183], v[204:207], v[18:21]
	v_mfma_f32_16x16x32_bf16 v[6:9], v[172:175], v[212:215], v[6:9]
	v_mfma_f32_16x16x32_bf16 v[2:5], v[180:183], v[212:215], v[2:5]
	s_setprio 0
	s_add_i32 s64, s64, 2
	s_add_u32 s39, s39, 0x8000
	s_addc_u32 s41, s41, 0
	s_add_u32 s0, s0, 0x100
	s_addc_u32 s1, s1, 0
	s_cmp_gt_u32 s64, 61
	s_cbranch_scc0 .LBB0_584
	s_and_b64 vcc, exec, s[24:25]
	s_cbranch_vccz .LBB0_587
	s_barrier

.LBB0_610:
	ds_read_b128 v[148:151], v163
	ds_read_b128 v[152:155], v163 offset:1024
	ds_read_b128 v[156:159], v163 offset:2048
	ds_read_b128 v[166:169], v163 offset:3072
	ds_read_b128 v[170:173], v164
	ds_read_b128 v[174:177], v164 offset:1024
	ds_read_b128 v[178:181], v164 offset:2048
	ds_read_b128 v[182:185], v164 offset:3072
	s_add_u32 s6, s0, 0x100
	s_addc_u32 s7, s1, 0
	s_cmp_eq_u32 s68, 28
	s_cselect_b32 s53, s45, s7
	s_cselect_b32 s52, s44, s6
	s_cselect_b32 s51, s47, s43
	s_cselect_b32 s50, s46, s41
	v_lshl_add_u64 v[160:161], s[0:1], 0, v[138:139]
	s_add_i32 m0, s49, 0xc000
	ds_read_b128 v[186:189], v165
	ds_read_b128 v[190:193], v165 offset:1024
	ds_read_b128 v[194:197], v165 offset:2048
	ds_read_b128 v[198:201], v165 offset:3072
	ds_read_b128 v[202:205], v165 offset:4096
	ds_read_b128 v[206:209], v165 offset:5120
	ds_read_b128 v[210:213], v165 offset:6144
	ds_read_b128 v[214:217], v165 offset:7168
	global_load_lds_dwordx4 v[160:161], off
	v_lshl_add_u64 v[160:161], s[0:1], 0, v[140:141]
	s_add_i32 m0, s49, 0xe000
	s_nop 0
	global_load_lds_dwordx4 v[160:161], off
	s_waitcnt vmcnt(8)
	s_waitcnt lgkmcnt(0)
	s_barrier
	s_setprio 2
	s_waitcnt lgkmcnt(0)
	v_mfma_i32_16x16x64_i8 v[126:129], v[148:151], v[186:189], v[126:129]
	v_mfma_i32_16x16x64_i8 v[122:125], v[156:159], v[186:189], v[122:125]
	v_mfma_i32_16x16x64_i8 v[118:121], v[148:151], v[194:197], v[118:121]
	v_mfma_i32_16x16x64_i8 v[114:117], v[156:159], v[194:197], v[114:117]
	v_mfma_i32_16x16x64_i8 v[110:113], v[148:151], v[202:205], v[110:113]
	v_mfma_i32_16x16x64_i8 v[106:109], v[156:159], v[202:205], v[106:109]
	v_mfma_i32_16x16x64_i8 v[102:105], v[148:151], v[210:213], v[102:105]
	v_mfma_i32_16x16x64_i8 v[98:101], v[156:159], v[210:213], v[98:101]
	v_mfma_i32_16x16x64_i8 v[126:129], v[152:155], v[190:193], v[126:129]
	v_mfma_i32_16x16x64_i8 v[122:125], v[166:169], v[190:193], v[122:125]
	v_mfma_i32_16x16x64_i8 v[118:121], v[152:155], v[198:201], v[118:121]
	v_mfma_i32_16x16x64_i8 v[114:117], v[166:169], v[198:201], v[114:117]
	v_mfma_i32_16x16x64_i8 v[110:113], v[152:155], v[206:209], v[110:113]
	v_mfma_i32_16x16x64_i8 v[106:109], v[166:169], v[206:209], v[106:109]
	v_mfma_i32_16x16x64_i8 v[102:105], v[152:155], v[214:217], v[102:105]
	v_mfma_i32_16x16x64_i8 v[98:101], v[166:169], v[214:217], v[98:101]
	s_setprio 0
	s_setprio 2
	v_mfma_i32_16x16x64_i8 v[62:65], v[170:173], v[186:189], v[62:65]
	v_mfma_i32_16x16x64_i8 v[58:61], v[178:181], v[186:189], v[58:61]
	v_mfma_i32_16x16x64_i8 v[54:57], v[170:173], v[194:197], v[54:57]
	v_mfma_i32_16x16x64_i8 v[50:53], v[178:181], v[194:197], v[50:53]
	v_mfma_i32_16x16x64_i8 v[46:49], v[170:173], v[202:205], v[46:49]
	v_mfma_i32_16x16x64_i8 v[42:45], v[178:181], v[202:205], v[42:45]
	v_mfma_i32_16x16x64_i8 v[38:41], v[170:173], v[210:213], v[38:41]
	v_mfma_i32_16x16x64_i8 v[34:37], v[178:181], v[210:213], v[34:37]
	v_mfma_i32_16x16x64_i8 v[62:65], v[174:177], v[190:193], v[62:65]
	v_mfma_i32_16x16x64_i8 v[58:61], v[182:185], v[190:193], v[58:61]
	v_mfma_i32_16x16x64_i8 v[54:57], v[174:177], v[198:201], v[54:57]
	v_mfma_i32_16x16x64_i8 v[50:53], v[182:185], v[198:201], v[50:53]
	s_setprio 3
	s_barrier
	v_mfma_i32_16x16x64_i8 v[46:49], v[174:177], v[206:209], v[46:49]
	v_mfma_i32_16x16x64_i8 v[42:45], v[182:185], v[206:209], v[42:45]
	v_mfma_i32_16x16x64_i8 v[38:41], v[174:177], v[214:217], v[38:41]
	v_mfma_i32_16x16x64_i8 v[34:37], v[182:185], v[214:217], v[34:37]
	s_setprio 0
	s_add_i32 s0, s63, s55
	v_lshl_add_u64 v[160:161], s[50:51], 0, v[130:131]
	s_mov_b32 m0, s0
	ds_read_b128 v[186:189], v165 offset:16384
	ds_read_b128 v[190:193], v165 offset:17408
	ds_read_b128 v[194:197], v165 offset:18432
	ds_read_b128 v[198:201], v165 offset:19456
	ds_read_b128 v[202:205], v165 offset:20480
	ds_read_b128 v[206:209], v165 offset:21504
	ds_read_b128 v[210:213], v165 offset:22528
	ds_read_b128 v[214:217], v165 offset:23552
	global_load_lds_dwordx4 v[160:161], off
	s_add_i32 m0, s0, 0x2000
	s_add_u32 s0, s50, 0x80000
	v_lshl_add_u64 v[160:161], s[50:51], 0, v[134:135]
	s_addc_u32 s1, s51, 0
	s_add_i32 s69, s64, s55
	global_load_lds_dwordx4 v[160:161], off
	v_lshl_add_u64 v[160:161], s[0:1], 0, v[130:131]
	s_mov_b32 m0, s69
	v_lshl_add_u64 v[218:219], s[52:53], 0, v[136:137]
	global_load_lds_dwordx4 v[160:161], off
	v_lshl_add_u64 v[160:161], s[0:1], 0, v[134:135]
	s_add_i32 m0, s69, 0x2000
	s_nop 0
	global_load_lds_dwordx4 v[160:161], off
	v_lshl_add_u64 v[160:161], s[52:53], 0, v[132:133]
	s_mov_b32 m0, s49
	s_nop 0
	global_load_lds_dwordx4 v[160:161], off
	s_mov_b32 m0, s56
	s_nop 0
	global_load_lds_dwordx4 v[218:219], off
	s_waitcnt vmcnt(8)
	s_waitcnt lgkmcnt(0)
	s_barrier
	s_setprio 2
	s_waitcnt lgkmcnt(0)
	v_mfma_i32_16x16x64_i8 v[94:97], v[148:151], v[186:189], v[94:97]
	v_mfma_i32_16x16x64_i8 v[90:93], v[156:159], v[186:189], v[90:93]
	v_mfma_i32_16x16x64_i8 v[86:89], v[148:151], v[194:197], v[86:89]
	v_mfma_i32_16x16x64_i8 v[82:85], v[156:159], v[194:197], v[82:85]
	v_mfma_i32_16x16x64_i8 v[78:81], v[148:151], v[202:205], v[78:81]
	v_mfma_i32_16x16x64_i8 v[74:77], v[156:159], v[202:205], v[74:77]
	v_mfma_i32_16x16x64_i8 v[70:73], v[148:151], v[210:213], v[70:73]
	v_mfma_i32_16x16x64_i8 v[66:69], v[156:159], v[210:213], v[66:69]
	v_mfma_i32_16x16x64_i8 v[94:97], v[152:155], v[190:193], v[94:97]
	v_mfma_i32_16x16x64_i8 v[90:93], v[166:169], v[190:193], v[90:93]
	v_mfma_i32_16x16x64_i8 v[86:89], v[152:155], v[198:201], v[86:89]
	v_mfma_i32_16x16x64_i8 v[82:85], v[166:169], v[198:201], v[82:85]
	v_mfma_i32_16x16x64_i8 v[78:81], v[152:155], v[206:209], v[78:81]
	v_mfma_i32_16x16x64_i8 v[74:77], v[166:169], v[206:209], v[74:77]
	v_mfma_i32_16x16x64_i8 v[70:73], v[152:155], v[214:217], v[70:73]
	v_mfma_i32_16x16x64_i8 v[66:69], v[166:169], v[214:217], v[66:69]
	s_setprio 0
	s_setprio 2
	v_mfma_i32_16x16x64_i8 v[30:33], v[170:173], v[186:189], v[30:33]
	v_mfma_i32_16x16x64_i8 v[26:29], v[178:181], v[186:189], v[26:29]
	v_mfma_i32_16x16x64_i8 v[22:25], v[170:173], v[194:197], v[22:25]
	v_mfma_i32_16x16x64_i8 v[18:21], v[178:181], v[194:197], v[18:21]
	v_mfma_i32_16x16x64_i8 v[14:17], v[170:173], v[202:205], v[14:17]
	v_mfma_i32_16x16x64_i8 v[10:13], v[178:181], v[202:205], v[10:13]
	v_mfma_i32_16x16x64_i8 v[6:9], v[170:173], v[210:213], v[6:9]
	v_mfma_i32_16x16x64_i8 v[2:5], v[178:181], v[210:213], v[2:5]
	v_mfma_i32_16x16x64_i8 v[30:33], v[174:177], v[190:193], v[30:33]
	v_mfma_i32_16x16x64_i8 v[26:29], v[182:185], v[190:193], v[26:29]
	v_mfma_i32_16x16x64_i8 v[22:25], v[174:177], v[198:201], v[22:25]
	v_mfma_i32_16x16x64_i8 v[18:21], v[182:185], v[198:201], v[18:21]
	s_setprio 3
	s_barrier
	v_mfma_i32_16x16x64_i8 v[14:17], v[174:177], v[206:209], v[14:17]
	v_mfma_i32_16x16x64_i8 v[10:13], v[182:185], v[206:209], v[10:13]
	v_mfma_i32_16x16x64_i8 v[6:9], v[174:177], v[214:217], v[6:9]
	v_mfma_i32_16x16x64_i8 v[2:5], v[182:185], v[214:217], v[2:5]
	s_setprio 0
	s_add_i32 s69, 0, 0x18000
	s_add_i32 s70, 0, 0x1c000
	v_add_u32_e32 v166, s69, v147
	v_add_u32_e32 v182, s70, v147
	ds_read_b128 v[148:151], v166
	ds_read_b128 v[152:155], v166 offset:1024
	ds_read_b128 v[156:159], v166 offset:2048
	ds_read_b128 v[166:169], v166 offset:3072
	ds_read_b128 v[170:173], v182
	ds_read_b128 v[174:177], v182 offset:1024
	ds_read_b128 v[178:181], v182 offset:2048
	ds_read_b128 v[182:185], v182 offset:3072
	s_add_u32 s0, s52, 0x80000
	s_addc_u32 s1, s53, 0
	s_mov_b32 m0, s57
	v_lshl_add_u64 v[220:221], s[0:1], 0, v[132:133]
	ds_read_b128 v[186:189], v165 offset:32768
	ds_read_b128 v[190:193], v165 offset:33792
	ds_read_b128 v[194:197], v165 offset:34816
	ds_read_b128 v[198:201], v165 offset:35840
	ds_read_b128 v[202:205], v165 offset:36864
	ds_read_b128 v[206:209], v165 offset:37888
	ds_read_b128 v[210:213], v165 offset:38912
	ds_read_b128 v[214:217], v165 offset:39936
	global_load_lds_dwordx4 v[220:221], off
	v_lshl_add_u64 v[220:221], s[0:1], 0, v[136:137]
	s_mov_b32 m0, s58
	s_nop 0
	global_load_lds_dwordx4 v[220:221], off
	s_waitcnt vmcnt(8)
	s_waitcnt lgkmcnt(0)
	s_barrier
	s_setprio 2
	s_waitcnt lgkmcnt(0)
	v_mfma_i32_16x16x64_i8 v[126:129], v[148:151], v[186:189], v[126:129]
	v_mfma_i32_16x16x64_i8 v[122:125], v[156:159], v[186:189], v[122:125]
	v_mfma_i32_16x16x64_i8 v[118:121], v[148:151], v[194:197], v[118:121]
	v_mfma_i32_16x16x64_i8 v[114:117], v[156:159], v[194:197], v[114:117]
	v_mfma_i32_16x16x64_i8 v[110:113], v[148:151], v[202:205], v[110:113]
	v_mfma_i32_16x16x64_i8 v[106:109], v[156:159], v[202:205], v[106:109]
	v_mfma_i32_16x16x64_i8 v[102:105], v[148:151], v[210:213], v[102:105]
	v_mfma_i32_16x16x64_i8 v[98:101], v[156:159], v[210:213], v[98:101]
	v_mfma_i32_16x16x64_i8 v[126:129], v[152:155], v[190:193], v[126:129]
	v_mfma_i32_16x16x64_i8 v[122:125], v[166:169], v[190:193], v[122:125]
	v_mfma_i32_16x16x64_i8 v[118:121], v[152:155], v[198:201], v[118:121]
	v_mfma_i32_16x16x64_i8 v[114:117], v[166:169], v[198:201], v[114:117]
	v_mfma_i32_16x16x64_i8 v[110:113], v[152:155], v[206:209], v[110:113]
	v_mfma_i32_16x16x64_i8 v[106:109], v[166:169], v[206:209], v[106:109]
	v_mfma_i32_16x16x64_i8 v[102:105], v[152:155], v[214:217], v[102:105]
	v_mfma_i32_16x16x64_i8 v[98:101], v[166:169], v[214:217], v[98:101]
	s_setprio 0
	s_setprio 2
	v_mfma_i32_16x16x64_i8 v[62:65], v[170:173], v[186:189], v[62:65]
	v_mfma_i32_16x16x64_i8 v[58:61], v[178:181], v[186:189], v[58:61]
	v_mfma_i32_16x16x64_i8 v[54:57], v[170:173], v[194:197], v[54:57]
	v_mfma_i32_16x16x64_i8 v[50:53], v[178:181], v[194:197], v[50:53]
	v_mfma_i32_16x16x64_i8 v[46:49], v[170:173], v[202:205], v[46:49]
	v_mfma_i32_16x16x64_i8 v[42:45], v[178:181], v[202:205], v[42:45]
	v_mfma_i32_16x16x64_i8 v[38:41], v[170:173], v[210:213], v[38:41]
	v_mfma_i32_16x16x64_i8 v[34:37], v[178:181], v[210:213], v[34:37]
	v_mfma_i32_16x16x64_i8 v[62:65], v[174:177], v[190:193], v[62:65]
	v_mfma_i32_16x16x64_i8 v[58:61], v[182:185], v[190:193], v[58:61]
	v_mfma_i32_16x16x64_i8 v[54:57], v[174:177], v[198:201], v[54:57]
	v_mfma_i32_16x16x64_i8 v[50:53], v[182:185], v[198:201], v[50:53]
	s_setprio 3
	s_barrier
	v_mfma_i32_16x16x64_i8 v[46:49], v[174:177], v[206:209], v[46:49]
	v_mfma_i32_16x16x64_i8 v[42:45], v[182:185], v[206:209], v[42:45]
	v_mfma_i32_16x16x64_i8 v[38:41], v[174:177], v[214:217], v[38:41]
	v_mfma_i32_16x16x64_i8 v[34:37], v[182:185], v[214:217], v[34:37]
	s_setprio 0
	s_add_u32 s0, s50, 0x4000
	s_addc_u32 s1, s51, 0
	s_add_i32 s52, s69, s55
	v_lshl_add_u64 v[220:221], s[0:1], 0, v[130:131]
	s_mov_b32 m0, s52
	ds_read_b128 v[186:189], v165 offset:49152
	ds_read_b128 v[190:193], v165 offset:50176
	ds_read_b128 v[194:197], v165 offset:51200
	ds_read_b128 v[198:201], v165 offset:52224
	ds_read_b128 v[202:205], v165 offset:53248
	ds_read_b128 v[206:209], v165 offset:54272
	ds_read_b128 v[210:213], v165 offset:55296
	ds_read_b128 v[214:217], v165 offset:56320
	global_load_lds_dwordx4 v[220:221], off
	s_add_i32 m0, s52, 0x2000
	v_lshl_add_u64 v[220:221], s[0:1], 0, v[134:135]
	s_add_u32 s0, s50, 0x84000
	s_addc_u32 s1, s51, 0
	s_add_i32 s50, s70, s55
	global_load_lds_dwordx4 v[220:221], off
	v_lshl_add_u64 v[220:221], s[0:1], 0, v[130:131]
	s_mov_b32 m0, s50
	v_lshl_add_u64 v[160:161], v[160:161], 0, s[20:21]
	global_load_lds_dwordx4 v[220:221], off
	v_lshl_add_u64 v[220:221], s[0:1], 0, v[134:135]
	s_add_i32 m0, s50, 0x2000
	s_nop 0
	global_load_lds_dwordx4 v[220:221], off
	s_mov_b32 m0, s60
	s_nop 0
	global_load_lds_dwordx4 v[160:161], off
	v_lshl_add_u64 v[160:161], v[218:219], 0, s[20:21]
	s_mov_b32 m0, s61
	s_nop 0
	global_load_lds_dwordx4 v[160:161], off
	s_waitcnt vmcnt(8)
	s_waitcnt lgkmcnt(0)
	s_barrier
	s_setprio 2
	s_waitcnt lgkmcnt(0)
	v_mfma_i32_16x16x64_i8 v[94:97], v[148:151], v[186:189], v[94:97]
	v_mfma_i32_16x16x64_i8 v[90:93], v[156:159], v[186:189], v[90:93]
	v_mfma_i32_16x16x64_i8 v[86:89], v[148:151], v[194:197], v[86:89]
	v_mfma_i32_16x16x64_i8 v[82:85], v[156:159], v[194:197], v[82:85]
	v_mfma_i32_16x16x64_i8 v[78:81], v[148:151], v[202:205], v[78:81]
	v_mfma_i32_16x16x64_i8 v[74:77], v[156:159], v[202:205], v[74:77]
	v_mfma_i32_16x16x64_i8 v[70:73], v[148:151], v[210:213], v[70:73]
	v_mfma_i32_16x16x64_i8 v[66:69], v[156:159], v[210:213], v[66:69]
	v_mfma_i32_16x16x64_i8 v[94:97], v[152:155], v[190:193], v[94:97]
	v_mfma_i32_16x16x64_i8 v[90:93], v[166:169], v[190:193], v[90:93]
	v_mfma_i32_16x16x64_i8 v[86:89], v[152:155], v[198:201], v[86:89]
	v_mfma_i32_16x16x64_i8 v[82:85], v[166:169], v[198:201], v[82:85]
	v_mfma_i32_16x16x64_i8 v[78:81], v[152:155], v[206:209], v[78:81]
	v_mfma_i32_16x16x64_i8 v[74:77], v[166:169], v[206:209], v[74:77]
	v_mfma_i32_16x16x64_i8 v[70:73], v[152:155], v[214:217], v[70:73]
	v_mfma_i32_16x16x64_i8 v[66:69], v[166:169], v[214:217], v[66:69]
	s_setprio 0
	s_setprio 2
	v_mfma_i32_16x16x64_i8 v[30:33], v[170:173], v[186:189], v[30:33]
	v_mfma_i32_16x16x64_i8 v[26:29], v[178:181], v[186:189], v[26:29]
	v_mfma_i32_16x16x64_i8 v[22:25], v[170:173], v[194:197], v[22:25]
	v_mfma_i32_16x16x64_i8 v[18:21], v[178:181], v[194:197], v[18:21]
	v_mfma_i32_16x16x64_i8 v[14:17], v[170:173], v[202:205], v[14:17]
	v_mfma_i32_16x16x64_i8 v[10:13], v[178:181], v[202:205], v[10:13]
	v_mfma_i32_16x16x64_i8 v[6:9], v[170:173], v[210:213], v[6:9]
	v_mfma_i32_16x16x64_i8 v[2:5], v[178:181], v[210:213], v[2:5]
	v_mfma_i32_16x16x64_i8 v[30:33], v[174:177], v[190:193], v[30:33]
	v_mfma_i32_16x16x64_i8 v[26:29], v[182:185], v[190:193], v[26:29]
	v_mfma_i32_16x16x64_i8 v[22:25], v[174:177], v[198:201], v[22:25]
	v_mfma_i32_16x16x64_i8 v[18:21], v[182:185], v[198:201], v[18:21]
	s_setprio 3
	s_barrier
	v_mfma_i32_16x16x64_i8 v[14:17], v[174:177], v[206:209], v[14:17]
	v_mfma_i32_16x16x64_i8 v[10:13], v[182:185], v[206:209], v[10:13]
	v_mfma_i32_16x16x64_i8 v[6:9], v[174:177], v[214:217], v[6:9]
	v_mfma_i32_16x16x64_i8 v[2:5], v[182:185], v[214:217], v[2:5]
	s_setprio 0
	s_add_i32 s68, s68, 2
	s_add_u32 s41, s41, 0x8000
	s_addc_u32 s43, s43, 0
	s_cmp_gt_u32 s68, 29
	s_mov_b64 s[0:1], s[6:7]
	s_cbranch_scc0 .LBB0_610
	s_and_b64 vcc, exec, s[24:25]
	s_cbranch_vccz .LBB0_613
	s_barrier

.LBB0_1103:
	s_lshl_b32 s47, s45, 7
	s_add_u32 s47, s52, s47
	s_addc_u32 s58, s53, 0
	s_add_u32 s59, s47, 0x100
	s_addc_u32 s60, s58, 0
	s_and_b64 s[56:57], s[54:55], exec
	s_cselect_b32 s61, s7, s60
	s_cselect_b32 s60, s6, s59
	s_lshl_b32 s45, s45, 14
	s_add_u32 s45, s50, s45
	s_addc_u32 s56, s51, 0
	s_add_u32 s45, s45, 0x8000
	s_addc_u32 s56, s56, 0
	s_and_b64 s[54:55], s[54:55], exec
	s_cselect_b32 s63, s41, s56
	s_cselect_b32 s62, s40, s45
	s_add_u32 s66, s47, 0x10080
	s_addc_u32 s67, s58, 0
	s_add_i32 s88, s78, s70
	s_add_i32 m0, s49, 0xc000
	s_add_i32 s89, s49, 0xe000
	s_add_i32 s85, s88, 0x2000
	s_add_u32 s64, s62, 0x10000
	ds_read_b128 v[130:133], v147
	ds_read_b128 v[134:137], v147 offset:1024
	ds_read_b128 v[152:155], v147 offset:2048
	ds_read_b128 v[156:159], v147 offset:3072
	ds_read_b128 v[164:167], v162
	ds_read_b128 v[168:171], v162 offset:1024
	ds_read_b128 v[172:175], v162 offset:2048
	ds_read_b128 v[176:179], v162 offset:3072
	s_addc_u32 s65, s63, 0
	s_add_i32 s87, s79, s70
	s_add_i32 s86, s87, 0x2000
	s_add_i32 s84, 0, 0x18000
	s_add_i32 s83, 0, 0x1c000
	s_add_u32 s58, s60, 0x10000
	s_addc_u32 s59, s61, 0
	s_add_u32 s54, s62, 0x4000
	s_addc_u32 s55, s63, 0
	s_add_i32 s82, s84, s70
	s_add_i32 s47, s82, 0x2000
	s_add_u32 s56, s62, 0x14000
	s_addc_u32 s57, s63, 0
	s_add_i32 s81, s83, s70
	s_add_i32 s45, s81, 0x2000
	v_lshl_add_u64 v[160:161], s[66:67], 0, v[140:141]
	ds_read_b128 v[180:183], v163
	ds_read_b128 v[184:187], v163 offset:1024
	ds_read_b128 v[188:191], v163 offset:2048
	ds_read_b128 v[192:195], v163 offset:3072
	ds_read_b128 v[196:199], v163 offset:4096
	ds_read_b128 v[200:203], v163 offset:5120
	ds_read_b128 v[204:207], v163 offset:6144
	ds_read_b128 v[208:211], v163 offset:7168
	global_load_lds_dwordx4 v[160:161], off
	v_lshl_add_u64 v[160:161], s[66:67], 0, v[144:145]
	s_mov_b32 m0, s89
	s_nop 0
	global_load_lds_dwordx4 v[160:161], off
	s_waitcnt vmcnt(8)
	s_waitcnt lgkmcnt(0)
	s_barrier
	s_setprio 2
	s_waitcnt lgkmcnt(0)
	v_mfma_f32_16x16x32_bf16 v[126:129], v[130:133], v[180:183], v[126:129]
	v_mfma_f32_16x16x32_bf16 v[122:125], v[152:155], v[180:183], v[122:125]
	v_mfma_f32_16x16x32_bf16 v[118:121], v[130:133], v[188:191], v[118:121]
	v_mfma_f32_16x16x32_bf16 v[114:117], v[152:155], v[188:191], v[114:117]
	v_mfma_f32_16x16x32_bf16 v[110:113], v[130:133], v[196:199], v[110:113]
	v_mfma_f32_16x16x32_bf16 v[106:109], v[152:155], v[196:199], v[106:109]
	v_mfma_f32_16x16x32_bf16 v[102:105], v[130:133], v[204:207], v[102:105]
	v_mfma_f32_16x16x32_bf16 v[98:101], v[152:155], v[204:207], v[98:101]
	v_mfma_f32_16x16x32_bf16 v[126:129], v[134:137], v[184:187], v[126:129]
	v_mfma_f32_16x16x32_bf16 v[122:125], v[156:159], v[184:187], v[122:125]
	v_mfma_f32_16x16x32_bf16 v[118:121], v[134:137], v[192:195], v[118:121]
	v_mfma_f32_16x16x32_bf16 v[114:117], v[156:159], v[192:195], v[114:117]
	v_mfma_f32_16x16x32_bf16 v[110:113], v[134:137], v[200:203], v[110:113]
	v_mfma_f32_16x16x32_bf16 v[106:109], v[156:159], v[200:203], v[106:109]
	v_mfma_f32_16x16x32_bf16 v[102:105], v[134:137], v[208:211], v[102:105]
	v_mfma_f32_16x16x32_bf16 v[98:101], v[156:159], v[208:211], v[98:101]
	s_setprio 0
	s_setprio 2
	v_mfma_f32_16x16x32_bf16 v[70:73], v[164:167], v[180:183], v[70:73]
	v_mfma_f32_16x16x32_bf16 v[66:69], v[172:175], v[180:183], v[66:69]
	v_mfma_f32_16x16x32_bf16 v[54:57], v[164:167], v[188:191], v[54:57]
	v_mfma_f32_16x16x32_bf16 v[50:53], v[172:175], v[188:191], v[50:53]
	v_mfma_f32_16x16x32_bf16 v[46:49], v[164:167], v[196:199], v[46:49]
	v_mfma_f32_16x16x32_bf16 v[42:45], v[172:175], v[196:199], v[42:45]
	v_mfma_f32_16x16x32_bf16 v[38:41], v[164:167], v[204:207], v[38:41]
	v_mfma_f32_16x16x32_bf16 v[34:37], v[172:175], v[204:207], v[34:37]
	v_mfma_f32_16x16x32_bf16 v[70:73], v[168:171], v[184:187], v[70:73]
	v_mfma_f32_16x16x32_bf16 v[66:69], v[176:179], v[184:187], v[66:69]
	v_mfma_f32_16x16x32_bf16 v[54:57], v[168:171], v[192:195], v[54:57]
	v_mfma_f32_16x16x32_bf16 v[50:53], v[176:179], v[192:195], v[50:53]
	s_setprio 3
	s_barrier
	v_mfma_f32_16x16x32_bf16 v[46:49], v[168:171], v[200:203], v[46:49]
	v_mfma_f32_16x16x32_bf16 v[42:45], v[176:179], v[200:203], v[42:45]
	v_mfma_f32_16x16x32_bf16 v[38:41], v[168:171], v[208:211], v[38:41]
	v_mfma_f32_16x16x32_bf16 v[34:37], v[176:179], v[208:211], v[34:37]
	s_setprio 0
	s_mov_b32 m0, s88
	v_lshl_add_u64 v[160:161], s[62:63], 0, v[138:139]
	ds_read_b128 v[180:183], v163 offset:16384
	ds_read_b128 v[184:187], v163 offset:17408
	ds_read_b128 v[188:191], v163 offset:18432
	ds_read_b128 v[192:195], v163 offset:19456
	ds_read_b128 v[196:199], v163 offset:20480
	ds_read_b128 v[200:203], v163 offset:21504
	ds_read_b128 v[204:207], v163 offset:22528
	ds_read_b128 v[208:211], v163 offset:23552
	global_load_lds_dwordx4 v[160:161], off
	v_lshl_add_u64 v[160:161], s[62:63], 0, v[142:143]
	s_mov_b32 m0, s85
	v_lshl_add_u64 v[212:213], s[60:61], 0, v[144:145]
	global_load_lds_dwordx4 v[160:161], off
	v_lshl_add_u64 v[160:161], s[64:65], 0, v[138:139]
	s_mov_b32 m0, s87
	s_nop 0
	global_load_lds_dwordx4 v[160:161], off
	v_lshl_add_u64 v[160:161], s[64:65], 0, v[142:143]
	s_mov_b32 m0, s86
	s_nop 0
	global_load_lds_dwordx4 v[160:161], off
	v_lshl_add_u64 v[160:161], s[60:61], 0, v[140:141]
	s_mov_b32 m0, s49
	s_nop 0
	global_load_lds_dwordx4 v[160:161], off
	s_mov_b32 m0, s71
	s_nop 0
	global_load_lds_dwordx4 v[212:213], off
	s_waitcnt vmcnt(8)
	s_waitcnt lgkmcnt(0)
	s_barrier
	s_setprio 2
	s_waitcnt lgkmcnt(0)
	v_mfma_f32_16x16x32_bf16 v[94:97], v[130:133], v[180:183], v[94:97]
	v_mfma_f32_16x16x32_bf16 v[90:93], v[152:155], v[180:183], v[90:93]
	v_mfma_f32_16x16x32_bf16 v[86:89], v[130:133], v[188:191], v[86:89]
	v_mfma_f32_16x16x32_bf16 v[82:85], v[152:155], v[188:191], v[82:85]
	v_mfma_f32_16x16x32_bf16 v[78:81], v[130:133], v[196:199], v[78:81]
	v_mfma_f32_16x16x32_bf16 v[74:77], v[152:155], v[196:199], v[74:77]
	v_mfma_f32_16x16x32_bf16 v[62:65], v[130:133], v[204:207], v[62:65]
	v_mfma_f32_16x16x32_bf16 v[58:61], v[152:155], v[204:207], v[58:61]
	v_mfma_f32_16x16x32_bf16 v[94:97], v[134:137], v[184:187], v[94:97]
	v_mfma_f32_16x16x32_bf16 v[90:93], v[156:159], v[184:187], v[90:93]
	v_mfma_f32_16x16x32_bf16 v[86:89], v[134:137], v[192:195], v[86:89]
	v_mfma_f32_16x16x32_bf16 v[82:85], v[156:159], v[192:195], v[82:85]
	v_mfma_f32_16x16x32_bf16 v[78:81], v[134:137], v[200:203], v[78:81]
	v_mfma_f32_16x16x32_bf16 v[74:77], v[156:159], v[200:203], v[74:77]
	v_mfma_f32_16x16x32_bf16 v[62:65], v[134:137], v[208:211], v[62:65]
	v_mfma_f32_16x16x32_bf16 v[58:61], v[156:159], v[208:211], v[58:61]
	s_setprio 0
	s_setprio 2
	v_mfma_f32_16x16x32_bf16 v[30:33], v[164:167], v[180:183], v[30:33]
	v_mfma_f32_16x16x32_bf16 v[26:29], v[172:175], v[180:183], v[26:29]
	v_mfma_f32_16x16x32_bf16 v[22:25], v[164:167], v[188:191], v[22:25]
	v_mfma_f32_16x16x32_bf16 v[18:21], v[172:175], v[188:191], v[18:21]
	v_mfma_f32_16x16x32_bf16 v[14:17], v[164:167], v[196:199], v[14:17]
	v_mfma_f32_16x16x32_bf16 v[10:13], v[172:175], v[196:199], v[10:13]
	v_mfma_f32_16x16x32_bf16 v[6:9], v[164:167], v[204:207], v[6:9]
	v_mfma_f32_16x16x32_bf16 v[2:5], v[172:175], v[204:207], v[2:5]
	v_mfma_f32_16x16x32_bf16 v[30:33], v[168:171], v[184:187], v[30:33]
	v_mfma_f32_16x16x32_bf16 v[26:29], v[176:179], v[184:187], v[26:29]
	v_mfma_f32_16x16x32_bf16 v[22:25], v[168:171], v[192:195], v[22:25]
	v_mfma_f32_16x16x32_bf16 v[18:21], v[176:179], v[192:195], v[18:21]
	s_setprio 3
	s_barrier
	v_mfma_f32_16x16x32_bf16 v[14:17], v[168:171], v[200:203], v[14:17]
	v_mfma_f32_16x16x32_bf16 v[10:13], v[176:179], v[200:203], v[10:13]
	v_mfma_f32_16x16x32_bf16 v[6:9], v[168:171], v[208:211], v[6:9]
	v_mfma_f32_16x16x32_bf16 v[2:5], v[176:179], v[208:211], v[2:5]
	s_setprio 0
	v_add_u32_e32 v156, s84, v1
	v_add_u32_e32 v176, s83, v1
	ds_read_b128 v[130:133], v156
	ds_read_b128 v[134:137], v156 offset:1024
	ds_read_b128 v[152:155], v156 offset:2048
	ds_read_b128 v[156:159], v156 offset:3072
	ds_read_b128 v[164:167], v176
	ds_read_b128 v[168:171], v176 offset:1024
	ds_read_b128 v[172:175], v176 offset:2048
	ds_read_b128 v[176:179], v176 offset:3072
	s_mov_b32 m0, s72
	v_lshl_add_u64 v[214:215], s[58:59], 0, v[140:141]
	ds_read_b128 v[180:183], v163 offset:32768
	ds_read_b128 v[184:187], v163 offset:33792
	ds_read_b128 v[188:191], v163 offset:34816
	ds_read_b128 v[192:195], v163 offset:35840
	ds_read_b128 v[196:199], v163 offset:36864
	ds_read_b128 v[200:203], v163 offset:37888
	ds_read_b128 v[204:207], v163 offset:38912
	ds_read_b128 v[208:211], v163 offset:39936
	global_load_lds_dwordx4 v[214:215], off
	v_lshl_add_u64 v[214:215], s[58:59], 0, v[144:145]
	s_mov_b32 m0, s73
	s_nop 0
	global_load_lds_dwordx4 v[214:215], off
	s_waitcnt vmcnt(8)
	s_waitcnt lgkmcnt(0)
	s_barrier
	s_setprio 2
	s_waitcnt lgkmcnt(0)
	v_mfma_f32_16x16x32_bf16 v[126:129], v[130:133], v[180:183], v[126:129]
	v_mfma_f32_16x16x32_bf16 v[122:125], v[152:155], v[180:183], v[122:125]
	v_mfma_f32_16x16x32_bf16 v[118:121], v[130:133], v[188:191], v[118:121]
	v_mfma_f32_16x16x32_bf16 v[114:117], v[152:155], v[188:191], v[114:117]
	v_mfma_f32_16x16x32_bf16 v[110:113], v[130:133], v[196:199], v[110:113]
	v_mfma_f32_16x16x32_bf16 v[106:109], v[152:155], v[196:199], v[106:109]
	v_mfma_f32_16x16x32_bf16 v[102:105], v[130:133], v[204:207], v[102:105]
	v_mfma_f32_16x16x32_bf16 v[98:101], v[152:155], v[204:207], v[98:101]
	v_mfma_f32_16x16x32_bf16 v[126:129], v[134:137], v[184:187], v[126:129]
	v_mfma_f32_16x16x32_bf16 v[122:125], v[156:159], v[184:187], v[122:125]
	v_mfma_f32_16x16x32_bf16 v[118:121], v[134:137], v[192:195], v[118:121]
	v_mfma_f32_16x16x32_bf16 v[114:117], v[156:159], v[192:195], v[114:117]
	v_mfma_f32_16x16x32_bf16 v[110:113], v[134:137], v[200:203], v[110:113]
	v_mfma_f32_16x16x32_bf16 v[106:109], v[156:159], v[200:203], v[106:109]
	v_mfma_f32_16x16x32_bf16 v[102:105], v[134:137], v[208:211], v[102:105]
	v_mfma_f32_16x16x32_bf16 v[98:101], v[156:159], v[208:211], v[98:101]
	s_setprio 0
	s_setprio 2
	v_mfma_f32_16x16x32_bf16 v[70:73], v[164:167], v[180:183], v[70:73]
	v_mfma_f32_16x16x32_bf16 v[66:69], v[172:175], v[180:183], v[66:69]
	v_mfma_f32_16x16x32_bf16 v[54:57], v[164:167], v[188:191], v[54:57]
	v_mfma_f32_16x16x32_bf16 v[50:53], v[172:175], v[188:191], v[50:53]
	v_mfma_f32_16x16x32_bf16 v[46:49], v[164:167], v[196:199], v[46:49]
	v_mfma_f32_16x16x32_bf16 v[42:45], v[172:175], v[196:199], v[42:45]
	v_mfma_f32_16x16x32_bf16 v[38:41], v[164:167], v[204:207], v[38:41]
	v_mfma_f32_16x16x32_bf16 v[34:37], v[172:175], v[204:207], v[34:37]
	v_mfma_f32_16x16x32_bf16 v[70:73], v[168:171], v[184:187], v[70:73]
	v_mfma_f32_16x16x32_bf16 v[66:69], v[176:179], v[184:187], v[66:69]
	v_mfma_f32_16x16x32_bf16 v[54:57], v[168:171], v[192:195], v[54:57]
	v_mfma_f32_16x16x32_bf16 v[50:53], v[176:179], v[192:195], v[50:53]
	s_setprio 3
	s_barrier
	v_mfma_f32_16x16x32_bf16 v[46:49], v[168:171], v[200:203], v[46:49]
	v_mfma_f32_16x16x32_bf16 v[42:45], v[176:179], v[200:203], v[42:45]
	v_mfma_f32_16x16x32_bf16 v[38:41], v[168:171], v[208:211], v[38:41]
	v_mfma_f32_16x16x32_bf16 v[34:37], v[176:179], v[208:211], v[34:37]
	s_setprio 0
	s_mov_b32 m0, s82
	v_lshl_add_u64 v[214:215], s[54:55], 0, v[138:139]
	ds_read_b128 v[180:183], v163 offset:49152
	ds_read_b128 v[184:187], v163 offset:50176
	ds_read_b128 v[188:191], v163 offset:51200
	ds_read_b128 v[192:195], v163 offset:52224
	ds_read_b128 v[196:199], v163 offset:53248
	ds_read_b128 v[200:203], v163 offset:54272
	ds_read_b128 v[204:207], v163 offset:55296
	ds_read_b128 v[208:211], v163 offset:56320
	global_load_lds_dwordx4 v[214:215], off
	v_lshl_add_u64 v[214:215], s[54:55], 0, v[142:143]
	s_mov_b32 m0, s47
	v_lshl_add_u64 v[160:161], v[160:161], 0, s[24:25]
	global_load_lds_dwordx4 v[214:215], off
	v_lshl_add_u64 v[214:215], s[56:57], 0, v[138:139]
	s_mov_b32 m0, s81
	s_nop 0
	global_load_lds_dwordx4 v[214:215], off
	v_lshl_add_u64 v[214:215], s[56:57], 0, v[142:143]
	s_mov_b32 m0, s45
	s_nop 0
	global_load_lds_dwordx4 v[214:215], off
	s_mov_b32 m0, s75
	s_nop 0
	global_load_lds_dwordx4 v[160:161], off
	v_lshl_add_u64 v[160:161], v[212:213], 0, s[24:25]
	s_mov_b32 m0, s76
	s_nop 0
	global_load_lds_dwordx4 v[160:161], off
	s_waitcnt vmcnt(8)
	s_waitcnt lgkmcnt(0)
	s_barrier
	s_setprio 2
	s_waitcnt lgkmcnt(0)
	v_mfma_f32_16x16x32_bf16 v[94:97], v[130:133], v[180:183], v[94:97]
	v_mfma_f32_16x16x32_bf16 v[90:93], v[152:155], v[180:183], v[90:93]
	v_mfma_f32_16x16x32_bf16 v[86:89], v[130:133], v[188:191], v[86:89]
	v_mfma_f32_16x16x32_bf16 v[82:85], v[152:155], v[188:191], v[82:85]
	v_mfma_f32_16x16x32_bf16 v[78:81], v[130:133], v[196:199], v[78:81]
	v_mfma_f32_16x16x32_bf16 v[74:77], v[152:155], v[196:199], v[74:77]
	v_mfma_f32_16x16x32_bf16 v[62:65], v[130:133], v[204:207], v[62:65]
	v_mfma_f32_16x16x32_bf16 v[58:61], v[152:155], v[204:207], v[58:61]
	v_mfma_f32_16x16x32_bf16 v[94:97], v[134:137], v[184:187], v[94:97]
	v_mfma_f32_16x16x32_bf16 v[90:93], v[156:159], v[184:187], v[90:93]
	v_mfma_f32_16x16x32_bf16 v[86:89], v[134:137], v[192:195], v[86:89]
	v_mfma_f32_16x16x32_bf16 v[82:85], v[156:159], v[192:195], v[82:85]
	v_mfma_f32_16x16x32_bf16 v[78:81], v[134:137], v[200:203], v[78:81]
	v_mfma_f32_16x16x32_bf16 v[74:77], v[156:159], v[200:203], v[74:77]
	v_mfma_f32_16x16x32_bf16 v[62:65], v[134:137], v[208:211], v[62:65]
	v_mfma_f32_16x16x32_bf16 v[58:61], v[156:159], v[208:211], v[58:61]
	s_setprio 0
	s_setprio 2
	v_mfma_f32_16x16x32_bf16 v[30:33], v[164:167], v[180:183], v[30:33]
	v_mfma_f32_16x16x32_bf16 v[26:29], v[172:175], v[180:183], v[26:29]
	v_mfma_f32_16x16x32_bf16 v[22:25], v[164:167], v[188:191], v[22:25]
	v_mfma_f32_16x16x32_bf16 v[18:21], v[172:175], v[188:191], v[18:21]
	v_mfma_f32_16x16x32_bf16 v[14:17], v[164:167], v[196:199], v[14:17]
	v_mfma_f32_16x16x32_bf16 v[10:13], v[172:175], v[196:199], v[10:13]
	v_mfma_f32_16x16x32_bf16 v[6:9], v[164:167], v[204:207], v[6:9]
	v_mfma_f32_16x16x32_bf16 v[2:5], v[172:175], v[204:207], v[2:5]
	v_mfma_f32_16x16x32_bf16 v[30:33], v[168:171], v[184:187], v[30:33]
	v_mfma_f32_16x16x32_bf16 v[26:29], v[176:179], v[184:187], v[26:29]
	v_mfma_f32_16x16x32_bf16 v[22:25], v[168:171], v[192:195], v[22:25]
	v_mfma_f32_16x16x32_bf16 v[18:21], v[176:179], v[192:195], v[18:21]
	s_setprio 3
	s_barrier
	v_mfma_f32_16x16x32_bf16 v[14:17], v[168:171], v[200:203], v[14:17]
	v_mfma_f32_16x16x32_bf16 v[10:13], v[176:179], v[200:203], v[10:13]
	v_mfma_f32_16x16x32_bf16 v[6:9], v[168:171], v[208:211], v[6:9]
	v_mfma_f32_16x16x32_bf16 v[2:5], v[176:179], v[208:211], v[2:5]
	s_setprio 0
	s_mov_b32 s45, 2
	s_andn2_b64 vcc, exec, s[0:1]
	s_mov_b64 s[54:55], -1
	s_mov_b64 s[0:1], 0
	s_cbranch_vccz .LBB0_1103
	s_and_b64 vcc, exec, s[42:43]
	s_cbranch_vccz .LBB0_1106
	s_barrier

.LBB0_1184:
	v_add_u32_e32 v142, s65, v1
	v_add_u32_e32 v176, s66, v1
	ds_read_b128 v[130:133], v142
	ds_read_b128 v[134:137], v142 offset:1024
	ds_read_b128 v[138:141], v142 offset:2048
	ds_read_b128 v[142:145], v142 offset:3072
	ds_read_b128 v[164:167], v176
	ds_read_b128 v[168:171], v176 offset:1024
	ds_read_b128 v[172:175], v176 offset:2048
	ds_read_b128 v[176:179], v176 offset:3072
	s_add_u32 s50, s0, 0xfffc0080
	s_addc_u32 s51, s1, -1
	s_cmp_eq_u32 s73, 12
	s_cselect_b32 s53, s7, s51
	s_cselect_b32 s52, s6, s50
	s_cselect_b32 s51, s47, s45
	s_cselect_b32 s50, s46, s43
	v_lshl_add_u64 v[212:213], s[0:1], 0, v[156:157]
	s_add_i32 m0, s57, 0xc000
	ds_read_b128 v[180:183], v147
	ds_read_b128 v[184:187], v147 offset:1024
	ds_read_b128 v[188:191], v147 offset:2048
	ds_read_b128 v[192:195], v147 offset:3072
	ds_read_b128 v[196:199], v147 offset:4096
	ds_read_b128 v[200:203], v147 offset:5120
	ds_read_b128 v[204:207], v147 offset:6144
	ds_read_b128 v[208:211], v147 offset:7168
	global_load_lds_dwordx4 v[212:213], off
	v_lshl_add_u64 v[212:213], s[0:1], 0, v[158:159]
	s_add_i32 m0, s57, 0xe000
	s_nop 0
	global_load_lds_dwordx4 v[212:213], off
	s_waitcnt vmcnt(8)
	s_waitcnt lgkmcnt(0)
	s_barrier
	s_setprio 2
	s_waitcnt lgkmcnt(0)
	v_mfma_f32_16x16x32_bf16 v[126:129], v[130:133], v[180:183], v[126:129]
	v_mfma_f32_16x16x32_bf16 v[122:125], v[138:141], v[180:183], v[122:125]
	v_mfma_f32_16x16x32_bf16 v[118:121], v[130:133], v[188:191], v[118:121]
	v_mfma_f32_16x16x32_bf16 v[114:117], v[138:141], v[188:191], v[114:117]
	v_mfma_f32_16x16x32_bf16 v[110:113], v[130:133], v[196:199], v[110:113]
	v_mfma_f32_16x16x32_bf16 v[106:109], v[138:141], v[196:199], v[106:109]
	v_mfma_f32_16x16x32_bf16 v[102:105], v[130:133], v[204:207], v[102:105]
	v_mfma_f32_16x16x32_bf16 v[98:101], v[138:141], v[204:207], v[98:101]
	v_mfma_f32_16x16x32_bf16 v[126:129], v[134:137], v[184:187], v[126:129]
	v_mfma_f32_16x16x32_bf16 v[122:125], v[142:145], v[184:187], v[122:125]
	v_mfma_f32_16x16x32_bf16 v[118:121], v[134:137], v[192:195], v[118:121]
	v_mfma_f32_16x16x32_bf16 v[114:117], v[142:145], v[192:195], v[114:117]
	v_mfma_f32_16x16x32_bf16 v[110:113], v[134:137], v[200:203], v[110:113]
	v_mfma_f32_16x16x32_bf16 v[106:109], v[142:145], v[200:203], v[106:109]
	v_mfma_f32_16x16x32_bf16 v[102:105], v[134:137], v[208:211], v[102:105]
	v_mfma_f32_16x16x32_bf16 v[98:101], v[142:145], v[208:211], v[98:101]
	s_setprio 0
	s_setprio 2
	v_mfma_f32_16x16x32_bf16 v[94:97], v[164:167], v[180:183], v[94:97]
	v_mfma_f32_16x16x32_bf16 v[90:93], v[172:175], v[180:183], v[90:93]
	v_mfma_f32_16x16x32_bf16 v[86:89], v[164:167], v[188:191], v[86:89]
	v_mfma_f32_16x16x32_bf16 v[82:85], v[172:175], v[188:191], v[82:85]
	v_mfma_f32_16x16x32_bf16 v[78:81], v[164:167], v[196:199], v[78:81]
	v_mfma_f32_16x16x32_bf16 v[74:77], v[172:175], v[196:199], v[74:77]
	v_mfma_f32_16x16x32_bf16 v[70:73], v[164:167], v[204:207], v[70:73]
	v_mfma_f32_16x16x32_bf16 v[66:69], v[172:175], v[204:207], v[66:69]
	v_mfma_f32_16x16x32_bf16 v[94:97], v[168:171], v[184:187], v[94:97]
	v_mfma_f32_16x16x32_bf16 v[90:93], v[176:179], v[184:187], v[90:93]
	v_mfma_f32_16x16x32_bf16 v[86:89], v[168:171], v[192:195], v[86:89]
	v_mfma_f32_16x16x32_bf16 v[82:85], v[176:179], v[192:195], v[82:85]
	s_setprio 3
	s_barrier
	v_mfma_f32_16x16x32_bf16 v[78:81], v[168:171], v[200:203], v[78:81]
	v_mfma_f32_16x16x32_bf16 v[74:77], v[176:179], v[200:203], v[74:77]
	v_mfma_f32_16x16x32_bf16 v[70:73], v[168:171], v[208:211], v[70:73]
	v_mfma_f32_16x16x32_bf16 v[66:69], v[176:179], v[208:211], v[66:69]
	s_setprio 0
	s_add_i32 s74, s65, s56
	v_lshl_add_u64 v[212:213], s[50:51], 0, v[148:149]
	s_mov_b32 m0, s74
	ds_read_b128 v[180:183], v147 offset:16384
	ds_read_b128 v[184:187], v147 offset:17408
	ds_read_b128 v[188:191], v147 offset:18432
	ds_read_b128 v[192:195], v147 offset:19456
	ds_read_b128 v[196:199], v147 offset:20480
	ds_read_b128 v[200:203], v147 offset:21504
	ds_read_b128 v[204:207], v147 offset:22528
	ds_read_b128 v[208:211], v147 offset:23552
	global_load_lds_dwordx4 v[212:213], off
	s_add_i32 m0, s74, 0x2000
	s_add_u32 s74, s50, 0x40000
	v_lshl_add_u64 v[212:213], s[50:51], 0, v[152:153]
	s_addc_u32 s75, s51, 0
	s_add_i32 s76, s66, s56
	global_load_lds_dwordx4 v[212:213], off
	v_lshl_add_u64 v[212:213], s[74:75], 0, v[148:149]
	s_mov_b32 m0, s76
	v_lshl_add_u64 v[214:215], s[52:53], 0, v[154:155]
	global_load_lds_dwordx4 v[212:213], off
	v_lshl_add_u64 v[212:213], s[74:75], 0, v[152:153]
	s_add_i32 m0, s76, 0x2000
	s_nop 0
	global_load_lds_dwordx4 v[212:213], off
	v_lshl_add_u64 v[212:213], s[52:53], 0, v[150:151]
	s_mov_b32 m0, s57
	s_nop 0
	global_load_lds_dwordx4 v[212:213], off
	s_mov_b32 m0, s58
	s_nop 0
	global_load_lds_dwordx4 v[214:215], off
	s_waitcnt vmcnt(8)
	s_waitcnt lgkmcnt(0)
	s_barrier
	s_setprio 2
	s_waitcnt lgkmcnt(0)
	v_mfma_f32_16x16x32_bf16 v[62:65], v[130:133], v[180:183], v[62:65]
	v_mfma_f32_16x16x32_bf16 v[58:61], v[138:141], v[180:183], v[58:61]
	v_mfma_f32_16x16x32_bf16 v[54:57], v[130:133], v[188:191], v[54:57]
	v_mfma_f32_16x16x32_bf16 v[50:53], v[138:141], v[188:191], v[50:53]
	v_mfma_f32_16x16x32_bf16 v[46:49], v[130:133], v[196:199], v[46:49]
	v_mfma_f32_16x16x32_bf16 v[42:45], v[138:141], v[196:199], v[42:45]
	v_mfma_f32_16x16x32_bf16 v[38:41], v[130:133], v[204:207], v[38:41]
	v_mfma_f32_16x16x32_bf16 v[34:37], v[138:141], v[204:207], v[34:37]
	v_mfma_f32_16x16x32_bf16 v[62:65], v[134:137], v[184:187], v[62:65]
	v_mfma_f32_16x16x32_bf16 v[58:61], v[142:145], v[184:187], v[58:61]
	v_mfma_f32_16x16x32_bf16 v[54:57], v[134:137], v[192:195], v[54:57]
	v_mfma_f32_16x16x32_bf16 v[50:53], v[142:145], v[192:195], v[50:53]
	v_mfma_f32_16x16x32_bf16 v[46:49], v[134:137], v[200:203], v[46:49]
	v_mfma_f32_16x16x32_bf16 v[42:45], v[142:145], v[200:203], v[42:45]
	v_mfma_f32_16x16x32_bf16 v[38:41], v[134:137], v[208:211], v[38:41]
	v_mfma_f32_16x16x32_bf16 v[34:37], v[142:145], v[208:211], v[34:37]
	s_setprio 0
	s_setprio 2
	v_mfma_f32_16x16x32_bf16 v[30:33], v[164:167], v[180:183], v[30:33]
	v_mfma_f32_16x16x32_bf16 v[26:29], v[172:175], v[180:183], v[26:29]
	v_mfma_f32_16x16x32_bf16 v[22:25], v[164:167], v[188:191], v[22:25]
	v_mfma_f32_16x16x32_bf16 v[18:21], v[172:175], v[188:191], v[18:21]
	v_mfma_f32_16x16x32_bf16 v[14:17], v[164:167], v[196:199], v[14:17]
	v_mfma_f32_16x16x32_bf16 v[10:13], v[172:175], v[196:199], v[10:13]
	v_mfma_f32_16x16x32_bf16 v[6:9], v[164:167], v[204:207], v[6:9]
	v_mfma_f32_16x16x32_bf16 v[2:5], v[172:175], v[204:207], v[2:5]
	v_mfma_f32_16x16x32_bf16 v[30:33], v[168:171], v[184:187], v[30:33]
	v_mfma_f32_16x16x32_bf16 v[26:29], v[176:179], v[184:187], v[26:29]
	v_mfma_f32_16x16x32_bf16 v[22:25], v[168:171], v[192:195], v[22:25]
	v_mfma_f32_16x16x32_bf16 v[18:21], v[176:179], v[192:195], v[18:21]
	s_setprio 3
	s_barrier
	v_mfma_f32_16x16x32_bf16 v[14:17], v[168:171], v[200:203], v[14:17]
	v_mfma_f32_16x16x32_bf16 v[10:13], v[176:179], v[200:203], v[10:13]
	v_mfma_f32_16x16x32_bf16 v[6:9], v[168:171], v[208:211], v[6:9]
	v_mfma_f32_16x16x32_bf16 v[2:5], v[176:179], v[208:211], v[2:5]
	s_setprio 0
	s_add_i32 s74, 0, 0x18000
	s_add_i32 s75, 0, 0x1c000
	v_add_u32_e32 v142, s74, v1
	v_add_u32_e32 v176, s75, v1
	ds_read_b128 v[130:133], v142
	ds_read_b128 v[134:137], v142 offset:1024
	ds_read_b128 v[138:141], v142 offset:2048
	ds_read_b128 v[142:145], v142 offset:3072
	ds_read_b128 v[164:167], v176
	ds_read_b128 v[168:171], v176 offset:1024
	ds_read_b128 v[172:175], v176 offset:2048
	ds_read_b128 v[176:179], v176 offset:3072
	s_add_u32 s52, s52, 0x40000
	s_addc_u32 s53, s53, 0
	s_mov_b32 m0, s59
	v_lshl_add_u64 v[216:217], s[52:53], 0, v[150:151]
	ds_read_b128 v[180:183], v147 offset:32768
	ds_read_b128 v[184:187], v147 offset:33792
	ds_read_b128 v[188:191], v147 offset:34816
	ds_read_b128 v[192:195], v147 offset:35840
	ds_read_b128 v[196:199], v147 offset:36864
	ds_read_b128 v[200:203], v147 offset:37888
	ds_read_b128 v[204:207], v147 offset:38912
	ds_read_b128 v[208:211], v147 offset:39936
	global_load_lds_dwordx4 v[216:217], off
	v_lshl_add_u64 v[216:217], s[52:53], 0, v[154:155]
	s_mov_b32 m0, s60
	s_nop 0
	global_load_lds_dwordx4 v[216:217], off
	s_waitcnt vmcnt(8)
	s_waitcnt lgkmcnt(0)
	s_barrier
	s_setprio 2
	s_waitcnt lgkmcnt(0)
	v_mfma_f32_16x16x32_bf16 v[126:129], v[130:133], v[180:183], v[126:129]
	v_mfma_f32_16x16x32_bf16 v[122:125], v[138:141], v[180:183], v[122:125]
	v_mfma_f32_16x16x32_bf16 v[118:121], v[130:133], v[188:191], v[118:121]
	v_mfma_f32_16x16x32_bf16 v[114:117], v[138:141], v[188:191], v[114:117]
	v_mfma_f32_16x16x32_bf16 v[110:113], v[130:133], v[196:199], v[110:113]
	v_mfma_f32_16x16x32_bf16 v[106:109], v[138:141], v[196:199], v[106:109]
	v_mfma_f32_16x16x32_bf16 v[102:105], v[130:133], v[204:207], v[102:105]
	v_mfma_f32_16x16x32_bf16 v[98:101], v[138:141], v[204:207], v[98:101]
	v_mfma_f32_16x16x32_bf16 v[126:129], v[134:137], v[184:187], v[126:129]
	v_mfma_f32_16x16x32_bf16 v[122:125], v[142:145], v[184:187], v[122:125]
	v_mfma_f32_16x16x32_bf16 v[118:121], v[134:137], v[192:195], v[118:121]
	v_mfma_f32_16x16x32_bf16 v[114:117], v[142:145], v[192:195], v[114:117]
	v_mfma_f32_16x16x32_bf16 v[110:113], v[134:137], v[200:203], v[110:113]
	v_mfma_f32_16x16x32_bf16 v[106:109], v[142:145], v[200:203], v[106:109]
	v_mfma_f32_16x16x32_bf16 v[102:105], v[134:137], v[208:211], v[102:105]
	v_mfma_f32_16x16x32_bf16 v[98:101], v[142:145], v[208:211], v[98:101]
	s_setprio 0
	s_setprio 2
	v_mfma_f32_16x16x32_bf16 v[94:97], v[164:167], v[180:183], v[94:97]
	v_mfma_f32_16x16x32_bf16 v[90:93], v[172:175], v[180:183], v[90:93]
	v_mfma_f32_16x16x32_bf16 v[86:89], v[164:167], v[188:191], v[86:89]
	v_mfma_f32_16x16x32_bf16 v[82:85], v[172:175], v[188:191], v[82:85]
	v_mfma_f32_16x16x32_bf16 v[78:81], v[164:167], v[196:199], v[78:81]
	v_mfma_f32_16x16x32_bf16 v[74:77], v[172:175], v[196:199], v[74:77]
	v_mfma_f32_16x16x32_bf16 v[70:73], v[164:167], v[204:207], v[70:73]
	v_mfma_f32_16x16x32_bf16 v[66:69], v[172:175], v[204:207], v[66:69]
	v_mfma_f32_16x16x32_bf16 v[94:97], v[168:171], v[184:187], v[94:97]
	v_mfma_f32_16x16x32_bf16 v[90:93], v[176:179], v[184:187], v[90:93]
	v_mfma_f32_16x16x32_bf16 v[86:89], v[168:171], v[192:195], v[86:89]
	v_mfma_f32_16x16x32_bf16 v[82:85], v[176:179], v[192:195], v[82:85]
	s_setprio 3
	s_barrier
	v_mfma_f32_16x16x32_bf16 v[78:81], v[168:171], v[200:203], v[78:81]
	v_mfma_f32_16x16x32_bf16 v[74:77], v[176:179], v[200:203], v[74:77]
	v_mfma_f32_16x16x32_bf16 v[70:73], v[168:171], v[208:211], v[70:73]
	v_mfma_f32_16x16x32_bf16 v[66:69], v[176:179], v[208:211], v[66:69]
	s_setprio 0
	s_add_u32 s52, s50, 0x4000
	s_addc_u32 s53, s51, 0
	s_add_i32 s74, s74, s56
	v_lshl_add_u64 v[216:217], s[52:53], 0, v[148:149]
	s_mov_b32 m0, s74
	ds_read_b128 v[180:183], v147 offset:49152
	ds_read_b128 v[184:187], v147 offset:50176
	ds_read_b128 v[188:191], v147 offset:51200
	ds_read_b128 v[192:195], v147 offset:52224
	ds_read_b128 v[196:199], v147 offset:53248
	ds_read_b128 v[200:203], v147 offset:54272
	ds_read_b128 v[204:207], v147 offset:55296
	ds_read_b128 v[208:211], v147 offset:56320
	global_load_lds_dwordx4 v[216:217], off
	s_add_i32 m0, s74, 0x2000
	s_add_u32 s50, s50, 0x44000
	v_lshl_add_u64 v[216:217], s[52:53], 0, v[152:153]
	s_addc_u32 s51, s51, 0
	s_add_i32 s52, s75, s56
	global_load_lds_dwordx4 v[216:217], off
	v_lshl_add_u64 v[216:217], s[50:51], 0, v[148:149]
	s_mov_b32 m0, s52
	v_lshl_add_u64 v[212:213], v[212:213], 0, s[20:21]
	global_load_lds_dwordx4 v[216:217], off
	v_lshl_add_u64 v[216:217], s[50:51], 0, v[152:153]
	s_add_i32 m0, s52, 0x2000
	s_nop 0
	global_load_lds_dwordx4 v[216:217], off
	s_mov_b32 m0, s63
	s_nop 0
	global_load_lds_dwordx4 v[212:213], off
	v_lshl_add_u64 v[212:213], v[214:215], 0, s[20:21]
	s_mov_b32 m0, s64
	s_nop 0
	global_load_lds_dwordx4 v[212:213], off
	s_waitcnt vmcnt(8)
	s_waitcnt lgkmcnt(0)
	s_barrier
	s_setprio 2
	s_waitcnt lgkmcnt(0)
	v_mfma_f32_16x16x32_bf16 v[62:65], v[130:133], v[180:183], v[62:65]
	v_mfma_f32_16x16x32_bf16 v[58:61], v[138:141], v[180:183], v[58:61]
	v_mfma_f32_16x16x32_bf16 v[54:57], v[130:133], v[188:191], v[54:57]
	v_mfma_f32_16x16x32_bf16 v[50:53], v[138:141], v[188:191], v[50:53]
	v_mfma_f32_16x16x32_bf16 v[46:49], v[130:133], v[196:199], v[46:49]
	v_mfma_f32_16x16x32_bf16 v[42:45], v[138:141], v[196:199], v[42:45]
	v_mfma_f32_16x16x32_bf16 v[38:41], v[130:133], v[204:207], v[38:41]
	v_mfma_f32_16x16x32_bf16 v[34:37], v[138:141], v[204:207], v[34:37]
	v_mfma_f32_16x16x32_bf16 v[62:65], v[134:137], v[184:187], v[62:65]
	v_mfma_f32_16x16x32_bf16 v[58:61], v[142:145], v[184:187], v[58:61]
	v_mfma_f32_16x16x32_bf16 v[54:57], v[134:137], v[192:195], v[54:57]
	v_mfma_f32_16x16x32_bf16 v[50:53], v[142:145], v[192:195], v[50:53]
	v_mfma_f32_16x16x32_bf16 v[46:49], v[134:137], v[200:203], v[46:49]
	v_mfma_f32_16x16x32_bf16 v[42:45], v[142:145], v[200:203], v[42:45]
	v_mfma_f32_16x16x32_bf16 v[38:41], v[134:137], v[208:211], v[38:41]
	v_mfma_f32_16x16x32_bf16 v[34:37], v[142:145], v[208:211], v[34:37]
	s_setprio 0
	s_setprio 2
	v_mfma_f32_16x16x32_bf16 v[30:33], v[164:167], v[180:183], v[30:33]
	v_mfma_f32_16x16x32_bf16 v[26:29], v[172:175], v[180:183], v[26:29]
	v_mfma_f32_16x16x32_bf16 v[22:25], v[164:167], v[188:191], v[22:25]
	v_mfma_f32_16x16x32_bf16 v[18:21], v[172:175], v[188:191], v[18:21]
	v_mfma_f32_16x16x32_bf16 v[14:17], v[164:167], v[196:199], v[14:17]
	v_mfma_f32_16x16x32_bf16 v[10:13], v[172:175], v[196:199], v[10:13]
	v_mfma_f32_16x16x32_bf16 v[6:9], v[164:167], v[204:207], v[6:9]
	v_mfma_f32_16x16x32_bf16 v[2:5], v[172:175], v[204:207], v[2:5]
	v_mfma_f32_16x16x32_bf16 v[30:33], v[168:171], v[184:187], v[30:33]
	v_mfma_f32_16x16x32_bf16 v[26:29], v[176:179], v[184:187], v[26:29]
	v_mfma_f32_16x16x32_bf16 v[22:25], v[168:171], v[192:195], v[22:25]
	v_mfma_f32_16x16x32_bf16 v[18:21], v[176:179], v[192:195], v[18:21]
	s_setprio 3
	s_barrier
	v_mfma_f32_16x16x32_bf16 v[14:17], v[168:171], v[200:203], v[14:17]
	v_mfma_f32_16x16x32_bf16 v[10:13], v[176:179], v[200:203], v[10:13]
	v_mfma_f32_16x16x32_bf16 v[6:9], v[168:171], v[208:211], v[6:9]
	v_mfma_f32_16x16x32_bf16 v[2:5], v[176:179], v[208:211], v[2:5]
	s_setprio 0
	s_add_i32 s73, s73, 2
	s_add_u32 s43, s43, 0x8000
	s_addc_u32 s45, s45, 0
	s_add_u32 s0, s0, 0x100
	s_addc_u32 s1, s1, 0
	s_cmp_gt_u32 s73, 13
	s_cbranch_scc0 .LBB0_1184
	s_and_b64 vcc, exec, s[24:25]
	s_cbranch_vccz .LBB0_1187
	s_barrier

.LBB0_1271:
	ds_read_b128 v[154:157], v151
	ds_read_b128 v[158:161], v151 offset:1024
	ds_read_b128 v[162:165], v151 offset:2048
	ds_read_b128 v[166:169], v151 offset:3072
	ds_read_b128 v[170:173], v152
	ds_read_b128 v[174:177], v152 offset:1024
	ds_read_b128 v[178:181], v152 offset:2048
	ds_read_b128 v[182:185], v152 offset:3072
	s_add_u32 s52, s0, 0xfff00080
	s_addc_u32 s53, s1, -1
	s_cmp_eq_u32 s73, 60
	s_cselect_b32 s55, s7, s53
	s_cselect_b32 s54, s6, s52
	s_cselect_b32 s53, s49, s47
	s_cselect_b32 s52, s48, s45
	v_lshl_add_u64 v[148:149], s[0:1], 0, v[138:139]
	s_add_i32 m0, s51, 0xc000
	ds_read_b128 v[186:189], v153
	ds_read_b128 v[190:193], v153 offset:1024
	ds_read_b128 v[194:197], v153 offset:2048
	ds_read_b128 v[198:201], v153 offset:3072
	ds_read_b128 v[202:205], v153 offset:4096
	ds_read_b128 v[206:209], v153 offset:5120
	ds_read_b128 v[210:213], v153 offset:6144
	ds_read_b128 v[214:217], v153 offset:7168
	global_load_lds_dwordx4 v[148:149], off
	v_lshl_add_u64 v[148:149], s[0:1], 0, v[140:141]
	s_add_i32 m0, s51, 0xe000
	s_nop 0
	global_load_lds_dwordx4 v[148:149], off
	s_waitcnt vmcnt(8)
	s_waitcnt lgkmcnt(0)
	s_barrier
	s_setprio 2
	s_waitcnt lgkmcnt(0)
	v_mfma_f32_16x16x32_bf16 v[126:129], v[154:157], v[186:189], v[126:129]
	v_mfma_f32_16x16x32_bf16 v[122:125], v[162:165], v[186:189], v[122:125]
	v_mfma_f32_16x16x32_bf16 v[118:121], v[154:157], v[194:197], v[118:121]
	v_mfma_f32_16x16x32_bf16 v[110:113], v[162:165], v[194:197], v[110:113]
	v_mfma_f32_16x16x32_bf16 v[102:105], v[154:157], v[202:205], v[102:105]
	v_mfma_f32_16x16x32_bf16 v[94:97], v[162:165], v[202:205], v[94:97]
	v_mfma_f32_16x16x32_bf16 v[86:89], v[154:157], v[210:213], v[86:89]
	v_mfma_f32_16x16x32_bf16 v[78:81], v[162:165], v[210:213], v[78:81]
	v_mfma_f32_16x16x32_bf16 v[126:129], v[158:161], v[190:193], v[126:129]
	v_mfma_f32_16x16x32_bf16 v[122:125], v[166:169], v[190:193], v[122:125]
	v_mfma_f32_16x16x32_bf16 v[118:121], v[158:161], v[198:201], v[118:121]
	v_mfma_f32_16x16x32_bf16 v[110:113], v[166:169], v[198:201], v[110:113]
	v_mfma_f32_16x16x32_bf16 v[102:105], v[158:161], v[206:209], v[102:105]
	v_mfma_f32_16x16x32_bf16 v[94:97], v[166:169], v[206:209], v[94:97]
	v_mfma_f32_16x16x32_bf16 v[86:89], v[158:161], v[214:217], v[86:89]
	v_mfma_f32_16x16x32_bf16 v[78:81], v[166:169], v[214:217], v[78:81]
	s_setprio 0
	s_setprio 2
	v_mfma_f32_16x16x32_bf16 v[114:117], v[170:173], v[186:189], v[114:117]
	v_mfma_f32_16x16x32_bf16 v[106:109], v[178:181], v[186:189], v[106:109]
	v_mfma_f32_16x16x32_bf16 v[98:101], v[170:173], v[194:197], v[98:101]
	v_mfma_f32_16x16x32_bf16 v[90:93], v[178:181], v[194:197], v[90:93]
	v_mfma_f32_16x16x32_bf16 v[82:85], v[170:173], v[202:205], v[82:85]
	v_mfma_f32_16x16x32_bf16 v[74:77], v[178:181], v[202:205], v[74:77]
	v_mfma_f32_16x16x32_bf16 v[70:73], v[170:173], v[210:213], v[70:73]
	v_mfma_f32_16x16x32_bf16 v[66:69], v[178:181], v[210:213], v[66:69]
	v_mfma_f32_16x16x32_bf16 v[114:117], v[174:177], v[190:193], v[114:117]
	v_mfma_f32_16x16x32_bf16 v[106:109], v[182:185], v[190:193], v[106:109]
	v_mfma_f32_16x16x32_bf16 v[98:101], v[174:177], v[198:201], v[98:101]
	v_mfma_f32_16x16x32_bf16 v[90:93], v[182:185], v[198:201], v[90:93]
	s_setprio 3
	s_barrier
	v_mfma_f32_16x16x32_bf16 v[82:85], v[174:177], v[206:209], v[82:85]
	v_mfma_f32_16x16x32_bf16 v[74:77], v[182:185], v[206:209], v[74:77]
	v_mfma_f32_16x16x32_bf16 v[70:73], v[174:177], v[214:217], v[70:73]
	v_mfma_f32_16x16x32_bf16 v[66:69], v[182:185], v[214:217], v[66:69]
	s_setprio 0
	s_add_i32 s74, s66, s58
	v_lshl_add_u64 v[148:149], s[52:53], 0, v[130:131]
	s_mov_b32 m0, s74
	ds_read_b128 v[186:189], v153 offset:16384
	ds_read_b128 v[190:193], v153 offset:17408
	ds_read_b128 v[194:197], v153 offset:18432
	ds_read_b128 v[198:201], v153 offset:19456
	ds_read_b128 v[202:205], v153 offset:20480
	ds_read_b128 v[206:209], v153 offset:21504
	ds_read_b128 v[210:213], v153 offset:22528
	ds_read_b128 v[214:217], v153 offset:23552
	global_load_lds_dwordx4 v[148:149], off
	s_add_i32 m0, s74, 0x2000
	s_add_u32 s74, s52, 0x100000
	v_lshl_add_u64 v[148:149], s[52:53], 0, v[134:135]
	s_addc_u32 s75, s53, 0
	s_add_i32 s76, s67, s58
	global_load_lds_dwordx4 v[148:149], off
	v_lshl_add_u64 v[148:149], s[74:75], 0, v[130:131]
	s_mov_b32 m0, s76
	v_lshl_add_u64 v[218:219], s[54:55], 0, v[136:137]
	global_load_lds_dwordx4 v[148:149], off
	v_lshl_add_u64 v[148:149], s[74:75], 0, v[134:135]
	s_add_i32 m0, s76, 0x2000
	s_nop 0
	global_load_lds_dwordx4 v[148:149], off
	v_lshl_add_u64 v[148:149], s[54:55], 0, v[132:133]
	s_mov_b32 m0, s51
	s_nop 0
	global_load_lds_dwordx4 v[148:149], off
	s_mov_b32 m0, s59
	s_nop 0
	global_load_lds_dwordx4 v[218:219], off
	s_waitcnt vmcnt(8)
	s_waitcnt lgkmcnt(0)
	s_barrier
	s_setprio 2
	s_waitcnt lgkmcnt(0)
	v_mfma_f32_16x16x32_bf16 v[62:65], v[154:157], v[186:189], v[62:65]
	v_mfma_f32_16x16x32_bf16 v[58:61], v[162:165], v[186:189], v[58:61]
	v_mfma_f32_16x16x32_bf16 v[54:57], v[154:157], v[194:197], v[54:57]
	v_mfma_f32_16x16x32_bf16 v[46:49], v[162:165], v[194:197], v[46:49]
	v_mfma_f32_16x16x32_bf16 v[38:41], v[154:157], v[202:205], v[38:41]
	v_mfma_f32_16x16x32_bf16 v[30:33], v[162:165], v[202:205], v[30:33]
	v_mfma_f32_16x16x32_bf16 v[22:25], v[154:157], v[210:213], v[22:25]
	v_mfma_f32_16x16x32_bf16 v[14:17], v[162:165], v[210:213], v[14:17]
	v_mfma_f32_16x16x32_bf16 v[62:65], v[158:161], v[190:193], v[62:65]
	v_mfma_f32_16x16x32_bf16 v[58:61], v[166:169], v[190:193], v[58:61]
	v_mfma_f32_16x16x32_bf16 v[54:57], v[158:161], v[198:201], v[54:57]
	v_mfma_f32_16x16x32_bf16 v[46:49], v[166:169], v[198:201], v[46:49]
	v_mfma_f32_16x16x32_bf16 v[38:41], v[158:161], v[206:209], v[38:41]
	v_mfma_f32_16x16x32_bf16 v[30:33], v[166:169], v[206:209], v[30:33]
	v_mfma_f32_16x16x32_bf16 v[22:25], v[158:161], v[214:217], v[22:25]
	v_mfma_f32_16x16x32_bf16 v[14:17], v[166:169], v[214:217], v[14:17]
	s_setprio 0
	s_setprio 2
	v_mfma_f32_16x16x32_bf16 v[50:53], v[170:173], v[186:189], v[50:53]
	v_mfma_f32_16x16x32_bf16 v[42:45], v[178:181], v[186:189], v[42:45]
	v_mfma_f32_16x16x32_bf16 v[34:37], v[170:173], v[194:197], v[34:37]
	v_mfma_f32_16x16x32_bf16 v[26:29], v[178:181], v[194:197], v[26:29]
	v_mfma_f32_16x16x32_bf16 v[18:21], v[170:173], v[202:205], v[18:21]
	v_mfma_f32_16x16x32_bf16 v[10:13], v[178:181], v[202:205], v[10:13]
	v_mfma_f32_16x16x32_bf16 v[6:9], v[170:173], v[210:213], v[6:9]
	v_mfma_f32_16x16x32_bf16 v[2:5], v[178:181], v[210:213], v[2:5]
	v_mfma_f32_16x16x32_bf16 v[50:53], v[174:177], v[190:193], v[50:53]
	v_mfma_f32_16x16x32_bf16 v[42:45], v[182:185], v[190:193], v[42:45]
	v_mfma_f32_16x16x32_bf16 v[34:37], v[174:177], v[198:201], v[34:37]
	v_mfma_f32_16x16x32_bf16 v[26:29], v[182:185], v[198:201], v[26:29]
	s_setprio 3
	s_barrier
	v_mfma_f32_16x16x32_bf16 v[18:21], v[174:177], v[206:209], v[18:21]
	v_mfma_f32_16x16x32_bf16 v[10:13], v[182:185], v[206:209], v[10:13]
	v_mfma_f32_16x16x32_bf16 v[6:9], v[174:177], v[214:217], v[6:9]
	v_mfma_f32_16x16x32_bf16 v[2:5], v[182:185], v[214:217], v[2:5]
	s_setprio 0
	s_add_i32 s74, 0, 0x18000
	s_add_i32 s75, 0, 0x1c000
	v_add_u32_e32 v166, s74, v147
	v_add_u32_e32 v182, s75, v147
	ds_read_b128 v[154:157], v166
	ds_read_b128 v[158:161], v166 offset:1024
	ds_read_b128 v[162:165], v166 offset:2048
	ds_read_b128 v[166:169], v166 offset:3072
	ds_read_b128 v[170:173], v182
	ds_read_b128 v[174:177], v182 offset:1024
	ds_read_b128 v[178:181], v182 offset:2048
	ds_read_b128 v[182:185], v182 offset:3072
	s_add_u32 s54, s54, 0x100000
	s_addc_u32 s55, s55, 0
	s_mov_b32 m0, s60
	v_lshl_add_u64 v[220:221], s[54:55], 0, v[132:133]
	ds_read_b128 v[186:189], v153 offset:32768
	ds_read_b128 v[190:193], v153 offset:33792
	ds_read_b128 v[194:197], v153 offset:34816
	ds_read_b128 v[198:201], v153 offset:35840
	ds_read_b128 v[202:205], v153 offset:36864
	ds_read_b128 v[206:209], v153 offset:37888
	ds_read_b128 v[210:213], v153 offset:38912
	ds_read_b128 v[214:217], v153 offset:39936
	global_load_lds_dwordx4 v[220:221], off
	v_lshl_add_u64 v[220:221], s[54:55], 0, v[136:137]
	s_mov_b32 m0, s61
	s_nop 0
	global_load_lds_dwordx4 v[220:221], off
	s_waitcnt vmcnt(8)
	s_waitcnt lgkmcnt(0)
	s_barrier
	s_setprio 2
	s_waitcnt lgkmcnt(0)
	v_mfma_f32_16x16x32_bf16 v[126:129], v[154:157], v[186:189], v[126:129]
	v_mfma_f32_16x16x32_bf16 v[122:125], v[162:165], v[186:189], v[122:125]
	v_mfma_f32_16x16x32_bf16 v[118:121], v[154:157], v[194:197], v[118:121]
	v_mfma_f32_16x16x32_bf16 v[110:113], v[162:165], v[194:197], v[110:113]
	v_mfma_f32_16x16x32_bf16 v[102:105], v[154:157], v[202:205], v[102:105]
	v_mfma_f32_16x16x32_bf16 v[94:97], v[162:165], v[202:205], v[94:97]
	v_mfma_f32_16x16x32_bf16 v[86:89], v[154:157], v[210:213], v[86:89]
	v_mfma_f32_16x16x32_bf16 v[78:81], v[162:165], v[210:213], v[78:81]
	v_mfma_f32_16x16x32_bf16 v[126:129], v[158:161], v[190:193], v[126:129]
	v_mfma_f32_16x16x32_bf16 v[122:125], v[166:169], v[190:193], v[122:125]
	v_mfma_f32_16x16x32_bf16 v[118:121], v[158:161], v[198:201], v[118:121]
	v_mfma_f32_16x16x32_bf16 v[110:113], v[166:169], v[198:201], v[110:113]
	v_mfma_f32_16x16x32_bf16 v[102:105], v[158:161], v[206:209], v[102:105]
	v_mfma_f32_16x16x32_bf16 v[94:97], v[166:169], v[206:209], v[94:97]
	v_mfma_f32_16x16x32_bf16 v[86:89], v[158:161], v[214:217], v[86:89]
	v_mfma_f32_16x16x32_bf16 v[78:81], v[166:169], v[214:217], v[78:81]
	s_setprio 0
	s_setprio 2
	v_mfma_f32_16x16x32_bf16 v[114:117], v[170:173], v[186:189], v[114:117]
	v_mfma_f32_16x16x32_bf16 v[106:109], v[178:181], v[186:189], v[106:109]
	v_mfma_f32_16x16x32_bf16 v[98:101], v[170:173], v[194:197], v[98:101]
	v_mfma_f32_16x16x32_bf16 v[90:93], v[178:181], v[194:197], v[90:93]
	v_mfma_f32_16x16x32_bf16 v[82:85], v[170:173], v[202:205], v[82:85]
	v_mfma_f32_16x16x32_bf16 v[74:77], v[178:181], v[202:205], v[74:77]
	v_mfma_f32_16x16x32_bf16 v[70:73], v[170:173], v[210:213], v[70:73]
	v_mfma_f32_16x16x32_bf16 v[66:69], v[178:181], v[210:213], v[66:69]
	v_mfma_f32_16x16x32_bf16 v[114:117], v[174:177], v[190:193], v[114:117]
	v_mfma_f32_16x16x32_bf16 v[106:109], v[182:185], v[190:193], v[106:109]
	v_mfma_f32_16x16x32_bf16 v[98:101], v[174:177], v[198:201], v[98:101]
	v_mfma_f32_16x16x32_bf16 v[90:93], v[182:185], v[198:201], v[90:93]
	s_setprio 3
	s_barrier
	v_mfma_f32_16x16x32_bf16 v[82:85], v[174:177], v[206:209], v[82:85]
	v_mfma_f32_16x16x32_bf16 v[74:77], v[182:185], v[206:209], v[74:77]
	v_mfma_f32_16x16x32_bf16 v[70:73], v[174:177], v[214:217], v[70:73]
	v_mfma_f32_16x16x32_bf16 v[66:69], v[182:185], v[214:217], v[66:69]
	s_setprio 0
	s_add_u32 s54, s52, 0x4000
	s_addc_u32 s55, s53, 0
	s_add_i32 s74, s74, s58
	v_lshl_add_u64 v[220:221], s[54:55], 0, v[130:131]
	s_mov_b32 m0, s74
	ds_read_b128 v[186:189], v153 offset:49152
	ds_read_b128 v[190:193], v153 offset:50176
	ds_read_b128 v[194:197], v153 offset:51200
	ds_read_b128 v[198:201], v153 offset:52224
	ds_read_b128 v[202:205], v153 offset:53248
	ds_read_b128 v[206:209], v153 offset:54272
	ds_read_b128 v[210:213], v153 offset:55296
	ds_read_b128 v[214:217], v153 offset:56320
	global_load_lds_dwordx4 v[220:221], off
	s_add_i32 m0, s74, 0x2000
	s_add_u32 s52, s52, 0x104000
	v_lshl_add_u64 v[220:221], s[54:55], 0, v[134:135]
	s_addc_u32 s53, s53, 0
	s_add_i32 s54, s75, s58
	global_load_lds_dwordx4 v[220:221], off
	v_lshl_add_u64 v[220:221], s[52:53], 0, v[130:131]
	s_mov_b32 m0, s54
	v_lshl_add_u64 v[148:149], v[148:149], 0, s[18:19]
	global_load_lds_dwordx4 v[220:221], off
	v_lshl_add_u64 v[220:221], s[52:53], 0, v[134:135]
	s_add_i32 m0, s54, 0x2000
	s_nop 0
	global_load_lds_dwordx4 v[220:221], off
	s_mov_b32 m0, s63
	s_nop 0
	global_load_lds_dwordx4 v[148:149], off
	v_lshl_add_u64 v[148:149], v[218:219], 0, s[18:19]
	s_mov_b32 m0, s64
	s_nop 0
	global_load_lds_dwordx4 v[148:149], off
	s_waitcnt vmcnt(8)
	s_waitcnt lgkmcnt(0)
	s_barrier
	s_setprio 2
	s_waitcnt lgkmcnt(0)
	v_mfma_f32_16x16x32_bf16 v[62:65], v[154:157], v[186:189], v[62:65]
	v_mfma_f32_16x16x32_bf16 v[58:61], v[162:165], v[186:189], v[58:61]
	v_mfma_f32_16x16x32_bf16 v[54:57], v[154:157], v[194:197], v[54:57]
	v_mfma_f32_16x16x32_bf16 v[46:49], v[162:165], v[194:197], v[46:49]
	v_mfma_f32_16x16x32_bf16 v[38:41], v[154:157], v[202:205], v[38:41]
	v_mfma_f32_16x16x32_bf16 v[30:33], v[162:165], v[202:205], v[30:33]
	v_mfma_f32_16x16x32_bf16 v[22:25], v[154:157], v[210:213], v[22:25]
	v_mfma_f32_16x16x32_bf16 v[14:17], v[162:165], v[210:213], v[14:17]
	v_mfma_f32_16x16x32_bf16 v[62:65], v[158:161], v[190:193], v[62:65]
	v_mfma_f32_16x16x32_bf16 v[58:61], v[166:169], v[190:193], v[58:61]
	v_mfma_f32_16x16x32_bf16 v[54:57], v[158:161], v[198:201], v[54:57]
	v_mfma_f32_16x16x32_bf16 v[46:49], v[166:169], v[198:201], v[46:49]
	v_mfma_f32_16x16x32_bf16 v[38:41], v[158:161], v[206:209], v[38:41]
	v_mfma_f32_16x16x32_bf16 v[30:33], v[166:169], v[206:209], v[30:33]
	v_mfma_f32_16x16x32_bf16 v[22:25], v[158:161], v[214:217], v[22:25]
	v_mfma_f32_16x16x32_bf16 v[14:17], v[166:169], v[214:217], v[14:17]
	s_setprio 0
	s_setprio 2
	v_mfma_f32_16x16x32_bf16 v[50:53], v[170:173], v[186:189], v[50:53]
	v_mfma_f32_16x16x32_bf16 v[42:45], v[178:181], v[186:189], v[42:45]
	v_mfma_f32_16x16x32_bf16 v[34:37], v[170:173], v[194:197], v[34:37]
	v_mfma_f32_16x16x32_bf16 v[26:29], v[178:181], v[194:197], v[26:29]
	v_mfma_f32_16x16x32_bf16 v[18:21], v[170:173], v[202:205], v[18:21]
	v_mfma_f32_16x16x32_bf16 v[10:13], v[178:181], v[202:205], v[10:13]
	v_mfma_f32_16x16x32_bf16 v[6:9], v[170:173], v[210:213], v[6:9]
	v_mfma_f32_16x16x32_bf16 v[2:5], v[178:181], v[210:213], v[2:5]
	v_mfma_f32_16x16x32_bf16 v[50:53], v[174:177], v[190:193], v[50:53]
	v_mfma_f32_16x16x32_bf16 v[42:45], v[182:185], v[190:193], v[42:45]
	v_mfma_f32_16x16x32_bf16 v[34:37], v[174:177], v[198:201], v[34:37]
	v_mfma_f32_16x16x32_bf16 v[26:29], v[182:185], v[198:201], v[26:29]
	s_setprio 3
	s_barrier
	v_mfma_f32_16x16x32_bf16 v[18:21], v[174:177], v[206:209], v[18:21]
	v_mfma_f32_16x16x32_bf16 v[10:13], v[182:185], v[206:209], v[10:13]
	v_mfma_f32_16x16x32_bf16 v[6:9], v[174:177], v[214:217], v[6:9]
	v_mfma_f32_16x16x32_bf16 v[2:5], v[182:185], v[214:217], v[2:5]
	s_setprio 0
	s_add_i32 s73, s73, 2
	s_add_u32 s45, s45, 0x8000
	s_addc_u32 s47, s47, 0
	s_add_u32 s0, s0, 0x100
	s_addc_u32 s1, s1, 0
	s_cmp_gt_u32 s73, 61
	s_cbranch_scc0 .LBB0_1271
	s_and_b64 vcc, exec, s[20:21]
	s_cbranch_vccz .LBB0_1274
	s_barrier

.LBB0_1339:
	s_cmp_ge_i32 s3, s42
	s_cselect_b64 s[38:39], -1, 0
	s_cmp_lt_i32 s3, s42
	s_cselect_b64 s[0:1], -1, 0
	s_or_b64 vcc, s[16:17], s[0:1]
	v_cndmask_b32_e32 v37, 0, v37, vcc
	s_nor_b64 s[8:9], s[4:5], vcc
	s_and_saveexec_b64 s[0:1], s[8:9]
	s_cbranch_execz .LBB0_1343
	s_mov_b64 s[40:41], exec
	v_mbcnt_lo_u32_b32 v12, s40, 0
	v_mbcnt_hi_u32_b32 v12, s41, v12
	v_cmp_eq_u32_e32 vcc, 0, v12
	s_and_saveexec_b64 s[8:9], vcc
	s_cbranch_execz .LBB0_1342
	s_bcnt1_i32_b64 s25, s[40:41]
	v_mov_b32_e32 v13, s25
	global_atomic_add v223, v3, v13, s[20:21] sc0

.LBB0_1343:
	s_or_b64 exec, exec, s[0:1]
	s_ashr_i32 s25, s24, 31
	s_lshl_b64 s[0:1], s[24:25], 13
	v_lshl_add_u64 v[12:13], v[6:7], 0, s[0:1]
	global_load_dwordx2 v[38:39], v[12:13], off
	global_load_dwordx2 v[40:41], v[12:13], off offset:512
	global_load_dwordx2 v[42:43], v[12:13], off offset:1024
	global_load_dwordx2 v[44:45], v[12:13], off offset:1536
	global_load_dwordx2 v[46:47], v[12:13], off offset:2048
	global_load_dwordx2 v[68:69], v[12:13], off offset:2560
	global_load_dwordx2 v[70:71], v[12:13], off offset:3072
	v_lshl_add_u64 v[14:15], v[4:5], 0, s[0:1]
	global_load_dwordx2 v[22:23], v[12:13], off offset:3584
	global_load_dwordx2 v[72:73], v[14:15], off
	global_load_dwordx2 v[74:75], v[14:15], off offset:512
	global_load_dwordx2 v[76:77], v[14:15], off offset:1024
	global_load_dwordx2 v[78:79], v[14:15], off offset:1536
	global_load_dwordx2 v[80:81], v[14:15], off offset:2048
	global_load_dwordx2 v[82:83], v[14:15], off offset:2560
	global_load_dwordx2 v[84:85], v[14:15], off offset:3072
	global_load_dwordx2 v[86:87], v[14:15], off offset:3584
	v_add_co_u32_e64 v12, s[8:9], s45, v12
	v_add_co_u32_e32 v48, vcc, 0x1000, v14
	s_nop 0
	v_addc_co_u32_e64 v13, s[8:9], 0, v13, s[8:9]
	v_addc_co_u32_e32 v49, vcc, 0, v15, vcc
	global_load_dwordx2 v[28:29], v[12:13], off
	global_load_dwordx2 v[26:27], v[12:13], off offset:512
	global_load_dwordx2 v[24:25], v[12:13], off offset:1024
	global_load_dwordx2 v[20:21], v[12:13], off offset:1536
	global_load_dwordx2 v[18:19], v[12:13], off offset:2048
	global_load_dwordx2 v[16:17], v[12:13], off offset:2560
	global_load_dwordx2 v[14:15], v[12:13], off offset:3072
	s_nop 0
	global_load_dwordx2 v[12:13], v[12:13], off offset:3584
	s_nop 0
	global_load_dwordx2 v[88:89], v[48:49], off
	global_load_dwordx2 v[90:91], v[48:49], off offset:512
	global_load_dwordx2 v[92:93], v[48:49], off offset:1024
	global_load_dwordx2 v[94:95], v[48:49], off offset:1536
	global_load_dwordx2 v[96:97], v[48:49], off offset:2048
	global_load_dwordx2 v[98:99], v[48:49], off offset:2560
	global_load_dwordx2 v[100:101], v[48:49], off offset:3072
	global_load_dwordx2 v[102:103], v[48:49], off offset:3584
	s_waitcnt vmcnt(31)
	v_readfirstlane_b32 s98, v223
	s_nop 1
	v_mov_b32_e32 v37, s98
	v_lshlrev_b32_e32 v66, 16, v38
	s_waitcnt vmcnt(23)
	v_and_b32_e32 v105, 0xffff0000, v72
	v_and_b32_e32 v107, 0xffff0000, v73
	v_lshlrev_b32_e32 v52, 16, v45
	v_and_b32_e32 v51, 0xffff0000, v45
	v_lshlrev_b32_e32 v48, 16, v46
	v_and_b32_e32 v49, 0xffff0000, v46
	v_lshlrev_b32_e32 v46, 16, v68
	v_and_b32_e32 v45, 0xffff0000, v68
	v_lshlrev_b32_e32 v104, 16, v72
	v_lshlrev_b32_e32 v106, 16, v73
	v_mul_f32_e32 v67, v105, v105
	v_mul_f32_e32 v68, v107, v107
	s_waitcnt vmcnt(22)
	v_and_b32_e32 v109, 0xffff0000, v74
	v_and_b32_e32 v111, 0xffff0000, v75
	v_fmac_f32_e32 v67, v104, v104
	v_fmac_f32_e32 v68, v106, v106
	v_lshlrev_b32_e32 v56, 16, v43
	v_and_b32_e32 v55, 0xffff0000, v43
	v_lshlrev_b32_e32 v54, 16, v44
	v_and_b32_e32 v53, 0xffff0000, v44
	v_lshlrev_b32_e32 v44, 16, v69
	v_and_b32_e32 v43, 0xffff0000, v69
	v_lshlrev_b32_e32 v108, 16, v74
	v_lshlrev_b32_e32 v110, 16, v75
	v_add_f32_e32 v67, v67, v68
	v_mul_f32_e32 v68, v109, v109
	v_mul_f32_e32 v69, v111, v111
	v_fmac_f32_e32 v68, v108, v108
	v_fmac_f32_e32 v69, v110, v110
	v_add_f32_e32 v68, v68, v69
	s_waitcnt vmcnt(21)
	v_and_b32_e32 v113, 0xffff0000, v76
	v_and_b32_e32 v115, 0xffff0000, v77
	v_add_f32_e32 v67, v67, v68
	v_lshlrev_b32_e32 v112, 16, v76
	v_lshlrev_b32_e32 v114, 16, v77
	v_mul_f32_e32 v68, v113, v113
	v_mul_f32_e32 v69, v115, v115
	v_fmac_f32_e32 v68, v112, v112
	v_fmac_f32_e32 v69, v114, v114
	v_add_f32_e32 v68, v68, v69
	s_waitcnt vmcnt(20)
	v_and_b32_e32 v117, 0xffff0000, v78
	v_and_b32_e32 v119, 0xffff0000, v79
	v_add_f32_e32 v67, v67, v68
	v_lshlrev_b32_e32 v116, 16, v78
	v_lshlrev_b32_e32 v118, 16, v79
	v_mul_f32_e32 v68, v117, v117
	v_mul_f32_e32 v69, v119, v119
	v_fmac_f32_e32 v68, v116, v116
	v_fmac_f32_e32 v69, v118, v118
	v_add_f32_e32 v68, v68, v69
	s_waitcnt vmcnt(19)
	v_and_b32_e32 v121, 0xffff0000, v80
	v_and_b32_e32 v123, 0xffff0000, v81
	v_add_f32_e32 v67, v67, v68
	v_lshlrev_b32_e32 v120, 16, v80
	v_lshlrev_b32_e32 v122, 16, v81
	v_mul_f32_e32 v68, v121, v121
	v_mul_f32_e32 v69, v123, v123
	v_fmac_f32_e32 v68, v120, v120
	v_fmac_f32_e32 v69, v122, v122
	v_add_f32_e32 v68, v68, v69
	s_waitcnt vmcnt(18)
	v_and_b32_e32 v125, 0xffff0000, v82
	v_and_b32_e32 v127, 0xffff0000, v83
	v_add_f32_e32 v67, v67, v68
	v_lshlrev_b32_e32 v124, 16, v82
	v_lshlrev_b32_e32 v126, 16, v83
	v_mul_f32_e32 v68, v125, v125
	v_mul_f32_e32 v69, v127, v127
	v_fmac_f32_e32 v68, v124, v124
	v_fmac_f32_e32 v69, v126, v126
	v_add_f32_e32 v68, v68, v69
	s_waitcnt vmcnt(17)
	v_and_b32_e32 v129, 0xffff0000, v84
	v_and_b32_e32 v131, 0xffff0000, v85
	v_add_f32_e32 v67, v67, v68
	v_lshlrev_b32_e32 v128, 16, v84
	v_lshlrev_b32_e32 v130, 16, v85
	v_mul_f32_e32 v68, v129, v129
	v_mul_f32_e32 v69, v131, v131
	v_fmac_f32_e32 v68, v128, v128
	v_fmac_f32_e32 v69, v130, v130
	v_add_f32_e32 v68, v68, v69
	s_waitcnt vmcnt(16)
	v_and_b32_e32 v133, 0xffff0000, v86
	v_and_b32_e32 v135, 0xffff0000, v87
	v_add_f32_e32 v67, v67, v68
	v_lshlrev_b32_e32 v132, 16, v86
	v_lshlrev_b32_e32 v134, 16, v87
	v_mul_f32_e32 v68, v133, v133
	v_mul_f32_e32 v69, v135, v135
	v_fmac_f32_e32 v68, v132, v132
	v_fmac_f32_e32 v69, v134, v134
	v_add_f32_e32 v68, v68, v69
	s_waitcnt vmcnt(7)
	v_and_b32_e32 v137, 0xffff0000, v88
	v_and_b32_e32 v139, 0xffff0000, v89
	v_add_f32_e32 v67, v67, v68
	v_lshlrev_b32_e32 v136, 16, v88
	v_lshlrev_b32_e32 v138, 16, v89
	v_mul_f32_e32 v68, v137, v137
	v_mul_f32_e32 v69, v139, v139
	v_fmac_f32_e32 v68, v136, v136
	v_fmac_f32_e32 v69, v138, v138
	v_add_f32_e32 v68, v68, v69
	s_waitcnt vmcnt(6)
	v_and_b32_e32 v141, 0xffff0000, v90
	v_and_b32_e32 v143, 0xffff0000, v91
	v_add_f32_e32 v67, v67, v68
	v_lshlrev_b32_e32 v140, 16, v90
	v_lshlrev_b32_e32 v142, 16, v91
	v_mul_f32_e32 v68, v141, v141
	v_mul_f32_e32 v69, v143, v143
	v_fmac_f32_e32 v68, v140, v140
	v_fmac_f32_e32 v69, v142, v142
	v_add_f32_e32 v68, v68, v69
	s_waitcnt vmcnt(5)
	v_lshlrev_b32_e32 v144, 16, v92
	v_and_b32_e32 v92, 0xffff0000, v92
	v_lshlrev_b32_e32 v145, 16, v93
	v_and_b32_e32 v93, 0xffff0000, v93
	v_add_f32_e32 v67, v67, v68
	v_mul_f32_e32 v68, v92, v92
	v_mul_f32_e32 v69, v93, v93
	v_fmac_f32_e32 v68, v144, v144
	v_fmac_f32_e32 v69, v145, v145
	v_add_f32_e32 v68, v68, v69
	s_waitcnt vmcnt(4)
	v_lshlrev_b32_e32 v147, 16, v94
	v_and_b32_e32 v94, 0xffff0000, v94
	v_lshlrev_b32_e32 v148, 16, v95
	v_and_b32_e32 v95, 0xffff0000, v95
	v_add_f32_e32 v67, v67, v68
	v_mul_f32_e32 v68, v94, v94
	v_mul_f32_e32 v69, v95, v95
	v_fmac_f32_e32 v68, v147, v147
	v_fmac_f32_e32 v69, v148, v148
	v_add_f32_e32 v68, v68, v69
	s_waitcnt vmcnt(3)
	v_lshlrev_b32_e32 v149, 16, v96
	v_and_b32_e32 v96, 0xffff0000, v96
	v_lshlrev_b32_e32 v150, 16, v97
	v_and_b32_e32 v97, 0xffff0000, v97
	v_add_f32_e32 v67, v67, v68
	v_mul_f32_e32 v68, v96, v96
	v_mul_f32_e32 v69, v97, v97
	v_fmac_f32_e32 v68, v149, v149
	v_fmac_f32_e32 v69, v150, v150
	v_add_f32_e32 v68, v68, v69
	s_waitcnt vmcnt(2)
	v_lshlrev_b32_e32 v151, 16, v98
	v_and_b32_e32 v98, 0xffff0000, v98
	v_lshlrev_b32_e32 v152, 16, v99
	v_and_b32_e32 v99, 0xffff0000, v99
	v_add_f32_e32 v67, v67, v68
	v_mul_f32_e32 v68, v98, v98
	v_mul_f32_e32 v69, v99, v99
	v_fmac_f32_e32 v68, v151, v151
	v_fmac_f32_e32 v69, v152, v152
	v_add_f32_e32 v68, v68, v69
	s_waitcnt vmcnt(1)
	v_lshlrev_b32_e32 v153, 16, v100
	v_and_b32_e32 v100, 0xffff0000, v100
	v_lshlrev_b32_e32 v154, 16, v101
	v_and_b32_e32 v101, 0xffff0000, v101
	v_add_f32_e32 v67, v67, v68
	v_mul_f32_e32 v68, v100, v100
	v_mul_f32_e32 v69, v101, v101
	v_fmac_f32_e32 v68, v153, v153
	v_fmac_f32_e32 v69, v154, v154
	v_add_f32_e32 v68, v68, v69
	s_waitcnt vmcnt(0)
	v_lshlrev_b32_e32 v155, 16, v102
	v_and_b32_e32 v102, 0xffff0000, v102
	v_lshlrev_b32_e32 v156, 16, v103
	v_and_b32_e32 v103, 0xffff0000, v103
	v_add_f32_e32 v67, v67, v68
	v_mul_f32_e32 v68, v102, v102
	v_mul_f32_e32 v69, v103, v103
	v_fmac_f32_e32 v68, v155, v155
	v_fmac_f32_e32 v69, v156, v156
	v_add_f32_e32 v68, v68, v69
	v_add_f32_e32 v67, v67, v68
	ds_bpermute_b32 v68, v1, v67
	v_and_b32_e32 v65, 0xffff0000, v38
	v_lshlrev_b32_e32 v38, 16, v22
	v_and_b32_e32 v81, 0xffff0000, v22
	v_lshlrev_b32_e32 v80, 16, v23
	s_waitcnt lgkmcnt(0)
	v_add_f32_e32 v22, v67, v68
	v_and_b32_e32 v79, 0xffff0000, v23
	ds_bpermute_b32 v23, v30, v22
	v_lshlrev_b32_e32 v73, 16, v28
	v_and_b32_e32 v77, 0xffff0000, v28
	v_lshlrev_b32_e32 v74, 16, v26
	v_and_b32_e32 v76, 0xffff0000, v26
	s_waitcnt lgkmcnt(0)
	v_add_f32_e32 v22, v22, v23
	ds_bpermute_b32 v23, v31, v22
	v_lshlrev_b32_e32 v28, 16, v21
	v_and_b32_e32 v26, 0xffff0000, v21
	v_lshlrev_b32_e32 v60, 16, v41
	v_and_b32_e32 v59, 0xffff0000, v41
	s_waitcnt lgkmcnt(0)
	v_add_f32_e32 v22, v22, v23
	ds_bpermute_b32 v23, v32, v22
	v_lshlrev_b32_e32 v58, 16, v42
	v_and_b32_e32 v57, 0xffff0000, v42
	v_lshlrev_b32_e32 v42, 16, v70
	v_and_b32_e32 v41, 0xffff0000, v70
	s_waitcnt lgkmcnt(0)
	v_add_f32_e32 v22, v22, v23
	ds_bpermute_b32 v23, v33, v22
	v_lshlrev_b32_e32 v68, 16, v24
	v_and_b32_e32 v70, 0xffff0000, v24
	v_lshlrev_b32_e32 v64, 16, v39
	v_and_b32_e32 v63, 0xffff0000, v39
	s_waitcnt lgkmcnt(0)
	v_add_f32_e32 v21, v22, v23
	ds_bpermute_b32 v24, v34, v21
	v_lshlrev_b32_e32 v62, 16, v40
	v_and_b32_e32 v61, 0xffff0000, v40
	v_lshlrev_b32_e32 v40, 16, v71
	v_and_b32_e32 v39, 0xffff0000, v71
	s_waitcnt lgkmcnt(0)
	v_add_f32_e32 v21, v21, v24
	v_fmamk_f32 v21, v21, 0x39800000, v2
	v_mul_f32_e32 v24, 0x4f800000, v21
	v_cmp_gt_f32_e32 vcc, s46, v21
	v_lshlrev_b32_e32 v78, 16, v29
	v_and_b32_e32 v75, 0xffff0000, v29
	v_cndmask_b32_e32 v24, v21, v24, vcc
	v_sqrt_f32_e32 v82, v24
	v_lshlrev_b32_e32 v72, 16, v27
	v_and_b32_e32 v71, 0xffff0000, v27
	v_lshlrev_b32_e32 v69, 16, v25
	v_and_b32_e32 v29, 0xffff0000, v25
	v_lshlrev_b32_e32 v27, 16, v20
	v_and_b32_e32 v67, 0xffff0000, v20
	v_lshlrev_b32_e32 v20, 16, v18
	v_and_b32_e32 v22, 0xffff0000, v18
	v_lshlrev_b32_e32 v18, 16, v16
	v_and_b32_e32 v25, 0xffff0000, v16
	v_lshlrev_b32_e32 v21, 16, v17
	v_and_b32_e32 v16, 0xffff0000, v17
	v_add_u32_e32 v17, -1, v82
	v_fma_f32 v83, -v17, v82, v24
	v_cmp_ge_f32_e64 s[8:9], 0, v83
	v_add_u32_e32 v83, 1, v82
	v_lshlrev_b32_e32 v50, 16, v47
	v_cndmask_b32_e64 v17, v82, v17, s[8:9]
	v_fma_f32 v82, -v83, v82, v24
	v_cmp_lt_f32_e64 s[8:9], 0, v82
	v_and_b32_e32 v47, 0xffff0000, v47
	v_lshlrev_b32_e32 v23, 16, v19
	v_cndmask_b32_e64 v17, v17, v83, s[8:9]
	v_mul_f32_e32 v82, 0x37800000, v17
	v_cndmask_b32_e32 v17, v17, v82, vcc
	v_cmp_class_f32_e32 vcc, v24, v36
	v_and_b32_e32 v19, 0xffff0000, v19
	s_nop 0
	v_cndmask_b32_e32 v86, v17, v24, vcc
	v_div_scale_f32 v82, s[8:9], v86, v86, 1.0
	v_rcp_f32_e32 v87, v82
	v_lshlrev_b32_e32 v24, 16, v14
	v_and_b32_e32 v17, 0xffff0000, v14
	v_lshlrev_b32_e32 v14, 16, v15
	v_fma_f32 v83, -v82, v87, 1.0
	v_fmac_f32_e32 v87, v83, v87
	v_div_scale_f32 v83, vcc, 1.0, v86, 1.0
	v_mul_f32_e32 v88, v83, v87
	v_fma_f32 v84, -v82, v88, v83
	v_fmac_f32_e32 v88, v84, v87
	v_fma_f32 v89, -v82, v88, v83
	ds_read_b128 v[82:85], v35
	v_div_fmas_f32 v87, v89, v87, v88
	v_div_fixup_f32 v157, v87, v86, 1.0
	v_mul_f32_e32 v86, v157, v104
	v_lshl_add_u64 v[88:89], v[8:9], 0, s[0:1]
	s_waitcnt lgkmcnt(0)
	v_fmac_f32_e32 v66, v82, v86
	v_mul_f32_e32 v82, v157, v105
	v_fmac_f32_e32 v65, v83, v82
	v_mul_f32_e32 v82, v157, v106
	v_fmac_f32_e32 v64, v84, v82
	v_mul_f32_e32 v82, v157, v107
	v_fmac_f32_e32 v63, v85, v82
	v_cvt_pk_bf16_f32 v86, v66, v65
	v_cvt_pk_bf16_f32 v87, v64, v63
	ds_read_b128 v[82:85], v35 offset:1024
	global_store_dwordx2 v[88:89], v[86:87], off
	v_mul_f32_e32 v86, v157, v108
	v_and_b32_e32 v15, 0xffff0000, v15
	s_waitcnt lgkmcnt(0)
	v_fmac_f32_e32 v62, v82, v86
	v_mul_f32_e32 v82, v157, v109
	v_fmac_f32_e32 v61, v83, v82
	v_mul_f32_e32 v82, v157, v110
	v_fmac_f32_e32 v60, v84, v82
	v_mul_f32_e32 v82, v157, v111
	v_fmac_f32_e32 v59, v85, v82
	v_cvt_pk_bf16_f32 v90, v62, v61
	v_cvt_pk_bf16_f32 v91, v60, v59
	ds_read_b128 v[84:87], v35 offset:2048
	v_mul_f32_e32 v83, v157, v112
	global_store_dwordx2 v[88:89], v[90:91], off offset:512
	v_lshlrev_b32_e32 v82, 16, v12
	v_and_b32_e32 v12, 0xffff0000, v12
	s_waitcnt lgkmcnt(0)
	v_fmac_f32_e32 v58, v83, v84
	v_mul_f32_e32 v83, v157, v113
	v_fmac_f32_e32 v57, v83, v85
	v_mul_f32_e32 v83, v157, v114
	v_fmac_f32_e32 v56, v83, v86
	v_mul_f32_e32 v83, v157, v115
	v_fmac_f32_e32 v55, v83, v87
	v_cvt_pk_bf16_f32 v90, v58, v57
	v_cvt_pk_bf16_f32 v91, v56, v55
	ds_read_b128 v[84:87], v35 offset:3072
	global_store_dwordx2 v[88:89], v[90:91], off offset:1024
	v_mul_f32_e32 v90, v157, v116
	v_lshlrev_b32_e32 v83, 16, v13
	v_and_b32_e32 v13, 0xffff0000, v13
	s_waitcnt lgkmcnt(0)
	v_fmac_f32_e32 v54, v90, v84
	v_mul_f32_e32 v84, v157, v117
	v_fmac_f32_e32 v53, v84, v85
	v_mul_f32_e32 v84, v157, v118
	v_fmac_f32_e32 v52, v84, v86
	v_mul_f32_e32 v84, v157, v119
	v_fmac_f32_e32 v51, v84, v87
	v_cvt_pk_bf16_f32 v84, v54, v53
	v_cvt_pk_bf16_f32 v85, v52, v51
	global_store_dwordx2 v[88:89], v[84:85], off offset:1536
	ds_read_b128 v[84:87], v35 offset:4096
	v_mul_f32_e32 v90, v157, v120
	v_mul_f32_e32 v91, v157, v121
	v_mul_f32_e32 v104, v157, v122
	s_waitcnt lgkmcnt(0)
	v_fmac_f32_e32 v48, v90, v84
	v_mul_f32_e32 v84, v157, v123
	v_fmac_f32_e32 v49, v91, v85
	v_fmac_f32_e32 v50, v104, v86
	v_fmac_f32_e32 v47, v84, v87
	v_cvt_pk_bf16_f32 v90, v48, v49
	v_cvt_pk_bf16_f32 v91, v50, v47
	ds_read_b128 v[84:87], v35 offset:5120
	global_store_dwordx2 v[88:89], v[90:91], off offset:2048
	v_mul_f32_e32 v90, v157, v124
	s_waitcnt lgkmcnt(0)
	v_fmac_f32_e32 v46, v90, v84
	v_mul_f32_e32 v84, v157, v125
	v_fmac_f32_e32 v45, v84, v85
	v_mul_f32_e32 v84, v157, v126
	v_fmac_f32_e32 v44, v84, v86
	v_mul_f32_e32 v84, v157, v127
	v_fmac_f32_e32 v43, v84, v87
	v_cvt_pk_bf16_f32 v90, v46, v45
	v_cvt_pk_bf16_f32 v91, v44, v43
	ds_read_b128 v[84:87], v35 offset:6144
	global_store_dwordx2 v[88:89], v[90:91], off offset:2560
	v_mul_f32_e32 v90, v157, v128
	s_waitcnt lgkmcnt(0)
	v_fmac_f32_e32 v42, v90, v84
	v_mul_f32_e32 v84, v157, v129
	v_fmac_f32_e32 v41, v84, v85
	v_mul_f32_e32 v84, v157, v130
	v_fmac_f32_e32 v40, v84, v86
	v_mul_f32_e32 v84, v157, v131
	v_fmac_f32_e32 v39, v84, v87
	v_cvt_pk_bf16_f32 v90, v42, v41
	v_cvt_pk_bf16_f32 v91, v40, v39
	ds_read_b128 v[84:87], v35 offset:7168
	global_store_dwordx2 v[88:89], v[90:91], off offset:3072
	v_mul_f32_e32 v90, v157, v132
	s_waitcnt lgkmcnt(0)
	v_fmac_f32_e32 v38, v90, v84
	v_mul_f32_e32 v84, v157, v133
	v_fmac_f32_e32 v81, v84, v85
	v_mul_f32_e32 v84, v157, v134
	v_fmac_f32_e32 v80, v84, v86
	v_mul_f32_e32 v84, v157, v135
	v_fmac_f32_e32 v79, v84, v87
	v_cvt_pk_bf16_f32 v84, v38, v81
	v_cvt_pk_bf16_f32 v85, v80, v79
	global_store_dwordx2 v[88:89], v[84:85], off offset:3584
	ds_read_b128 v[84:87], v35 offset:8192
	v_mul_f32_e32 v90, v157, v136
	v_mul_f32_e32 v91, v157, v137
	v_mul_f32_e32 v104, v157, v138
	v_add_co_u32_e32 v88, vcc, s45, v88
	s_waitcnt lgkmcnt(0)
	v_fmac_f32_e32 v73, v90, v84
	v_mul_f32_e32 v84, v157, v139
	v_fmac_f32_e32 v77, v91, v85
	v_fmac_f32_e32 v78, v104, v86
	v_fmac_f32_e32 v75, v84, v87
	v_cvt_pk_bf16_f32 v90, v73, v77
	v_cvt_pk_bf16_f32 v91, v78, v75
	ds_read_b128 v[84:87], v35 offset:9216
	v_addc_co_u32_e32 v89, vcc, 0, v89, vcc
	global_store_dwordx2 v[88:89], v[90:91], off
	v_mul_f32_e32 v90, v157, v140
	s_waitcnt lgkmcnt(0)
	v_fmac_f32_e32 v74, v90, v84
	v_mul_f32_e32 v84, v157, v141
	v_fmac_f32_e32 v76, v84, v85
	v_mul_f32_e32 v84, v157, v142
	v_fmac_f32_e32 v72, v84, v86
	v_mul_f32_e32 v84, v157, v143
	v_fmac_f32_e32 v71, v84, v87
	v_cvt_pk_bf16_f32 v90, v74, v76
	v_cvt_pk_bf16_f32 v91, v72, v71
	ds_read_b128 v[84:87], v35 offset:10240
	global_store_dwordx2 v[88:89], v[90:91], off offset:512
	v_mul_f32_e32 v90, v157, v144
	s_waitcnt lgkmcnt(0)
	v_fmac_f32_e32 v68, v90, v84
	v_mul_f32_e32 v84, v157, v92
	v_fmac_f32_e32 v70, v84, v85
	v_mul_f32_e32 v84, v157, v145
	v_fmac_f32_e32 v69, v84, v86
	v_mul_f32_e32 v84, v157, v93
	v_fmac_f32_e32 v29, v84, v87
	v_cvt_pk_bf16_f32 v90, v68, v70
	v_cvt_pk_bf16_f32 v91, v69, v29
	ds_read_b128 v[84:87], v35 offset:11264
	global_store_dwordx2 v[88:89], v[90:91], off offset:1024
	v_mul_f32_e32 v90, v157, v147
	s_waitcnt lgkmcnt(0)
	v_fmac_f32_e32 v27, v90, v84
	v_mul_f32_e32 v84, v157, v94
	v_fmac_f32_e32 v67, v84, v85
	v_mul_f32_e32 v84, v157, v148
	v_fmac_f32_e32 v28, v84, v86
	v_mul_f32_e32 v84, v157, v95
	v_fmac_f32_e32 v26, v84, v87
	v_cvt_pk_bf16_f32 v84, v27, v67
	v_cvt_pk_bf16_f32 v85, v28, v26
	global_store_dwordx2 v[88:89], v[84:85], off offset:1536
	ds_read_b128 v[84:87], v35 offset:12288
	v_mul_f32_e32 v90, v157, v149
	v_mul_f32_e32 v91, v157, v96
	v_mul_f32_e32 v92, v157, v150
	s_waitcnt lgkmcnt(0)
	v_fmac_f32_e32 v20, v90, v84
	v_mul_f32_e32 v84, v157, v97
	v_fmac_f32_e32 v22, v91, v85
	v_fmac_f32_e32 v23, v92, v86
	v_fmac_f32_e32 v19, v84, v87
	v_cvt_pk_bf16_f32 v90, v20, v22
	v_cvt_pk_bf16_f32 v91, v23, v19
	ds_read_b128 v[84:87], v35 offset:13312
	global_store_dwordx2 v[88:89], v[90:91], off offset:2048
	v_mul_f32_e32 v90, v157, v151
	s_waitcnt lgkmcnt(0)
	v_fmac_f32_e32 v18, v90, v84
	v_mul_f32_e32 v84, v157, v98
	v_fmac_f32_e32 v25, v84, v85
	v_mul_f32_e32 v84, v157, v152
	v_fmac_f32_e32 v21, v84, v86
	v_mul_f32_e32 v84, v157, v99
	v_fmac_f32_e32 v16, v84, v87
	v_cvt_pk_bf16_f32 v90, v18, v25
	v_cvt_pk_bf16_f32 v91, v21, v16
	ds_read_b128 v[84:87], v35 offset:14336
	global_store_dwordx2 v[88:89], v[90:91], off offset:2560
	v_mul_f32_e32 v90, v157, v153
	s_waitcnt lgkmcnt(0)
	v_fmac_f32_e32 v24, v90, v84
	v_mul_f32_e32 v84, v157, v100
	v_fmac_f32_e32 v17, v84, v85
	v_mul_f32_e32 v84, v157, v154
	v_fmac_f32_e32 v14, v84, v86
	v_mul_f32_e32 v84, v157, v101
	v_fmac_f32_e32 v15, v84, v87
	v_cvt_pk_bf16_f32 v90, v24, v17
	v_cvt_pk_bf16_f32 v91, v14, v15
	ds_read_b128 v[84:87], v35 offset:15360
	global_store_dwordx2 v[88:89], v[90:91], off offset:3072
	v_mul_f32_e32 v90, v157, v155
	s_waitcnt lgkmcnt(0)
	v_fmac_f32_e32 v82, v90, v84
	v_mul_f32_e32 v84, v157, v102
	v_fmac_f32_e32 v12, v84, v85
	v_mul_f32_e32 v84, v157, v156
	v_fmac_f32_e32 v83, v84, v86
	v_mul_f32_e32 v84, v157, v103
	v_fmac_f32_e32 v13, v84, v87
	v_cvt_pk_bf16_f32 v84, v82, v12
	v_cvt_pk_bf16_f32 v85, v83, v13
	global_store_dwordx2 v[88:89], v[84:85], off offset:3584
	v_mul_f32_e32 v84, v65, v65
	v_mul_f32_e32 v85, v63, v63
	v_fmac_f32_e32 v84, v66, v66
	v_fmac_f32_e32 v85, v64, v64
	v_add_f32_e32 v84, v84, v85
	v_mul_f32_e32 v85, v61, v61
	v_mul_f32_e32 v86, v59, v59
	v_fmac_f32_e32 v85, v62, v62
	v_fmac_f32_e32 v86, v60, v60
	v_add_f32_e32 v85, v85, v86
	v_add_f32_e32 v84, v84, v85
	v_mul_f32_e32 v85, v57, v57
	v_mul_f32_e32 v86, v55, v55
	v_fmac_f32_e32 v85, v58, v58
	v_fmac_f32_e32 v86, v56, v56
	v_add_f32_e32 v85, v85, v86
	v_add_f32_e32 v84, v84, v85
	v_mul_f32_e32 v85, v53, v53
	v_mul_f32_e32 v86, v51, v51
	v_fmac_f32_e32 v85, v54, v54
	v_fmac_f32_e32 v86, v52, v52
	v_add_f32_e32 v85, v85, v86
	v_add_f32_e32 v84, v84, v85
	v_mul_f32_e32 v85, v49, v49
	v_mul_f32_e32 v86, v47, v47
	v_fmac_f32_e32 v85, v48, v48
	v_fmac_f32_e32 v86, v50, v50
	v_add_f32_e32 v85, v85, v86
	v_add_f32_e32 v84, v84, v85
	v_mul_f32_e32 v85, v45, v45
	v_mul_f32_e32 v86, v43, v43
	v_fmac_f32_e32 v85, v46, v46
	v_fmac_f32_e32 v86, v44, v44
	v_add_f32_e32 v85, v85, v86
	v_add_f32_e32 v84, v84, v85
	v_mul_f32_e32 v85, v41, v41
	v_mul_f32_e32 v86, v39, v39
	v_fmac_f32_e32 v85, v42, v42
	v_fmac_f32_e32 v86, v40, v40
	v_add_f32_e32 v85, v85, v86
	v_add_f32_e32 v84, v84, v85
	v_mul_f32_e32 v85, v81, v81
	v_mul_f32_e32 v86, v79, v79
	v_fmac_f32_e32 v85, v38, v38
	v_fmac_f32_e32 v86, v80, v80
	v_add_f32_e32 v85, v85, v86
	v_add_f32_e32 v84, v84, v85
	v_mul_f32_e32 v85, v77, v77
	v_mul_f32_e32 v86, v75, v75
	v_fmac_f32_e32 v85, v73, v73
	v_fmac_f32_e32 v86, v78, v78
	v_add_f32_e32 v85, v85, v86
	v_add_f32_e32 v84, v84, v85
	v_mul_f32_e32 v85, v76, v76
	v_mul_f32_e32 v86, v71, v71
	v_fmac_f32_e32 v85, v74, v74
	v_fmac_f32_e32 v86, v72, v72
	v_add_f32_e32 v85, v85, v86
	v_add_f32_e32 v84, v84, v85
	v_mul_f32_e32 v85, v70, v70
	v_mul_f32_e32 v86, v29, v29
	v_fmac_f32_e32 v85, v68, v68
	v_fmac_f32_e32 v86, v69, v69
	v_add_f32_e32 v85, v85, v86
	v_add_f32_e32 v84, v84, v85
	v_mul_f32_e32 v85, v67, v67
	v_mul_f32_e32 v86, v26, v26
	v_fmac_f32_e32 v85, v27, v27
	v_fmac_f32_e32 v86, v28, v28
	v_add_f32_e32 v85, v85, v86
	v_add_f32_e32 v84, v84, v85
	v_mul_f32_e32 v85, v22, v22
	v_mul_f32_e32 v86, v19, v19
	v_fmac_f32_e32 v85, v20, v20
	v_fmac_f32_e32 v86, v23, v23
	v_add_f32_e32 v85, v85, v86
	v_add_f32_e32 v84, v84, v85
	v_mul_f32_e32 v85, v25, v25
	v_mul_f32_e32 v86, v16, v16
	v_fmac_f32_e32 v85, v18, v18
	v_fmac_f32_e32 v86, v21, v21
	v_add_f32_e32 v85, v85, v86
	v_add_f32_e32 v84, v84, v85
	v_mul_f32_e32 v85, v17, v17
	v_mul_f32_e32 v86, v15, v15
	v_fmac_f32_e32 v85, v24, v24
	v_fmac_f32_e32 v86, v14, v14
	v_add_f32_e32 v85, v85, v86
	v_add_f32_e32 v84, v84, v85
	v_mul_f32_e32 v85, v12, v12
	v_mul_f32_e32 v86, v13, v13
	v_fmac_f32_e32 v85, v82, v82
	v_fmac_f32_e32 v86, v83, v83
	v_add_f32_e32 v85, v85, v86
	v_add_f32_e32 v84, v84, v85
	ds_bpermute_b32 v85, v1, v84
	s_waitcnt lgkmcnt(0)
	v_add_f32_e32 v84, v84, v85
	ds_bpermute_b32 v85, v30, v84
	s_waitcnt lgkmcnt(0)
	v_add_f32_e32 v84, v84, v85
	ds_bpermute_b32 v85, v31, v84
	s_waitcnt lgkmcnt(0)
	v_add_f32_e32 v84, v84, v85
	ds_bpermute_b32 v85, v32, v84
	s_waitcnt lgkmcnt(0)
	v_add_f32_e32 v84, v84, v85
	ds_bpermute_b32 v85, v33, v84
	s_waitcnt lgkmcnt(0)
	v_add_f32_e32 v84, v84, v85
	ds_bpermute_b32 v85, v34, v84
	s_waitcnt lgkmcnt(0)
	v_add_f32_e32 v84, v84, v85
	v_fmamk_f32 v84, v84, 0x39800000, v2
	v_mul_f32_e32 v85, 0x4f800000, v84
	v_cmp_gt_f32_e32 vcc, s46, v84
	s_nop 1
	v_cndmask_b32_e32 v84, v84, v85, vcc
	v_sqrt_f32_e32 v85, v84
	s_nop 0
	v_add_u32_e32 v86, -1, v85
	v_fma_f32 v87, -v86, v85, v84
	v_cmp_ge_f32_e64 s[8:9], 0, v87
	v_add_u32_e32 v87, 1, v85
	s_nop 0
	v_cndmask_b32_e64 v86, v85, v86, s[8:9]
	v_fma_f32 v85, -v87, v85, v84
	v_cmp_lt_f32_e64 s[8:9], 0, v85
	s_nop 1
	v_cndmask_b32_e64 v85, v86, v87, s[8:9]
	v_mul_f32_e32 v86, 0x37800000, v85
	v_cndmask_b32_e32 v85, v85, v86, vcc
	v_cmp_class_f32_e32 vcc, v84, v36
	s_nop 1
	v_cndmask_b32_e32 v88, v85, v84, vcc
	v_div_scale_f32 v84, s[0:1], v88, v88, 1.0
	v_rcp_f32_e32 v89, v84
	s_nop 0
	v_fma_f32 v85, -v84, v89, 1.0
	v_fmac_f32_e32 v89, v85, v89
	v_div_scale_f32 v85, vcc, 1.0, v88, 1.0
	v_mul_f32_e32 v90, v85, v89
	v_fma_f32 v86, -v84, v90, v85
	v_fmac_f32_e32 v90, v86, v89
	v_fma_f32 v91, -v84, v90, v85
	ds_read_b128 v[84:87], v35 offset:16384
	v_div_fmas_f32 v89, v91, v89, v90
	v_div_fixup_f32 v94, v89, v88, 1.0
	ds_read_b128 v[88:91], v35 offset:17408
	s_waitcnt lgkmcnt(1)
	v_mul_f32_e32 v84, v84, v94
	v_mul_f32_e32 v66, v66, v84
	v_mul_f32_e32 v84, v85, v94
	v_mul_f32_e32 v65, v65, v84
	v_mul_f32_e32 v84, v86, v94
	v_mul_f32_e32 v64, v64, v84
	v_mul_f32_e32 v84, v87, v94
	v_mul_f32_e32 v63, v63, v84
	s_waitcnt lgkmcnt(0)
	v_mul_f32_e32 v84, v88, v94
	v_mul_f32_e32 v62, v62, v84
	v_mul_f32_e32 v84, v89, v94
	v_mul_f32_e32 v61, v61, v84
	ds_read_b128 v[84:87], v35 offset:18432
	v_mul_f32_e32 v88, v90, v94
	v_mul_f32_e32 v60, v60, v88
	v_mul_f32_e32 v88, v91, v94
	v_mul_f32_e32 v59, v59, v88
	ds_read_b128 v[88:91], v35 offset:19456
	s_waitcnt lgkmcnt(1)
	v_mul_f32_e32 v84, v84, v94
	v_mul_f32_e32 v58, v58, v84
	v_mul_f32_e32 v84, v85, v94
	v_mul_f32_e32 v57, v57, v84
	v_mul_f32_e32 v84, v86, v94
	v_mul_f32_e32 v56, v56, v84
	v_mul_f32_e32 v84, v87, v94
	v_mul_f32_e32 v55, v55, v84
	s_waitcnt lgkmcnt(0)
	v_mul_f32_e32 v84, v88, v94
	v_mul_f32_e32 v54, v54, v84
	v_mul_f32_e32 v84, v89, v94
	v_mul_f32_e32 v53, v53, v84
	v_mul_f32_e32 v84, v90, v94
	v_mul_f32_e32 v52, v52, v84
	v_mul_f32_e32 v84, v91, v94
	v_mul_f32_e32 v51, v51, v84
	ds_read_b128 v[84:87], v35 offset:20480
	ds_read_b128 v[88:91], v35 offset:21504
	s_waitcnt lgkmcnt(1)
	v_mul_f32_e32 v84, v94, v84
	v_mul_f32_e32 v86, v94, v86
	v_mul_f32_e32 v84, v48, v84
	v_mul_f32_e32 v48, v50, v86
	v_mul_f32_e32 v50, v94, v87
	v_mul_f32_e32 v47, v47, v50
	s_waitcnt lgkmcnt(0)
	v_mul_f32_e32 v50, v94, v88
	v_mul_f32_e32 v46, v46, v50
	v_mul_f32_e32 v50, v94, v89
	ds_read_b128 v[86:89], v35 offset:22528
	v_mul_f32_e32 v45, v45, v50
	v_mul_f32_e32 v50, v94, v90
	v_mul_f32_e32 v44, v44, v50
	v_mul_f32_e32 v50, v94, v91
	ds_read_b128 v[90:93], v35 offset:23552
	v_mul_f32_e32 v43, v43, v50
	s_waitcnt lgkmcnt(1)
	v_mul_f32_e32 v50, v94, v86
	v_mul_f32_e32 v42, v42, v50
	v_mul_f32_e32 v50, v94, v87
	v_mul_f32_e32 v41, v41, v50
	v_mul_f32_e32 v50, v94, v88
	v_mul_f32_e32 v85, v94, v85
	v_mul_f32_e32 v40, v40, v50
	v_mul_f32_e32 v50, v94, v89
	v_mul_f32_e32 v49, v49, v85
	v_mul_f32_e32 v85, v39, v50
	s_waitcnt lgkmcnt(0)
	v_mul_f32_e32 v39, v94, v90
	v_mul_f32_e32 v38, v38, v39
	v_mul_f32_e32 v39, v94, v91
	v_mul_f32_e32 v50, v81, v39
	v_mul_f32_e32 v39, v94, v92
	v_mul_f32_e32 v39, v80, v39
	v_mul_f32_e32 v80, v94, v93
	v_mul_f32_e32 v79, v79, v80
	ds_read_b128 v[86:89], v35 offset:24576
	ds_read_b128 v[90:93], v35 offset:25600
	s_waitcnt lgkmcnt(1)
	v_mul_f32_e32 v80, v94, v86
	v_mul_f32_e32 v81, v94, v87
	v_mul_f32_e32 v86, v94, v88
	v_mul_f32_e32 v80, v73, v80
	v_mul_f32_e32 v81, v77, v81
	v_mul_f32_e32 v77, v78, v86
	v_mul_f32_e32 v73, v94, v89
	ds_read_b128 v[86:89], v35 offset:26624
	v_mul_f32_e32 v75, v75, v73
	s_waitcnt lgkmcnt(1)
	v_mul_f32_e32 v73, v94, v90
	v_mul_f32_e32 v73, v74, v73
	v_mul_f32_e32 v74, v94, v91
	v_mul_f32_e32 v74, v76, v74
	v_mul_f32_e32 v76, v94, v92
	v_mul_f32_e32 v72, v72, v76
	v_mul_f32_e32 v76, v94, v93
	ds_read_b128 v[90:93], v35 offset:27648
	v_mul_f32_e32 v71, v71, v76
	s_waitcnt lgkmcnt(1)
	v_mul_f32_e32 v76, v94, v86
	v_mul_f32_e32 v68, v68, v76
	v_mul_f32_e32 v76, v94, v87
	v_mul_f32_e32 v70, v70, v76
	v_mul_f32_e32 v76, v94, v88
	v_mul_f32_e32 v69, v69, v76
	v_mul_f32_e32 v76, v94, v89
	v_mul_f32_e32 v76, v29, v76
	s_waitcnt lgkmcnt(0)
	v_mul_f32_e32 v29, v94, v90
	v_mul_f32_e32 v27, v27, v29
	v_mul_f32_e32 v29, v94, v91
	v_mul_f32_e32 v29, v67, v29
	v_mul_f32_e32 v67, v94, v92
	v_mul_f32_e32 v28, v28, v67
	v_mul_f32_e32 v67, v94, v93
	v_mul_f32_e32 v26, v26, v67
	ds_read_b128 v[86:89], v35 offset:28672
	ds_read_b128 v[90:93], v35 offset:29696
	s_waitcnt lgkmcnt(1)
	v_mul_f32_e32 v67, v94, v86
	v_mul_f32_e32 v86, v94, v88
	v_mul_f32_e32 v78, v94, v87
	v_mul_f32_e32 v67, v20, v67
	v_mul_f32_e32 v20, v23, v86
	v_mul_f32_e32 v23, v94, v89
	ds_read_b128 v[86:89], v35 offset:30720
	v_mul_f32_e32 v23, v19, v23
	s_waitcnt lgkmcnt(1)
	v_mul_f32_e32 v19, v94, v90
	v_mul_f32_e32 v18, v18, v19
	v_mul_f32_e32 v19, v94, v91
	v_mul_f32_e32 v19, v25, v19
	v_mul_f32_e32 v25, v94, v92
	v_mul_f32_e32 v21, v21, v25
	v_mul_f32_e32 v25, v94, v93
	ds_read_b128 v[90:93], v35 offset:31744
	v_mul_f32_e32 v16, v16, v25
	s_waitcnt lgkmcnt(1)
	v_mul_f32_e32 v25, v94, v86
	v_mul_f32_e32 v24, v24, v25
	v_mul_f32_e32 v25, v94, v87
	v_mul_f32_e32 v25, v17, v25
	v_mul_f32_e32 v17, v94, v88
	v_mul_f32_e32 v17, v14, v17
	v_mul_f32_e32 v14, v94, v89
	v_mul_f32_e32 v22, v22, v78
	v_mul_f32_e32 v78, v15, v14
	s_waitcnt lgkmcnt(0)
	v_mul_f32_e32 v14, v94, v90
	v_mul_f32_e32 v15, v94, v91
	v_mul_f32_e32 v14, v82, v14
	v_mul_f32_e32 v15, v12, v15
	v_mul_f32_e32 v12, v94, v92
	v_mul_f32_e32 v82, v94, v93
	v_mul_f32_e32 v12, v83, v12
	v_mul_f32_e32 v13, v13, v82
	v_max_f32_e64 v82, |v66|, |v65|
	v_max_f32_e64 v83, |v64|, |v63|
	v_max3_f32 v82, v82, 0, v83
	v_max_f32_e64 v83, |v62|, |v61|
	v_max_f32_e64 v86, |v60|, |v59|
	v_max3_f32 v82, v82, v83, v86
	v_max_f32_e64 v83, |v58|, |v57|
	v_max_f32_e64 v86, |v56|, |v55|
	v_max3_f32 v82, v82, v83, v86
	v_max_f32_e64 v83, |v54|, |v53|
	v_max_f32_e64 v86, |v52|, |v51|
	v_max3_f32 v82, v82, v83, v86
	v_max_f32_e64 v83, |v84|, |v49|
	v_max_f32_e64 v86, |v48|, |v47|
	v_max3_f32 v82, v82, v83, v86
	v_max_f32_e64 v83, |v46|, |v45|
	v_max_f32_e64 v86, |v44|, |v43|
	v_max3_f32 v82, v82, v83, v86
	v_max_f32_e64 v83, |v42|, |v41|
	v_max_f32_e64 v86, |v40|, |v85|
	v_max3_f32 v82, v82, v83, v86
	v_max_f32_e64 v83, |v38|, |v50|
	v_max_f32_e64 v86, |v39|, |v79|
	v_max3_f32 v82, v82, v83, v86
	v_max_f32_e64 v83, |v80|, |v81|
	v_max_f32_e64 v86, |v77|, |v75|
	v_max3_f32 v82, v82, v83, v86
	v_max_f32_e64 v83, |v73|, |v74|
	v_max_f32_e64 v86, |v72|, |v71|
	v_max3_f32 v82, v82, v83, v86
	v_max_f32_e64 v83, |v68|, |v70|
	v_max_f32_e64 v86, |v69|, |v76|
	v_max3_f32 v82, v82, v83, v86
	v_max_f32_e64 v83, |v27|, |v29|
	v_max_f32_e64 v86, |v28|, |v26|
	v_max3_f32 v82, v82, v83, v86
	v_max_f32_e64 v83, |v67|, |v22|
	v_max_f32_e64 v86, |v20|, |v23|
	v_max3_f32 v82, v82, v83, v86
	v_max_f32_e64 v83, |v18|, |v19|
	v_max_f32_e64 v86, |v21|, |v16|
	v_max3_f32 v82, v82, v83, v86
	v_max_f32_e64 v83, |v24|, |v25|
	v_max_f32_e64 v86, |v17|, |v78|
	v_max3_f32 v82, v82, v83, v86
	v_max_f32_e64 v83, |v14|, |v15|
	v_max_f32_e64 v86, |v12|, |v13|
	v_max3_f32 v82, v82, v83, v86
	ds_bpermute_b32 v83, v1, v82
	s_waitcnt lgkmcnt(0)
	v_max_f32_e32 v83, v83, v83
	v_max_f32_e32 v82, v82, v83
	ds_bpermute_b32 v83, v30, v82
	s_waitcnt lgkmcnt(0)
	v_max_f32_e32 v83, v83, v83
	v_max_f32_e32 v82, v82, v83
	ds_bpermute_b32 v83, v31, v82
	s_waitcnt lgkmcnt(0)
	v_max_f32_e32 v83, v83, v83
	v_max_f32_e32 v82, v82, v83
	ds_bpermute_b32 v83, v32, v82
	s_waitcnt lgkmcnt(0)
	v_max_f32_e32 v83, v83, v83
	v_max_f32_e32 v82, v82, v83
	ds_bpermute_b32 v83, v33, v82
	s_waitcnt lgkmcnt(0)
	v_max_f32_e32 v83, v83, v83
	v_max_f32_e32 v82, v82, v83
	ds_bpermute_b32 v83, v34, v82
	s_waitcnt lgkmcnt(0)
	v_max3_f32 v82, v82, v83, s47
	s_and_saveexec_b64 s[0:1], s[6:7]
	s_cbranch_execz .LBB0_1345
	s_lshl_b64 s[8:9], s[24:25], 2
	s_add_u32 s8, s26, s8
	v_mul_f32_e32 v83, 0x3c010204, v82
	s_addc_u32 s9, s27, s9
	global_store_dword v3, v83, s[8:9]

.LBB0_1427:
	v_add_u32_e32 v162, s74, v147
	v_add_u32_e32 v178, s75, v147
	ds_read_b128 v[148:151], v162
	ds_read_b128 v[152:155], v162 offset:1024
	ds_read_b128 v[158:161], v162 offset:2048
	ds_read_b128 v[162:165], v162 offset:3072
	ds_read_b128 v[166:169], v178
	ds_read_b128 v[170:173], v178 offset:1024
	ds_read_b128 v[174:177], v178 offset:2048
	ds_read_b128 v[178:181], v178 offset:3072
	s_add_u32 s49, s54, 0xfff80080
	s_addc_u32 s51, s55, -1
	s_and_b64 s[56:57], s[56:57], exec
	s_cselect_b32 s59, s17, s51
	s_cselect_b32 s58, s16, s49
	s_cselect_b32 s57, s11, s79
	s_cselect_b32 s56, s10, s78
	v_lshl_add_u64 v[214:215], s[54:55], 0, v[138:139]
	s_add_i32 m0, s53, 0xc000
	ds_read_b128 v[182:185], v157
	ds_read_b128 v[186:189], v157 offset:1024
	ds_read_b128 v[190:193], v157 offset:2048
	ds_read_b128 v[194:197], v157 offset:3072
	ds_read_b128 v[198:201], v157 offset:4096
	ds_read_b128 v[202:205], v157 offset:5120
	ds_read_b128 v[206:209], v157 offset:6144
	ds_read_b128 v[210:213], v157 offset:7168
	global_load_lds_dwordx4 v[214:215], off
	v_lshl_add_u64 v[214:215], s[54:55], 0, v[140:141]
	s_add_i32 m0, s53, 0xe000
	s_nop 0
	global_load_lds_dwordx4 v[214:215], off
	s_waitcnt vmcnt(8)
	s_waitcnt lgkmcnt(0)
	s_barrier
	s_setprio 2
	s_waitcnt lgkmcnt(0)
	v_mfma_i32_16x16x64_i8 v[126:129], v[148:151], v[182:185], v[126:129]
	v_mfma_i32_16x16x64_i8 v[118:121], v[158:161], v[182:185], v[118:121]
	v_mfma_i32_16x16x64_i8 v[110:113], v[148:151], v[190:193], v[110:113]
	v_mfma_i32_16x16x64_i8 v[102:105], v[158:161], v[190:193], v[102:105]
	v_mfma_i32_16x16x64_i8 v[94:97], v[148:151], v[198:201], v[94:97]
	v_mfma_i32_16x16x64_i8 v[86:89], v[158:161], v[198:201], v[86:89]
	v_mfma_i32_16x16x64_i8 v[78:81], v[148:151], v[206:209], v[78:81]
	v_mfma_i32_16x16x64_i8 v[70:73], v[158:161], v[206:209], v[70:73]
	v_mfma_i32_16x16x64_i8 v[126:129], v[152:155], v[186:189], v[126:129]
	v_mfma_i32_16x16x64_i8 v[118:121], v[162:165], v[186:189], v[118:121]
	v_mfma_i32_16x16x64_i8 v[110:113], v[152:155], v[194:197], v[110:113]
	v_mfma_i32_16x16x64_i8 v[102:105], v[162:165], v[194:197], v[102:105]
	v_mfma_i32_16x16x64_i8 v[94:97], v[152:155], v[202:205], v[94:97]
	v_mfma_i32_16x16x64_i8 v[86:89], v[162:165], v[202:205], v[86:89]
	v_mfma_i32_16x16x64_i8 v[78:81], v[152:155], v[210:213], v[78:81]
	v_mfma_i32_16x16x64_i8 v[70:73], v[162:165], v[210:213], v[70:73]
	s_setprio 0
	s_setprio 2
	v_mfma_i32_16x16x64_i8 v[122:125], v[166:169], v[182:185], v[122:125]
	v_mfma_i32_16x16x64_i8 v[114:117], v[174:177], v[182:185], v[114:117]
	v_mfma_i32_16x16x64_i8 v[106:109], v[166:169], v[190:193], v[106:109]
	v_mfma_i32_16x16x64_i8 v[98:101], v[174:177], v[190:193], v[98:101]
	v_mfma_i32_16x16x64_i8 v[90:93], v[166:169], v[198:201], v[90:93]
	v_mfma_i32_16x16x64_i8 v[82:85], v[174:177], v[198:201], v[82:85]
	v_mfma_i32_16x16x64_i8 v[74:77], v[166:169], v[206:209], v[74:77]
	v_mfma_i32_16x16x64_i8 v[66:69], v[174:177], v[206:209], v[66:69]
	v_mfma_i32_16x16x64_i8 v[122:125], v[170:173], v[186:189], v[122:125]
	v_mfma_i32_16x16x64_i8 v[114:117], v[178:181], v[186:189], v[114:117]
	v_mfma_i32_16x16x64_i8 v[106:109], v[170:173], v[194:197], v[106:109]
	v_mfma_i32_16x16x64_i8 v[98:101], v[178:181], v[194:197], v[98:101]
	s_setprio 3
	s_barrier
	v_mfma_i32_16x16x64_i8 v[90:93], v[170:173], v[202:205], v[90:93]
	v_mfma_i32_16x16x64_i8 v[82:85], v[178:181], v[202:205], v[82:85]
	v_mfma_i32_16x16x64_i8 v[74:77], v[170:173], v[210:213], v[74:77]
	v_mfma_i32_16x16x64_i8 v[66:69], v[178:181], v[210:213], v[66:69]
	s_setprio 0
	s_add_i32 s49, s74, s61
	v_lshl_add_u64 v[214:215], s[56:57], 0, v[130:131]
	s_mov_b32 m0, s49
	ds_read_b128 v[182:185], v157 offset:16384
	ds_read_b128 v[186:189], v157 offset:17408
	ds_read_b128 v[190:193], v157 offset:18432
	ds_read_b128 v[194:197], v157 offset:19456
	ds_read_b128 v[198:201], v157 offset:20480
	ds_read_b128 v[202:205], v157 offset:21504
	ds_read_b128 v[206:209], v157 offset:22528
	ds_read_b128 v[210:213], v157 offset:23552
	global_load_lds_dwordx4 v[214:215], off
	s_add_i32 m0, s49, 0x2000
	s_add_u32 s82, s56, 0x80000
	v_lshl_add_u64 v[214:215], s[56:57], 0, v[132:133]
	s_addc_u32 s83, s57, 0
	s_add_i32 s49, s75, s61
	global_load_lds_dwordx4 v[214:215], off
	v_lshl_add_u64 v[214:215], s[82:83], 0, v[130:131]
	s_mov_b32 m0, s49
	v_lshl_add_u64 v[216:217], s[58:59], 0, v[134:135]
	global_load_lds_dwordx4 v[214:215], off
	v_lshl_add_u64 v[214:215], s[82:83], 0, v[132:133]
	s_add_i32 m0, s49, 0x2000
	s_nop 0
	global_load_lds_dwordx4 v[214:215], off
	v_lshl_add_u64 v[214:215], s[58:59], 0, v[136:137]
	s_mov_b32 m0, s53
	s_nop 0
	global_load_lds_dwordx4 v[214:215], off
	s_mov_b32 m0, s64
	s_nop 0
	global_load_lds_dwordx4 v[216:217], off
	s_waitcnt vmcnt(8)
	s_waitcnt lgkmcnt(0)
	s_barrier
	s_setprio 2
	s_waitcnt lgkmcnt(0)
	v_mfma_i32_16x16x64_i8 v[62:65], v[148:151], v[182:185], v[62:65]
	v_mfma_i32_16x16x64_i8 v[54:57], v[158:161], v[182:185], v[54:57]
	v_mfma_i32_16x16x64_i8 v[46:49], v[148:151], v[190:193], v[46:49]
	v_mfma_i32_16x16x64_i8 v[38:41], v[158:161], v[190:193], v[38:41]
	v_mfma_i32_16x16x64_i8 v[30:33], v[148:151], v[198:201], v[30:33]
	v_mfma_i32_16x16x64_i8 v[22:25], v[158:161], v[198:201], v[22:25]
	v_mfma_i32_16x16x64_i8 v[14:17], v[148:151], v[206:209], v[14:17]
	v_mfma_i32_16x16x64_i8 v[6:9], v[158:161], v[206:209], v[6:9]
	v_mfma_i32_16x16x64_i8 v[62:65], v[152:155], v[186:189], v[62:65]
	v_mfma_i32_16x16x64_i8 v[54:57], v[162:165], v[186:189], v[54:57]
	v_mfma_i32_16x16x64_i8 v[46:49], v[152:155], v[194:197], v[46:49]
	v_mfma_i32_16x16x64_i8 v[38:41], v[162:165], v[194:197], v[38:41]
	v_mfma_i32_16x16x64_i8 v[30:33], v[152:155], v[202:205], v[30:33]
	v_mfma_i32_16x16x64_i8 v[22:25], v[162:165], v[202:205], v[22:25]
	v_mfma_i32_16x16x64_i8 v[14:17], v[152:155], v[210:213], v[14:17]
	v_mfma_i32_16x16x64_i8 v[6:9], v[162:165], v[210:213], v[6:9]
	s_setprio 0
	s_setprio 2
	v_mfma_i32_16x16x64_i8 v[58:61], v[166:169], v[182:185], v[58:61]
	v_mfma_i32_16x16x64_i8 v[50:53], v[174:177], v[182:185], v[50:53]
	v_mfma_i32_16x16x64_i8 v[42:45], v[166:169], v[190:193], v[42:45]
	v_mfma_i32_16x16x64_i8 v[34:37], v[174:177], v[190:193], v[34:37]
	v_mfma_i32_16x16x64_i8 v[26:29], v[166:169], v[198:201], v[26:29]
	v_mfma_i32_16x16x64_i8 v[18:21], v[174:177], v[198:201], v[18:21]
	v_mfma_i32_16x16x64_i8 v[10:13], v[166:169], v[206:209], v[10:13]
	v_mfma_i32_16x16x64_i8 v[2:5], v[174:177], v[206:209], v[2:5]
	v_mfma_i32_16x16x64_i8 v[58:61], v[170:173], v[186:189], v[58:61]
	v_mfma_i32_16x16x64_i8 v[50:53], v[178:181], v[186:189], v[50:53]
	v_mfma_i32_16x16x64_i8 v[42:45], v[170:173], v[194:197], v[42:45]
	v_mfma_i32_16x16x64_i8 v[34:37], v[178:181], v[194:197], v[34:37]
	s_setprio 3
	s_barrier
	v_mfma_i32_16x16x64_i8 v[26:29], v[170:173], v[202:205], v[26:29]
	v_mfma_i32_16x16x64_i8 v[18:21], v[178:181], v[202:205], v[18:21]
	v_mfma_i32_16x16x64_i8 v[10:13], v[170:173], v[210:213], v[10:13]
	v_mfma_i32_16x16x64_i8 v[2:5], v[178:181], v[210:213], v[2:5]
	s_setprio 0
	s_add_i32 s49, 0, 0x18000
	s_add_i32 s51, 0, 0x1c000
	v_add_u32_e32 v162, s49, v147
	v_add_u32_e32 v178, s51, v147
	ds_read_b128 v[148:151], v162
	ds_read_b128 v[152:155], v162 offset:1024
	ds_read_b128 v[158:161], v162 offset:2048
	ds_read_b128 v[162:165], v162 offset:3072
	ds_read_b128 v[166:169], v178
	ds_read_b128 v[170:173], v178 offset:1024
	ds_read_b128 v[174:177], v178 offset:2048
	ds_read_b128 v[178:181], v178 offset:3072
	s_add_u32 s58, s58, 0x80000
	s_addc_u32 s59, s59, 0
	s_mov_b32 m0, s65
	v_lshl_add_u64 v[218:219], s[58:59], 0, v[136:137]
	ds_read_b128 v[182:185], v157 offset:32768
	ds_read_b128 v[186:189], v157 offset:33792
	ds_read_b128 v[190:193], v157 offset:34816
	ds_read_b128 v[194:197], v157 offset:35840
	ds_read_b128 v[198:201], v157 offset:36864
	ds_read_b128 v[202:205], v157 offset:37888
	ds_read_b128 v[206:209], v157 offset:38912
	ds_read_b128 v[210:213], v157 offset:39936
	global_load_lds_dwordx4 v[218:219], off
	v_lshl_add_u64 v[218:219], s[58:59], 0, v[134:135]
	s_mov_b32 m0, s66
	s_nop 0
	global_load_lds_dwordx4 v[218:219], off
	s_waitcnt vmcnt(8)
	s_waitcnt lgkmcnt(0)
	s_barrier
	s_setprio 2
	s_waitcnt lgkmcnt(0)
	v_mfma_i32_16x16x64_i8 v[126:129], v[148:151], v[182:185], v[126:129]
	v_mfma_i32_16x16x64_i8 v[118:121], v[158:161], v[182:185], v[118:121]
	v_mfma_i32_16x16x64_i8 v[110:113], v[148:151], v[190:193], v[110:113]
	v_mfma_i32_16x16x64_i8 v[102:105], v[158:161], v[190:193], v[102:105]
	v_mfma_i32_16x16x64_i8 v[94:97], v[148:151], v[198:201], v[94:97]
	v_mfma_i32_16x16x64_i8 v[86:89], v[158:161], v[198:201], v[86:89]
	v_mfma_i32_16x16x64_i8 v[78:81], v[148:151], v[206:209], v[78:81]
	v_mfma_i32_16x16x64_i8 v[70:73], v[158:161], v[206:209], v[70:73]
	v_mfma_i32_16x16x64_i8 v[126:129], v[152:155], v[186:189], v[126:129]
	v_mfma_i32_16x16x64_i8 v[118:121], v[162:165], v[186:189], v[118:121]
	v_mfma_i32_16x16x64_i8 v[110:113], v[152:155], v[194:197], v[110:113]
	v_mfma_i32_16x16x64_i8 v[102:105], v[162:165], v[194:197], v[102:105]
	v_mfma_i32_16x16x64_i8 v[94:97], v[152:155], v[202:205], v[94:97]
	v_mfma_i32_16x16x64_i8 v[86:89], v[162:165], v[202:205], v[86:89]
	v_mfma_i32_16x16x64_i8 v[78:81], v[152:155], v[210:213], v[78:81]
	v_mfma_i32_16x16x64_i8 v[70:73], v[162:165], v[210:213], v[70:73]
	s_setprio 0
	s_setprio 2
	v_mfma_i32_16x16x64_i8 v[122:125], v[166:169], v[182:185], v[122:125]
	v_mfma_i32_16x16x64_i8 v[114:117], v[174:177], v[182:185], v[114:117]
	v_mfma_i32_16x16x64_i8 v[106:109], v[166:169], v[190:193], v[106:109]
	v_mfma_i32_16x16x64_i8 v[98:101], v[174:177], v[190:193], v[98:101]
	v_mfma_i32_16x16x64_i8 v[90:93], v[166:169], v[198:201], v[90:93]
	v_mfma_i32_16x16x64_i8 v[82:85], v[174:177], v[198:201], v[82:85]
	v_mfma_i32_16x16x64_i8 v[74:77], v[166:169], v[206:209], v[74:77]
	v_mfma_i32_16x16x64_i8 v[66:69], v[174:177], v[206:209], v[66:69]
	v_mfma_i32_16x16x64_i8 v[122:125], v[170:173], v[186:189], v[122:125]
	v_mfma_i32_16x16x64_i8 v[114:117], v[178:181], v[186:189], v[114:117]
	v_mfma_i32_16x16x64_i8 v[106:109], v[170:173], v[194:197], v[106:109]
	v_mfma_i32_16x16x64_i8 v[98:101], v[178:181], v[194:197], v[98:101]
	s_setprio 3
	s_barrier
	v_mfma_i32_16x16x64_i8 v[90:93], v[170:173], v[202:205], v[90:93]
	v_mfma_i32_16x16x64_i8 v[82:85], v[178:181], v[202:205], v[82:85]
	v_mfma_i32_16x16x64_i8 v[74:77], v[170:173], v[210:213], v[74:77]
	v_mfma_i32_16x16x64_i8 v[66:69], v[178:181], v[210:213], v[66:69]
	s_setprio 0
	s_add_u32 s58, s56, 0x4000
	s_addc_u32 s59, s57, 0
	s_add_i32 s49, s49, s61
	v_lshl_add_u64 v[218:219], s[58:59], 0, v[130:131]
	s_mov_b32 m0, s49
	ds_read_b128 v[182:185], v157 offset:49152
	ds_read_b128 v[186:189], v157 offset:50176
	ds_read_b128 v[190:193], v157 offset:51200
	ds_read_b128 v[194:197], v157 offset:52224
	ds_read_b128 v[198:201], v157 offset:53248
	ds_read_b128 v[202:205], v157 offset:54272
	ds_read_b128 v[206:209], v157 offset:55296
	ds_read_b128 v[210:213], v157 offset:56320
	global_load_lds_dwordx4 v[218:219], off
	s_add_i32 m0, s49, 0x2000
	s_add_u32 s56, s56, 0x84000
	v_lshl_add_u64 v[218:219], s[58:59], 0, v[132:133]
	s_addc_u32 s57, s57, 0
	s_add_i32 s49, s51, s61
	global_load_lds_dwordx4 v[218:219], off
	v_lshl_add_u64 v[218:219], s[56:57], 0, v[130:131]
	s_mov_b32 m0, s49
	v_lshl_add_u64 v[214:215], v[214:215], 0, s[42:43]
	global_load_lds_dwordx4 v[218:219], off
	v_lshl_add_u64 v[218:219], s[56:57], 0, v[132:133]
	s_add_i32 m0, s49, 0x2000
	s_nop 0
	global_load_lds_dwordx4 v[218:219], off
	s_mov_b32 m0, s70
	s_nop 0
	global_load_lds_dwordx4 v[214:215], off
	v_lshl_add_u64 v[214:215], v[216:217], 0, s[42:43]
	s_mov_b32 m0, s71
	s_nop 0
	global_load_lds_dwordx4 v[214:215], off
	s_waitcnt vmcnt(8)
	s_waitcnt lgkmcnt(0)
	s_barrier
	s_setprio 2
	s_waitcnt lgkmcnt(0)
	v_mfma_i32_16x16x64_i8 v[62:65], v[148:151], v[182:185], v[62:65]
	v_mfma_i32_16x16x64_i8 v[54:57], v[158:161], v[182:185], v[54:57]
	v_mfma_i32_16x16x64_i8 v[46:49], v[148:151], v[190:193], v[46:49]
	v_mfma_i32_16x16x64_i8 v[38:41], v[158:161], v[190:193], v[38:41]
	v_mfma_i32_16x16x64_i8 v[30:33], v[148:151], v[198:201], v[30:33]
	v_mfma_i32_16x16x64_i8 v[22:25], v[158:161], v[198:201], v[22:25]
	v_mfma_i32_16x16x64_i8 v[14:17], v[148:151], v[206:209], v[14:17]
	v_mfma_i32_16x16x64_i8 v[6:9], v[158:161], v[206:209], v[6:9]
	v_mfma_i32_16x16x64_i8 v[62:65], v[152:155], v[186:189], v[62:65]
	v_mfma_i32_16x16x64_i8 v[54:57], v[162:165], v[186:189], v[54:57]
	v_mfma_i32_16x16x64_i8 v[46:49], v[152:155], v[194:197], v[46:49]
	v_mfma_i32_16x16x64_i8 v[38:41], v[162:165], v[194:197], v[38:41]
	v_mfma_i32_16x16x64_i8 v[30:33], v[152:155], v[202:205], v[30:33]
	v_mfma_i32_16x16x64_i8 v[22:25], v[162:165], v[202:205], v[22:25]
	v_mfma_i32_16x16x64_i8 v[14:17], v[152:155], v[210:213], v[14:17]
	v_mfma_i32_16x16x64_i8 v[6:9], v[162:165], v[210:213], v[6:9]
	s_setprio 0
	s_setprio 2
	v_mfma_i32_16x16x64_i8 v[58:61], v[166:169], v[182:185], v[58:61]
	v_mfma_i32_16x16x64_i8 v[50:53], v[174:177], v[182:185], v[50:53]
	v_mfma_i32_16x16x64_i8 v[42:45], v[166:169], v[190:193], v[42:45]
	v_mfma_i32_16x16x64_i8 v[34:37], v[174:177], v[190:193], v[34:37]
	v_mfma_i32_16x16x64_i8 v[26:29], v[166:169], v[198:201], v[26:29]
	v_mfma_i32_16x16x64_i8 v[18:21], v[174:177], v[198:201], v[18:21]
	v_mfma_i32_16x16x64_i8 v[10:13], v[166:169], v[206:209], v[10:13]
	v_mfma_i32_16x16x64_i8 v[2:5], v[174:177], v[206:209], v[2:5]
	v_mfma_i32_16x16x64_i8 v[58:61], v[170:173], v[186:189], v[58:61]
	v_mfma_i32_16x16x64_i8 v[50:53], v[178:181], v[186:189], v[50:53]
	v_mfma_i32_16x16x64_i8 v[42:45], v[170:173], v[194:197], v[42:45]
	v_mfma_i32_16x16x64_i8 v[34:37], v[178:181], v[194:197], v[34:37]
	s_setprio 3
	s_barrier
	v_mfma_i32_16x16x64_i8 v[26:29], v[170:173], v[202:205], v[26:29]
	v_mfma_i32_16x16x64_i8 v[18:21], v[178:181], v[202:205], v[18:21]
	v_mfma_i32_16x16x64_i8 v[10:13], v[170:173], v[210:213], v[10:13]
	v_mfma_i32_16x16x64_i8 v[2:5], v[178:181], v[210:213], v[2:5]
	s_setprio 0
	s_add_i32 s80, s80, 2
	s_add_u32 s78, s78, 0x8000
	s_addc_u32 s79, s79, 0
	s_add_u32 s54, s54, 0x100
	s_addc_u32 s55, s55, 0
	s_cmp_gt_u32 s80, 29
	s_cbranch_scc1 .LBB0_1433

.LBB0_1450:
	s_or_b64 exec, exec, s[16:17]
	s_ashr_i32 s6, s63, 31
	s_lshr_b32 s6, s6, 25
	s_add_i32 s6, s63, s6
	s_ashr_i32 s6, s6, 7
	s_waitcnt lgkmcnt(0)
	v_lshl_add_u32 v10, s6, 6, v6
	s_lshl_b32 s7, s6, 12
	s_lshl_b32 s16, s63, 5
	v_ashrrev_i32_e32 v11, 31, v10
	s_sub_i32 s16, s16, s7
	v_lshlrev_b64 v[10:11], 14, v[10:11]
	s_waitcnt lgkmcnt(0)
	v_lshl_add_u64 v[10:11], s[0:1], 0, v[10:11]
	s_ashr_i32 s17, s16, 31
	v_lshl_add_u64 v[10:11], s[16:17], 2, v[10:11]
	v_lshl_add_u64 v[10:11], v[10:11], 0, v[2:3]
	v_add_co_u32_e64 v12, s[6:7], s24, v10
	s_nop 1
	v_addc_co_u32_e64 v13, s[6:7], 0, v11, s[6:7]
	v_add_co_u32_e64 v14, s[6:7], s25, v10
	s_nop 1
	v_addc_co_u32_e64 v15, s[6:7], 0, v11, s[6:7]
	v_add_co_u32_e64 v16, s[6:7], s26, v10
	s_nop 1
	v_addc_co_u32_e64 v17, s[6:7], 0, v11, s[6:7]
	v_add_co_u32_e64 v18, s[6:7], s27, v10
	s_nop 1
	v_addc_co_u32_e64 v19, s[6:7], 0, v11, s[6:7]
	v_add_co_u32_e64 v20, s[6:7], s28, v10
	s_nop 1
	v_addc_co_u32_e64 v21, s[6:7], 0, v11, s[6:7]
	v_add_co_u32_e64 v22, s[6:7], s29, v10
	s_nop 1
	v_addc_co_u32_e64 v23, s[6:7], 0, v11, s[6:7]
	v_add_co_u32_e64 v24, s[6:7], s38, v10
	s_nop 1
	v_addc_co_u32_e64 v25, s[6:7], 0, v11, s[6:7]
	global_load_dword v9, v[10:11], off nt
	global_load_dword v28, v[12:13], off nt
	global_load_dword v29, v[14:15], off nt
	global_load_dword v30, v[16:17], off nt
	global_load_dword v31, v[18:19], off nt
	global_load_dword v32, v[20:21], off nt
	global_load_dword v33, v[22:23], off nt
	global_load_dword v34, v[24:25], off nt
	v_add_co_u32_e64 v12, s[6:7], s39, v10
	s_nop 1
	v_addc_co_u32_e64 v13, s[6:7], 0, v11, s[6:7]
	v_add_co_u32_e64 v14, s[6:7], s40, v10
	s_nop 1
	v_addc_co_u32_e64 v15, s[6:7], 0, v11, s[6:7]
	v_add_co_u32_e64 v16, s[6:7], s41, v10
	s_nop 1
	v_addc_co_u32_e64 v17, s[6:7], 0, v11, s[6:7]
	v_add_co_u32_e64 v18, s[6:7], s42, v10
	s_nop 1
	v_addc_co_u32_e64 v19, s[6:7], 0, v11, s[6:7]
	v_add_co_u32_e64 v20, s[6:7], s43, v10
	s_nop 1
	v_addc_co_u32_e64 v21, s[6:7], 0, v11, s[6:7]
	v_add_co_u32_e64 v22, s[6:7], s44, v10
	s_nop 1
	v_addc_co_u32_e64 v23, s[6:7], 0, v11, s[6:7]
	v_add_co_u32_e64 v24, s[6:7], s45, v10
	s_nop 1
	v_addc_co_u32_e64 v25, s[6:7], 0, v11, s[6:7]
	v_add_co_u32_e64 v26, s[6:7], s46, v10
	s_nop 1
	v_addc_co_u32_e64 v27, s[6:7], 0, v11, s[6:7]
	global_load_dword v35, v[12:13], off nt
	global_load_dword v36, v[14:15], off nt
	global_load_dword v37, v[16:17], off nt
	global_load_dword v38, v[18:19], off nt
	global_load_dword v39, v[20:21], off nt
	global_load_dword v40, v[22:23], off nt
	global_load_dword v41, v[24:25], off nt
	global_load_dword v42, v[26:27], off nt
	v_add_co_u32_e64 v12, s[6:7], s47, v10
	s_nop 1
	v_addc_co_u32_e64 v13, s[6:7], 0, v11, s[6:7]
	v_add_co_u32_e64 v14, s[6:7], s48, v10
	s_nop 1
	v_addc_co_u32_e64 v15, s[6:7], 0, v11, s[6:7]
	v_add_co_u32_e64 v16, s[6:7], s49, v10
	s_nop 1
	v_addc_co_u32_e64 v17, s[6:7], 0, v11, s[6:7]
	v_add_co_u32_e64 v18, s[6:7], s50, v10
	s_nop 1
	v_addc_co_u32_e64 v19, s[6:7], 0, v11, s[6:7]
	v_add_co_u32_e64 v20, s[6:7], s51, v10
	s_nop 1
	v_addc_co_u32_e64 v21, s[6:7], 0, v11, s[6:7]
	v_add_co_u32_e64 v22, s[6:7], s52, v10
	s_nop 1
	v_addc_co_u32_e64 v23, s[6:7], 0, v11, s[6:7]
	v_add_co_u32_e64 v24, s[6:7], s53, v10
	s_nop 1
	v_addc_co_u32_e64 v25, s[6:7], 0, v11, s[6:7]
	v_add_co_u32_e64 v26, s[6:7], s54, v10
	s_nop 1
	v_addc_co_u32_e64 v27, s[6:7], 0, v11, s[6:7]
	global_load_dword v43, v[12:13], off nt
	global_load_dword v44, v[14:15], off nt
	global_load_dword v45, v[16:17], off nt
	global_load_dword v46, v[18:19], off nt
	global_load_dword v47, v[20:21], off nt
	global_load_dword v48, v[22:23], off nt
	global_load_dword v49, v[24:25], off nt
	s_nop 0
	global_load_dword v26, v[26:27], off nt
	v_add_co_u32_e64 v12, s[6:7], s55, v10
	s_waitcnt vmcnt(0)
	v_readfirstlane_b32 s98, v223
	s_nop 1
	v_mov_b32_e32 v8, s98
	v_sub_f32_e32 v27, v35, v36
	v_addc_co_u32_e64 v13, s[6:7], 0, v11, s[6:7]
	v_add_co_u32_e64 v14, s[6:7], s56, v10
	s_nop 1
	v_addc_co_u32_e64 v15, s[6:7], 0, v11, s[6:7]
	v_add_co_u32_e64 v16, s[6:7], s57, v10
	s_nop 1
	v_addc_co_u32_e64 v17, s[6:7], 0, v11, s[6:7]
	v_add_co_u32_e64 v18, s[6:7], s58, v10
	s_nop 1
	v_addc_co_u32_e64 v19, s[6:7], 0, v11, s[6:7]
	v_add_co_u32_e64 v20, s[6:7], s59, v10
	s_nop 1
	v_addc_co_u32_e64 v21, s[6:7], 0, v11, s[6:7]
	v_add_co_u32_e64 v22, s[6:7], s60, v10
	s_nop 1
	v_addc_co_u32_e64 v23, s[6:7], 0, v11, s[6:7]
	v_add_co_u32_e64 v24, s[6:7], s61, v10
	s_nop 1
	v_addc_co_u32_e64 v25, s[6:7], 0, v11, s[6:7]
	v_add_co_u32_e64 v10, s[6:7], s62, v10
	s_nop 1
	v_addc_co_u32_e64 v11, s[6:7], 0, v11, s[6:7]
	global_load_dword v12, v[12:13], off nt
	s_nop 0
	global_load_dword v13, v[14:15], off nt
	s_nop 0
	global_load_dword v14, v[16:17], off nt
	global_load_dword v15, v[18:19], off nt
	s_nop 0
	global_load_dword v16, v[20:21], off nt
	global_load_dword v17, v[22:23], off nt
	global_load_dword v18, v[24:25], off nt
	s_nop 0
	global_load_dword v10, v[10:11], off nt
	v_add_f32_e32 v11, v9, v28
	v_sub_f32_e32 v9, v9, v28
	v_add_f32_e32 v19, v29, v30
	v_sub_f32_e32 v20, v29, v30
	v_add_f32_e32 v21, v31, v32
	v_sub_f32_e32 v22, v31, v32
	v_add_f32_e32 v23, v33, v34
	v_sub_f32_e32 v24, v33, v34
	v_add_f32_e32 v25, v35, v36
	v_add_f32_e32 v28, v37, v38
	v_sub_f32_e32 v29, v37, v38
	v_add_f32_e32 v30, v39, v40
	v_sub_f32_e32 v31, v39, v40
	v_add_f32_e32 v32, v41, v42
	v_sub_f32_e32 v33, v41, v42
	v_add_f32_e32 v34, v43, v44
	v_sub_f32_e32 v35, v43, v44
	v_add_f32_e32 v36, v45, v46
	v_sub_f32_e32 v37, v45, v46
	v_add_f32_e32 v38, v47, v48
	v_sub_f32_e32 v39, v47, v48
	v_add_f32_e32 v40, v49, v26
	v_sub_f32_e32 v26, v49, v26
	s_waitcnt vmcnt(6)
	v_add_f32_e32 v41, v12, v13
	v_sub_f32_e32 v12, v12, v13
	s_waitcnt vmcnt(4)
	v_add_f32_e32 v13, v14, v15
	v_sub_f32_e32 v14, v14, v15
	s_waitcnt vmcnt(2)
	v_add_f32_e32 v15, v16, v17
	v_sub_f32_e32 v16, v16, v17
	s_waitcnt vmcnt(0)
	v_add_f32_e32 v17, v18, v10
	v_sub_f32_e32 v10, v18, v10
	v_add_f32_e32 v18, v11, v19
	v_sub_f32_e32 v11, v11, v19
	v_add_f32_e32 v19, v9, v20
	v_sub_f32_e32 v9, v9, v20
	v_add_f32_e32 v20, v21, v23
	v_sub_f32_e32 v21, v21, v23
	v_add_f32_e32 v23, v22, v24
	v_sub_f32_e32 v22, v22, v24
	v_add_f32_e32 v24, v25, v28
	v_sub_f32_e32 v25, v25, v28
	v_add_f32_e32 v28, v27, v29
	v_sub_f32_e32 v27, v27, v29
	v_add_f32_e32 v29, v30, v32
	v_sub_f32_e32 v30, v30, v32
	v_add_f32_e32 v32, v31, v33
	v_sub_f32_e32 v31, v31, v33
	v_add_f32_e32 v33, v34, v36
	v_sub_f32_e32 v34, v34, v36
	v_add_f32_e32 v36, v35, v37
	v_sub_f32_e32 v35, v35, v37
	v_add_f32_e32 v37, v38, v40
	v_sub_f32_e32 v38, v38, v40
	v_add_f32_e32 v40, v39, v26
	v_sub_f32_e32 v26, v39, v26
	v_add_f32_e32 v39, v41, v13
	v_sub_f32_e32 v13, v41, v13
	v_add_f32_e32 v41, v12, v14
	v_sub_f32_e32 v12, v12, v14
	v_add_f32_e32 v14, v15, v17
	v_sub_f32_e32 v15, v15, v17
	v_add_f32_e32 v17, v16, v10
	v_sub_f32_e32 v10, v16, v10
	v_add_f32_e32 v16, v18, v20
	v_sub_f32_e32 v18, v18, v20
	v_add_f32_e32 v20, v19, v23
	v_sub_f32_e32 v19, v19, v23
	v_add_f32_e32 v23, v11, v21
	v_sub_f32_e32 v11, v11, v21
	v_add_f32_e32 v21, v9, v22
	v_sub_f32_e32 v9, v9, v22
	v_add_f32_e32 v22, v24, v29
	v_sub_f32_e32 v24, v24, v29
	v_add_f32_e32 v29, v28, v32
	v_sub_f32_e32 v28, v28, v32
	v_add_f32_e32 v32, v25, v30
	v_sub_f32_e32 v25, v25, v30
	v_add_f32_e32 v30, v27, v31
	v_sub_f32_e32 v27, v27, v31
	v_add_f32_e32 v31, v33, v37
	v_sub_f32_e32 v33, v33, v37
	v_add_f32_e32 v37, v36, v40
	v_sub_f32_e32 v36, v36, v40
	v_add_f32_e32 v40, v34, v38
	v_sub_f32_e32 v34, v34, v38
	v_add_f32_e32 v38, v35, v26
	v_sub_f32_e32 v26, v35, v26
	v_add_f32_e32 v35, v39, v14
	v_sub_f32_e32 v14, v39, v14
	v_add_f32_e32 v39, v41, v17
	v_sub_f32_e32 v17, v41, v17
	v_add_f32_e32 v41, v13, v15
	v_sub_f32_e32 v13, v13, v15
	v_add_f32_e32 v15, v12, v10
	v_sub_f32_e32 v10, v12, v10
	v_add_f32_e32 v12, v16, v22
	v_sub_f32_e32 v16, v16, v22
	v_add_f32_e32 v22, v20, v29
	v_sub_f32_e32 v20, v20, v29
	v_add_f32_e32 v29, v23, v32
	v_sub_f32_e32 v23, v23, v32
	v_add_f32_e32 v32, v21, v30
	v_sub_f32_e32 v21, v21, v30
	v_add_f32_e32 v30, v18, v24
	v_sub_f32_e32 v18, v18, v24
	v_add_f32_e32 v24, v19, v28
	v_sub_f32_e32 v19, v19, v28
	v_add_f32_e32 v28, v11, v25
	v_sub_f32_e32 v11, v11, v25
	v_add_f32_e32 v25, v9, v27
	v_sub_f32_e32 v9, v9, v27
	v_add_f32_e32 v27, v31, v35
	v_sub_f32_e32 v31, v31, v35
	v_add_f32_e32 v35, v37, v39
	v_sub_f32_e32 v37, v37, v39
	v_add_f32_e32 v39, v40, v41
	v_sub_f32_e32 v40, v40, v41
	v_add_f32_e32 v41, v38, v15
	v_sub_f32_e32 v15, v38, v15
	v_add_f32_e32 v38, v33, v14
	v_sub_f32_e32 v14, v33, v14
	v_add_f32_e32 v33, v36, v17
	v_sub_f32_e32 v17, v36, v17
	v_add_f32_e32 v36, v34, v13
	v_sub_f32_e32 v13, v34, v13
	v_add_f32_e32 v34, v26, v10
	v_sub_f32_e32 v10, v26, v10
	v_add_f32_e32 v26, v12, v27
	v_sub_f32_e32 v12, v12, v27
	v_add_f32_e32 v27, v22, v35
	ds_bpermute_b32 v43, v7, v27
	v_sub_f32_e32 v22, v22, v35
	v_add_f32_e32 v35, v29, v39
	v_sub_f32_e32 v29, v29, v39
	v_add_f32_e32 v39, v32, v41
	v_sub_f32_e32 v32, v32, v41
	v_add_f32_e32 v41, v30, v38
	s_waitcnt lgkmcnt(0)
	v_fmac_f32_e32 v43, v27, v1
	ds_bpermute_b32 v27, v7, v41
	v_sub_f32_e32 v30, v30, v38
	v_add_f32_e32 v38, v24, v33
	v_sub_f32_e32 v24, v24, v33
	v_add_f32_e32 v33, v28, v36
	v_sub_f32_e32 v28, v28, v36
	v_add_f32_e32 v36, v25, v34
	v_sub_f32_e32 v25, v25, v34
	v_add_f32_e32 v34, v16, v31
	v_sub_f32_e32 v16, v16, v31
	v_add_f32_e32 v31, v20, v37
	v_sub_f32_e32 v20, v20, v37
	v_add_f32_e32 v37, v23, v40
	v_sub_f32_e32 v23, v23, v40
	v_add_f32_e32 v40, v21, v15
	s_waitcnt lgkmcnt(0)
	v_fmac_f32_e32 v27, v41, v1
	ds_bpermute_b32 v41, v7, v40
	ds_bpermute_b32 v42, v7, v26
	v_sub_f32_e32 v15, v21, v15
	v_add_f32_e32 v21, v18, v14
	v_sub_f32_e32 v14, v18, v14
	s_waitcnt lgkmcnt(1)
	v_fmac_f32_e32 v41, v40, v1
	ds_bpermute_b32 v40, v7, v12
	s_waitcnt lgkmcnt(1)
	v_fmac_f32_e32 v42, v26, v1
	ds_bpermute_b32 v26, v7, v39
	v_add_f32_e32 v18, v19, v17
	v_sub_f32_e32 v17, v19, v17
	v_add_f32_e32 v19, v11, v13
	v_sub_f32_e32 v11, v11, v13
	v_add_f32_e32 v13, v9, v10
	v_sub_f32_e32 v9, v9, v10
	ds_bpermute_b32 v10, v7, v35
	ds_bpermute_b32 v45, v7, v33
	ds_bpermute_b32 v44, v7, v38
	s_waitcnt lgkmcnt(4)
	v_fmac_f32_e32 v40, v12, v1
	ds_bpermute_b32 v12, v7, v22
	s_waitcnt lgkmcnt(4)
	v_fmac_f32_e32 v26, v39, v1
	ds_bpermute_b32 v39, v7, v37
	s_waitcnt lgkmcnt(4)
	v_fmac_f32_e32 v10, v35, v1
	s_waitcnt lgkmcnt(3)
	v_fmac_f32_e32 v45, v33, v1
	ds_bpermute_b32 v33, v7, v36
	ds_bpermute_b32 v35, v7, v34
	s_waitcnt lgkmcnt(4)
	v_fmac_f32_e32 v44, v38, v1
	ds_bpermute_b32 v38, v7, v31
	s_waitcnt lgkmcnt(4)
	v_fmac_f32_e32 v12, v22, v1
	ds_bpermute_b32 v22, v7, v28
	s_waitcnt lgkmcnt(4)
	v_fmac_f32_e32 v39, v37, v1
	ds_bpermute_b32 v37, v7, v13
	s_waitcnt lgkmcnt(4)
	v_fmac_f32_e32 v33, v36, v1
	s_waitcnt lgkmcnt(3)
	v_fmac_f32_e32 v35, v34, v1
	ds_bpermute_b32 v34, v7, v18
	ds_bpermute_b32 v36, v7, v19
	s_waitcnt lgkmcnt(4)
	v_fmac_f32_e32 v38, v31, v1
	ds_bpermute_b32 v31, v7, v21
	s_waitcnt lgkmcnt(4)
	v_fmac_f32_e32 v22, v28, v1
	ds_bpermute_b32 v28, v7, v9
	s_waitcnt lgkmcnt(4)
	v_fmac_f32_e32 v37, v13, v1
	ds_bpermute_b32 v13, v7, v29
	s_waitcnt lgkmcnt(4)
	v_fmac_f32_e32 v34, v18, v1
	s_waitcnt lgkmcnt(3)
	v_fmac_f32_e32 v36, v19, v1
	ds_bpermute_b32 v18, v7, v32
	ds_bpermute_b32 v19, v7, v30
	s_waitcnt lgkmcnt(4)
	v_fmac_f32_e32 v31, v21, v1
	ds_bpermute_b32 v21, v7, v24
	s_waitcnt lgkmcnt(4)
	v_fmac_f32_e32 v28, v9, v1
	v_max3_f32 v9, |v42|, 0, |v43|
	v_max3_f32 v9, v9, |v10|, |v26|
	s_waitcnt lgkmcnt(3)
	v_fmac_f32_e32 v13, v29, v1
	ds_bpermute_b32 v29, v7, v16
	v_max3_f32 v9, v9, |v27|, |v44|
	s_waitcnt lgkmcnt(3)
	v_fmac_f32_e32 v18, v32, v1
	s_waitcnt lgkmcnt(2)
	v_fmac_f32_e32 v19, v30, v1
	ds_bpermute_b32 v30, v7, v20
	ds_bpermute_b32 v32, v7, v23
	v_max3_f32 v9, v9, |v45|, |v33|
	s_waitcnt lgkmcnt(3)
	v_fmac_f32_e32 v21, v24, v1
	ds_bpermute_b32 v24, v7, v25
	v_max3_f32 v9, v9, |v35|, |v38|
	v_max3_f32 v9, v9, |v39|, |v41|
	v_max3_f32 v9, v9, |v31|, |v34|
	s_waitcnt lgkmcnt(3)
	v_fmac_f32_e32 v29, v16, v1
	ds_bpermute_b32 v16, v7, v15
	v_max3_f32 v9, v9, |v36|, |v37|
	s_waitcnt lgkmcnt(3)
	v_fmac_f32_e32 v30, v20, v1
	s_waitcnt lgkmcnt(2)
	v_fmac_f32_e32 v32, v23, v1
	ds_bpermute_b32 v20, v7, v14
	ds_bpermute_b32 v23, v7, v17
	v_max3_f32 v9, v9, |v40|, |v12|
	s_waitcnt lgkmcnt(3)
	v_fmac_f32_e32 v24, v25, v1
	ds_bpermute_b32 v25, v7, v11
	v_max3_f32 v9, v9, |v13|, |v18|
	v_max3_f32 v9, v9, |v19|, |v21|
	v_max3_f32 v9, v9, |v22|, |v24|
	s_waitcnt lgkmcnt(3)
	v_fmac_f32_e32 v16, v15, v1
	v_max3_f32 v9, v9, |v29|, |v30|
	s_waitcnt lgkmcnt(2)
	v_fmac_f32_e32 v20, v14, v1
	s_waitcnt lgkmcnt(1)
	v_fmac_f32_e32 v23, v17, v1
	v_max3_f32 v9, v9, |v32|, |v16|
	s_waitcnt lgkmcnt(0)
	v_fmac_f32_e32 v25, v11, v1
	v_max3_f32 v9, v9, |v20|, |v23|
	v_max3_f32 v9, v9, |v25|, |v28|
	ds_bpermute_b32 v10, v7, v9
	s_and_saveexec_b64 s[6:7], s[4:5]
	s_cbranch_execz .LBB0_1445
	s_waitcnt lgkmcnt(0)
	v_max_f32_e32 v10, v10, v10
	v_max_f32_e32 v9, v9, v9
	v_lshl_add_u64 v[12:13], s[16:17], 2, v[4:5]
	v_max_f32_e32 v9, v9, v10
	global_atomic_umax v[12:13], v9, off
	s_branch .LBB0_1445

.LBB0_1513:
	s_cmp_ge_i32 s40, s41
	s_cselect_b64 s[28:29], -1, 0
	s_cmp_lt_i32 s40, s41
	s_cselect_b64 s[0:1], -1, 0
	s_or_b64 vcc, s[18:19], s[0:1]
	v_cndmask_b32_e32 v100, 0, v100, vcc
	s_nor_b64 s[36:37], vcc, s[4:5]
	s_and_saveexec_b64 s[0:1], s[36:37]
	s_cbranch_execz .LBB0_1517
	s_mov_b64 s[38:39], exec
	v_mbcnt_lo_u32_b32 v2, s38, 0
	v_mbcnt_hi_u32_b32 v2, s39, v2
	v_cmp_eq_u32_e32 vcc, 0, v2
	s_and_saveexec_b64 s[36:37], vcc
	s_cbranch_execz .LBB0_1516
	s_bcnt1_i32_b64 s27, s[38:39]
	v_mov_b32_e32 v3, s27
	global_atomic_add v223, v1, v3, s[24:25] sc0
.LBB0_1516:
	s_or_b64 exec, exec, s[36:37]
.LBB0_1517:
	s_or_b64 exec, exec, s[0:1]
	s_mul_hi_i32 s37, s26, 0x2b00
	s_mul_i32 s36, s26, 0x2b00
	v_lshl_add_u64 v[94:95], s[36:37], 1, v[90:91]
	v_add_co_u32_e32 v2, vcc, 0x1000, v94
	global_load_dwordx4 v[86:89], v[94:95], off
	global_load_dwordx4 v[82:85], v[94:95], off offset:1024
	global_load_dwordx4 v[78:81], v[94:95], off offset:2048
	global_load_dwordx4 v[74:77], v[94:95], off offset:3072
	v_addc_co_u32_e32 v3, vcc, 0, v95, vcc
	global_load_dwordx4 v[70:73], v[2:3], off
	global_load_dwordx4 v[66:69], v[2:3], off offset:1024
	global_load_dwordx4 v[62:65], v[2:3], off offset:2048
	global_load_dwordx4 v[58:61], v[2:3], off offset:3072
	v_add_co_u32_e32 v2, vcc, 0x2000, v94
	v_mov_b32_e32 v4, 0
	s_nop 0
	v_addc_co_u32_e32 v3, vcc, 0, v95, vcc
	global_load_dwordx4 v[54:57], v[2:3], off
	global_load_dwordx4 v[50:53], v[2:3], off offset:1024
	global_load_dwordx4 v[46:49], v[2:3], off offset:2048
	global_load_dwordx4 v[42:45], v[2:3], off offset:3072
	v_add_co_u32_e32 v2, vcc, 0x3000, v94
	v_mov_b32_e32 v5, 0
	s_nop 0
	v_addc_co_u32_e32 v3, vcc, 0, v95, vcc
	global_load_dwordx4 v[38:41], v[2:3], off
	global_load_dwordx4 v[34:37], v[2:3], off offset:1024
	global_load_dwordx4 v[30:33], v[2:3], off offset:2048
	global_load_dwordx4 v[26:29], v[2:3], off offset:3072
	v_add_co_u32_e32 v2, vcc, 0x4000, v94
	s_nop 1
	v_addc_co_u32_e32 v3, vcc, 0, v95, vcc
	global_load_dwordx4 v[22:25], v[2:3], off
	global_load_dwordx4 v[18:21], v[2:3], off offset:1024
	global_load_dwordx4 v[14:17], v[2:3], off offset:2048
	global_load_dwordx4 v[10:13], v[2:3], off offset:3072
	v_add_co_u32_e32 v2, vcc, 0x5000, v94
	s_nop 1
	v_addc_co_u32_e32 v3, vcc, 0, v95, vcc
	global_load_dwordx4 v[6:9], v[2:3], off
	v_mov_b32_e32 v2, 0
	v_mov_b32_e32 v3, 0
	s_and_saveexec_b64 s[0:1], s[6:7]
	s_cbranch_execz .LBB0_1519
	v_add_co_u32_e32 v2, vcc, 0x5000, v94
	s_nop 1
	v_addc_co_u32_e32 v3, vcc, 0, v95, vcc
	global_load_dwordx4 v[2:5], v[2:3], off offset:1024
.LBB0_1519:
	s_or_b64 exec, exec, s[0:1]
	s_waitcnt vmcnt(0)
	v_readfirstlane_b32 s98, v223
	s_nop 1
	v_mov_b32_e32 v100, s98
	v_lshlrev_b32_e32 v94, 16, v86
	v_and_b32_e32 v86, 0xffff0000, v86
	v_lshlrev_b32_e32 v95, 16, v87
	v_and_b32_e32 v87, 0xffff0000, v87
	v_lshlrev_b32_e32 v101, 16, v88
	v_and_b32_e32 v88, 0xffff0000, v88
	v_lshlrev_b32_e32 v102, 16, v89
	v_and_b32_e32 v89, 0xffff0000, v89
	v_add_f32_e32 v103, v94, v86
	v_sub_f32_e32 v86, v94, v86
	v_add_f32_e32 v94, v95, v87
	v_sub_f32_e32 v87, v95, v87
	v_add_f32_e32 v95, v101, v88
	v_sub_f32_e32 v88, v101, v88
	v_add_f32_e32 v101, v102, v89
	v_sub_f32_e32 v89, v102, v89
	v_add_f32_e32 v102, v103, v94
	v_sub_f32_e32 v94, v103, v94
	v_add_f32_e32 v103, v86, v87
	v_sub_f32_e32 v86, v86, v87
	v_add_f32_e32 v87, v95, v101
	v_sub_f32_e32 v95, v95, v101
	v_add_f32_e32 v101, v88, v89
	v_sub_f32_e32 v88, v88, v89
	v_add_f32_e32 v89, v102, v87
	v_sub_f32_e32 v87, v102, v87
	v_add_f32_e32 v102, v103, v101
	v_sub_f32_e32 v101, v103, v101
	v_add_f32_e32 v103, v94, v95
	v_sub_f32_e32 v94, v94, v95
	v_add_f32_e32 v95, v86, v88
	v_sub_f32_e32 v86, v86, v88
	v_mov_b32_dpp v88, v89 quad_perm:[1,0,3,2] row_mask:0xf bank_mask:0xf bound_ctrl:1
	v_fmac_f32_e32 v88, v89, v96
	v_mov_b32_dpp v89, v102 quad_perm:[1,0,3,2] row_mask:0xf bank_mask:0xf bound_ctrl:1
	v_fmac_f32_e32 v89, v102, v96
	v_mov_b32_dpp v102, v103 quad_perm:[1,0,3,2] row_mask:0xf bank_mask:0xf bound_ctrl:1
	v_fmac_f32_e32 v102, v103, v96
	v_mov_b32_dpp v103, v95 quad_perm:[1,0,3,2] row_mask:0xf bank_mask:0xf bound_ctrl:1
	v_fmac_f32_e32 v103, v95, v96
	v_mov_b32_dpp v95, v87 quad_perm:[1,0,3,2] row_mask:0xf bank_mask:0xf bound_ctrl:1
	v_fmac_f32_e32 v95, v87, v96
	v_mov_b32_dpp v87, v101 quad_perm:[1,0,3,2] row_mask:0xf bank_mask:0xf bound_ctrl:1
	v_fmac_f32_e32 v87, v101, v96
	v_mov_b32_dpp v101, v94 quad_perm:[1,0,3,2] row_mask:0xf bank_mask:0xf bound_ctrl:1
	v_fmac_f32_e32 v101, v94, v96
	v_mov_b32_dpp v94, v86 quad_perm:[1,0,3,2] row_mask:0xf bank_mask:0xf bound_ctrl:1
	v_fmac_f32_e32 v94, v86, v96
	v_mov_b32_dpp v86, v88 quad_perm:[2,3,0,1] row_mask:0xf bank_mask:0xf bound_ctrl:1
	v_fmac_f32_e32 v86, v88, v97
	v_mov_b32_dpp v88, v89 quad_perm:[2,3,0,1] row_mask:0xf bank_mask:0xf bound_ctrl:1
	v_fmac_f32_e32 v88, v89, v97
	v_mov_b32_dpp v89, v102 quad_perm:[2,3,0,1] row_mask:0xf bank_mask:0xf bound_ctrl:1
	v_fmac_f32_e32 v89, v102, v97
	v_mov_b32_dpp v102, v103 quad_perm:[2,3,0,1] row_mask:0xf bank_mask:0xf bound_ctrl:1
	v_fmac_f32_e32 v102, v103, v97
	v_mov_b32_dpp v103, v95 quad_perm:[2,3,0,1] row_mask:0xf bank_mask:0xf bound_ctrl:1
	v_fmac_f32_e32 v103, v95, v97
	v_mov_b32_dpp v95, v87 quad_perm:[2,3,0,1] row_mask:0xf bank_mask:0xf bound_ctrl:1
	v_mov_b32_dpp v106, v94 quad_perm:[2,3,0,1] row_mask:0xf bank_mask:0xf bound_ctrl:1
	v_fmac_f32_e32 v95, v87, v97
	v_fmac_f32_e32 v106, v94, v97
	ds_swizzle_b32 v94, v102 offset:swizzle(SWAP,4)
	ds_swizzle_b32 v107, v103 offset:swizzle(SWAP,4)
	ds_swizzle_b32 v108, v95 offset:swizzle(SWAP,4)
	ds_swizzle_b32 v110, v106 offset:swizzle(SWAP,4)
	v_mov_b32_dpp v87, v101 quad_perm:[2,3,0,1] row_mask:0xf bank_mask:0xf bound_ctrl:1
	s_waitcnt lgkmcnt(3)
	v_fmac_f32_e32 v94, v102, v98
	s_waitcnt lgkmcnt(2)
	v_fmac_f32_e32 v107, v103, v98
	s_waitcnt lgkmcnt(1)
	v_fmac_f32_e32 v108, v95, v98
	s_waitcnt lgkmcnt(0)
	v_fmac_f32_e32 v110, v106, v98
	v_lshlrev_b32_e32 v95, 16, v82
	v_and_b32_e32 v82, 0xffff0000, v82
	v_lshlrev_b32_e32 v102, 16, v83
	v_and_b32_e32 v83, 0xffff0000, v83
	v_lshlrev_b32_e32 v103, 16, v84
	v_and_b32_e32 v84, 0xffff0000, v84
	v_lshlrev_b32_e32 v106, 16, v85
	v_and_b32_e32 v85, 0xffff0000, v85
	v_add_f32_e32 v111, v95, v82
	v_sub_f32_e32 v82, v95, v82
	v_add_f32_e32 v95, v102, v83
	v_sub_f32_e32 v83, v102, v83
	v_add_f32_e32 v102, v103, v84
	v_sub_f32_e32 v84, v103, v84
	v_add_f32_e32 v103, v106, v85
	v_sub_f32_e32 v85, v106, v85
	v_add_f32_e32 v106, v111, v95
	v_sub_f32_e32 v95, v111, v95
	v_add_f32_e32 v111, v82, v83
	v_sub_f32_e32 v82, v82, v83
	v_add_f32_e32 v83, v102, v103
	v_sub_f32_e32 v102, v102, v103
	v_add_f32_e32 v103, v84, v85
	v_sub_f32_e32 v84, v84, v85
	v_add_f32_e32 v85, v106, v83
	v_sub_f32_e32 v83, v106, v83
	v_add_f32_e32 v106, v111, v103
	v_sub_f32_e32 v103, v111, v103
	v_add_f32_e32 v111, v95, v102
	v_sub_f32_e32 v95, v95, v102
	v_add_f32_e32 v102, v82, v84
	v_sub_f32_e32 v82, v82, v84
	v_mov_b32_dpp v84, v85 quad_perm:[1,0,3,2] row_mask:0xf bank_mask:0xf bound_ctrl:1
	v_fmac_f32_e32 v84, v85, v96
	v_mov_b32_dpp v85, v106 quad_perm:[1,0,3,2] row_mask:0xf bank_mask:0xf bound_ctrl:1
	v_fmac_f32_e32 v85, v106, v96
	v_mov_b32_dpp v106, v111 quad_perm:[1,0,3,2] row_mask:0xf bank_mask:0xf bound_ctrl:1
	v_fmac_f32_e32 v106, v111, v96
	v_mov_b32_dpp v111, v102 quad_perm:[1,0,3,2] row_mask:0xf bank_mask:0xf bound_ctrl:1
	v_fmac_f32_e32 v111, v102, v96
	v_mov_b32_dpp v102, v83 quad_perm:[1,0,3,2] row_mask:0xf bank_mask:0xf bound_ctrl:1
	v_fmac_f32_e32 v102, v83, v96
	v_mov_b32_dpp v83, v103 quad_perm:[1,0,3,2] row_mask:0xf bank_mask:0xf bound_ctrl:1
	v_fmac_f32_e32 v83, v103, v96
	v_mov_b32_dpp v103, v95 quad_perm:[1,0,3,2] row_mask:0xf bank_mask:0xf bound_ctrl:1
	v_fmac_f32_e32 v103, v95, v96
	v_mov_b32_dpp v95, v82 quad_perm:[1,0,3,2] row_mask:0xf bank_mask:0xf bound_ctrl:1
	v_fmac_f32_e32 v95, v82, v96
	v_mov_b32_dpp v82, v84 quad_perm:[2,3,0,1] row_mask:0xf bank_mask:0xf bound_ctrl:1
	v_fmac_f32_e32 v82, v84, v97
	v_mov_b32_dpp v84, v85 quad_perm:[2,3,0,1] row_mask:0xf bank_mask:0xf bound_ctrl:1
	v_fmac_f32_e32 v84, v85, v97
	v_mov_b32_dpp v85, v106 quad_perm:[2,3,0,1] row_mask:0xf bank_mask:0xf bound_ctrl:1
	v_fmac_f32_e32 v85, v106, v97
	v_mov_b32_dpp v106, v111 quad_perm:[2,3,0,1] row_mask:0xf bank_mask:0xf bound_ctrl:1
	v_fmac_f32_e32 v106, v111, v97
	v_mov_b32_dpp v111, v102 quad_perm:[2,3,0,1] row_mask:0xf bank_mask:0xf bound_ctrl:1
	v_fmac_f32_e32 v111, v102, v97
	v_mov_b32_dpp v102, v83 quad_perm:[2,3,0,1] row_mask:0xf bank_mask:0xf bound_ctrl:1
	v_mov_b32_dpp v114, v95 quad_perm:[2,3,0,1] row_mask:0xf bank_mask:0xf bound_ctrl:1
	v_fmac_f32_e32 v102, v83, v97
	v_fmac_f32_e32 v114, v95, v97
	ds_swizzle_b32 v95, v106 offset:swizzle(SWAP,4)
	ds_swizzle_b32 v115, v111 offset:swizzle(SWAP,4)
	ds_swizzle_b32 v116, v102 offset:swizzle(SWAP,4)
	ds_swizzle_b32 v118, v114 offset:swizzle(SWAP,4)
	v_fmac_f32_e32 v87, v101, v97
	s_waitcnt lgkmcnt(3)
	v_fmac_f32_e32 v95, v106, v98
	s_waitcnt lgkmcnt(2)
	v_fmac_f32_e32 v115, v111, v98
	s_waitcnt lgkmcnt(1)
	v_fmac_f32_e32 v116, v102, v98
	s_waitcnt lgkmcnt(0)
	v_fmac_f32_e32 v118, v114, v98
	v_lshlrev_b32_e32 v102, 16, v78
	v_and_b32_e32 v78, 0xffff0000, v78
	v_lshlrev_b32_e32 v106, 16, v79
	v_and_b32_e32 v79, 0xffff0000, v79
	v_lshlrev_b32_e32 v111, 16, v80
	v_and_b32_e32 v80, 0xffff0000, v80
	v_lshlrev_b32_e32 v114, 16, v81
	v_and_b32_e32 v81, 0xffff0000, v81
	v_add_f32_e32 v119, v102, v78
	v_sub_f32_e32 v78, v102, v78
	v_add_f32_e32 v102, v106, v79
	v_sub_f32_e32 v79, v106, v79
	v_add_f32_e32 v106, v111, v80
	v_sub_f32_e32 v80, v111, v80
	v_add_f32_e32 v111, v114, v81
	v_sub_f32_e32 v81, v114, v81
	v_add_f32_e32 v114, v119, v102
	v_sub_f32_e32 v102, v119, v102
	v_add_f32_e32 v119, v78, v79
	v_sub_f32_e32 v78, v78, v79
	v_add_f32_e32 v79, v106, v111
	v_sub_f32_e32 v106, v106, v111
	v_add_f32_e32 v111, v80, v81
	v_sub_f32_e32 v80, v80, v81
	v_add_f32_e32 v81, v114, v79
	v_sub_f32_e32 v79, v114, v79
	v_add_f32_e32 v114, v119, v111
	v_sub_f32_e32 v111, v119, v111
	v_add_f32_e32 v119, v102, v106
	v_sub_f32_e32 v102, v102, v106
	v_add_f32_e32 v106, v78, v80
	v_sub_f32_e32 v78, v78, v80
	v_mov_b32_dpp v80, v81 quad_perm:[1,0,3,2] row_mask:0xf bank_mask:0xf bound_ctrl:1
	v_fmac_f32_e32 v80, v81, v96
	v_mov_b32_dpp v81, v114 quad_perm:[1,0,3,2] row_mask:0xf bank_mask:0xf bound_ctrl:1
	v_fmac_f32_e32 v81, v114, v96
	v_mov_b32_dpp v114, v119 quad_perm:[1,0,3,2] row_mask:0xf bank_mask:0xf bound_ctrl:1
	v_fmac_f32_e32 v114, v119, v96
	v_mov_b32_dpp v119, v106 quad_perm:[1,0,3,2] row_mask:0xf bank_mask:0xf bound_ctrl:1
	v_fmac_f32_e32 v119, v106, v96
	v_mov_b32_dpp v106, v79 quad_perm:[1,0,3,2] row_mask:0xf bank_mask:0xf bound_ctrl:1
	v_fmac_f32_e32 v106, v79, v96
	v_mov_b32_dpp v79, v111 quad_perm:[1,0,3,2] row_mask:0xf bank_mask:0xf bound_ctrl:1
	v_fmac_f32_e32 v79, v111, v96
	v_mov_b32_dpp v111, v102 quad_perm:[1,0,3,2] row_mask:0xf bank_mask:0xf bound_ctrl:1
	v_fmac_f32_e32 v111, v102, v96
	v_mov_b32_dpp v102, v78 quad_perm:[1,0,3,2] row_mask:0xf bank_mask:0xf bound_ctrl:1
	v_fmac_f32_e32 v102, v78, v96
	v_mov_b32_dpp v78, v80 quad_perm:[2,3,0,1] row_mask:0xf bank_mask:0xf bound_ctrl:1
	v_fmac_f32_e32 v78, v80, v97
	v_mov_b32_dpp v80, v81 quad_perm:[2,3,0,1] row_mask:0xf bank_mask:0xf bound_ctrl:1
	ds_swizzle_b32 v101, v86 offset:swizzle(SWAP,4)
	ds_swizzle_b32 v104, v88 offset:swizzle(SWAP,4)
	ds_swizzle_b32 v105, v89 offset:swizzle(SWAP,4)
	v_fmac_f32_e32 v80, v81, v97
	v_mov_b32_dpp v81, v114 quad_perm:[2,3,0,1] row_mask:0xf bank_mask:0xf bound_ctrl:1
	ds_swizzle_b32 v109, v87 offset:swizzle(SWAP,4)
	v_mov_b32_dpp v83, v103 quad_perm:[2,3,0,1] row_mask:0xf bank_mask:0xf bound_ctrl:1
	v_fmac_f32_e32 v81, v114, v97
	v_mov_b32_dpp v114, v119 quad_perm:[2,3,0,1] row_mask:0xf bank_mask:0xf bound_ctrl:1
	v_fmac_f32_e32 v83, v103, v97
	ds_swizzle_b32 v103, v82 offset:swizzle(SWAP,4)
	ds_swizzle_b32 v112, v84 offset:swizzle(SWAP,4)
	v_fmac_f32_e32 v114, v119, v97
	v_mov_b32_dpp v119, v106 quad_perm:[2,3,0,1] row_mask:0xf bank_mask:0xf bound_ctrl:1
	ds_swizzle_b32 v117, v83 offset:swizzle(SWAP,4)
	v_fmac_f32_e32 v119, v106, v97
	v_mov_b32_dpp v106, v79 quad_perm:[2,3,0,1] row_mask:0xf bank_mask:0xf bound_ctrl:1
	ds_swizzle_b32 v113, v85 offset:swizzle(SWAP,4)
	v_fmac_f32_e32 v106, v79, v97
	v_mov_b32_dpp v79, v111 quad_perm:[2,3,0,1] row_mask:0xf bank_mask:0xf bound_ctrl:1
	v_mov_b32_dpp v122, v102 quad_perm:[2,3,0,1] row_mask:0xf bank_mask:0xf bound_ctrl:1
	s_waitcnt lgkmcnt(7)
	v_fmac_f32_e32 v101, v86, v98
	s_waitcnt lgkmcnt(6)
	v_fmac_f32_e32 v104, v88, v98
	s_waitcnt lgkmcnt(5)
	v_fmac_f32_e32 v105, v89, v98
	v_fmac_f32_e32 v79, v111, v97
	ds_swizzle_b32 v111, v78 offset:swizzle(SWAP,4)
	ds_swizzle_b32 v120, v80 offset:swizzle(SWAP,4)
	ds_swizzle_b32 v121, v81 offset:swizzle(SWAP,4)
	v_fmac_f32_e32 v122, v102, v97
	ds_swizzle_b32 v102, v114 offset:swizzle(SWAP,4)
	s_waitcnt lgkmcnt(8)
	v_fmac_f32_e32 v109, v87, v98
	v_cvt_pk_bf16_f32 v88, v101, v104
	v_cvt_pk_bf16_f32 v89, v105, v94
	v_max_f32_e64 v101, |v101|, |v104|
	v_max_f32_e64 v94, |v105|, |v94|
	s_waitcnt lgkmcnt(7)
	v_fmac_f32_e32 v103, v82, v98
	s_waitcnt lgkmcnt(6)
	v_fmac_f32_e32 v112, v84, v98
	v_max3_f32 v94, v101, 0, v94
	v_max_f32_e64 v101, |v109|, |v110|
	v_cvt_pk_bf16_f32 v86, v107, v108
	v_cvt_pk_bf16_f32 v87, v109, v110
	s_waitcnt lgkmcnt(5)
	v_fmac_f32_e32 v117, v83, v98
	v_cvt_pk_bf16_f32 v84, v103, v112
	v_max3_f32 v101, |v107|, |v108|, v101
	v_max_f32_e64 v103, |v103|, |v112|
	s_waitcnt lgkmcnt(4)
	v_fmac_f32_e32 v113, v85, v98
	v_max3_f32 v94, v94, v101, v103
	v_max_f32_e64 v101, |v117|, |v118|
	v_cvt_pk_bf16_f32 v85, v113, v95
	s_waitcnt lgkmcnt(3)
	v_fmac_f32_e32 v111, v78, v98
	s_waitcnt lgkmcnt(2)
	v_fmac_f32_e32 v120, v80, v98
	s_waitcnt lgkmcnt(1)
	v_fmac_f32_e32 v121, v81, v98
	s_waitcnt lgkmcnt(0)
	v_fmac_f32_e32 v102, v114, v98
	v_max_f32_e64 v95, |v113|, |v95|
	v_max3_f32 v101, |v115|, |v116|, v101
	v_max3_f32 v94, v94, v95, v101
	v_max_f32_e64 v95, |v111|, |v120|
	v_max_f32_e64 v101, |v121|, |v102|
	v_cvt_pk_bf16_f32 v82, v115, v116
	v_cvt_pk_bf16_f32 v83, v117, v118
	v_cvt_pk_bf16_f32 v80, v111, v120
	v_cvt_pk_bf16_f32 v81, v121, v102
	v_max3_f32 v94, v94, v95, v101
	v_lshlrev_b32_e32 v101, 16, v74
	v_and_b32_e32 v74, 0xffff0000, v74
	v_lshlrev_b32_e32 v102, 16, v75
	v_and_b32_e32 v75, 0xffff0000, v75
	v_lshlrev_b32_e32 v103, 16, v76
	v_and_b32_e32 v76, 0xffff0000, v76
	v_lshlrev_b32_e32 v104, 16, v77
	v_and_b32_e32 v77, 0xffff0000, v77
	v_add_f32_e32 v105, v101, v74
	v_sub_f32_e32 v74, v101, v74
	v_add_f32_e32 v101, v102, v75
	v_sub_f32_e32 v75, v102, v75
	v_add_f32_e32 v102, v103, v76
	v_sub_f32_e32 v76, v103, v76
	v_add_f32_e32 v103, v104, v77
	v_sub_f32_e32 v77, v104, v77
	v_add_f32_e32 v104, v105, v101
	v_sub_f32_e32 v101, v105, v101
	v_add_f32_e32 v105, v74, v75
	v_sub_f32_e32 v74, v74, v75
	v_add_f32_e32 v75, v102, v103
	v_sub_f32_e32 v102, v102, v103
	v_add_f32_e32 v103, v76, v77
	v_sub_f32_e32 v76, v76, v77
	v_add_f32_e32 v77, v104, v75
	v_sub_f32_e32 v75, v104, v75
	v_add_f32_e32 v104, v105, v103
	v_sub_f32_e32 v103, v105, v103
	v_add_f32_e32 v105, v101, v102
	v_sub_f32_e32 v101, v101, v102
	v_add_f32_e32 v102, v74, v76
	v_sub_f32_e32 v74, v74, v76
	v_mov_b32_dpp v76, v77 quad_perm:[1,0,3,2] row_mask:0xf bank_mask:0xf bound_ctrl:1
	v_fmac_f32_e32 v76, v77, v96
	v_mov_b32_dpp v77, v104 quad_perm:[1,0,3,2] row_mask:0xf bank_mask:0xf bound_ctrl:1
	v_fmac_f32_e32 v77, v104, v96
	v_mov_b32_dpp v104, v105 quad_perm:[1,0,3,2] row_mask:0xf bank_mask:0xf bound_ctrl:1
	v_fmac_f32_e32 v104, v105, v96
	v_mov_b32_dpp v105, v102 quad_perm:[1,0,3,2] row_mask:0xf bank_mask:0xf bound_ctrl:1
	v_fmac_f32_e32 v105, v102, v96
	v_mov_b32_dpp v102, v75 quad_perm:[1,0,3,2] row_mask:0xf bank_mask:0xf bound_ctrl:1
	v_fmac_f32_e32 v102, v75, v96
	v_mov_b32_dpp v75, v103 quad_perm:[1,0,3,2] row_mask:0xf bank_mask:0xf bound_ctrl:1
	v_fmac_f32_e32 v75, v103, v96
	v_mov_b32_dpp v103, v101 quad_perm:[1,0,3,2] row_mask:0xf bank_mask:0xf bound_ctrl:1
	v_fmac_f32_e32 v103, v101, v96
	v_mov_b32_dpp v101, v74 quad_perm:[1,0,3,2] row_mask:0xf bank_mask:0xf bound_ctrl:1
	v_fmac_f32_e32 v101, v74, v96
	v_mov_b32_dpp v74, v76 quad_perm:[2,3,0,1] row_mask:0xf bank_mask:0xf bound_ctrl:1
	v_fmac_f32_e32 v74, v76, v97
	v_mov_b32_dpp v76, v77 quad_perm:[2,3,0,1] row_mask:0xf bank_mask:0xf bound_ctrl:1
	ds_swizzle_b32 v124, v106 offset:swizzle(SWAP,4)
	v_fmac_f32_e32 v76, v77, v97
	v_mov_b32_dpp v77, v104 quad_perm:[2,3,0,1] row_mask:0xf bank_mask:0xf bound_ctrl:1
	v_fmac_f32_e32 v77, v104, v97
	v_mov_b32_dpp v104, v105 quad_perm:[2,3,0,1] row_mask:0xf bank_mask:0xf bound_ctrl:1
	v_fmac_f32_e32 v104, v105, v97
	v_mov_b32_dpp v105, v102 quad_perm:[2,3,0,1] row_mask:0xf bank_mask:0xf bound_ctrl:1
	v_fmac_f32_e32 v105, v102, v97
	v_mov_b32_dpp v102, v75 quad_perm:[2,3,0,1] row_mask:0xf bank_mask:0xf bound_ctrl:1
	ds_swizzle_b32 v125, v79 offset:swizzle(SWAP,4)
	ds_swizzle_b32 v126, v122 offset:swizzle(SWAP,4)
	v_fmac_f32_e32 v102, v75, v97
	v_mov_b32_dpp v75, v103 quad_perm:[2,3,0,1] row_mask:0xf bank_mask:0xf bound_ctrl:1
	v_mov_b32_dpp v108, v101 quad_perm:[2,3,0,1] row_mask:0xf bank_mask:0xf bound_ctrl:1
	ds_swizzle_b32 v123, v119 offset:swizzle(SWAP,4)
	s_waitcnt lgkmcnt(3)
	v_fmac_f32_e32 v124, v106, v98
	v_fmac_f32_e32 v75, v103, v97
	ds_swizzle_b32 v103, v74 offset:swizzle(SWAP,4)
	ds_swizzle_b32 v106, v76 offset:swizzle(SWAP,4)
	v_fmac_f32_e32 v108, v101, v97
	ds_swizzle_b32 v107, v77 offset:swizzle(SWAP,4)
	ds_swizzle_b32 v101, v104 offset:swizzle(SWAP,4)
	ds_swizzle_b32 v110, v102 offset:swizzle(SWAP,4)
	ds_swizzle_b32 v111, v75 offset:swizzle(SWAP,4)
	ds_swizzle_b32 v112, v108 offset:swizzle(SWAP,4)
	ds_swizzle_b32 v109, v105 offset:swizzle(SWAP,4)
	s_waitcnt lgkmcnt(10)
	v_fmac_f32_e32 v125, v79, v98
	s_waitcnt lgkmcnt(9)
	v_fmac_f32_e32 v126, v122, v98
	s_waitcnt lgkmcnt(8)
	v_fmac_f32_e32 v123, v119, v98
	v_max_f32_e64 v95, |v125|, |v126|
	s_waitcnt lgkmcnt(7)
	v_fmac_f32_e32 v103, v74, v98
	s_waitcnt lgkmcnt(6)
	v_fmac_f32_e32 v106, v76, v98
	v_max3_f32 v95, |v123|, |v124|, v95
	s_waitcnt lgkmcnt(5)
	v_fmac_f32_e32 v107, v77, v98
	s_waitcnt lgkmcnt(4)
	v_fmac_f32_e32 v101, v104, v98
	s_waitcnt lgkmcnt(3)
	v_fmac_f32_e32 v110, v102, v98
	s_waitcnt lgkmcnt(2)
	v_fmac_f32_e32 v111, v75, v98
	s_waitcnt lgkmcnt(1)
	v_fmac_f32_e32 v112, v108, v98
	v_max_f32_e64 v102, |v103|, |v106|
	v_cvt_pk_bf16_f32 v78, v123, v124
	v_cvt_pk_bf16_f32 v79, v125, v126
	s_waitcnt lgkmcnt(0)
	v_fmac_f32_e32 v109, v105, v98
	v_cvt_pk_bf16_f32 v76, v103, v106
	v_cvt_pk_bf16_f32 v77, v107, v101
	v_max3_f32 v94, v94, v95, v102
	v_max_f32_e64 v95, |v107|, |v101|
	v_max_f32_e64 v101, |v111|, |v112|
	v_max3_f32 v101, |v109|, |v110|, v101
	v_max3_f32 v94, v94, v95, v101
	v_cvt_pk_bf16_f32 v74, v109, v110
	v_cvt_pk_bf16_f32 v75, v111, v112
	v_lshlrev_b32_e32 v95, 16, v70
	v_and_b32_e32 v70, 0xffff0000, v70
	v_lshlrev_b32_e32 v101, 16, v71
	v_and_b32_e32 v71, 0xffff0000, v71
	v_lshlrev_b32_e32 v102, 16, v72
	v_and_b32_e32 v72, 0xffff0000, v72
	v_lshlrev_b32_e32 v103, 16, v73
	v_and_b32_e32 v73, 0xffff0000, v73
	v_add_f32_e32 v104, v95, v70
	v_sub_f32_e32 v70, v95, v70
	v_add_f32_e32 v95, v101, v71
	v_sub_f32_e32 v71, v101, v71
	v_add_f32_e32 v101, v102, v72
	v_sub_f32_e32 v72, v102, v72
	v_add_f32_e32 v102, v103, v73
	v_sub_f32_e32 v73, v103, v73
	v_add_f32_e32 v103, v104, v95
	v_sub_f32_e32 v95, v104, v95
	v_add_f32_e32 v104, v70, v71
	v_sub_f32_e32 v70, v70, v71
	v_add_f32_e32 v71, v101, v102
	v_sub_f32_e32 v101, v101, v102
	v_add_f32_e32 v102, v72, v73
	v_sub_f32_e32 v72, v72, v73
	v_add_f32_e32 v73, v103, v71
	v_sub_f32_e32 v71, v103, v71
	v_add_f32_e32 v103, v104, v102
	v_sub_f32_e32 v102, v104, v102
	v_add_f32_e32 v104, v95, v101
	v_sub_f32_e32 v95, v95, v101
	v_add_f32_e32 v101, v70, v72
	v_sub_f32_e32 v70, v70, v72
	v_mov_b32_dpp v72, v73 quad_perm:[1,0,3,2] row_mask:0xf bank_mask:0xf bound_ctrl:1
	v_fmac_f32_e32 v72, v73, v96
	v_mov_b32_dpp v73, v103 quad_perm:[1,0,3,2] row_mask:0xf bank_mask:0xf bound_ctrl:1
	v_fmac_f32_e32 v73, v103, v96
	v_mov_b32_dpp v103, v104 quad_perm:[1,0,3,2] row_mask:0xf bank_mask:0xf bound_ctrl:1
	v_fmac_f32_e32 v103, v104, v96
	v_mov_b32_dpp v104, v101 quad_perm:[1,0,3,2] row_mask:0xf bank_mask:0xf bound_ctrl:1
	v_fmac_f32_e32 v104, v101, v96
	v_mov_b32_dpp v101, v71 quad_perm:[1,0,3,2] row_mask:0xf bank_mask:0xf bound_ctrl:1
	v_fmac_f32_e32 v101, v71, v96
	v_mov_b32_dpp v71, v102 quad_perm:[1,0,3,2] row_mask:0xf bank_mask:0xf bound_ctrl:1
	v_fmac_f32_e32 v71, v102, v96
	v_mov_b32_dpp v102, v95 quad_perm:[1,0,3,2] row_mask:0xf bank_mask:0xf bound_ctrl:1
	v_fmac_f32_e32 v102, v95, v96
	v_mov_b32_dpp v95, v70 quad_perm:[1,0,3,2] row_mask:0xf bank_mask:0xf bound_ctrl:1
	v_fmac_f32_e32 v95, v70, v96
	v_mov_b32_dpp v70, v72 quad_perm:[2,3,0,1] row_mask:0xf bank_mask:0xf bound_ctrl:1
	v_fmac_f32_e32 v70, v72, v97
	v_mov_b32_dpp v72, v73 quad_perm:[2,3,0,1] row_mask:0xf bank_mask:0xf bound_ctrl:1
	v_fmac_f32_e32 v72, v73, v97
	v_mov_b32_dpp v73, v103 quad_perm:[2,3,0,1] row_mask:0xf bank_mask:0xf bound_ctrl:1
	v_fmac_f32_e32 v73, v103, v97
	v_mov_b32_dpp v103, v104 quad_perm:[2,3,0,1] row_mask:0xf bank_mask:0xf bound_ctrl:1
	v_fmac_f32_e32 v103, v104, v97
	v_mov_b32_dpp v104, v101 quad_perm:[2,3,0,1] row_mask:0xf bank_mask:0xf bound_ctrl:1
	v_fmac_f32_e32 v104, v101, v97
	v_mov_b32_dpp v101, v71 quad_perm:[2,3,0,1] row_mask:0xf bank_mask:0xf bound_ctrl:1
	v_mov_b32_dpp v107, v95 quad_perm:[2,3,0,1] row_mask:0xf bank_mask:0xf bound_ctrl:1
	v_fmac_f32_e32 v101, v71, v97
	v_fmac_f32_e32 v107, v95, v97
	ds_swizzle_b32 v95, v103 offset:swizzle(SWAP,4)
	ds_swizzle_b32 v108, v104 offset:swizzle(SWAP,4)
	ds_swizzle_b32 v109, v101 offset:swizzle(SWAP,4)
	ds_swizzle_b32 v111, v107 offset:swizzle(SWAP,4)
	v_mov_b32_dpp v71, v102 quad_perm:[2,3,0,1] row_mask:0xf bank_mask:0xf bound_ctrl:1
	s_waitcnt lgkmcnt(3)
	v_fmac_f32_e32 v95, v103, v98
	s_waitcnt lgkmcnt(2)
	v_fmac_f32_e32 v108, v104, v98
	s_waitcnt lgkmcnt(1)
	v_fmac_f32_e32 v109, v101, v98
	s_waitcnt lgkmcnt(0)
	v_fmac_f32_e32 v111, v107, v98
	v_lshlrev_b32_e32 v101, 16, v66
	v_and_b32_e32 v66, 0xffff0000, v66
	v_lshlrev_b32_e32 v103, 16, v67
	v_and_b32_e32 v67, 0xffff0000, v67
	v_lshlrev_b32_e32 v104, 16, v68
	v_and_b32_e32 v68, 0xffff0000, v68
	v_lshlrev_b32_e32 v107, 16, v69
	v_and_b32_e32 v69, 0xffff0000, v69
	v_add_f32_e32 v112, v101, v66
	v_sub_f32_e32 v66, v101, v66
	v_add_f32_e32 v101, v103, v67
	v_sub_f32_e32 v67, v103, v67
	v_add_f32_e32 v103, v104, v68
	v_sub_f32_e32 v68, v104, v68
	v_add_f32_e32 v104, v107, v69
	v_sub_f32_e32 v69, v107, v69
	v_add_f32_e32 v107, v112, v101
	v_sub_f32_e32 v101, v112, v101
	v_add_f32_e32 v112, v66, v67
	v_sub_f32_e32 v66, v66, v67
	v_add_f32_e32 v67, v103, v104
	v_sub_f32_e32 v103, v103, v104
	v_add_f32_e32 v104, v68, v69
	v_sub_f32_e32 v68, v68, v69
	v_add_f32_e32 v69, v107, v67
	v_sub_f32_e32 v67, v107, v67
	v_add_f32_e32 v107, v112, v104
	v_sub_f32_e32 v104, v112, v104
	v_add_f32_e32 v112, v101, v103
	v_sub_f32_e32 v101, v101, v103
	v_add_f32_e32 v103, v66, v68
	v_sub_f32_e32 v66, v66, v68
	v_mov_b32_dpp v68, v69 quad_perm:[1,0,3,2] row_mask:0xf bank_mask:0xf bound_ctrl:1
	v_fmac_f32_e32 v68, v69, v96
	v_mov_b32_dpp v69, v107 quad_perm:[1,0,3,2] row_mask:0xf bank_mask:0xf bound_ctrl:1
	v_fmac_f32_e32 v69, v107, v96
	v_mov_b32_dpp v107, v112 quad_perm:[1,0,3,2] row_mask:0xf bank_mask:0xf bound_ctrl:1
	v_fmac_f32_e32 v107, v112, v96
	v_mov_b32_dpp v112, v103 quad_perm:[1,0,3,2] row_mask:0xf bank_mask:0xf bound_ctrl:1
	v_fmac_f32_e32 v112, v103, v96
	v_mov_b32_dpp v103, v67 quad_perm:[1,0,3,2] row_mask:0xf bank_mask:0xf bound_ctrl:1
	v_fmac_f32_e32 v103, v67, v96
	v_mov_b32_dpp v67, v104 quad_perm:[1,0,3,2] row_mask:0xf bank_mask:0xf bound_ctrl:1
	v_fmac_f32_e32 v67, v104, v96
	v_mov_b32_dpp v104, v101 quad_perm:[1,0,3,2] row_mask:0xf bank_mask:0xf bound_ctrl:1
	v_fmac_f32_e32 v104, v101, v96
	v_mov_b32_dpp v101, v66 quad_perm:[1,0,3,2] row_mask:0xf bank_mask:0xf bound_ctrl:1
	v_fmac_f32_e32 v101, v66, v96
	v_mov_b32_dpp v66, v68 quad_perm:[2,3,0,1] row_mask:0xf bank_mask:0xf bound_ctrl:1
	v_fmac_f32_e32 v66, v68, v97
	v_mov_b32_dpp v68, v69 quad_perm:[2,3,0,1] row_mask:0xf bank_mask:0xf bound_ctrl:1
	v_fmac_f32_e32 v68, v69, v97
	v_mov_b32_dpp v69, v107 quad_perm:[2,3,0,1] row_mask:0xf bank_mask:0xf bound_ctrl:1
	v_fmac_f32_e32 v69, v107, v97
	v_mov_b32_dpp v107, v112 quad_perm:[2,3,0,1] row_mask:0xf bank_mask:0xf bound_ctrl:1
	v_fmac_f32_e32 v107, v112, v97
	v_mov_b32_dpp v112, v103 quad_perm:[2,3,0,1] row_mask:0xf bank_mask:0xf bound_ctrl:1
	v_fmac_f32_e32 v112, v103, v97
	v_mov_b32_dpp v103, v67 quad_perm:[2,3,0,1] row_mask:0xf bank_mask:0xf bound_ctrl:1
	v_mov_b32_dpp v115, v101 quad_perm:[2,3,0,1] row_mask:0xf bank_mask:0xf bound_ctrl:1
	v_fmac_f32_e32 v103, v67, v97
	v_fmac_f32_e32 v115, v101, v97
	ds_swizzle_b32 v101, v107 offset:swizzle(SWAP,4)
	ds_swizzle_b32 v116, v112 offset:swizzle(SWAP,4)
	ds_swizzle_b32 v117, v103 offset:swizzle(SWAP,4)
	ds_swizzle_b32 v119, v115 offset:swizzle(SWAP,4)
	v_fmac_f32_e32 v71, v102, v97
	s_waitcnt lgkmcnt(3)
	v_fmac_f32_e32 v101, v107, v98
	s_waitcnt lgkmcnt(2)
	v_fmac_f32_e32 v116, v112, v98
	s_waitcnt lgkmcnt(1)
	v_fmac_f32_e32 v117, v103, v98
	s_waitcnt lgkmcnt(0)
	v_fmac_f32_e32 v119, v115, v98
	v_lshlrev_b32_e32 v103, 16, v62
	v_and_b32_e32 v62, 0xffff0000, v62
	v_lshlrev_b32_e32 v107, 16, v63
	v_and_b32_e32 v63, 0xffff0000, v63
	v_lshlrev_b32_e32 v112, 16, v64
	v_and_b32_e32 v64, 0xffff0000, v64
	v_lshlrev_b32_e32 v115, 16, v65
	v_and_b32_e32 v65, 0xffff0000, v65
	v_add_f32_e32 v120, v103, v62
	v_sub_f32_e32 v62, v103, v62
	v_add_f32_e32 v103, v107, v63
	v_sub_f32_e32 v63, v107, v63
	v_add_f32_e32 v107, v112, v64
	v_sub_f32_e32 v64, v112, v64
	v_add_f32_e32 v112, v115, v65
	v_sub_f32_e32 v65, v115, v65
	v_add_f32_e32 v115, v120, v103
	v_sub_f32_e32 v103, v120, v103
	v_add_f32_e32 v120, v62, v63
	v_sub_f32_e32 v62, v62, v63
	v_add_f32_e32 v63, v107, v112
	v_sub_f32_e32 v107, v107, v112
	v_add_f32_e32 v112, v64, v65
	v_sub_f32_e32 v64, v64, v65
	v_add_f32_e32 v65, v115, v63
	v_sub_f32_e32 v63, v115, v63
	v_add_f32_e32 v115, v120, v112
	v_sub_f32_e32 v112, v120, v112
	v_add_f32_e32 v120, v103, v107
	v_sub_f32_e32 v103, v103, v107
	v_add_f32_e32 v107, v62, v64
	v_sub_f32_e32 v62, v62, v64
	v_mov_b32_dpp v64, v65 quad_perm:[1,0,3,2] row_mask:0xf bank_mask:0xf bound_ctrl:1
	v_fmac_f32_e32 v64, v65, v96
	v_mov_b32_dpp v65, v115 quad_perm:[1,0,3,2] row_mask:0xf bank_mask:0xf bound_ctrl:1
	v_fmac_f32_e32 v65, v115, v96
	v_mov_b32_dpp v115, v120 quad_perm:[1,0,3,2] row_mask:0xf bank_mask:0xf bound_ctrl:1
	v_fmac_f32_e32 v115, v120, v96
	v_mov_b32_dpp v120, v107 quad_perm:[1,0,3,2] row_mask:0xf bank_mask:0xf bound_ctrl:1
	v_fmac_f32_e32 v120, v107, v96
	v_mov_b32_dpp v107, v63 quad_perm:[1,0,3,2] row_mask:0xf bank_mask:0xf bound_ctrl:1
	v_fmac_f32_e32 v107, v63, v96
	v_mov_b32_dpp v63, v112 quad_perm:[1,0,3,2] row_mask:0xf bank_mask:0xf bound_ctrl:1
	v_fmac_f32_e32 v63, v112, v96
	v_mov_b32_dpp v112, v103 quad_perm:[1,0,3,2] row_mask:0xf bank_mask:0xf bound_ctrl:1
	v_fmac_f32_e32 v112, v103, v96
	v_mov_b32_dpp v103, v62 quad_perm:[1,0,3,2] row_mask:0xf bank_mask:0xf bound_ctrl:1
	v_fmac_f32_e32 v103, v62, v96
	v_mov_b32_dpp v62, v64 quad_perm:[2,3,0,1] row_mask:0xf bank_mask:0xf bound_ctrl:1
	v_fmac_f32_e32 v62, v64, v97
	v_mov_b32_dpp v64, v65 quad_perm:[2,3,0,1] row_mask:0xf bank_mask:0xf bound_ctrl:1
	ds_swizzle_b32 v102, v70 offset:swizzle(SWAP,4)
	ds_swizzle_b32 v105, v72 offset:swizzle(SWAP,4)
	ds_swizzle_b32 v106, v73 offset:swizzle(SWAP,4)
	v_fmac_f32_e32 v64, v65, v97
	v_mov_b32_dpp v65, v115 quad_perm:[2,3,0,1] row_mask:0xf bank_mask:0xf bound_ctrl:1
	ds_swizzle_b32 v110, v71 offset:swizzle(SWAP,4)
	v_mov_b32_dpp v67, v104 quad_perm:[2,3,0,1] row_mask:0xf bank_mask:0xf bound_ctrl:1
	v_fmac_f32_e32 v65, v115, v97
	v_mov_b32_dpp v115, v120 quad_perm:[2,3,0,1] row_mask:0xf bank_mask:0xf bound_ctrl:1
	v_fmac_f32_e32 v67, v104, v97
	ds_swizzle_b32 v104, v66 offset:swizzle(SWAP,4)
	ds_swizzle_b32 v113, v68 offset:swizzle(SWAP,4)
	v_fmac_f32_e32 v115, v120, v97
	v_mov_b32_dpp v120, v107 quad_perm:[2,3,0,1] row_mask:0xf bank_mask:0xf bound_ctrl:1
	ds_swizzle_b32 v114, v69 offset:swizzle(SWAP,4)
	ds_swizzle_b32 v118, v67 offset:swizzle(SWAP,4)
	v_fmac_f32_e32 v120, v107, v97
	v_mov_b32_dpp v107, v63 quad_perm:[2,3,0,1] row_mask:0xf bank_mask:0xf bound_ctrl:1
	v_fmac_f32_e32 v107, v63, v97
	v_mov_b32_dpp v63, v112 quad_perm:[2,3,0,1] row_mask:0xf bank_mask:0xf bound_ctrl:1
	v_mov_b32_dpp v123, v103 quad_perm:[2,3,0,1] row_mask:0xf bank_mask:0xf bound_ctrl:1
	s_waitcnt lgkmcnt(7)
	v_fmac_f32_e32 v102, v70, v98
	s_waitcnt lgkmcnt(6)
	v_fmac_f32_e32 v105, v72, v98
	s_waitcnt lgkmcnt(5)
	v_fmac_f32_e32 v106, v73, v98
	v_fmac_f32_e32 v63, v112, v97
	ds_swizzle_b32 v112, v62 offset:swizzle(SWAP,4)
	ds_swizzle_b32 v121, v64 offset:swizzle(SWAP,4)
	ds_swizzle_b32 v122, v65 offset:swizzle(SWAP,4)
	v_fmac_f32_e32 v123, v103, v97
	ds_swizzle_b32 v103, v115 offset:swizzle(SWAP,4)
	s_waitcnt lgkmcnt(8)
	v_fmac_f32_e32 v110, v71, v98
	v_cvt_pk_bf16_f32 v72, v102, v105
	v_cvt_pk_bf16_f32 v73, v106, v95
	v_max_f32_e64 v102, |v102|, |v105|
	v_max_f32_e64 v95, |v106|, |v95|
	s_waitcnt lgkmcnt(7)
	v_fmac_f32_e32 v104, v66, v98
	s_waitcnt lgkmcnt(6)
	v_fmac_f32_e32 v113, v68, v98
	v_max3_f32 v94, v94, v102, v95
	v_max_f32_e64 v95, |v110|, |v111|
	s_waitcnt lgkmcnt(5)
	v_fmac_f32_e32 v114, v69, v98
	s_waitcnt lgkmcnt(4)
	v_fmac_f32_e32 v118, v67, v98
	v_max3_f32 v95, |v108|, |v109|, v95
	v_max_f32_e64 v102, |v104|, |v113|
	v_cvt_pk_bf16_f32 v70, v108, v109
	v_cvt_pk_bf16_f32 v71, v110, v111
	v_cvt_pk_bf16_f32 v68, v104, v113
	v_cvt_pk_bf16_f32 v69, v114, v101
	v_max3_f32 v94, v94, v95, v102
	v_max_f32_e64 v95, |v114|, |v101|
	v_max_f32_e64 v101, |v118|, |v119|
	s_waitcnt lgkmcnt(3)
	v_fmac_f32_e32 v112, v62, v98
	s_waitcnt lgkmcnt(2)
	v_fmac_f32_e32 v121, v64, v98
	s_waitcnt lgkmcnt(1)
	v_fmac_f32_e32 v122, v65, v98
	s_waitcnt lgkmcnt(0)
	v_fmac_f32_e32 v103, v115, v98
	v_max3_f32 v101, |v116|, |v117|, v101
	v_max3_f32 v94, v94, v95, v101
	v_max_f32_e64 v95, |v112|, |v121|
	v_max_f32_e64 v101, |v122|, |v103|
	v_cvt_pk_bf16_f32 v66, v116, v117
	v_cvt_pk_bf16_f32 v67, v118, v119
	v_cvt_pk_bf16_f32 v64, v112, v121
	v_cvt_pk_bf16_f32 v65, v122, v103
	v_max3_f32 v94, v94, v95, v101
	v_lshlrev_b32_e32 v101, 16, v58
	v_and_b32_e32 v58, 0xffff0000, v58
	v_lshlrev_b32_e32 v102, 16, v59
	v_and_b32_e32 v59, 0xffff0000, v59
	v_lshlrev_b32_e32 v103, 16, v60
	v_and_b32_e32 v60, 0xffff0000, v60
	v_lshlrev_b32_e32 v104, 16, v61
	v_and_b32_e32 v61, 0xffff0000, v61
	v_add_f32_e32 v105, v101, v58
	v_sub_f32_e32 v58, v101, v58
	v_add_f32_e32 v101, v102, v59
	v_sub_f32_e32 v59, v102, v59
	v_add_f32_e32 v102, v103, v60
	v_sub_f32_e32 v60, v103, v60
	v_add_f32_e32 v103, v104, v61
	v_sub_f32_e32 v61, v104, v61
	v_add_f32_e32 v104, v105, v101
	v_sub_f32_e32 v101, v105, v101
	v_add_f32_e32 v105, v58, v59
	v_sub_f32_e32 v58, v58, v59
	v_add_f32_e32 v59, v102, v103
	v_sub_f32_e32 v102, v102, v103
	v_add_f32_e32 v103, v60, v61
	v_sub_f32_e32 v60, v60, v61
	v_add_f32_e32 v61, v104, v59
	v_sub_f32_e32 v59, v104, v59
	v_add_f32_e32 v104, v105, v103
	v_sub_f32_e32 v103, v105, v103
	v_add_f32_e32 v105, v101, v102
	v_sub_f32_e32 v101, v101, v102
	v_add_f32_e32 v102, v58, v60
	v_sub_f32_e32 v58, v58, v60
	v_mov_b32_dpp v60, v61 quad_perm:[1,0,3,2] row_mask:0xf bank_mask:0xf bound_ctrl:1
	v_fmac_f32_e32 v60, v61, v96
	v_mov_b32_dpp v61, v104 quad_perm:[1,0,3,2] row_mask:0xf bank_mask:0xf bound_ctrl:1
	v_fmac_f32_e32 v61, v104, v96
	v_mov_b32_dpp v104, v105 quad_perm:[1,0,3,2] row_mask:0xf bank_mask:0xf bound_ctrl:1
	v_fmac_f32_e32 v104, v105, v96
	v_mov_b32_dpp v105, v102 quad_perm:[1,0,3,2] row_mask:0xf bank_mask:0xf bound_ctrl:1
	v_fmac_f32_e32 v105, v102, v96
	v_mov_b32_dpp v102, v59 quad_perm:[1,0,3,2] row_mask:0xf bank_mask:0xf bound_ctrl:1
	v_fmac_f32_e32 v102, v59, v96
	v_mov_b32_dpp v59, v103 quad_perm:[1,0,3,2] row_mask:0xf bank_mask:0xf bound_ctrl:1
	v_fmac_f32_e32 v59, v103, v96
	v_mov_b32_dpp v103, v101 quad_perm:[1,0,3,2] row_mask:0xf bank_mask:0xf bound_ctrl:1
	v_fmac_f32_e32 v103, v101, v96
	v_mov_b32_dpp v101, v58 quad_perm:[1,0,3,2] row_mask:0xf bank_mask:0xf bound_ctrl:1
	v_fmac_f32_e32 v101, v58, v96
	v_mov_b32_dpp v58, v60 quad_perm:[2,3,0,1] row_mask:0xf bank_mask:0xf bound_ctrl:1
	v_fmac_f32_e32 v58, v60, v97
	v_mov_b32_dpp v60, v61 quad_perm:[2,3,0,1] row_mask:0xf bank_mask:0xf bound_ctrl:1
	v_fmac_f32_e32 v60, v61, v97
	v_mov_b32_dpp v61, v104 quad_perm:[2,3,0,1] row_mask:0xf bank_mask:0xf bound_ctrl:1
	ds_swizzle_b32 v125, v107 offset:swizzle(SWAP,4)
	v_fmac_f32_e32 v61, v104, v97
	v_mov_b32_dpp v104, v105 quad_perm:[2,3,0,1] row_mask:0xf bank_mask:0xf bound_ctrl:1
	v_fmac_f32_e32 v104, v105, v97
	v_mov_b32_dpp v105, v102 quad_perm:[2,3,0,1] row_mask:0xf bank_mask:0xf bound_ctrl:1
	v_fmac_f32_e32 v105, v102, v97
	v_mov_b32_dpp v102, v59 quad_perm:[2,3,0,1] row_mask:0xf bank_mask:0xf bound_ctrl:1
	ds_swizzle_b32 v126, v63 offset:swizzle(SWAP,4)
	ds_swizzle_b32 v127, v123 offset:swizzle(SWAP,4)
	v_fmac_f32_e32 v102, v59, v97
	v_mov_b32_dpp v59, v103 quad_perm:[2,3,0,1] row_mask:0xf bank_mask:0xf bound_ctrl:1
	v_mov_b32_dpp v108, v101 quad_perm:[2,3,0,1] row_mask:0xf bank_mask:0xf bound_ctrl:1
	ds_swizzle_b32 v124, v120 offset:swizzle(SWAP,4)
	v_fmac_f32_e32 v59, v103, v97
	ds_swizzle_b32 v103, v58 offset:swizzle(SWAP,4)
	ds_swizzle_b32 v106, v60 offset:swizzle(SWAP,4)
	v_fmac_f32_e32 v108, v101, v97
	s_waitcnt lgkmcnt(5)
	v_fmac_f32_e32 v125, v107, v98
	ds_swizzle_b32 v107, v61 offset:swizzle(SWAP,4)
	ds_swizzle_b32 v101, v104 offset:swizzle(SWAP,4)
	ds_swizzle_b32 v110, v102 offset:swizzle(SWAP,4)
	ds_swizzle_b32 v111, v59 offset:swizzle(SWAP,4)
	ds_swizzle_b32 v112, v108 offset:swizzle(SWAP,4)
	ds_swizzle_b32 v109, v105 offset:swizzle(SWAP,4)
	s_waitcnt lgkmcnt(10)
	v_fmac_f32_e32 v126, v63, v98
	s_waitcnt lgkmcnt(9)
	v_fmac_f32_e32 v127, v123, v98
	s_waitcnt lgkmcnt(8)
	v_fmac_f32_e32 v124, v120, v98
	v_max_f32_e64 v95, |v126|, |v127|
	s_waitcnt lgkmcnt(7)
	v_fmac_f32_e32 v103, v58, v98
	s_waitcnt lgkmcnt(6)
	v_fmac_f32_e32 v106, v60, v98
	v_max3_f32 v95, |v124|, |v125|, v95
	s_waitcnt lgkmcnt(5)
	v_fmac_f32_e32 v107, v61, v98
	s_waitcnt lgkmcnt(4)
	v_fmac_f32_e32 v101, v104, v98
	s_waitcnt lgkmcnt(3)
	v_fmac_f32_e32 v110, v102, v98
	s_waitcnt lgkmcnt(2)
	v_fmac_f32_e32 v111, v59, v98
	s_waitcnt lgkmcnt(1)
	v_fmac_f32_e32 v112, v108, v98
	v_max_f32_e64 v102, |v103|, |v106|
	v_cvt_pk_bf16_f32 v62, v124, v125
	v_cvt_pk_bf16_f32 v63, v126, v127
	s_waitcnt lgkmcnt(0)
	v_fmac_f32_e32 v109, v105, v98
	v_cvt_pk_bf16_f32 v60, v103, v106
	v_cvt_pk_bf16_f32 v61, v107, v101
	v_max3_f32 v94, v94, v95, v102
	v_max_f32_e64 v95, |v107|, |v101|
	v_max_f32_e64 v101, |v111|, |v112|
	v_max3_f32 v101, |v109|, |v110|, v101
	v_max3_f32 v94, v94, v95, v101
	v_cvt_pk_bf16_f32 v58, v109, v110
	v_cvt_pk_bf16_f32 v59, v111, v112
	v_lshlrev_b32_e32 v95, 16, v54
	v_and_b32_e32 v54, 0xffff0000, v54
	v_lshlrev_b32_e32 v101, 16, v55
	v_and_b32_e32 v55, 0xffff0000, v55
	v_lshlrev_b32_e32 v102, 16, v56
	v_and_b32_e32 v56, 0xffff0000, v56
	v_lshlrev_b32_e32 v103, 16, v57
	v_and_b32_e32 v57, 0xffff0000, v57
	v_add_f32_e32 v104, v95, v54
	v_sub_f32_e32 v54, v95, v54
	v_add_f32_e32 v95, v101, v55
	v_sub_f32_e32 v55, v101, v55
	v_add_f32_e32 v101, v102, v56
	v_sub_f32_e32 v56, v102, v56
	v_add_f32_e32 v102, v103, v57
	v_sub_f32_e32 v57, v103, v57
	v_add_f32_e32 v103, v104, v95
	v_sub_f32_e32 v95, v104, v95
	v_add_f32_e32 v104, v54, v55
	v_sub_f32_e32 v54, v54, v55
	v_add_f32_e32 v55, v101, v102
	v_sub_f32_e32 v101, v101, v102
	v_add_f32_e32 v102, v56, v57
	v_sub_f32_e32 v56, v56, v57
	v_add_f32_e32 v57, v103, v55
	v_sub_f32_e32 v55, v103, v55
	v_add_f32_e32 v103, v104, v102
	v_sub_f32_e32 v102, v104, v102
	v_add_f32_e32 v104, v95, v101
	v_sub_f32_e32 v95, v95, v101
	v_add_f32_e32 v101, v54, v56
	v_sub_f32_e32 v54, v54, v56
	v_mov_b32_dpp v56, v57 quad_perm:[1,0,3,2] row_mask:0xf bank_mask:0xf bound_ctrl:1
	v_fmac_f32_e32 v56, v57, v96
	v_mov_b32_dpp v57, v103 quad_perm:[1,0,3,2] row_mask:0xf bank_mask:0xf bound_ctrl:1
	v_fmac_f32_e32 v57, v103, v96
	v_mov_b32_dpp v103, v104 quad_perm:[1,0,3,2] row_mask:0xf bank_mask:0xf bound_ctrl:1
	v_fmac_f32_e32 v103, v104, v96
	v_mov_b32_dpp v104, v101 quad_perm:[1,0,3,2] row_mask:0xf bank_mask:0xf bound_ctrl:1
	v_fmac_f32_e32 v104, v101, v96
	v_mov_b32_dpp v101, v55 quad_perm:[1,0,3,2] row_mask:0xf bank_mask:0xf bound_ctrl:1
	v_fmac_f32_e32 v101, v55, v96
	v_mov_b32_dpp v55, v102 quad_perm:[1,0,3,2] row_mask:0xf bank_mask:0xf bound_ctrl:1
	v_fmac_f32_e32 v55, v102, v96
	v_mov_b32_dpp v102, v95 quad_perm:[1,0,3,2] row_mask:0xf bank_mask:0xf bound_ctrl:1
	v_fmac_f32_e32 v102, v95, v96
	v_mov_b32_dpp v95, v54 quad_perm:[1,0,3,2] row_mask:0xf bank_mask:0xf bound_ctrl:1
	v_fmac_f32_e32 v95, v54, v96
	v_mov_b32_dpp v54, v56 quad_perm:[2,3,0,1] row_mask:0xf bank_mask:0xf bound_ctrl:1
	v_fmac_f32_e32 v54, v56, v97
	v_mov_b32_dpp v56, v57 quad_perm:[2,3,0,1] row_mask:0xf bank_mask:0xf bound_ctrl:1
	v_fmac_f32_e32 v56, v57, v97
	v_mov_b32_dpp v57, v103 quad_perm:[2,3,0,1] row_mask:0xf bank_mask:0xf bound_ctrl:1
	v_fmac_f32_e32 v57, v103, v97
	v_mov_b32_dpp v103, v104 quad_perm:[2,3,0,1] row_mask:0xf bank_mask:0xf bound_ctrl:1
	v_fmac_f32_e32 v103, v104, v97
	v_mov_b32_dpp v104, v101 quad_perm:[2,3,0,1] row_mask:0xf bank_mask:0xf bound_ctrl:1
	v_fmac_f32_e32 v104, v101, v97
	v_mov_b32_dpp v101, v55 quad_perm:[2,3,0,1] row_mask:0xf bank_mask:0xf bound_ctrl:1
	v_mov_b32_dpp v107, v95 quad_perm:[2,3,0,1] row_mask:0xf bank_mask:0xf bound_ctrl:1
	v_fmac_f32_e32 v101, v55, v97
	v_fmac_f32_e32 v107, v95, v97
	ds_swizzle_b32 v95, v103 offset:swizzle(SWAP,4)
	ds_swizzle_b32 v108, v104 offset:swizzle(SWAP,4)
	ds_swizzle_b32 v109, v101 offset:swizzle(SWAP,4)
	ds_swizzle_b32 v111, v107 offset:swizzle(SWAP,4)
	v_mov_b32_dpp v55, v102 quad_perm:[2,3,0,1] row_mask:0xf bank_mask:0xf bound_ctrl:1
	s_waitcnt lgkmcnt(3)
	v_fmac_f32_e32 v95, v103, v98
	s_waitcnt lgkmcnt(2)
	v_fmac_f32_e32 v108, v104, v98
	s_waitcnt lgkmcnt(1)
	v_fmac_f32_e32 v109, v101, v98
	s_waitcnt lgkmcnt(0)
	v_fmac_f32_e32 v111, v107, v98
	v_lshlrev_b32_e32 v101, 16, v50
	v_and_b32_e32 v50, 0xffff0000, v50
	v_lshlrev_b32_e32 v103, 16, v51
	v_and_b32_e32 v51, 0xffff0000, v51
	v_lshlrev_b32_e32 v104, 16, v52
	v_and_b32_e32 v52, 0xffff0000, v52
	v_lshlrev_b32_e32 v107, 16, v53
	v_and_b32_e32 v53, 0xffff0000, v53
	v_add_f32_e32 v112, v101, v50
	v_sub_f32_e32 v50, v101, v50
	v_add_f32_e32 v101, v103, v51
	v_sub_f32_e32 v51, v103, v51
	v_add_f32_e32 v103, v104, v52
	v_sub_f32_e32 v52, v104, v52
	v_add_f32_e32 v104, v107, v53
	v_sub_f32_e32 v53, v107, v53
	v_add_f32_e32 v107, v112, v101
	v_sub_f32_e32 v101, v112, v101
	v_add_f32_e32 v112, v50, v51
	v_sub_f32_e32 v50, v50, v51
	v_add_f32_e32 v51, v103, v104
	v_sub_f32_e32 v103, v103, v104
	v_add_f32_e32 v104, v52, v53
	v_sub_f32_e32 v52, v52, v53
	v_add_f32_e32 v53, v107, v51
	v_sub_f32_e32 v51, v107, v51
	v_add_f32_e32 v107, v112, v104
	v_sub_f32_e32 v104, v112, v104
	v_add_f32_e32 v112, v101, v103
	v_sub_f32_e32 v101, v101, v103
	v_add_f32_e32 v103, v50, v52
	v_sub_f32_e32 v50, v50, v52
	v_mov_b32_dpp v52, v53 quad_perm:[1,0,3,2] row_mask:0xf bank_mask:0xf bound_ctrl:1
	v_fmac_f32_e32 v52, v53, v96
	v_mov_b32_dpp v53, v107 quad_perm:[1,0,3,2] row_mask:0xf bank_mask:0xf bound_ctrl:1
	v_fmac_f32_e32 v53, v107, v96
	v_mov_b32_dpp v107, v112 quad_perm:[1,0,3,2] row_mask:0xf bank_mask:0xf bound_ctrl:1
	v_fmac_f32_e32 v107, v112, v96
	v_mov_b32_dpp v112, v103 quad_perm:[1,0,3,2] row_mask:0xf bank_mask:0xf bound_ctrl:1
	v_fmac_f32_e32 v112, v103, v96
	v_mov_b32_dpp v103, v51 quad_perm:[1,0,3,2] row_mask:0xf bank_mask:0xf bound_ctrl:1
	v_fmac_f32_e32 v103, v51, v96
	v_mov_b32_dpp v51, v104 quad_perm:[1,0,3,2] row_mask:0xf bank_mask:0xf bound_ctrl:1
	v_fmac_f32_e32 v51, v104, v96
	v_mov_b32_dpp v104, v101 quad_perm:[1,0,3,2] row_mask:0xf bank_mask:0xf bound_ctrl:1
	v_fmac_f32_e32 v104, v101, v96
	v_mov_b32_dpp v101, v50 quad_perm:[1,0,3,2] row_mask:0xf bank_mask:0xf bound_ctrl:1
	v_fmac_f32_e32 v101, v50, v96
	v_mov_b32_dpp v50, v52 quad_perm:[2,3,0,1] row_mask:0xf bank_mask:0xf bound_ctrl:1
	v_fmac_f32_e32 v50, v52, v97
	v_mov_b32_dpp v52, v53 quad_perm:[2,3,0,1] row_mask:0xf bank_mask:0xf bound_ctrl:1
	v_fmac_f32_e32 v52, v53, v97
	v_mov_b32_dpp v53, v107 quad_perm:[2,3,0,1] row_mask:0xf bank_mask:0xf bound_ctrl:1
	v_fmac_f32_e32 v53, v107, v97
	v_mov_b32_dpp v107, v112 quad_perm:[2,3,0,1] row_mask:0xf bank_mask:0xf bound_ctrl:1
	v_fmac_f32_e32 v107, v112, v97
	v_mov_b32_dpp v112, v103 quad_perm:[2,3,0,1] row_mask:0xf bank_mask:0xf bound_ctrl:1
	v_fmac_f32_e32 v112, v103, v97
	v_mov_b32_dpp v103, v51 quad_perm:[2,3,0,1] row_mask:0xf bank_mask:0xf bound_ctrl:1
	v_mov_b32_dpp v115, v101 quad_perm:[2,3,0,1] row_mask:0xf bank_mask:0xf bound_ctrl:1
	v_fmac_f32_e32 v103, v51, v97
	v_fmac_f32_e32 v115, v101, v97
	ds_swizzle_b32 v101, v107 offset:swizzle(SWAP,4)
	ds_swizzle_b32 v116, v112 offset:swizzle(SWAP,4)
	ds_swizzle_b32 v117, v103 offset:swizzle(SWAP,4)
	ds_swizzle_b32 v119, v115 offset:swizzle(SWAP,4)
	v_fmac_f32_e32 v55, v102, v97
	s_waitcnt lgkmcnt(3)
	v_fmac_f32_e32 v101, v107, v98
	s_waitcnt lgkmcnt(2)
	v_fmac_f32_e32 v116, v112, v98
	s_waitcnt lgkmcnt(1)
	v_fmac_f32_e32 v117, v103, v98
	s_waitcnt lgkmcnt(0)
	v_fmac_f32_e32 v119, v115, v98
	v_lshlrev_b32_e32 v103, 16, v46
	v_and_b32_e32 v46, 0xffff0000, v46
	v_lshlrev_b32_e32 v107, 16, v47
	v_and_b32_e32 v47, 0xffff0000, v47
	v_lshlrev_b32_e32 v112, 16, v48
	v_and_b32_e32 v48, 0xffff0000, v48
	v_lshlrev_b32_e32 v115, 16, v49
	v_and_b32_e32 v49, 0xffff0000, v49
	v_add_f32_e32 v120, v103, v46
	v_sub_f32_e32 v46, v103, v46
	v_add_f32_e32 v103, v107, v47
	v_sub_f32_e32 v47, v107, v47
	v_add_f32_e32 v107, v112, v48
	v_sub_f32_e32 v48, v112, v48
	v_add_f32_e32 v112, v115, v49
	v_sub_f32_e32 v49, v115, v49
	v_add_f32_e32 v115, v120, v103
	v_sub_f32_e32 v103, v120, v103
	v_add_f32_e32 v120, v46, v47
	v_sub_f32_e32 v46, v46, v47
	v_add_f32_e32 v47, v107, v112
	v_sub_f32_e32 v107, v107, v112
	v_add_f32_e32 v112, v48, v49
	v_sub_f32_e32 v48, v48, v49
	v_add_f32_e32 v49, v115, v47
	v_sub_f32_e32 v47, v115, v47
	v_add_f32_e32 v115, v120, v112
	v_sub_f32_e32 v112, v120, v112
	v_add_f32_e32 v120, v103, v107
	v_sub_f32_e32 v103, v103, v107
	v_add_f32_e32 v107, v46, v48
	v_sub_f32_e32 v46, v46, v48
	v_mov_b32_dpp v48, v49 quad_perm:[1,0,3,2] row_mask:0xf bank_mask:0xf bound_ctrl:1
	v_fmac_f32_e32 v48, v49, v96
	v_mov_b32_dpp v49, v115 quad_perm:[1,0,3,2] row_mask:0xf bank_mask:0xf bound_ctrl:1
	v_fmac_f32_e32 v49, v115, v96
	v_mov_b32_dpp v115, v120 quad_perm:[1,0,3,2] row_mask:0xf bank_mask:0xf bound_ctrl:1
	v_fmac_f32_e32 v115, v120, v96
	v_mov_b32_dpp v120, v107 quad_perm:[1,0,3,2] row_mask:0xf bank_mask:0xf bound_ctrl:1
	v_fmac_f32_e32 v120, v107, v96
	v_mov_b32_dpp v107, v47 quad_perm:[1,0,3,2] row_mask:0xf bank_mask:0xf bound_ctrl:1
	v_fmac_f32_e32 v107, v47, v96
	v_mov_b32_dpp v47, v112 quad_perm:[1,0,3,2] row_mask:0xf bank_mask:0xf bound_ctrl:1
	v_fmac_f32_e32 v47, v112, v96
	v_mov_b32_dpp v112, v103 quad_perm:[1,0,3,2] row_mask:0xf bank_mask:0xf bound_ctrl:1
	v_fmac_f32_e32 v112, v103, v96
	v_mov_b32_dpp v103, v46 quad_perm:[1,0,3,2] row_mask:0xf bank_mask:0xf bound_ctrl:1
	v_fmac_f32_e32 v103, v46, v96
	v_mov_b32_dpp v46, v48 quad_perm:[2,3,0,1] row_mask:0xf bank_mask:0xf bound_ctrl:1
	v_fmac_f32_e32 v46, v48, v97
	v_mov_b32_dpp v48, v49 quad_perm:[2,3,0,1] row_mask:0xf bank_mask:0xf bound_ctrl:1
	ds_swizzle_b32 v102, v54 offset:swizzle(SWAP,4)
	ds_swizzle_b32 v105, v56 offset:swizzle(SWAP,4)
	ds_swizzle_b32 v106, v57 offset:swizzle(SWAP,4)
	v_fmac_f32_e32 v48, v49, v97
	v_mov_b32_dpp v49, v115 quad_perm:[2,3,0,1] row_mask:0xf bank_mask:0xf bound_ctrl:1
	ds_swizzle_b32 v110, v55 offset:swizzle(SWAP,4)
	v_mov_b32_dpp v51, v104 quad_perm:[2,3,0,1] row_mask:0xf bank_mask:0xf bound_ctrl:1
	v_fmac_f32_e32 v49, v115, v97
	v_mov_b32_dpp v115, v120 quad_perm:[2,3,0,1] row_mask:0xf bank_mask:0xf bound_ctrl:1
	v_fmac_f32_e32 v51, v104, v97
	ds_swizzle_b32 v104, v50 offset:swizzle(SWAP,4)
	ds_swizzle_b32 v113, v52 offset:swizzle(SWAP,4)
	v_fmac_f32_e32 v115, v120, v97
	v_mov_b32_dpp v120, v107 quad_perm:[2,3,0,1] row_mask:0xf bank_mask:0xf bound_ctrl:1
	ds_swizzle_b32 v114, v53 offset:swizzle(SWAP,4)
	ds_swizzle_b32 v118, v51 offset:swizzle(SWAP,4)
	v_fmac_f32_e32 v120, v107, v97
	v_mov_b32_dpp v107, v47 quad_perm:[2,3,0,1] row_mask:0xf bank_mask:0xf bound_ctrl:1
	v_fmac_f32_e32 v107, v47, v97
	v_mov_b32_dpp v47, v112 quad_perm:[2,3,0,1] row_mask:0xf bank_mask:0xf bound_ctrl:1
	v_mov_b32_dpp v123, v103 quad_perm:[2,3,0,1] row_mask:0xf bank_mask:0xf bound_ctrl:1
	s_waitcnt lgkmcnt(7)
	v_fmac_f32_e32 v102, v54, v98
	s_waitcnt lgkmcnt(6)
	v_fmac_f32_e32 v105, v56, v98
	s_waitcnt lgkmcnt(5)
	v_fmac_f32_e32 v106, v57, v98
	v_fmac_f32_e32 v47, v112, v97
	ds_swizzle_b32 v112, v46 offset:swizzle(SWAP,4)
	ds_swizzle_b32 v121, v48 offset:swizzle(SWAP,4)
	ds_swizzle_b32 v122, v49 offset:swizzle(SWAP,4)
	v_fmac_f32_e32 v123, v103, v97
	ds_swizzle_b32 v103, v115 offset:swizzle(SWAP,4)
	s_waitcnt lgkmcnt(8)
	v_fmac_f32_e32 v110, v55, v98
	v_cvt_pk_bf16_f32 v56, v102, v105
	v_cvt_pk_bf16_f32 v57, v106, v95
	v_max_f32_e64 v102, |v102|, |v105|
	v_max_f32_e64 v95, |v106|, |v95|
	s_waitcnt lgkmcnt(7)
	v_fmac_f32_e32 v104, v50, v98
	s_waitcnt lgkmcnt(6)
	v_fmac_f32_e32 v113, v52, v98
	v_max3_f32 v94, v94, v102, v95
	v_max_f32_e64 v95, |v110|, |v111|
	s_waitcnt lgkmcnt(5)
	v_fmac_f32_e32 v114, v53, v98
	s_waitcnt lgkmcnt(4)
	v_fmac_f32_e32 v118, v51, v98
	v_max3_f32 v95, |v108|, |v109|, v95
	v_max_f32_e64 v102, |v104|, |v113|
	v_cvt_pk_bf16_f32 v54, v108, v109
	v_cvt_pk_bf16_f32 v55, v110, v111
	v_cvt_pk_bf16_f32 v52, v104, v113
	v_cvt_pk_bf16_f32 v53, v114, v101
	v_max3_f32 v94, v94, v95, v102
	v_max_f32_e64 v95, |v114|, |v101|
	v_max_f32_e64 v101, |v118|, |v119|
	s_waitcnt lgkmcnt(3)
	v_fmac_f32_e32 v112, v46, v98
	s_waitcnt lgkmcnt(2)
	v_fmac_f32_e32 v121, v48, v98
	s_waitcnt lgkmcnt(1)
	v_fmac_f32_e32 v122, v49, v98
	s_waitcnt lgkmcnt(0)
	v_fmac_f32_e32 v103, v115, v98
	v_max3_f32 v101, |v116|, |v117|, v101
	v_max3_f32 v94, v94, v95, v101
	v_max_f32_e64 v95, |v112|, |v121|
	v_max_f32_e64 v101, |v122|, |v103|
	v_cvt_pk_bf16_f32 v50, v116, v117
	v_cvt_pk_bf16_f32 v51, v118, v119
	v_cvt_pk_bf16_f32 v48, v112, v121
	v_cvt_pk_bf16_f32 v49, v122, v103
	v_max3_f32 v94, v94, v95, v101
	v_lshlrev_b32_e32 v101, 16, v42
	v_and_b32_e32 v42, 0xffff0000, v42
	v_lshlrev_b32_e32 v102, 16, v43
	v_and_b32_e32 v43, 0xffff0000, v43
	v_lshlrev_b32_e32 v103, 16, v44
	v_and_b32_e32 v44, 0xffff0000, v44
	v_lshlrev_b32_e32 v104, 16, v45
	v_and_b32_e32 v45, 0xffff0000, v45
	v_add_f32_e32 v105, v101, v42
	v_sub_f32_e32 v42, v101, v42
	v_add_f32_e32 v101, v102, v43
	v_sub_f32_e32 v43, v102, v43
	v_add_f32_e32 v102, v103, v44
	v_sub_f32_e32 v44, v103, v44
	v_add_f32_e32 v103, v104, v45
	v_sub_f32_e32 v45, v104, v45
	v_add_f32_e32 v104, v105, v101
	v_sub_f32_e32 v101, v105, v101
	v_add_f32_e32 v105, v42, v43
	v_sub_f32_e32 v42, v42, v43
	v_add_f32_e32 v43, v102, v103
	v_sub_f32_e32 v102, v102, v103
	v_add_f32_e32 v103, v44, v45
	v_sub_f32_e32 v44, v44, v45
	v_add_f32_e32 v45, v104, v43
	v_sub_f32_e32 v43, v104, v43
	v_add_f32_e32 v104, v105, v103
	v_sub_f32_e32 v103, v105, v103
	v_add_f32_e32 v105, v101, v102
	v_sub_f32_e32 v101, v101, v102
	v_add_f32_e32 v102, v42, v44
	v_sub_f32_e32 v42, v42, v44
	v_mov_b32_dpp v44, v45 quad_perm:[1,0,3,2] row_mask:0xf bank_mask:0xf bound_ctrl:1
	v_fmac_f32_e32 v44, v45, v96
	v_mov_b32_dpp v45, v104 quad_perm:[1,0,3,2] row_mask:0xf bank_mask:0xf bound_ctrl:1
	v_fmac_f32_e32 v45, v104, v96
	v_mov_b32_dpp v104, v105 quad_perm:[1,0,3,2] row_mask:0xf bank_mask:0xf bound_ctrl:1
	v_fmac_f32_e32 v104, v105, v96
	v_mov_b32_dpp v105, v102 quad_perm:[1,0,3,2] row_mask:0xf bank_mask:0xf bound_ctrl:1
	v_fmac_f32_e32 v105, v102, v96
	v_mov_b32_dpp v102, v43 quad_perm:[1,0,3,2] row_mask:0xf bank_mask:0xf bound_ctrl:1
	v_fmac_f32_e32 v102, v43, v96
	v_mov_b32_dpp v43, v103 quad_perm:[1,0,3,2] row_mask:0xf bank_mask:0xf bound_ctrl:1
	v_fmac_f32_e32 v43, v103, v96
	v_mov_b32_dpp v103, v101 quad_perm:[1,0,3,2] row_mask:0xf bank_mask:0xf bound_ctrl:1
	v_fmac_f32_e32 v103, v101, v96
	v_mov_b32_dpp v101, v42 quad_perm:[1,0,3,2] row_mask:0xf bank_mask:0xf bound_ctrl:1
	v_fmac_f32_e32 v101, v42, v96
	v_mov_b32_dpp v42, v44 quad_perm:[2,3,0,1] row_mask:0xf bank_mask:0xf bound_ctrl:1
	v_fmac_f32_e32 v42, v44, v97
	v_mov_b32_dpp v44, v45 quad_perm:[2,3,0,1] row_mask:0xf bank_mask:0xf bound_ctrl:1
	v_fmac_f32_e32 v44, v45, v97
	v_mov_b32_dpp v45, v104 quad_perm:[2,3,0,1] row_mask:0xf bank_mask:0xf bound_ctrl:1
	ds_swizzle_b32 v125, v107 offset:swizzle(SWAP,4)
	v_fmac_f32_e32 v45, v104, v97
	v_mov_b32_dpp v104, v105 quad_perm:[2,3,0,1] row_mask:0xf bank_mask:0xf bound_ctrl:1
	v_fmac_f32_e32 v104, v105, v97
	v_mov_b32_dpp v105, v102 quad_perm:[2,3,0,1] row_mask:0xf bank_mask:0xf bound_ctrl:1
	v_fmac_f32_e32 v105, v102, v97
	v_mov_b32_dpp v102, v43 quad_perm:[2,3,0,1] row_mask:0xf bank_mask:0xf bound_ctrl:1
	ds_swizzle_b32 v126, v47 offset:swizzle(SWAP,4)
	ds_swizzle_b32 v127, v123 offset:swizzle(SWAP,4)
	v_fmac_f32_e32 v102, v43, v97
	v_mov_b32_dpp v43, v103 quad_perm:[2,3,0,1] row_mask:0xf bank_mask:0xf bound_ctrl:1
	v_mov_b32_dpp v108, v101 quad_perm:[2,3,0,1] row_mask:0xf bank_mask:0xf bound_ctrl:1
	ds_swizzle_b32 v124, v120 offset:swizzle(SWAP,4)
	v_fmac_f32_e32 v43, v103, v97
	ds_swizzle_b32 v103, v42 offset:swizzle(SWAP,4)
	ds_swizzle_b32 v106, v44 offset:swizzle(SWAP,4)
	v_fmac_f32_e32 v108, v101, v97
	s_waitcnt lgkmcnt(5)
	v_fmac_f32_e32 v125, v107, v98
	ds_swizzle_b32 v107, v45 offset:swizzle(SWAP,4)
	ds_swizzle_b32 v101, v104 offset:swizzle(SWAP,4)
	ds_swizzle_b32 v110, v102 offset:swizzle(SWAP,4)
	ds_swizzle_b32 v111, v43 offset:swizzle(SWAP,4)
	ds_swizzle_b32 v112, v108 offset:swizzle(SWAP,4)
	ds_swizzle_b32 v109, v105 offset:swizzle(SWAP,4)
	s_waitcnt lgkmcnt(10)
	v_fmac_f32_e32 v126, v47, v98
	s_waitcnt lgkmcnt(9)
	v_fmac_f32_e32 v127, v123, v98
	s_waitcnt lgkmcnt(8)
	v_fmac_f32_e32 v124, v120, v98
	v_max_f32_e64 v95, |v126|, |v127|
	s_waitcnt lgkmcnt(7)
	v_fmac_f32_e32 v103, v42, v98
	s_waitcnt lgkmcnt(6)
	v_fmac_f32_e32 v106, v44, v98
	v_max3_f32 v95, |v124|, |v125|, v95
	s_waitcnt lgkmcnt(5)
	v_fmac_f32_e32 v107, v45, v98
	s_waitcnt lgkmcnt(4)
	v_fmac_f32_e32 v101, v104, v98
	s_waitcnt lgkmcnt(3)
	v_fmac_f32_e32 v110, v102, v98
	s_waitcnt lgkmcnt(2)
	v_fmac_f32_e32 v111, v43, v98
	s_waitcnt lgkmcnt(1)
	v_fmac_f32_e32 v112, v108, v98
	v_max_f32_e64 v102, |v103|, |v106|
	v_cvt_pk_bf16_f32 v46, v124, v125
	v_cvt_pk_bf16_f32 v47, v126, v127
	s_waitcnt lgkmcnt(0)
	v_fmac_f32_e32 v109, v105, v98
	v_cvt_pk_bf16_f32 v44, v103, v106
	v_cvt_pk_bf16_f32 v45, v107, v101
	v_max3_f32 v94, v94, v95, v102
	v_max_f32_e64 v95, |v107|, |v101|
	v_max_f32_e64 v101, |v111|, |v112|
	v_max3_f32 v101, |v109|, |v110|, v101
	v_max3_f32 v94, v94, v95, v101
	v_cvt_pk_bf16_f32 v42, v109, v110
	v_cvt_pk_bf16_f32 v43, v111, v112
	v_lshlrev_b32_e32 v95, 16, v38
	v_and_b32_e32 v38, 0xffff0000, v38
	v_lshlrev_b32_e32 v101, 16, v39
	v_and_b32_e32 v39, 0xffff0000, v39
	v_lshlrev_b32_e32 v102, 16, v40
	v_and_b32_e32 v40, 0xffff0000, v40
	v_lshlrev_b32_e32 v103, 16, v41
	v_and_b32_e32 v41, 0xffff0000, v41
	v_add_f32_e32 v104, v95, v38
	v_sub_f32_e32 v38, v95, v38
	v_add_f32_e32 v95, v101, v39
	v_sub_f32_e32 v39, v101, v39
	v_add_f32_e32 v101, v102, v40
	v_sub_f32_e32 v40, v102, v40
	v_add_f32_e32 v102, v103, v41
	v_sub_f32_e32 v41, v103, v41
	v_add_f32_e32 v103, v104, v95
	v_sub_f32_e32 v95, v104, v95
	v_add_f32_e32 v104, v38, v39
	v_sub_f32_e32 v38, v38, v39
	v_add_f32_e32 v39, v101, v102
	v_sub_f32_e32 v101, v101, v102
	v_add_f32_e32 v102, v40, v41
	v_sub_f32_e32 v40, v40, v41
	v_add_f32_e32 v41, v103, v39
	v_sub_f32_e32 v39, v103, v39
	v_add_f32_e32 v103, v104, v102
	v_sub_f32_e32 v102, v104, v102
	v_add_f32_e32 v104, v95, v101
	v_sub_f32_e32 v95, v95, v101
	v_add_f32_e32 v101, v38, v40
	v_sub_f32_e32 v38, v38, v40
	v_mov_b32_dpp v40, v41 quad_perm:[1,0,3,2] row_mask:0xf bank_mask:0xf bound_ctrl:1
	v_fmac_f32_e32 v40, v41, v96
	v_mov_b32_dpp v41, v103 quad_perm:[1,0,3,2] row_mask:0xf bank_mask:0xf bound_ctrl:1
	v_fmac_f32_e32 v41, v103, v96
	v_mov_b32_dpp v103, v104 quad_perm:[1,0,3,2] row_mask:0xf bank_mask:0xf bound_ctrl:1
	v_fmac_f32_e32 v103, v104, v96
	v_mov_b32_dpp v104, v101 quad_perm:[1,0,3,2] row_mask:0xf bank_mask:0xf bound_ctrl:1
	v_fmac_f32_e32 v104, v101, v96
	v_mov_b32_dpp v101, v39 quad_perm:[1,0,3,2] row_mask:0xf bank_mask:0xf bound_ctrl:1
	v_fmac_f32_e32 v101, v39, v96
	v_mov_b32_dpp v39, v102 quad_perm:[1,0,3,2] row_mask:0xf bank_mask:0xf bound_ctrl:1
	v_fmac_f32_e32 v39, v102, v96
	v_mov_b32_dpp v102, v95 quad_perm:[1,0,3,2] row_mask:0xf bank_mask:0xf bound_ctrl:1
	v_fmac_f32_e32 v102, v95, v96
	v_mov_b32_dpp v95, v38 quad_perm:[1,0,3,2] row_mask:0xf bank_mask:0xf bound_ctrl:1
	v_fmac_f32_e32 v95, v38, v96
	v_mov_b32_dpp v38, v40 quad_perm:[2,3,0,1] row_mask:0xf bank_mask:0xf bound_ctrl:1
	v_fmac_f32_e32 v38, v40, v97
	v_mov_b32_dpp v40, v41 quad_perm:[2,3,0,1] row_mask:0xf bank_mask:0xf bound_ctrl:1
	v_fmac_f32_e32 v40, v41, v97
	v_mov_b32_dpp v41, v103 quad_perm:[2,3,0,1] row_mask:0xf bank_mask:0xf bound_ctrl:1
	v_fmac_f32_e32 v41, v103, v97
	v_mov_b32_dpp v103, v104 quad_perm:[2,3,0,1] row_mask:0xf bank_mask:0xf bound_ctrl:1
	v_fmac_f32_e32 v103, v104, v97
	v_mov_b32_dpp v104, v101 quad_perm:[2,3,0,1] row_mask:0xf bank_mask:0xf bound_ctrl:1
	v_fmac_f32_e32 v104, v101, v97
	v_mov_b32_dpp v101, v39 quad_perm:[2,3,0,1] row_mask:0xf bank_mask:0xf bound_ctrl:1
	v_mov_b32_dpp v107, v95 quad_perm:[2,3,0,1] row_mask:0xf bank_mask:0xf bound_ctrl:1
	v_fmac_f32_e32 v101, v39, v97
	v_fmac_f32_e32 v107, v95, v97
	ds_swizzle_b32 v95, v103 offset:swizzle(SWAP,4)
	ds_swizzle_b32 v108, v104 offset:swizzle(SWAP,4)
	ds_swizzle_b32 v109, v101 offset:swizzle(SWAP,4)
	ds_swizzle_b32 v111, v107 offset:swizzle(SWAP,4)
	v_mov_b32_dpp v39, v102 quad_perm:[2,3,0,1] row_mask:0xf bank_mask:0xf bound_ctrl:1
	s_waitcnt lgkmcnt(3)
	v_fmac_f32_e32 v95, v103, v98
	s_waitcnt lgkmcnt(2)
	v_fmac_f32_e32 v108, v104, v98
	s_waitcnt lgkmcnt(1)
	v_fmac_f32_e32 v109, v101, v98
	s_waitcnt lgkmcnt(0)
	v_fmac_f32_e32 v111, v107, v98
	v_lshlrev_b32_e32 v101, 16, v34
	v_and_b32_e32 v34, 0xffff0000, v34
	v_lshlrev_b32_e32 v103, 16, v35
	v_and_b32_e32 v35, 0xffff0000, v35
	v_lshlrev_b32_e32 v104, 16, v36
	v_and_b32_e32 v36, 0xffff0000, v36
	v_lshlrev_b32_e32 v107, 16, v37
	v_and_b32_e32 v37, 0xffff0000, v37
	v_add_f32_e32 v112, v101, v34
	v_sub_f32_e32 v34, v101, v34
	v_add_f32_e32 v101, v103, v35
	v_sub_f32_e32 v35, v103, v35
	v_add_f32_e32 v103, v104, v36
	v_sub_f32_e32 v36, v104, v36
	v_add_f32_e32 v104, v107, v37
	v_sub_f32_e32 v37, v107, v37
	v_add_f32_e32 v107, v112, v101
	v_sub_f32_e32 v101, v112, v101
	v_add_f32_e32 v112, v34, v35
	v_sub_f32_e32 v34, v34, v35
	v_add_f32_e32 v35, v103, v104
	v_sub_f32_e32 v103, v103, v104
	v_add_f32_e32 v104, v36, v37
	v_sub_f32_e32 v36, v36, v37
	v_add_f32_e32 v37, v107, v35
	v_sub_f32_e32 v35, v107, v35
	v_add_f32_e32 v107, v112, v104
	v_sub_f32_e32 v104, v112, v104
	v_add_f32_e32 v112, v101, v103
	v_sub_f32_e32 v101, v101, v103
	v_add_f32_e32 v103, v34, v36
	v_sub_f32_e32 v34, v34, v36
	v_mov_b32_dpp v36, v37 quad_perm:[1,0,3,2] row_mask:0xf bank_mask:0xf bound_ctrl:1
	v_fmac_f32_e32 v36, v37, v96
	v_mov_b32_dpp v37, v107 quad_perm:[1,0,3,2] row_mask:0xf bank_mask:0xf bound_ctrl:1
	v_fmac_f32_e32 v37, v107, v96
	v_mov_b32_dpp v107, v112 quad_perm:[1,0,3,2] row_mask:0xf bank_mask:0xf bound_ctrl:1
	v_fmac_f32_e32 v107, v112, v96
	v_mov_b32_dpp v112, v103 quad_perm:[1,0,3,2] row_mask:0xf bank_mask:0xf bound_ctrl:1
	v_fmac_f32_e32 v112, v103, v96
	v_mov_b32_dpp v103, v35 quad_perm:[1,0,3,2] row_mask:0xf bank_mask:0xf bound_ctrl:1
	v_fmac_f32_e32 v103, v35, v96
	v_mov_b32_dpp v35, v104 quad_perm:[1,0,3,2] row_mask:0xf bank_mask:0xf bound_ctrl:1
	v_fmac_f32_e32 v35, v104, v96
	v_mov_b32_dpp v104, v101 quad_perm:[1,0,3,2] row_mask:0xf bank_mask:0xf bound_ctrl:1
	v_fmac_f32_e32 v104, v101, v96
	v_mov_b32_dpp v101, v34 quad_perm:[1,0,3,2] row_mask:0xf bank_mask:0xf bound_ctrl:1
	v_fmac_f32_e32 v101, v34, v96
	v_mov_b32_dpp v34, v36 quad_perm:[2,3,0,1] row_mask:0xf bank_mask:0xf bound_ctrl:1
	v_fmac_f32_e32 v34, v36, v97
	v_mov_b32_dpp v36, v37 quad_perm:[2,3,0,1] row_mask:0xf bank_mask:0xf bound_ctrl:1
	v_fmac_f32_e32 v36, v37, v97
	v_mov_b32_dpp v37, v107 quad_perm:[2,3,0,1] row_mask:0xf bank_mask:0xf bound_ctrl:1
	v_fmac_f32_e32 v37, v107, v97
	v_mov_b32_dpp v107, v112 quad_perm:[2,3,0,1] row_mask:0xf bank_mask:0xf bound_ctrl:1
	v_fmac_f32_e32 v107, v112, v97
	v_mov_b32_dpp v112, v103 quad_perm:[2,3,0,1] row_mask:0xf bank_mask:0xf bound_ctrl:1
	v_fmac_f32_e32 v112, v103, v97
	v_mov_b32_dpp v103, v35 quad_perm:[2,3,0,1] row_mask:0xf bank_mask:0xf bound_ctrl:1
	v_mov_b32_dpp v115, v101 quad_perm:[2,3,0,1] row_mask:0xf bank_mask:0xf bound_ctrl:1
	v_fmac_f32_e32 v103, v35, v97
	v_fmac_f32_e32 v115, v101, v97
	ds_swizzle_b32 v101, v107 offset:swizzle(SWAP,4)
	ds_swizzle_b32 v116, v112 offset:swizzle(SWAP,4)
	ds_swizzle_b32 v117, v103 offset:swizzle(SWAP,4)
	ds_swizzle_b32 v119, v115 offset:swizzle(SWAP,4)
	v_fmac_f32_e32 v39, v102, v97
	s_waitcnt lgkmcnt(3)
	v_fmac_f32_e32 v101, v107, v98
	s_waitcnt lgkmcnt(2)
	v_fmac_f32_e32 v116, v112, v98
	s_waitcnt lgkmcnt(1)
	v_fmac_f32_e32 v117, v103, v98
	s_waitcnt lgkmcnt(0)
	v_fmac_f32_e32 v119, v115, v98
	v_lshlrev_b32_e32 v103, 16, v30
	v_and_b32_e32 v30, 0xffff0000, v30
	v_lshlrev_b32_e32 v107, 16, v31
	v_and_b32_e32 v31, 0xffff0000, v31
	v_lshlrev_b32_e32 v112, 16, v32
	v_and_b32_e32 v32, 0xffff0000, v32
	v_lshlrev_b32_e32 v115, 16, v33
	v_and_b32_e32 v33, 0xffff0000, v33
	v_add_f32_e32 v120, v103, v30
	v_sub_f32_e32 v30, v103, v30
	v_add_f32_e32 v103, v107, v31
	v_sub_f32_e32 v31, v107, v31
	v_add_f32_e32 v107, v112, v32
	v_sub_f32_e32 v32, v112, v32
	v_add_f32_e32 v112, v115, v33
	v_sub_f32_e32 v33, v115, v33
	v_add_f32_e32 v115, v120, v103
	v_sub_f32_e32 v103, v120, v103
	v_add_f32_e32 v120, v30, v31
	v_sub_f32_e32 v30, v30, v31
	v_add_f32_e32 v31, v107, v112
	v_sub_f32_e32 v107, v107, v112
	v_add_f32_e32 v112, v32, v33
	v_sub_f32_e32 v32, v32, v33
	v_add_f32_e32 v33, v115, v31
	v_sub_f32_e32 v31, v115, v31
	v_add_f32_e32 v115, v120, v112
	v_sub_f32_e32 v112, v120, v112
	v_add_f32_e32 v120, v103, v107
	v_sub_f32_e32 v103, v103, v107
	v_add_f32_e32 v107, v30, v32
	v_sub_f32_e32 v30, v30, v32
	v_mov_b32_dpp v32, v33 quad_perm:[1,0,3,2] row_mask:0xf bank_mask:0xf bound_ctrl:1
	v_fmac_f32_e32 v32, v33, v96
	v_mov_b32_dpp v33, v115 quad_perm:[1,0,3,2] row_mask:0xf bank_mask:0xf bound_ctrl:1
	v_fmac_f32_e32 v33, v115, v96
	v_mov_b32_dpp v115, v120 quad_perm:[1,0,3,2] row_mask:0xf bank_mask:0xf bound_ctrl:1
	v_fmac_f32_e32 v115, v120, v96
	v_mov_b32_dpp v120, v107 quad_perm:[1,0,3,2] row_mask:0xf bank_mask:0xf bound_ctrl:1
	v_fmac_f32_e32 v120, v107, v96
	v_mov_b32_dpp v107, v31 quad_perm:[1,0,3,2] row_mask:0xf bank_mask:0xf bound_ctrl:1
	v_fmac_f32_e32 v107, v31, v96
	v_mov_b32_dpp v31, v112 quad_perm:[1,0,3,2] row_mask:0xf bank_mask:0xf bound_ctrl:1
	v_fmac_f32_e32 v31, v112, v96
	v_mov_b32_dpp v112, v103 quad_perm:[1,0,3,2] row_mask:0xf bank_mask:0xf bound_ctrl:1
	v_fmac_f32_e32 v112, v103, v96
	v_mov_b32_dpp v103, v30 quad_perm:[1,0,3,2] row_mask:0xf bank_mask:0xf bound_ctrl:1
	v_fmac_f32_e32 v103, v30, v96
	v_mov_b32_dpp v30, v32 quad_perm:[2,3,0,1] row_mask:0xf bank_mask:0xf bound_ctrl:1
	v_fmac_f32_e32 v30, v32, v97
	v_mov_b32_dpp v32, v33 quad_perm:[2,3,0,1] row_mask:0xf bank_mask:0xf bound_ctrl:1
	ds_swizzle_b32 v102, v38 offset:swizzle(SWAP,4)
	ds_swizzle_b32 v105, v40 offset:swizzle(SWAP,4)
	ds_swizzle_b32 v106, v41 offset:swizzle(SWAP,4)
	v_fmac_f32_e32 v32, v33, v97
	v_mov_b32_dpp v33, v115 quad_perm:[2,3,0,1] row_mask:0xf bank_mask:0xf bound_ctrl:1
	ds_swizzle_b32 v110, v39 offset:swizzle(SWAP,4)
	v_mov_b32_dpp v35, v104 quad_perm:[2,3,0,1] row_mask:0xf bank_mask:0xf bound_ctrl:1
	v_fmac_f32_e32 v33, v115, v97
	v_mov_b32_dpp v115, v120 quad_perm:[2,3,0,1] row_mask:0xf bank_mask:0xf bound_ctrl:1
	v_fmac_f32_e32 v35, v104, v97
	ds_swizzle_b32 v104, v34 offset:swizzle(SWAP,4)
	ds_swizzle_b32 v113, v36 offset:swizzle(SWAP,4)
	v_fmac_f32_e32 v115, v120, v97
	v_mov_b32_dpp v120, v107 quad_perm:[2,3,0,1] row_mask:0xf bank_mask:0xf bound_ctrl:1
	ds_swizzle_b32 v114, v37 offset:swizzle(SWAP,4)
	ds_swizzle_b32 v118, v35 offset:swizzle(SWAP,4)
	v_fmac_f32_e32 v120, v107, v97
	v_mov_b32_dpp v107, v31 quad_perm:[2,3,0,1] row_mask:0xf bank_mask:0xf bound_ctrl:1
	v_fmac_f32_e32 v107, v31, v97
	v_mov_b32_dpp v31, v112 quad_perm:[2,3,0,1] row_mask:0xf bank_mask:0xf bound_ctrl:1
	v_mov_b32_dpp v123, v103 quad_perm:[2,3,0,1] row_mask:0xf bank_mask:0xf bound_ctrl:1
	s_waitcnt lgkmcnt(7)
	v_fmac_f32_e32 v102, v38, v98
	s_waitcnt lgkmcnt(6)
	v_fmac_f32_e32 v105, v40, v98
	s_waitcnt lgkmcnt(5)
	v_fmac_f32_e32 v106, v41, v98
	v_fmac_f32_e32 v31, v112, v97
	ds_swizzle_b32 v112, v30 offset:swizzle(SWAP,4)
	ds_swizzle_b32 v121, v32 offset:swizzle(SWAP,4)
	ds_swizzle_b32 v122, v33 offset:swizzle(SWAP,4)
	v_fmac_f32_e32 v123, v103, v97
	ds_swizzle_b32 v103, v115 offset:swizzle(SWAP,4)
	s_waitcnt lgkmcnt(8)
	v_fmac_f32_e32 v110, v39, v98
	v_cvt_pk_bf16_f32 v40, v102, v105
	v_cvt_pk_bf16_f32 v41, v106, v95
	v_max_f32_e64 v102, |v102|, |v105|
	v_max_f32_e64 v95, |v106|, |v95|
	s_waitcnt lgkmcnt(7)
	v_fmac_f32_e32 v104, v34, v98
	s_waitcnt lgkmcnt(6)
	v_fmac_f32_e32 v113, v36, v98
	v_max3_f32 v94, v94, v102, v95
	v_max_f32_e64 v95, |v110|, |v111|
	s_waitcnt lgkmcnt(5)
	v_fmac_f32_e32 v114, v37, v98
	s_waitcnt lgkmcnt(4)
	v_fmac_f32_e32 v118, v35, v98
	v_max3_f32 v95, |v108|, |v109|, v95
	v_max_f32_e64 v102, |v104|, |v113|
	v_cvt_pk_bf16_f32 v38, v108, v109
	v_cvt_pk_bf16_f32 v39, v110, v111
	v_cvt_pk_bf16_f32 v36, v104, v113
	v_cvt_pk_bf16_f32 v37, v114, v101
	v_max3_f32 v94, v94, v95, v102
	v_max_f32_e64 v95, |v114|, |v101|
	v_max_f32_e64 v101, |v118|, |v119|
	s_waitcnt lgkmcnt(3)
	v_fmac_f32_e32 v112, v30, v98
	s_waitcnt lgkmcnt(2)
	v_fmac_f32_e32 v121, v32, v98
	s_waitcnt lgkmcnt(1)
	v_fmac_f32_e32 v122, v33, v98
	s_waitcnt lgkmcnt(0)
	v_fmac_f32_e32 v103, v115, v98
	v_max3_f32 v101, |v116|, |v117|, v101
	v_max3_f32 v94, v94, v95, v101
	v_max_f32_e64 v95, |v112|, |v121|
	v_max_f32_e64 v101, |v122|, |v103|
	v_cvt_pk_bf16_f32 v34, v116, v117
	v_cvt_pk_bf16_f32 v35, v118, v119
	v_cvt_pk_bf16_f32 v32, v112, v121
	v_cvt_pk_bf16_f32 v33, v122, v103
	v_max3_f32 v94, v94, v95, v101
	v_lshlrev_b32_e32 v101, 16, v26
	v_and_b32_e32 v26, 0xffff0000, v26
	v_lshlrev_b32_e32 v102, 16, v27
	v_and_b32_e32 v27, 0xffff0000, v27
	v_lshlrev_b32_e32 v103, 16, v28
	v_and_b32_e32 v28, 0xffff0000, v28
	v_lshlrev_b32_e32 v104, 16, v29
	v_and_b32_e32 v29, 0xffff0000, v29
	v_add_f32_e32 v105, v101, v26
	v_sub_f32_e32 v26, v101, v26
	v_add_f32_e32 v101, v102, v27
	v_sub_f32_e32 v27, v102, v27
	v_add_f32_e32 v102, v103, v28
	v_sub_f32_e32 v28, v103, v28
	v_add_f32_e32 v103, v104, v29
	v_sub_f32_e32 v29, v104, v29
	v_add_f32_e32 v104, v105, v101
	v_sub_f32_e32 v101, v105, v101
	v_add_f32_e32 v105, v26, v27
	v_sub_f32_e32 v26, v26, v27
	v_add_f32_e32 v27, v102, v103
	v_sub_f32_e32 v102, v102, v103
	v_add_f32_e32 v103, v28, v29
	v_sub_f32_e32 v28, v28, v29
	v_add_f32_e32 v29, v104, v27
	v_sub_f32_e32 v27, v104, v27
	v_add_f32_e32 v104, v105, v103
	v_sub_f32_e32 v103, v105, v103
	v_add_f32_e32 v105, v101, v102
	v_sub_f32_e32 v101, v101, v102
	v_add_f32_e32 v102, v26, v28
	v_sub_f32_e32 v26, v26, v28
	v_mov_b32_dpp v28, v29 quad_perm:[1,0,3,2] row_mask:0xf bank_mask:0xf bound_ctrl:1
	v_fmac_f32_e32 v28, v29, v96
	v_mov_b32_dpp v29, v104 quad_perm:[1,0,3,2] row_mask:0xf bank_mask:0xf bound_ctrl:1
	v_fmac_f32_e32 v29, v104, v96
	v_mov_b32_dpp v104, v105 quad_perm:[1,0,3,2] row_mask:0xf bank_mask:0xf bound_ctrl:1
	v_fmac_f32_e32 v104, v105, v96
	v_mov_b32_dpp v105, v102 quad_perm:[1,0,3,2] row_mask:0xf bank_mask:0xf bound_ctrl:1
	v_fmac_f32_e32 v105, v102, v96
	v_mov_b32_dpp v102, v27 quad_perm:[1,0,3,2] row_mask:0xf bank_mask:0xf bound_ctrl:1
	v_fmac_f32_e32 v102, v27, v96
	v_mov_b32_dpp v27, v103 quad_perm:[1,0,3,2] row_mask:0xf bank_mask:0xf bound_ctrl:1
	v_fmac_f32_e32 v27, v103, v96
	v_mov_b32_dpp v103, v101 quad_perm:[1,0,3,2] row_mask:0xf bank_mask:0xf bound_ctrl:1
	v_fmac_f32_e32 v103, v101, v96
	v_mov_b32_dpp v101, v26 quad_perm:[1,0,3,2] row_mask:0xf bank_mask:0xf bound_ctrl:1
	v_fmac_f32_e32 v101, v26, v96
	v_mov_b32_dpp v26, v28 quad_perm:[2,3,0,1] row_mask:0xf bank_mask:0xf bound_ctrl:1
	v_fmac_f32_e32 v26, v28, v97
	v_mov_b32_dpp v28, v29 quad_perm:[2,3,0,1] row_mask:0xf bank_mask:0xf bound_ctrl:1
	v_fmac_f32_e32 v28, v29, v97
	v_mov_b32_dpp v29, v104 quad_perm:[2,3,0,1] row_mask:0xf bank_mask:0xf bound_ctrl:1
	ds_swizzle_b32 v125, v107 offset:swizzle(SWAP,4)
	v_fmac_f32_e32 v29, v104, v97
	v_mov_b32_dpp v104, v105 quad_perm:[2,3,0,1] row_mask:0xf bank_mask:0xf bound_ctrl:1
	v_fmac_f32_e32 v104, v105, v97
	v_mov_b32_dpp v105, v102 quad_perm:[2,3,0,1] row_mask:0xf bank_mask:0xf bound_ctrl:1
	v_fmac_f32_e32 v105, v102, v97
	v_mov_b32_dpp v102, v27 quad_perm:[2,3,0,1] row_mask:0xf bank_mask:0xf bound_ctrl:1
	ds_swizzle_b32 v126, v31 offset:swizzle(SWAP,4)
	ds_swizzle_b32 v127, v123 offset:swizzle(SWAP,4)
	v_fmac_f32_e32 v102, v27, v97
	v_mov_b32_dpp v27, v103 quad_perm:[2,3,0,1] row_mask:0xf bank_mask:0xf bound_ctrl:1
	v_mov_b32_dpp v108, v101 quad_perm:[2,3,0,1] row_mask:0xf bank_mask:0xf bound_ctrl:1
	ds_swizzle_b32 v124, v120 offset:swizzle(SWAP,4)
	v_fmac_f32_e32 v27, v103, v97
	ds_swizzle_b32 v103, v26 offset:swizzle(SWAP,4)
	ds_swizzle_b32 v106, v28 offset:swizzle(SWAP,4)
	v_fmac_f32_e32 v108, v101, v97
	s_waitcnt lgkmcnt(5)
	v_fmac_f32_e32 v125, v107, v98
	ds_swizzle_b32 v107, v29 offset:swizzle(SWAP,4)
	ds_swizzle_b32 v101, v104 offset:swizzle(SWAP,4)
	ds_swizzle_b32 v110, v102 offset:swizzle(SWAP,4)
	ds_swizzle_b32 v111, v27 offset:swizzle(SWAP,4)
	ds_swizzle_b32 v112, v108 offset:swizzle(SWAP,4)
	ds_swizzle_b32 v109, v105 offset:swizzle(SWAP,4)
	s_waitcnt lgkmcnt(10)
	v_fmac_f32_e32 v126, v31, v98
	s_waitcnt lgkmcnt(9)
	v_fmac_f32_e32 v127, v123, v98
	s_waitcnt lgkmcnt(8)
	v_fmac_f32_e32 v124, v120, v98
	v_max_f32_e64 v95, |v126|, |v127|
	s_waitcnt lgkmcnt(7)
	v_fmac_f32_e32 v103, v26, v98
	s_waitcnt lgkmcnt(6)
	v_fmac_f32_e32 v106, v28, v98
	v_max3_f32 v95, |v124|, |v125|, v95
	s_waitcnt lgkmcnt(5)
	v_fmac_f32_e32 v107, v29, v98
	s_waitcnt lgkmcnt(4)
	v_fmac_f32_e32 v101, v104, v98
	s_waitcnt lgkmcnt(3)
	v_fmac_f32_e32 v110, v102, v98
	s_waitcnt lgkmcnt(2)
	v_fmac_f32_e32 v111, v27, v98
	s_waitcnt lgkmcnt(1)
	v_fmac_f32_e32 v112, v108, v98
	v_max_f32_e64 v102, |v103|, |v106|
	v_cvt_pk_bf16_f32 v30, v124, v125
	v_cvt_pk_bf16_f32 v31, v126, v127
	s_waitcnt lgkmcnt(0)
	v_fmac_f32_e32 v109, v105, v98
	v_cvt_pk_bf16_f32 v28, v103, v106
	v_cvt_pk_bf16_f32 v29, v107, v101
	v_max3_f32 v94, v94, v95, v102
	v_max_f32_e64 v95, |v107|, |v101|
	v_max_f32_e64 v101, |v111|, |v112|
	v_max3_f32 v101, |v109|, |v110|, v101
	v_max3_f32 v94, v94, v95, v101
	v_cvt_pk_bf16_f32 v26, v109, v110
	v_cvt_pk_bf16_f32 v27, v111, v112
	v_lshlrev_b32_e32 v95, 16, v22
	v_and_b32_e32 v22, 0xffff0000, v22
	v_lshlrev_b32_e32 v101, 16, v23
	v_and_b32_e32 v23, 0xffff0000, v23
	v_lshlrev_b32_e32 v102, 16, v24
	v_and_b32_e32 v24, 0xffff0000, v24
	v_lshlrev_b32_e32 v103, 16, v25
	v_and_b32_e32 v25, 0xffff0000, v25
	v_add_f32_e32 v104, v95, v22
	v_sub_f32_e32 v22, v95, v22
	v_add_f32_e32 v95, v101, v23
	v_sub_f32_e32 v23, v101, v23
	v_add_f32_e32 v101, v102, v24
	v_sub_f32_e32 v24, v102, v24
	v_add_f32_e32 v102, v103, v25
	v_sub_f32_e32 v25, v103, v25
	v_add_f32_e32 v103, v104, v95
	v_sub_f32_e32 v95, v104, v95
	v_add_f32_e32 v104, v22, v23
	v_sub_f32_e32 v22, v22, v23
	v_add_f32_e32 v23, v101, v102
	v_sub_f32_e32 v101, v101, v102
	v_add_f32_e32 v102, v24, v25
	v_sub_f32_e32 v24, v24, v25
	v_add_f32_e32 v25, v103, v23
	v_sub_f32_e32 v23, v103, v23
	v_add_f32_e32 v103, v104, v102
	v_sub_f32_e32 v102, v104, v102
	v_add_f32_e32 v104, v95, v101
	v_sub_f32_e32 v95, v95, v101
	v_add_f32_e32 v101, v22, v24
	v_sub_f32_e32 v22, v22, v24
	v_mov_b32_dpp v24, v25 quad_perm:[1,0,3,2] row_mask:0xf bank_mask:0xf bound_ctrl:1
	v_fmac_f32_e32 v24, v25, v96
	v_mov_b32_dpp v25, v103 quad_perm:[1,0,3,2] row_mask:0xf bank_mask:0xf bound_ctrl:1
	v_fmac_f32_e32 v25, v103, v96
	v_mov_b32_dpp v103, v104 quad_perm:[1,0,3,2] row_mask:0xf bank_mask:0xf bound_ctrl:1
	v_fmac_f32_e32 v103, v104, v96
	v_mov_b32_dpp v104, v101 quad_perm:[1,0,3,2] row_mask:0xf bank_mask:0xf bound_ctrl:1
	v_fmac_f32_e32 v104, v101, v96
	v_mov_b32_dpp v101, v23 quad_perm:[1,0,3,2] row_mask:0xf bank_mask:0xf bound_ctrl:1
	v_fmac_f32_e32 v101, v23, v96
	v_mov_b32_dpp v23, v102 quad_perm:[1,0,3,2] row_mask:0xf bank_mask:0xf bound_ctrl:1
	v_fmac_f32_e32 v23, v102, v96
	v_mov_b32_dpp v102, v95 quad_perm:[1,0,3,2] row_mask:0xf bank_mask:0xf bound_ctrl:1
	v_fmac_f32_e32 v102, v95, v96
	v_mov_b32_dpp v95, v22 quad_perm:[1,0,3,2] row_mask:0xf bank_mask:0xf bound_ctrl:1
	v_fmac_f32_e32 v95, v22, v96
	v_mov_b32_dpp v22, v24 quad_perm:[2,3,0,1] row_mask:0xf bank_mask:0xf bound_ctrl:1
	v_fmac_f32_e32 v22, v24, v97
	v_mov_b32_dpp v24, v25 quad_perm:[2,3,0,1] row_mask:0xf bank_mask:0xf bound_ctrl:1
	v_fmac_f32_e32 v24, v25, v97
	v_mov_b32_dpp v25, v103 quad_perm:[2,3,0,1] row_mask:0xf bank_mask:0xf bound_ctrl:1
	v_fmac_f32_e32 v25, v103, v97
	v_mov_b32_dpp v103, v104 quad_perm:[2,3,0,1] row_mask:0xf bank_mask:0xf bound_ctrl:1
	v_fmac_f32_e32 v103, v104, v97
	v_mov_b32_dpp v104, v101 quad_perm:[2,3,0,1] row_mask:0xf bank_mask:0xf bound_ctrl:1
	v_fmac_f32_e32 v104, v101, v97
	v_mov_b32_dpp v101, v23 quad_perm:[2,3,0,1] row_mask:0xf bank_mask:0xf bound_ctrl:1
	v_mov_b32_dpp v107, v95 quad_perm:[2,3,0,1] row_mask:0xf bank_mask:0xf bound_ctrl:1
	v_fmac_f32_e32 v101, v23, v97
	v_fmac_f32_e32 v107, v95, v97
	ds_swizzle_b32 v95, v103 offset:swizzle(SWAP,4)
	ds_swizzle_b32 v108, v104 offset:swizzle(SWAP,4)
	ds_swizzle_b32 v109, v101 offset:swizzle(SWAP,4)
	ds_swizzle_b32 v111, v107 offset:swizzle(SWAP,4)
	v_mov_b32_dpp v23, v102 quad_perm:[2,3,0,1] row_mask:0xf bank_mask:0xf bound_ctrl:1
	s_waitcnt lgkmcnt(3)
	v_fmac_f32_e32 v95, v103, v98
	s_waitcnt lgkmcnt(2)
	v_fmac_f32_e32 v108, v104, v98
	s_waitcnt lgkmcnt(1)
	v_fmac_f32_e32 v109, v101, v98
	s_waitcnt lgkmcnt(0)
	v_fmac_f32_e32 v111, v107, v98
	v_lshlrev_b32_e32 v101, 16, v18
	v_and_b32_e32 v18, 0xffff0000, v18
	v_lshlrev_b32_e32 v103, 16, v19
	v_and_b32_e32 v19, 0xffff0000, v19
	v_lshlrev_b32_e32 v104, 16, v20
	v_and_b32_e32 v20, 0xffff0000, v20
	v_lshlrev_b32_e32 v107, 16, v21
	v_and_b32_e32 v21, 0xffff0000, v21
	v_add_f32_e32 v112, v101, v18
	v_sub_f32_e32 v18, v101, v18
	v_add_f32_e32 v101, v103, v19
	v_sub_f32_e32 v19, v103, v19
	v_add_f32_e32 v103, v104, v20
	v_sub_f32_e32 v20, v104, v20
	v_add_f32_e32 v104, v107, v21
	v_sub_f32_e32 v21, v107, v21
	v_add_f32_e32 v107, v112, v101
	v_sub_f32_e32 v101, v112, v101
	v_add_f32_e32 v112, v18, v19
	v_sub_f32_e32 v18, v18, v19
	v_add_f32_e32 v19, v103, v104
	v_sub_f32_e32 v103, v103, v104
	v_add_f32_e32 v104, v20, v21
	v_sub_f32_e32 v20, v20, v21
	v_add_f32_e32 v21, v107, v19
	v_sub_f32_e32 v19, v107, v19
	v_add_f32_e32 v107, v112, v104
	v_sub_f32_e32 v104, v112, v104
	v_add_f32_e32 v112, v101, v103
	v_sub_f32_e32 v101, v101, v103
	v_add_f32_e32 v103, v18, v20
	v_sub_f32_e32 v18, v18, v20
	v_mov_b32_dpp v20, v21 quad_perm:[1,0,3,2] row_mask:0xf bank_mask:0xf bound_ctrl:1
	v_fmac_f32_e32 v20, v21, v96
	v_mov_b32_dpp v21, v107 quad_perm:[1,0,3,2] row_mask:0xf bank_mask:0xf bound_ctrl:1
	v_fmac_f32_e32 v21, v107, v96
	v_mov_b32_dpp v107, v112 quad_perm:[1,0,3,2] row_mask:0xf bank_mask:0xf bound_ctrl:1
	v_fmac_f32_e32 v107, v112, v96
	v_mov_b32_dpp v112, v103 quad_perm:[1,0,3,2] row_mask:0xf bank_mask:0xf bound_ctrl:1
	v_fmac_f32_e32 v112, v103, v96
	v_mov_b32_dpp v103, v19 quad_perm:[1,0,3,2] row_mask:0xf bank_mask:0xf bound_ctrl:1
	v_fmac_f32_e32 v103, v19, v96
	v_mov_b32_dpp v19, v104 quad_perm:[1,0,3,2] row_mask:0xf bank_mask:0xf bound_ctrl:1
	v_fmac_f32_e32 v19, v104, v96
	v_mov_b32_dpp v104, v101 quad_perm:[1,0,3,2] row_mask:0xf bank_mask:0xf bound_ctrl:1
	v_fmac_f32_e32 v104, v101, v96
	v_mov_b32_dpp v101, v18 quad_perm:[1,0,3,2] row_mask:0xf bank_mask:0xf bound_ctrl:1
	v_fmac_f32_e32 v101, v18, v96
	v_mov_b32_dpp v18, v20 quad_perm:[2,3,0,1] row_mask:0xf bank_mask:0xf bound_ctrl:1
	v_fmac_f32_e32 v18, v20, v97
	v_mov_b32_dpp v20, v21 quad_perm:[2,3,0,1] row_mask:0xf bank_mask:0xf bound_ctrl:1
	v_fmac_f32_e32 v20, v21, v97
	v_mov_b32_dpp v21, v107 quad_perm:[2,3,0,1] row_mask:0xf bank_mask:0xf bound_ctrl:1
	v_fmac_f32_e32 v21, v107, v97
	v_mov_b32_dpp v107, v112 quad_perm:[2,3,0,1] row_mask:0xf bank_mask:0xf bound_ctrl:1
	v_fmac_f32_e32 v107, v112, v97
	v_mov_b32_dpp v112, v103 quad_perm:[2,3,0,1] row_mask:0xf bank_mask:0xf bound_ctrl:1
	v_fmac_f32_e32 v112, v103, v97
	v_mov_b32_dpp v103, v19 quad_perm:[2,3,0,1] row_mask:0xf bank_mask:0xf bound_ctrl:1
	v_mov_b32_dpp v115, v101 quad_perm:[2,3,0,1] row_mask:0xf bank_mask:0xf bound_ctrl:1
	v_fmac_f32_e32 v103, v19, v97
	v_fmac_f32_e32 v115, v101, v97
	ds_swizzle_b32 v101, v107 offset:swizzle(SWAP,4)
	ds_swizzle_b32 v116, v112 offset:swizzle(SWAP,4)
	ds_swizzle_b32 v117, v103 offset:swizzle(SWAP,4)
	ds_swizzle_b32 v119, v115 offset:swizzle(SWAP,4)
	v_fmac_f32_e32 v23, v102, v97
	s_waitcnt lgkmcnt(3)
	v_fmac_f32_e32 v101, v107, v98
	s_waitcnt lgkmcnt(2)
	v_fmac_f32_e32 v116, v112, v98
	s_waitcnt lgkmcnt(1)
	v_fmac_f32_e32 v117, v103, v98
	s_waitcnt lgkmcnt(0)
	v_fmac_f32_e32 v119, v115, v98
	v_lshlrev_b32_e32 v103, 16, v14
	v_and_b32_e32 v14, 0xffff0000, v14
	v_lshlrev_b32_e32 v107, 16, v15
	v_and_b32_e32 v15, 0xffff0000, v15
	v_lshlrev_b32_e32 v112, 16, v16
	v_and_b32_e32 v16, 0xffff0000, v16
	v_lshlrev_b32_e32 v115, 16, v17
	v_and_b32_e32 v17, 0xffff0000, v17
	v_add_f32_e32 v120, v103, v14
	v_sub_f32_e32 v14, v103, v14
	v_add_f32_e32 v103, v107, v15
	v_sub_f32_e32 v15, v107, v15
	v_add_f32_e32 v107, v112, v16
	v_sub_f32_e32 v16, v112, v16
	v_add_f32_e32 v112, v115, v17
	v_sub_f32_e32 v17, v115, v17
	v_add_f32_e32 v115, v120, v103
	v_sub_f32_e32 v103, v120, v103
	v_add_f32_e32 v120, v14, v15
	v_sub_f32_e32 v14, v14, v15
	v_add_f32_e32 v15, v107, v112
	v_sub_f32_e32 v107, v107, v112
	v_add_f32_e32 v112, v16, v17
	v_sub_f32_e32 v16, v16, v17
	v_add_f32_e32 v17, v115, v15
	v_sub_f32_e32 v15, v115, v15
	v_add_f32_e32 v115, v120, v112
	v_sub_f32_e32 v112, v120, v112
	v_add_f32_e32 v120, v103, v107
	v_sub_f32_e32 v103, v103, v107
	v_add_f32_e32 v107, v14, v16
	v_sub_f32_e32 v14, v14, v16
	v_mov_b32_dpp v16, v17 quad_perm:[1,0,3,2] row_mask:0xf bank_mask:0xf bound_ctrl:1
	v_fmac_f32_e32 v16, v17, v96
	v_mov_b32_dpp v17, v115 quad_perm:[1,0,3,2] row_mask:0xf bank_mask:0xf bound_ctrl:1
	v_fmac_f32_e32 v17, v115, v96
	v_mov_b32_dpp v115, v120 quad_perm:[1,0,3,2] row_mask:0xf bank_mask:0xf bound_ctrl:1
	v_fmac_f32_e32 v115, v120, v96
	v_mov_b32_dpp v120, v107 quad_perm:[1,0,3,2] row_mask:0xf bank_mask:0xf bound_ctrl:1
	v_fmac_f32_e32 v120, v107, v96
	v_mov_b32_dpp v107, v15 quad_perm:[1,0,3,2] row_mask:0xf bank_mask:0xf bound_ctrl:1
	v_fmac_f32_e32 v107, v15, v96
	v_mov_b32_dpp v15, v112 quad_perm:[1,0,3,2] row_mask:0xf bank_mask:0xf bound_ctrl:1
	v_fmac_f32_e32 v15, v112, v96
	v_mov_b32_dpp v112, v103 quad_perm:[1,0,3,2] row_mask:0xf bank_mask:0xf bound_ctrl:1
	v_fmac_f32_e32 v112, v103, v96
	v_mov_b32_dpp v103, v14 quad_perm:[1,0,3,2] row_mask:0xf bank_mask:0xf bound_ctrl:1
	v_fmac_f32_e32 v103, v14, v96
	v_mov_b32_dpp v14, v16 quad_perm:[2,3,0,1] row_mask:0xf bank_mask:0xf bound_ctrl:1
	v_fmac_f32_e32 v14, v16, v97
	v_mov_b32_dpp v16, v17 quad_perm:[2,3,0,1] row_mask:0xf bank_mask:0xf bound_ctrl:1
	ds_swizzle_b32 v102, v22 offset:swizzle(SWAP,4)
	ds_swizzle_b32 v105, v24 offset:swizzle(SWAP,4)
	ds_swizzle_b32 v106, v25 offset:swizzle(SWAP,4)
	v_fmac_f32_e32 v16, v17, v97
	v_mov_b32_dpp v17, v115 quad_perm:[2,3,0,1] row_mask:0xf bank_mask:0xf bound_ctrl:1
	ds_swizzle_b32 v110, v23 offset:swizzle(SWAP,4)
	v_mov_b32_dpp v19, v104 quad_perm:[2,3,0,1] row_mask:0xf bank_mask:0xf bound_ctrl:1
	v_fmac_f32_e32 v17, v115, v97
	v_mov_b32_dpp v115, v120 quad_perm:[2,3,0,1] row_mask:0xf bank_mask:0xf bound_ctrl:1
	v_fmac_f32_e32 v19, v104, v97
	ds_swizzle_b32 v104, v18 offset:swizzle(SWAP,4)
	ds_swizzle_b32 v113, v20 offset:swizzle(SWAP,4)
	v_fmac_f32_e32 v115, v120, v97
	v_mov_b32_dpp v120, v107 quad_perm:[2,3,0,1] row_mask:0xf bank_mask:0xf bound_ctrl:1
	ds_swizzle_b32 v114, v21 offset:swizzle(SWAP,4)
	ds_swizzle_b32 v118, v19 offset:swizzle(SWAP,4)
	v_fmac_f32_e32 v120, v107, v97
	v_mov_b32_dpp v107, v15 quad_perm:[2,3,0,1] row_mask:0xf bank_mask:0xf bound_ctrl:1
	v_fmac_f32_e32 v107, v15, v97
	v_mov_b32_dpp v15, v112 quad_perm:[2,3,0,1] row_mask:0xf bank_mask:0xf bound_ctrl:1
	v_mov_b32_dpp v123, v103 quad_perm:[2,3,0,1] row_mask:0xf bank_mask:0xf bound_ctrl:1
	s_waitcnt lgkmcnt(7)
	v_fmac_f32_e32 v102, v22, v98
	s_waitcnt lgkmcnt(6)
	v_fmac_f32_e32 v105, v24, v98
	s_waitcnt lgkmcnt(5)
	v_fmac_f32_e32 v106, v25, v98
	v_fmac_f32_e32 v15, v112, v97
	ds_swizzle_b32 v112, v14 offset:swizzle(SWAP,4)
	ds_swizzle_b32 v121, v16 offset:swizzle(SWAP,4)
	ds_swizzle_b32 v122, v17 offset:swizzle(SWAP,4)
	v_fmac_f32_e32 v123, v103, v97
	ds_swizzle_b32 v103, v115 offset:swizzle(SWAP,4)
	s_waitcnt lgkmcnt(8)
	v_fmac_f32_e32 v110, v23, v98
	v_cvt_pk_bf16_f32 v24, v102, v105
	v_cvt_pk_bf16_f32 v25, v106, v95
	v_max_f32_e64 v102, |v102|, |v105|
	v_max_f32_e64 v95, |v106|, |v95|
	s_waitcnt lgkmcnt(7)
	v_fmac_f32_e32 v104, v18, v98
	s_waitcnt lgkmcnt(6)
	v_fmac_f32_e32 v113, v20, v98
	v_max3_f32 v94, v94, v102, v95
	v_max_f32_e64 v95, |v110|, |v111|
	s_waitcnt lgkmcnt(5)
	v_fmac_f32_e32 v114, v21, v98
	s_waitcnt lgkmcnt(4)
	v_fmac_f32_e32 v118, v19, v98
	v_max3_f32 v95, |v108|, |v109|, v95
	v_max_f32_e64 v102, |v104|, |v113|
	v_cvt_pk_bf16_f32 v22, v108, v109
	v_cvt_pk_bf16_f32 v23, v110, v111
	v_cvt_pk_bf16_f32 v20, v104, v113
	v_cvt_pk_bf16_f32 v21, v114, v101
	v_max3_f32 v94, v94, v95, v102
	v_max_f32_e64 v95, |v114|, |v101|
	v_max_f32_e64 v101, |v118|, |v119|
	s_waitcnt lgkmcnt(3)
	v_fmac_f32_e32 v112, v14, v98
	s_waitcnt lgkmcnt(2)
	v_fmac_f32_e32 v121, v16, v98
	s_waitcnt lgkmcnt(1)
	v_fmac_f32_e32 v122, v17, v98
	s_waitcnt lgkmcnt(0)
	v_fmac_f32_e32 v103, v115, v98
	v_max3_f32 v101, |v116|, |v117|, v101
	v_max3_f32 v94, v94, v95, v101
	v_max_f32_e64 v95, |v112|, |v121|
	v_max_f32_e64 v101, |v122|, |v103|
	v_cvt_pk_bf16_f32 v18, v116, v117
	v_cvt_pk_bf16_f32 v19, v118, v119
	v_cvt_pk_bf16_f32 v16, v112, v121
	v_cvt_pk_bf16_f32 v17, v122, v103
	v_max3_f32 v94, v94, v95, v101
	v_lshlrev_b32_e32 v101, 16, v10
	v_and_b32_e32 v10, 0xffff0000, v10
	v_lshlrev_b32_e32 v102, 16, v11
	v_and_b32_e32 v11, 0xffff0000, v11
	v_lshlrev_b32_e32 v103, 16, v12
	v_and_b32_e32 v12, 0xffff0000, v12
	v_lshlrev_b32_e32 v104, 16, v13
	v_and_b32_e32 v13, 0xffff0000, v13
	v_add_f32_e32 v105, v101, v10
	v_sub_f32_e32 v10, v101, v10
	v_add_f32_e32 v101, v102, v11
	v_sub_f32_e32 v11, v102, v11
	v_add_f32_e32 v102, v103, v12
	v_sub_f32_e32 v12, v103, v12
	v_add_f32_e32 v103, v104, v13
	v_sub_f32_e32 v13, v104, v13
	v_add_f32_e32 v104, v105, v101
	v_sub_f32_e32 v101, v105, v101
	v_add_f32_e32 v105, v10, v11
	v_sub_f32_e32 v10, v10, v11
	v_add_f32_e32 v11, v102, v103
	v_sub_f32_e32 v102, v102, v103
	v_add_f32_e32 v103, v12, v13
	v_sub_f32_e32 v12, v12, v13
	v_add_f32_e32 v13, v104, v11
	v_sub_f32_e32 v11, v104, v11
	v_add_f32_e32 v104, v105, v103
	v_sub_f32_e32 v103, v105, v103
	v_add_f32_e32 v105, v101, v102
	v_sub_f32_e32 v101, v101, v102
	v_add_f32_e32 v102, v10, v12
	v_sub_f32_e32 v10, v10, v12
	v_mov_b32_dpp v12, v13 quad_perm:[1,0,3,2] row_mask:0xf bank_mask:0xf bound_ctrl:1
	v_fmac_f32_e32 v12, v13, v96
	v_mov_b32_dpp v13, v104 quad_perm:[1,0,3,2] row_mask:0xf bank_mask:0xf bound_ctrl:1
	v_fmac_f32_e32 v13, v104, v96
	v_mov_b32_dpp v104, v105 quad_perm:[1,0,3,2] row_mask:0xf bank_mask:0xf bound_ctrl:1
	v_fmac_f32_e32 v104, v105, v96
	v_mov_b32_dpp v105, v102 quad_perm:[1,0,3,2] row_mask:0xf bank_mask:0xf bound_ctrl:1
	v_fmac_f32_e32 v105, v102, v96
	v_mov_b32_dpp v102, v11 quad_perm:[1,0,3,2] row_mask:0xf bank_mask:0xf bound_ctrl:1
	v_fmac_f32_e32 v102, v11, v96
	v_mov_b32_dpp v11, v103 quad_perm:[1,0,3,2] row_mask:0xf bank_mask:0xf bound_ctrl:1
	v_fmac_f32_e32 v11, v103, v96
	v_mov_b32_dpp v103, v101 quad_perm:[1,0,3,2] row_mask:0xf bank_mask:0xf bound_ctrl:1
	v_fmac_f32_e32 v103, v101, v96
	v_mov_b32_dpp v101, v10 quad_perm:[1,0,3,2] row_mask:0xf bank_mask:0xf bound_ctrl:1
	v_fmac_f32_e32 v101, v10, v96
	v_mov_b32_dpp v10, v12 quad_perm:[2,3,0,1] row_mask:0xf bank_mask:0xf bound_ctrl:1
	v_fmac_f32_e32 v10, v12, v97
	v_mov_b32_dpp v12, v13 quad_perm:[2,3,0,1] row_mask:0xf bank_mask:0xf bound_ctrl:1
	v_fmac_f32_e32 v12, v13, v97
	v_mov_b32_dpp v13, v104 quad_perm:[2,3,0,1] row_mask:0xf bank_mask:0xf bound_ctrl:1
	ds_swizzle_b32 v125, v107 offset:swizzle(SWAP,4)
	v_fmac_f32_e32 v13, v104, v97
	v_mov_b32_dpp v104, v105 quad_perm:[2,3,0,1] row_mask:0xf bank_mask:0xf bound_ctrl:1
	v_fmac_f32_e32 v104, v105, v97
	v_mov_b32_dpp v105, v102 quad_perm:[2,3,0,1] row_mask:0xf bank_mask:0xf bound_ctrl:1
	v_fmac_f32_e32 v105, v102, v97
	v_mov_b32_dpp v102, v11 quad_perm:[2,3,0,1] row_mask:0xf bank_mask:0xf bound_ctrl:1
	ds_swizzle_b32 v126, v15 offset:swizzle(SWAP,4)
	ds_swizzle_b32 v127, v123 offset:swizzle(SWAP,4)
	v_fmac_f32_e32 v102, v11, v97
	v_mov_b32_dpp v11, v103 quad_perm:[2,3,0,1] row_mask:0xf bank_mask:0xf bound_ctrl:1
	v_mov_b32_dpp v108, v101 quad_perm:[2,3,0,1] row_mask:0xf bank_mask:0xf bound_ctrl:1
	ds_swizzle_b32 v124, v120 offset:swizzle(SWAP,4)
	v_fmac_f32_e32 v11, v103, v97
	ds_swizzle_b32 v103, v10 offset:swizzle(SWAP,4)
	ds_swizzle_b32 v106, v12 offset:swizzle(SWAP,4)
	v_fmac_f32_e32 v108, v101, v97
	s_waitcnt lgkmcnt(5)
	v_fmac_f32_e32 v125, v107, v98
	ds_swizzle_b32 v107, v13 offset:swizzle(SWAP,4)
	ds_swizzle_b32 v101, v104 offset:swizzle(SWAP,4)
	ds_swizzle_b32 v110, v102 offset:swizzle(SWAP,4)
	ds_swizzle_b32 v111, v11 offset:swizzle(SWAP,4)
	ds_swizzle_b32 v112, v108 offset:swizzle(SWAP,4)
	ds_swizzle_b32 v109, v105 offset:swizzle(SWAP,4)
	s_waitcnt lgkmcnt(10)
	v_fmac_f32_e32 v126, v15, v98
	s_waitcnt lgkmcnt(9)
	v_fmac_f32_e32 v127, v123, v98
	s_waitcnt lgkmcnt(8)
	v_fmac_f32_e32 v124, v120, v98
	v_max_f32_e64 v95, |v126|, |v127|
	s_waitcnt lgkmcnt(7)
	v_fmac_f32_e32 v103, v10, v98
	s_waitcnt lgkmcnt(6)
	v_fmac_f32_e32 v106, v12, v98
	v_max3_f32 v95, |v124|, |v125|, v95
	s_waitcnt lgkmcnt(5)
	v_fmac_f32_e32 v107, v13, v98
	s_waitcnt lgkmcnt(4)
	v_fmac_f32_e32 v101, v104, v98
	s_waitcnt lgkmcnt(3)
	v_fmac_f32_e32 v110, v102, v98
	s_waitcnt lgkmcnt(2)
	v_fmac_f32_e32 v111, v11, v98
	s_waitcnt lgkmcnt(1)
	v_fmac_f32_e32 v112, v108, v98
	v_max_f32_e64 v102, |v103|, |v106|
	v_cvt_pk_bf16_f32 v14, v124, v125
	v_cvt_pk_bf16_f32 v15, v126, v127
	s_waitcnt lgkmcnt(0)
	v_fmac_f32_e32 v109, v105, v98
	v_cvt_pk_bf16_f32 v12, v103, v106
	v_cvt_pk_bf16_f32 v13, v107, v101
	v_max3_f32 v94, v94, v95, v102
	v_max_f32_e64 v95, |v107|, |v101|
	v_max_f32_e64 v101, |v111|, |v112|
	v_max3_f32 v101, |v109|, |v110|, v101
	v_max3_f32 v94, v94, v95, v101
	v_cvt_pk_bf16_f32 v10, v109, v110
	v_cvt_pk_bf16_f32 v11, v111, v112
	v_lshlrev_b32_e32 v95, 16, v6
	v_and_b32_e32 v6, 0xffff0000, v6
	v_lshlrev_b32_e32 v101, 16, v7
	v_and_b32_e32 v7, 0xffff0000, v7
	v_lshlrev_b32_e32 v102, 16, v8
	v_and_b32_e32 v8, 0xffff0000, v8
	v_lshlrev_b32_e32 v103, 16, v9
	v_and_b32_e32 v9, 0xffff0000, v9
	v_add_f32_e32 v104, v95, v6
	v_sub_f32_e32 v6, v95, v6
	v_add_f32_e32 v95, v101, v7
	v_sub_f32_e32 v7, v101, v7
	v_add_f32_e32 v101, v102, v8
	v_sub_f32_e32 v8, v102, v8
	v_add_f32_e32 v102, v103, v9
	v_sub_f32_e32 v9, v103, v9
	v_add_f32_e32 v103, v104, v95
	v_sub_f32_e32 v95, v104, v95
	v_add_f32_e32 v104, v6, v7
	v_sub_f32_e32 v6, v6, v7
	v_add_f32_e32 v7, v101, v102
	v_sub_f32_e32 v101, v101, v102
	v_add_f32_e32 v102, v8, v9
	v_sub_f32_e32 v8, v8, v9
	v_add_f32_e32 v9, v103, v7
	v_sub_f32_e32 v7, v103, v7
	v_add_f32_e32 v103, v104, v102
	v_sub_f32_e32 v102, v104, v102
	v_add_f32_e32 v104, v95, v101
	v_sub_f32_e32 v95, v95, v101
	v_add_f32_e32 v101, v6, v8
	v_sub_f32_e32 v6, v6, v8
	v_mov_b32_dpp v8, v9 quad_perm:[1,0,3,2] row_mask:0xf bank_mask:0xf bound_ctrl:1
	v_fmac_f32_e32 v8, v9, v96
	v_mov_b32_dpp v9, v103 quad_perm:[1,0,3,2] row_mask:0xf bank_mask:0xf bound_ctrl:1
	v_fmac_f32_e32 v9, v103, v96
	v_mov_b32_dpp v103, v104 quad_perm:[1,0,3,2] row_mask:0xf bank_mask:0xf bound_ctrl:1
	v_fmac_f32_e32 v103, v104, v96
	v_mov_b32_dpp v104, v101 quad_perm:[1,0,3,2] row_mask:0xf bank_mask:0xf bound_ctrl:1
	v_fmac_f32_e32 v104, v101, v96
	v_mov_b32_dpp v101, v7 quad_perm:[1,0,3,2] row_mask:0xf bank_mask:0xf bound_ctrl:1
	v_fmac_f32_e32 v101, v7, v96
	v_mov_b32_dpp v7, v102 quad_perm:[1,0,3,2] row_mask:0xf bank_mask:0xf bound_ctrl:1
	v_fmac_f32_e32 v7, v102, v96
	v_mov_b32_dpp v102, v95 quad_perm:[1,0,3,2] row_mask:0xf bank_mask:0xf bound_ctrl:1
	v_fmac_f32_e32 v102, v95, v96
	v_mov_b32_dpp v95, v6 quad_perm:[1,0,3,2] row_mask:0xf bank_mask:0xf bound_ctrl:1
	v_fmac_f32_e32 v95, v6, v96
	v_mov_b32_dpp v6, v8 quad_perm:[2,3,0,1] row_mask:0xf bank_mask:0xf bound_ctrl:1
	v_fmac_f32_e32 v6, v8, v97
	v_mov_b32_dpp v8, v9 quad_perm:[2,3,0,1] row_mask:0xf bank_mask:0xf bound_ctrl:1
	v_fmac_f32_e32 v8, v9, v97
	v_mov_b32_dpp v9, v103 quad_perm:[2,3,0,1] row_mask:0xf bank_mask:0xf bound_ctrl:1
	v_fmac_f32_e32 v9, v103, v97
	v_mov_b32_dpp v103, v104 quad_perm:[2,3,0,1] row_mask:0xf bank_mask:0xf bound_ctrl:1
	v_fmac_f32_e32 v103, v104, v97
	v_mov_b32_dpp v104, v101 quad_perm:[2,3,0,1] row_mask:0xf bank_mask:0xf bound_ctrl:1
	v_fmac_f32_e32 v104, v101, v97
	v_mov_b32_dpp v101, v7 quad_perm:[2,3,0,1] row_mask:0xf bank_mask:0xf bound_ctrl:1
	v_fmac_f32_e32 v101, v7, v97
	v_mov_b32_dpp v7, v102 quad_perm:[2,3,0,1] row_mask:0xf bank_mask:0xf bound_ctrl:1
	v_fmac_f32_e32 v7, v102, v97
	ds_swizzle_b32 v102, v6 offset:swizzle(SWAP,4)
	ds_swizzle_b32 v105, v8 offset:swizzle(SWAP,4)
	ds_swizzle_b32 v106, v9 offset:swizzle(SWAP,4)
	v_mov_b32_dpp v107, v95 quad_perm:[2,3,0,1] row_mask:0xf bank_mask:0xf bound_ctrl:1
	v_fmac_f32_e32 v107, v95, v97
	s_waitcnt lgkmcnt(2)
	v_fmac_f32_e32 v102, v6, v98
	s_waitcnt lgkmcnt(1)
	v_fmac_f32_e32 v105, v8, v98
	s_waitcnt lgkmcnt(0)
	v_fmac_f32_e32 v106, v9, v98
	ds_swizzle_b32 v6, v103 offset:swizzle(SWAP,4)
	ds_swizzle_b32 v8, v104 offset:swizzle(SWAP,4)
	ds_swizzle_b32 v9, v101 offset:swizzle(SWAP,4)
	ds_swizzle_b32 v95, v7 offset:swizzle(SWAP,4)
	ds_swizzle_b32 v108, v107 offset:swizzle(SWAP,4)
	s_waitcnt lgkmcnt(4)
	v_fmac_f32_e32 v6, v103, v98
	s_waitcnt lgkmcnt(3)
	v_fmac_f32_e32 v8, v104, v98
	s_waitcnt lgkmcnt(2)
	v_fmac_f32_e32 v9, v101, v98
	s_waitcnt lgkmcnt(1)
	v_fmac_f32_e32 v95, v7, v98
	v_lshlrev_b32_e32 v7, 16, v2
	v_and_b32_e32 v2, 0xffff0000, v2
	v_lshlrev_b32_e32 v101, 16, v3
	v_and_b32_e32 v3, 0xffff0000, v3
	v_lshlrev_b32_e32 v103, 16, v4
	v_and_b32_e32 v4, 0xffff0000, v4
	v_lshlrev_b32_e32 v104, 16, v5
	v_and_b32_e32 v5, 0xffff0000, v5
	s_waitcnt lgkmcnt(0)
	v_fmac_f32_e32 v108, v107, v98
	v_add_f32_e32 v107, v7, v2
	v_sub_f32_e32 v2, v7, v2
	v_add_f32_e32 v7, v101, v3
	v_sub_f32_e32 v3, v101, v3
	v_add_f32_e32 v101, v103, v4
	v_sub_f32_e32 v4, v103, v4
	v_add_f32_e32 v103, v104, v5
	v_sub_f32_e32 v5, v104, v5
	v_add_f32_e32 v104, v107, v7
	v_sub_f32_e32 v7, v107, v7
	v_add_f32_e32 v107, v2, v3
	v_sub_f32_e32 v2, v2, v3
	v_add_f32_e32 v3, v101, v103
	v_sub_f32_e32 v101, v101, v103
	v_add_f32_e32 v103, v4, v5
	v_sub_f32_e32 v4, v4, v5
	v_add_f32_e32 v5, v104, v3
	v_sub_f32_e32 v3, v104, v3
	v_add_f32_e32 v104, v107, v103
	v_sub_f32_e32 v103, v107, v103
	v_add_f32_e32 v107, v7, v101
	v_sub_f32_e32 v7, v7, v101
	v_add_f32_e32 v101, v2, v4
	v_sub_f32_e32 v2, v2, v4
	v_mov_b32_dpp v4, v5 quad_perm:[1,0,3,2] row_mask:0xf bank_mask:0xf bound_ctrl:1
	v_fmac_f32_e32 v4, v5, v96
	v_mov_b32_dpp v5, v104 quad_perm:[1,0,3,2] row_mask:0xf bank_mask:0xf bound_ctrl:1
	v_fmac_f32_e32 v5, v104, v96
	v_mov_b32_dpp v104, v107 quad_perm:[1,0,3,2] row_mask:0xf bank_mask:0xf bound_ctrl:1
	v_fmac_f32_e32 v104, v107, v96
	v_mov_b32_dpp v107, v101 quad_perm:[1,0,3,2] row_mask:0xf bank_mask:0xf bound_ctrl:1
	v_fmac_f32_e32 v107, v101, v96
	v_mov_b32_dpp v101, v3 quad_perm:[1,0,3,2] row_mask:0xf bank_mask:0xf bound_ctrl:1
	v_fmac_f32_e32 v101, v3, v96
	v_mov_b32_dpp v3, v103 quad_perm:[1,0,3,2] row_mask:0xf bank_mask:0xf bound_ctrl:1
	v_fmac_f32_e32 v3, v103, v96
	v_mov_b32_dpp v103, v7 quad_perm:[1,0,3,2] row_mask:0xf bank_mask:0xf bound_ctrl:1
	v_fmac_f32_e32 v103, v7, v96
	v_mov_b32_dpp v7, v2 quad_perm:[1,0,3,2] row_mask:0xf bank_mask:0xf bound_ctrl:1
	v_fmac_f32_e32 v7, v2, v96
	v_mov_b32_dpp v2, v4 quad_perm:[2,3,0,1] row_mask:0xf bank_mask:0xf bound_ctrl:1
	v_fmac_f32_e32 v2, v4, v97
	v_mov_b32_dpp v4, v5 quad_perm:[2,3,0,1] row_mask:0xf bank_mask:0xf bound_ctrl:1
	v_fmac_f32_e32 v4, v5, v97
	v_mov_b32_dpp v5, v104 quad_perm:[2,3,0,1] row_mask:0xf bank_mask:0xf bound_ctrl:1
	v_fmac_f32_e32 v5, v104, v97
	v_mov_b32_dpp v104, v107 quad_perm:[2,3,0,1] row_mask:0xf bank_mask:0xf bound_ctrl:1
	ds_swizzle_b32 v111, v5 offset:swizzle(SWAP,4)
	v_fmac_f32_e32 v104, v107, v97
	v_mov_b32_dpp v107, v101 quad_perm:[2,3,0,1] row_mask:0xf bank_mask:0xf bound_ctrl:1
	v_fmac_f32_e32 v107, v101, v97
	v_mov_b32_dpp v101, v3 quad_perm:[2,3,0,1] row_mask:0xf bank_mask:0xf bound_ctrl:1
	v_fmac_f32_e32 v101, v3, v97
	v_mov_b32_dpp v3, v103 quad_perm:[2,3,0,1] row_mask:0xf bank_mask:0xf bound_ctrl:1
	ds_swizzle_b32 v109, v2 offset:swizzle(SWAP,4)
	ds_swizzle_b32 v110, v4 offset:swizzle(SWAP,4)
	v_fmac_f32_e32 v3, v103, v97
	v_mov_b32_dpp v103, v7 quad_perm:[2,3,0,1] row_mask:0xf bank_mask:0xf bound_ctrl:1
	v_fmac_f32_e32 v103, v7, v97
	s_waitcnt lgkmcnt(2)
	v_fmac_f32_e32 v111, v5, v98
	ds_swizzle_b32 v5, v101 offset:swizzle(SWAP,4)
	ds_swizzle_b32 v7, v3 offset:swizzle(SWAP,4)
	ds_swizzle_b32 v112, v103 offset:swizzle(SWAP,4)
	s_waitcnt lgkmcnt(4)
	v_fmac_f32_e32 v109, v2, v98
	s_waitcnt lgkmcnt(3)
	v_fmac_f32_e32 v110, v4, v98
	ds_swizzle_b32 v2, v104 offset:swizzle(SWAP,4)
	ds_swizzle_b32 v4, v107 offset:swizzle(SWAP,4)
	s_waitcnt lgkmcnt(4)
	v_fmac_f32_e32 v5, v101, v98
	s_waitcnt lgkmcnt(3)
	v_fmac_f32_e32 v7, v3, v98
	v_max_f32_e64 v3, |v102|, |v105|
	v_max_f32_e64 v101, |v106|, |v6|
	v_max3_f32 v3, v94, v3, v101
	v_max_f32_e64 v94, |v95|, |v108|
	s_waitcnt lgkmcnt(2)
	v_fmac_f32_e32 v112, v103, v98
	v_max3_f32 v94, |v8|, |v9|, v94
	v_max_f32_e64 v101, |v109|, |v110|
	s_waitcnt lgkmcnt(1)
	v_fmac_f32_e32 v2, v104, v98
	s_waitcnt lgkmcnt(0)
	v_fmac_f32_e32 v4, v107, v98
	v_max3_f32 v3, v3, v94, v101
	v_max_f32_e64 v101, |v7|, |v112|
	v_max_f32_e64 v94, |v111|, |v2|
	v_max3_f32 v101, |v4|, |v5|, v101
	v_max3_f32 v3, v3, v94, v101
	v_and_b32_e32 v94, 64, v99
	v_add_u32_e32 v104, 64, v94
	v_xor_b32_e32 v94, 1, v99
	v_cmp_lt_i32_e32 vcc, v94, v104
	v_cvt_pk_bf16_f32 v101, v102, v105
	v_cvt_pk_bf16_f32 v103, v106, v6
	s_nop 1
	v_cndmask_b32_e32 v94, v99, v94, vcc
	v_lshlrev_b32_e32 v94, 2, v94
	ds_bpermute_b32 v94, v94, v3
	s_waitcnt lgkmcnt(0)
	v_max_f32_e32 v94, v94, v94
	v_max_f32_e32 v3, v3, v94
	v_xor_b32_e32 v94, 2, v99
	v_cmp_lt_i32_e32 vcc, v94, v104
	s_nop 1
	v_cndmask_b32_e32 v94, v99, v94, vcc
	v_lshlrev_b32_e32 v94, 2, v94
	ds_bpermute_b32 v94, v94, v3
	s_waitcnt lgkmcnt(0)
	v_max_f32_e32 v94, v94, v94
	v_max_f32_e32 v3, v3, v94
	v_xor_b32_e32 v94, 4, v99
	v_cmp_lt_i32_e32 vcc, v94, v104
	s_nop 1
	v_cndmask_b32_e32 v94, v99, v94, vcc
	v_lshlrev_b32_e32 v94, 2, v94
	ds_bpermute_b32 v94, v94, v3
	s_waitcnt lgkmcnt(0)
	v_max_f32_e32 v94, v94, v94
	v_max_f32_e32 v3, v3, v94
	v_xor_b32_e32 v94, 8, v99
	v_cmp_lt_i32_e32 vcc, v94, v104
	s_nop 1
	v_cndmask_b32_e32 v94, v99, v94, vcc
	v_lshlrev_b32_e32 v94, 2, v94
	ds_bpermute_b32 v94, v94, v3
	s_waitcnt lgkmcnt(0)
	v_max_f32_e32 v94, v94, v94
	v_max_f32_e32 v3, v3, v94
	v_xor_b32_e32 v94, 16, v99
	v_cmp_lt_i32_e32 vcc, v94, v104
	s_nop 1
	v_cndmask_b32_e32 v94, v99, v94, vcc
	v_lshlrev_b32_e32 v94, 2, v94
	ds_bpermute_b32 v107, v94, v3
	v_cvt_pk_bf16_f32 v94, v8, v9
	v_cvt_pk_bf16_f32 v95, v95, v108
	v_cvt_pk_bf16_f32 v8, v109, v110
	v_cvt_pk_bf16_f32 v9, v111, v2
	s_waitcnt lgkmcnt(0)
	v_max_f32_e32 v6, v107, v107
	v_max_f32_e32 v3, v3, v6
	v_xor_b32_e32 v6, 32, v99
	v_cmp_lt_i32_e32 vcc, v6, v104
	s_nop 1
	v_cndmask_b32_e32 v6, v99, v6, vcc
	v_lshlrev_b32_e32 v6, 2, v6
	ds_bpermute_b32 v102, v6, v3
	v_cvt_pk_bf16_f32 v6, v4, v5
	v_cvt_pk_bf16_f32 v7, v7, v112
	s_waitcnt lgkmcnt(0)
	v_max3_f32 v2, v3, v102, s46
	s_and_saveexec_b64 s[0:1], s[8:9]
	s_cbranch_execz .LBB0_1521
	s_ashr_i32 s27, s26, 31
	s_lshl_b64 s[38:39], s[26:27], 2
	s_add_u32 s38, s34, s38
	v_mul_f32_e32 v3, 0x3a810204, v2
	s_addc_u32 s39, s35, s39
	global_store_dword v1, v3, s[38:39]

.LBB0_1600:
	ds_read_b128 v[146:149], v156
	ds_read_b128 v[150:153], v156 offset:1024
	ds_read_b128 v[160:163], v156 offset:2048
	ds_read_b128 v[164:167], v156 offset:3072
	ds_read_b128 v[168:171], v157
	ds_read_b128 v[172:175], v157 offset:1024
	ds_read_b128 v[176:179], v157 offset:2048
	ds_read_b128 v[180:183], v157 offset:3072
	s_add_u32 s42, s0, 0x100
	s_addc_u32 s43, s1, 0
	s_cmpk_eq_i32 s70, 0x52
	s_cselect_b32 s47, s7, s43
	s_cselect_b32 s46, s6, s42
	s_cselect_b32 s45, s41, s69
	s_cselect_b32 s44, s40, s68
	v_lshl_add_u64 v[216:217], s[0:1], 0, v[138:139]
	s_add_i32 m0, s49, 0xc000
	ds_read_b128 v[184:187], v158
	ds_read_b128 v[188:191], v158 offset:1024
	ds_read_b128 v[192:195], v158 offset:2048
	ds_read_b128 v[196:199], v158 offset:3072
	ds_read_b128 v[200:203], v158 offset:4096
	ds_read_b128 v[204:207], v158 offset:5120
	ds_read_b128 v[208:211], v158 offset:6144
	ds_read_b128 v[212:215], v158 offset:7168
	global_load_lds_dwordx4 v[216:217], off
	v_lshl_add_u64 v[216:217], s[0:1], 0, v[140:141]
	s_add_i32 m0, s49, 0xe000
	s_nop 0
	global_load_lds_dwordx4 v[216:217], off
	s_waitcnt vmcnt(8)
	s_waitcnt lgkmcnt(0)
	s_barrier
	s_setprio 2
	s_waitcnt lgkmcnt(0)
	v_mfma_i32_16x16x64_i8 v[126:129], v[146:149], v[184:187], v[126:129]
	v_mfma_i32_16x16x64_i8 v[122:125], v[160:163], v[184:187], v[122:125]
	v_mfma_i32_16x16x64_i8 v[118:121], v[146:149], v[192:195], v[118:121]
	v_mfma_i32_16x16x64_i8 v[114:117], v[160:163], v[192:195], v[114:117]
	v_mfma_i32_16x16x64_i8 v[110:113], v[146:149], v[200:203], v[110:113]
	v_mfma_i32_16x16x64_i8 v[106:109], v[160:163], v[200:203], v[106:109]
	v_mfma_i32_16x16x64_i8 v[102:105], v[146:149], v[208:211], v[102:105]
	v_mfma_i32_16x16x64_i8 v[98:101], v[160:163], v[208:211], v[98:101]
	v_mfma_i32_16x16x64_i8 v[126:129], v[150:153], v[188:191], v[126:129]
	v_mfma_i32_16x16x64_i8 v[122:125], v[164:167], v[188:191], v[122:125]
	v_mfma_i32_16x16x64_i8 v[118:121], v[150:153], v[196:199], v[118:121]
	v_mfma_i32_16x16x64_i8 v[114:117], v[164:167], v[196:199], v[114:117]
	v_mfma_i32_16x16x64_i8 v[110:113], v[150:153], v[204:207], v[110:113]
	v_mfma_i32_16x16x64_i8 v[106:109], v[164:167], v[204:207], v[106:109]
	v_mfma_i32_16x16x64_i8 v[102:105], v[150:153], v[212:215], v[102:105]
	v_mfma_i32_16x16x64_i8 v[98:101], v[164:167], v[212:215], v[98:101]
	s_setprio 0
	s_setprio 2
	v_mfma_i32_16x16x64_i8 v[62:65], v[168:171], v[184:187], v[62:65]
	v_mfma_i32_16x16x64_i8 v[58:61], v[176:179], v[184:187], v[58:61]
	v_mfma_i32_16x16x64_i8 v[54:57], v[168:171], v[192:195], v[54:57]
	v_mfma_i32_16x16x64_i8 v[50:53], v[176:179], v[192:195], v[50:53]
	v_mfma_i32_16x16x64_i8 v[46:49], v[168:171], v[200:203], v[46:49]
	v_mfma_i32_16x16x64_i8 v[42:45], v[176:179], v[200:203], v[42:45]
	v_mfma_i32_16x16x64_i8 v[38:41], v[168:171], v[208:211], v[38:41]
	v_mfma_i32_16x16x64_i8 v[34:37], v[176:179], v[208:211], v[34:37]
	v_mfma_i32_16x16x64_i8 v[62:65], v[172:175], v[188:191], v[62:65]
	v_mfma_i32_16x16x64_i8 v[58:61], v[180:183], v[188:191], v[58:61]
	v_mfma_i32_16x16x64_i8 v[54:57], v[172:175], v[196:199], v[54:57]
	v_mfma_i32_16x16x64_i8 v[50:53], v[180:183], v[196:199], v[50:53]
	s_setprio 3
	s_barrier
	v_mfma_i32_16x16x64_i8 v[46:49], v[172:175], v[204:207], v[46:49]
	v_mfma_i32_16x16x64_i8 v[42:45], v[180:183], v[204:207], v[42:45]
	v_mfma_i32_16x16x64_i8 v[38:41], v[172:175], v[212:215], v[38:41]
	v_mfma_i32_16x16x64_i8 v[34:37], v[180:183], v[212:215], v[34:37]
	s_setprio 0
	s_add_i32 s0, s57, s48
	v_lshl_add_u64 v[216:217], s[44:45], 0, v[130:131]
	s_mov_b32 m0, s0
	ds_read_b128 v[184:187], v158 offset:16384
	ds_read_b128 v[188:191], v158 offset:17408
	ds_read_b128 v[192:195], v158 offset:18432
	ds_read_b128 v[196:199], v158 offset:19456
	ds_read_b128 v[200:203], v158 offset:20480
	ds_read_b128 v[204:207], v158 offset:21504
	ds_read_b128 v[208:211], v158 offset:22528
	ds_read_b128 v[212:215], v158 offset:23552
	global_load_lds_dwordx4 v[216:217], off
	s_add_i32 m0, s0, 0x2000
	s_add_u32 s0, s44, 0x158000
	v_lshl_add_u64 v[216:217], s[44:45], 0, v[134:135]
	s_addc_u32 s1, s45, 0
	s_add_i32 s71, s58, s48
	global_load_lds_dwordx4 v[216:217], off
	v_lshl_add_u64 v[216:217], s[0:1], 0, v[130:131]
	s_mov_b32 m0, s71
	v_lshl_add_u64 v[218:219], s[46:47], 0, v[136:137]
	global_load_lds_dwordx4 v[216:217], off
	v_lshl_add_u64 v[216:217], s[0:1], 0, v[134:135]
	s_add_i32 m0, s71, 0x2000
	s_nop 0
	global_load_lds_dwordx4 v[216:217], off
	v_lshl_add_u64 v[216:217], s[46:47], 0, v[132:133]
	s_mov_b32 m0, s49
	s_nop 0
	global_load_lds_dwordx4 v[216:217], off
	s_mov_b32 m0, s50
	s_nop 0
	global_load_lds_dwordx4 v[218:219], off
	s_waitcnt vmcnt(8)
	s_waitcnt lgkmcnt(0)
	s_barrier
	s_setprio 2
	s_waitcnt lgkmcnt(0)
	v_mfma_i32_16x16x64_i8 v[94:97], v[146:149], v[184:187], v[94:97]
	v_mfma_i32_16x16x64_i8 v[90:93], v[160:163], v[184:187], v[90:93]
	v_mfma_i32_16x16x64_i8 v[86:89], v[146:149], v[192:195], v[86:89]
	v_mfma_i32_16x16x64_i8 v[82:85], v[160:163], v[192:195], v[82:85]
	v_mfma_i32_16x16x64_i8 v[78:81], v[146:149], v[200:203], v[78:81]
	v_mfma_i32_16x16x64_i8 v[74:77], v[160:163], v[200:203], v[74:77]
	v_mfma_i32_16x16x64_i8 v[70:73], v[146:149], v[208:211], v[70:73]
	v_mfma_i32_16x16x64_i8 v[66:69], v[160:163], v[208:211], v[66:69]
	v_mfma_i32_16x16x64_i8 v[94:97], v[150:153], v[188:191], v[94:97]
	v_mfma_i32_16x16x64_i8 v[90:93], v[164:167], v[188:191], v[90:93]
	v_mfma_i32_16x16x64_i8 v[86:89], v[150:153], v[196:199], v[86:89]
	v_mfma_i32_16x16x64_i8 v[82:85], v[164:167], v[196:199], v[82:85]
	v_mfma_i32_16x16x64_i8 v[78:81], v[150:153], v[204:207], v[78:81]
	v_mfma_i32_16x16x64_i8 v[74:77], v[164:167], v[204:207], v[74:77]
	v_mfma_i32_16x16x64_i8 v[70:73], v[150:153], v[212:215], v[70:73]
	v_mfma_i32_16x16x64_i8 v[66:69], v[164:167], v[212:215], v[66:69]
	s_setprio 0
	s_setprio 2
	v_mfma_i32_16x16x64_i8 v[30:33], v[168:171], v[184:187], v[30:33]
	v_mfma_i32_16x16x64_i8 v[26:29], v[176:179], v[184:187], v[26:29]
	v_mfma_i32_16x16x64_i8 v[22:25], v[168:171], v[192:195], v[22:25]
	v_mfma_i32_16x16x64_i8 v[18:21], v[176:179], v[192:195], v[18:21]
	v_mfma_i32_16x16x64_i8 v[14:17], v[168:171], v[200:203], v[14:17]
	v_mfma_i32_16x16x64_i8 v[10:13], v[176:179], v[200:203], v[10:13]
	v_mfma_i32_16x16x64_i8 v[6:9], v[168:171], v[208:211], v[6:9]
	v_mfma_i32_16x16x64_i8 v[2:5], v[176:179], v[208:211], v[2:5]
	v_mfma_i32_16x16x64_i8 v[30:33], v[172:175], v[188:191], v[30:33]
	v_mfma_i32_16x16x64_i8 v[26:29], v[180:183], v[188:191], v[26:29]
	v_mfma_i32_16x16x64_i8 v[22:25], v[172:175], v[196:199], v[22:25]
	v_mfma_i32_16x16x64_i8 v[18:21], v[180:183], v[196:199], v[18:21]
	s_setprio 3
	s_barrier
	v_mfma_i32_16x16x64_i8 v[14:17], v[172:175], v[204:207], v[14:17]
	v_mfma_i32_16x16x64_i8 v[10:13], v[180:183], v[204:207], v[10:13]
	v_mfma_i32_16x16x64_i8 v[6:9], v[172:175], v[212:215], v[6:9]
	v_mfma_i32_16x16x64_i8 v[2:5], v[180:183], v[212:215], v[2:5]
	s_setprio 0
	s_add_i32 s71, 0, 0x18000
	v_add_u32_e32 v159, s71, v154
	s_add_i32 s72, 0, 0x1c000
	ds_read_b128 v[146:149], v159
	ds_read_b128 v[150:153], v159 offset:1024
	ds_read_b128 v[160:163], v159 offset:2048
	ds_read_b128 v[164:167], v159 offset:3072
	v_add_u32_e32 v159, s72, v154
	ds_read_b128 v[168:171], v159
	ds_read_b128 v[172:175], v159 offset:1024
	ds_read_b128 v[176:179], v159 offset:2048
	ds_read_b128 v[180:183], v159 offset:3072
	s_add_u32 s0, s46, 0x158000
	s_addc_u32 s1, s47, 0
	s_mov_b32 m0, s51
	v_lshl_add_u64 v[220:221], s[0:1], 0, v[132:133]
	ds_read_b128 v[184:187], v158 offset:32768
	ds_read_b128 v[188:191], v158 offset:33792
	ds_read_b128 v[192:195], v158 offset:34816
	ds_read_b128 v[196:199], v158 offset:35840
	ds_read_b128 v[200:203], v158 offset:36864
	ds_read_b128 v[204:207], v158 offset:37888
	ds_read_b128 v[208:211], v158 offset:38912
	ds_read_b128 v[212:215], v158 offset:39936
	global_load_lds_dwordx4 v[220:221], off
	v_lshl_add_u64 v[220:221], s[0:1], 0, v[136:137]
	s_mov_b32 m0, s52
	s_nop 0
	global_load_lds_dwordx4 v[220:221], off
	s_waitcnt vmcnt(8)
	s_waitcnt lgkmcnt(0)
	s_barrier
	s_setprio 2
	s_waitcnt lgkmcnt(0)
	v_mfma_i32_16x16x64_i8 v[126:129], v[146:149], v[184:187], v[126:129]
	v_mfma_i32_16x16x64_i8 v[122:125], v[160:163], v[184:187], v[122:125]
	v_mfma_i32_16x16x64_i8 v[118:121], v[146:149], v[192:195], v[118:121]
	v_mfma_i32_16x16x64_i8 v[114:117], v[160:163], v[192:195], v[114:117]
	v_mfma_i32_16x16x64_i8 v[110:113], v[146:149], v[200:203], v[110:113]
	v_mfma_i32_16x16x64_i8 v[106:109], v[160:163], v[200:203], v[106:109]
	v_mfma_i32_16x16x64_i8 v[102:105], v[146:149], v[208:211], v[102:105]
	v_mfma_i32_16x16x64_i8 v[98:101], v[160:163], v[208:211], v[98:101]
	v_mfma_i32_16x16x64_i8 v[126:129], v[150:153], v[188:191], v[126:129]
	v_mfma_i32_16x16x64_i8 v[122:125], v[164:167], v[188:191], v[122:125]
	v_mfma_i32_16x16x64_i8 v[118:121], v[150:153], v[196:199], v[118:121]
	v_mfma_i32_16x16x64_i8 v[114:117], v[164:167], v[196:199], v[114:117]
	v_mfma_i32_16x16x64_i8 v[110:113], v[150:153], v[204:207], v[110:113]
	v_mfma_i32_16x16x64_i8 v[106:109], v[164:167], v[204:207], v[106:109]
	v_mfma_i32_16x16x64_i8 v[102:105], v[150:153], v[212:215], v[102:105]
	v_mfma_i32_16x16x64_i8 v[98:101], v[164:167], v[212:215], v[98:101]
	s_setprio 0
	s_setprio 2
	v_mfma_i32_16x16x64_i8 v[62:65], v[168:171], v[184:187], v[62:65]
	v_mfma_i32_16x16x64_i8 v[58:61], v[176:179], v[184:187], v[58:61]
	v_mfma_i32_16x16x64_i8 v[54:57], v[168:171], v[192:195], v[54:57]
	v_mfma_i32_16x16x64_i8 v[50:53], v[176:179], v[192:195], v[50:53]
	v_mfma_i32_16x16x64_i8 v[46:49], v[168:171], v[200:203], v[46:49]
	v_mfma_i32_16x16x64_i8 v[42:45], v[176:179], v[200:203], v[42:45]
	v_mfma_i32_16x16x64_i8 v[38:41], v[168:171], v[208:211], v[38:41]
	v_mfma_i32_16x16x64_i8 v[34:37], v[176:179], v[208:211], v[34:37]
	v_mfma_i32_16x16x64_i8 v[62:65], v[172:175], v[188:191], v[62:65]
	v_mfma_i32_16x16x64_i8 v[58:61], v[180:183], v[188:191], v[58:61]
	v_mfma_i32_16x16x64_i8 v[54:57], v[172:175], v[196:199], v[54:57]
	v_mfma_i32_16x16x64_i8 v[50:53], v[180:183], v[196:199], v[50:53]
	s_setprio 3
	s_barrier
	v_mfma_i32_16x16x64_i8 v[46:49], v[172:175], v[204:207], v[46:49]
	v_mfma_i32_16x16x64_i8 v[42:45], v[180:183], v[204:207], v[42:45]
	v_mfma_i32_16x16x64_i8 v[38:41], v[172:175], v[212:215], v[38:41]
	v_mfma_i32_16x16x64_i8 v[34:37], v[180:183], v[212:215], v[34:37]
	s_setprio 0
	s_add_u32 s0, s44, 0x4000
	s_addc_u32 s1, s45, 0
	s_add_i32 s46, s71, s48
	v_lshl_add_u64 v[220:221], s[0:1], 0, v[130:131]
	s_mov_b32 m0, s46
	ds_read_b128 v[184:187], v158 offset:49152
	ds_read_b128 v[188:191], v158 offset:50176
	ds_read_b128 v[192:195], v158 offset:51200
	ds_read_b128 v[196:199], v158 offset:52224
	ds_read_b128 v[200:203], v158 offset:53248
	ds_read_b128 v[204:207], v158 offset:54272
	ds_read_b128 v[208:211], v158 offset:55296
	ds_read_b128 v[212:215], v158 offset:56320
	global_load_lds_dwordx4 v[220:221], off
	s_add_i32 m0, s46, 0x2000
	v_lshl_add_u64 v[220:221], s[0:1], 0, v[134:135]
	s_add_u32 s0, s44, 0x15c000
	s_addc_u32 s1, s45, 0
	s_add_i32 s44, s72, s48
	global_load_lds_dwordx4 v[220:221], off
	v_lshl_add_u64 v[220:221], s[0:1], 0, v[130:131]
	s_mov_b32 m0, s44
	v_lshl_add_u64 v[216:217], v[216:217], 0, s[18:19]
	global_load_lds_dwordx4 v[220:221], off
	v_lshl_add_u64 v[220:221], s[0:1], 0, v[134:135]
	s_add_i32 m0, s44, 0x2000
	s_nop 0
	global_load_lds_dwordx4 v[220:221], off
	s_mov_b32 m0, s54
	s_nop 0
	global_load_lds_dwordx4 v[216:217], off
	v_lshl_add_u64 v[216:217], v[218:219], 0, s[18:19]
	s_mov_b32 m0, s55
	s_nop 0
	global_load_lds_dwordx4 v[216:217], off
	s_waitcnt vmcnt(8)
	s_waitcnt lgkmcnt(0)
	s_barrier
	s_setprio 2
	s_waitcnt lgkmcnt(0)
	v_mfma_i32_16x16x64_i8 v[94:97], v[146:149], v[184:187], v[94:97]
	v_mfma_i32_16x16x64_i8 v[90:93], v[160:163], v[184:187], v[90:93]
	v_mfma_i32_16x16x64_i8 v[86:89], v[146:149], v[192:195], v[86:89]
	v_mfma_i32_16x16x64_i8 v[82:85], v[160:163], v[192:195], v[82:85]
	v_mfma_i32_16x16x64_i8 v[78:81], v[146:149], v[200:203], v[78:81]
	v_mfma_i32_16x16x64_i8 v[74:77], v[160:163], v[200:203], v[74:77]
	v_mfma_i32_16x16x64_i8 v[70:73], v[146:149], v[208:211], v[70:73]
	v_mfma_i32_16x16x64_i8 v[66:69], v[160:163], v[208:211], v[66:69]
	v_mfma_i32_16x16x64_i8 v[94:97], v[150:153], v[188:191], v[94:97]
	v_mfma_i32_16x16x64_i8 v[90:93], v[164:167], v[188:191], v[90:93]
	v_mfma_i32_16x16x64_i8 v[86:89], v[150:153], v[196:199], v[86:89]
	v_mfma_i32_16x16x64_i8 v[82:85], v[164:167], v[196:199], v[82:85]
	v_mfma_i32_16x16x64_i8 v[78:81], v[150:153], v[204:207], v[78:81]
	v_mfma_i32_16x16x64_i8 v[74:77], v[164:167], v[204:207], v[74:77]
	v_mfma_i32_16x16x64_i8 v[70:73], v[150:153], v[212:215], v[70:73]
	v_mfma_i32_16x16x64_i8 v[66:69], v[164:167], v[212:215], v[66:69]
	s_setprio 0
	s_setprio 2
	v_mfma_i32_16x16x64_i8 v[30:33], v[168:171], v[184:187], v[30:33]
	v_mfma_i32_16x16x64_i8 v[26:29], v[176:179], v[184:187], v[26:29]
	v_mfma_i32_16x16x64_i8 v[22:25], v[168:171], v[192:195], v[22:25]
	v_mfma_i32_16x16x64_i8 v[18:21], v[176:179], v[192:195], v[18:21]
	v_mfma_i32_16x16x64_i8 v[14:17], v[168:171], v[200:203], v[14:17]
	v_mfma_i32_16x16x64_i8 v[10:13], v[176:179], v[200:203], v[10:13]
	v_mfma_i32_16x16x64_i8 v[6:9], v[168:171], v[208:211], v[6:9]
	v_mfma_i32_16x16x64_i8 v[2:5], v[176:179], v[208:211], v[2:5]
	v_mfma_i32_16x16x64_i8 v[30:33], v[172:175], v[188:191], v[30:33]
	v_mfma_i32_16x16x64_i8 v[26:29], v[180:183], v[188:191], v[26:29]
	v_mfma_i32_16x16x64_i8 v[22:25], v[172:175], v[196:199], v[22:25]
	v_mfma_i32_16x16x64_i8 v[18:21], v[180:183], v[196:199], v[18:21]
	s_setprio 3
	s_barrier
	v_mfma_i32_16x16x64_i8 v[14:17], v[172:175], v[204:207], v[14:17]
	v_mfma_i32_16x16x64_i8 v[10:13], v[180:183], v[204:207], v[10:13]
	v_mfma_i32_16x16x64_i8 v[6:9], v[172:175], v[212:215], v[6:9]
	v_mfma_i32_16x16x64_i8 v[2:5], v[180:183], v[212:215], v[2:5]
	s_setprio 0
	s_add_i32 s70, s70, 2
	s_add_u32 s68, s68, 0x8000
	s_addc_u32 s69, s69, 0
	s_cmpk_gt_u32 s70, 0x53
	s_mov_b64 s[0:1], s[42:43]
	s_cbranch_scc0 .LBB0_1600
	s_and_b64 vcc, exec, s[20:21]
	s_cbranch_vccz .LBB0_1603
	s_barrier

.LBB0_1668:
	s_cmp_ge_i32 s18, s19
	s_cselect_b64 s[10:11], -1, 0
	s_cmp_lt_i32 s18, s19
	s_cselect_b64 s[2:3], -1, 0
	s_or_b64 vcc, s[4:5], s[2:3]
	v_cndmask_b32_e32 v166, 0, v166, vcc
	s_nor_b64 s[14:15], s[0:1], vcc
	s_and_saveexec_b64 s[2:3], s[14:15]
	s_cbranch_execz .LBB0_1672
	s_mov_b64 s[16:17], exec
	v_mbcnt_lo_u32_b32 v0, s16, 0
	v_mbcnt_hi_u32_b32 v0, s17, v0
	v_cmp_eq_u32_e32 vcc, 0, v0
	s_and_saveexec_b64 s[14:15], vcc
	s_cbranch_execz .LBB0_1671
	s_bcnt1_i32_b64 s13, s[16:17]
	v_mov_b32_e32 v1, s13
	global_atomic_add v223, v17, v1, s[8:9] sc0

.LBB0_1672:
	s_or_b64 exec, exec, s[2:3]
	s_ashr_i32 s13, s12, 31
	s_lshl_b64 s[2:3], s[12:13], 13
	v_lshl_add_u64 v[0:1], v[18:19], 0, s[2:3]
	v_add_co_u32_e32 v12, vcc, 0x1000, v0
	global_load_dwordx2 v[2:3], v[0:1], off offset:512
	global_load_dwordx2 v[4:5], v[0:1], off offset:1024
	global_load_dwordx2 v[6:7], v[0:1], off offset:2048
	global_load_dwordx2 v[8:9], v[0:1], off offset:2560
	global_load_dwordx2 v[10:11], v[0:1], off offset:3072
	v_addc_co_u32_e32 v13, vcc, 0, v1, vcc
	global_load_dwordx2 v[14:15], v[12:13], off
	global_load_dwordx2 v[24:25], v[12:13], off offset:512
	v_lshl_add_u64 v[26:27], v[20:21], 0, s[2:3]
	global_load_dwordx2 v[28:29], v[12:13], off offset:1024
	global_load_dwordx2 v[78:79], v[0:1], off
	global_load_dwordx2 v[106:107], v[0:1], off offset:1536
	global_load_dwordx2 v[112:113], v[0:1], off offset:3584
	global_load_dwordx2 v[76:77], v[26:27], off
	global_load_dwordx2 v[86:87], v[26:27], off offset:512
	global_load_dwordx2 v[94:95], v[26:27], off offset:1024
	global_load_dwordx2 v[108:109], v[26:27], off offset:1536
	global_load_dwordx2 v[30:31], v[12:13], off offset:2048
	global_load_dwordx2 v[102:103], v[26:27], off offset:2048
	global_load_dwordx2 v[92:93], v[26:27], off offset:2560
	global_load_dwordx2 v[100:101], v[26:27], off offset:3072
	global_load_dwordx2 v[120:121], v[26:27], off offset:3584
	global_load_dwordx2 v[38:39], v[12:13], off offset:2560
	v_add_co_u32_e32 v0, vcc, s22, v26
	s_lshl_b64 s[2:3], s[12:13], 14
	s_nop 0
	v_addc_co_u32_e32 v1, vcc, 0, v27, vcc
	global_load_dwordx2 v[114:115], v[0:1], off
	global_load_dwordx2 v[98:99], v[0:1], off offset:512
	global_load_dwordx2 v[66:67], v[0:1], off offset:1024
	global_load_dwordx2 v[64:65], v[0:1], off offset:1536
	global_load_dwordx2 v[70:71], v[12:13], off offset:3072
	global_load_dwordx2 v[62:63], v[0:1], off offset:2048
	global_load_dwordx2 v[60:61], v[0:1], off offset:2560
	global_load_dwordx2 v[58:59], v[0:1], off offset:3072
	global_load_dwordx2 v[56:57], v[0:1], off offset:3584
	global_load_dwordx2 v[72:73], v[12:13], off offset:1536
	global_load_dwordx2 v[68:69], v[12:13], off offset:3584
	s_waitcnt vmcnt(24)
	v_readfirstlane_b32 s98, v223
	s_nop 1
	v_mov_b32_e32 v166, s98
	v_and_b32_e32 v35, 0xffff0000, v28
	v_lshlrev_b32_e32 v34, 16, v28
	v_and_b32_e32 v33, 0xffff0000, v29
	v_lshlrev_b32_e32 v32, 16, v29
	v_and_b32_e32 v51, 0xffff0000, v3
	v_and_b32_e32 v50, 0xffff0000, v2
	v_lshlrev_b32_e32 v13, 16, v3
	v_lshlrev_b32_e32 v12, 16, v2
	v_pk_mul_f32 v[0:1], v[50:51], v[50:51]
	s_waitcnt vmcnt(16)
	v_lshlrev_b32_e32 v85, 16, v31
	v_pk_fma_f32 v[0:1], v[12:13], v[12:13], v[0:1]
	v_and_b32_e32 v43, 0xffff0000, v15
	v_and_b32_e32 v42, 0xffff0000, v14
	v_lshlrev_b32_e32 v137, 16, v15
	v_lshlrev_b32_e32 v136, 16, v14
	v_pk_add_f32 v[126:127], v[0:1], v[0:1] op_sel:[0,1] op_sel_hi:[1,0]
	v_pk_mul_f32 v[0:1], v[42:43], v[42:43]
	v_and_b32_e32 v41, 0xffff0000, v25
	v_pk_fma_f32 v[0:1], v[136:137], v[136:137], v[0:1]
	v_and_b32_e32 v40, 0xffff0000, v24
	v_pk_add_f32 v[140:141], v[0:1], v[0:1] op_sel:[0,1] op_sel_hi:[1,0]
	v_lshlrev_b32_e32 v169, 16, v25
	v_lshlrev_b32_e32 v168, 16, v24
	v_pk_mul_f32 v[0:1], v[40:41], v[40:41]
	v_lshlrev_b32_e32 v84, 16, v30
	v_pk_fma_f32 v[0:1], v[168:169], v[168:169], v[0:1]
	v_and_b32_e32 v31, 0xffff0000, v31
	v_pk_add_f32 v[156:157], v[0:1], v[0:1] op_sel:[0,1] op_sel_hi:[1,0]
	v_mul_f32_e32 v0, v35, v35
	v_pk_fma_f32 v[152:153], v[34:35], v[34:35], v[0:1] op_sel_hi:[1,1,0]
	v_mul_f32_e32 v0, v33, v33
	v_and_b32_e32 v30, 0xffff0000, v30
	v_pk_fma_f32 v[154:155], v[32:33], v[32:33], v[0:1] op_sel_hi:[1,1,0]
	v_pk_mul_f32 v[0:1], v[30:31], v[30:31]
	v_and_b32_e32 v37, 0xffff0000, v11
	v_pk_fma_f32 v[0:1], v[84:85], v[84:85], v[0:1]
	s_waitcnt vmcnt(11)
	v_and_b32_e32 v29, 0xffff0000, v39
	v_and_b32_e32 v28, 0xffff0000, v38
	v_lshlrev_b32_e32 v36, 16, v11
	v_mul_f32_e32 v26, v37, v37
	v_pk_add_f32 v[146:147], v[0:1], v[0:1] op_sel:[0,1] op_sel_hi:[1,0]
	v_lshlrev_b32_e32 v83, 16, v39
	v_lshlrev_b32_e32 v82, 16, v38
	v_pk_mul_f32 v[0:1], v[28:29], v[28:29]
	v_pk_fma_f32 v[130:131], v[36:37], v[36:37], v[26:27] op_sel_hi:[1,1,0]
	v_pk_fma_f32 v[0:1], v[82:83], v[82:83], v[0:1]
	s_waitcnt vmcnt(6)
	v_and_b32_e32 v27, 0xffff0000, v70
	v_pk_add_f32 v[150:151], v[0:1], v[0:1] op_sel:[0,1] op_sel_hi:[1,0]
	v_lshlrev_b32_e32 v26, 16, v70
	v_mul_f32_e32 v0, v27, v27
	v_and_b32_e32 v25, 0xffff0000, v71
	v_pk_fma_f32 v[144:145], v[26:27], v[26:27], v[0:1] op_sel_hi:[1,1,0]
	v_lshlrev_b32_e32 v24, 16, v71
	v_mul_f32_e32 v0, v25, v25
	v_and_b32_e32 v75, 0xffff0000, v78
	v_pk_fma_f32 v[148:149], v[24:25], v[24:25], v[0:1] op_sel_hi:[1,1,0]
	v_lshlrev_b32_e32 v74, 16, v78
	v_mul_f32_e32 v0, v75, v75
	v_lshlrev_b32_e32 v78, 16, v79
	v_and_b32_e32 v79, 0xffff0000, v79
	v_pk_fma_f32 v[128:129], v[74:75], v[74:75], v[0:1] op_sel_hi:[1,1,0]
	v_mul_f32_e32 v0, v79, v79
	v_and_b32_e32 v53, 0xffff0000, v4
	v_and_b32_e32 v55, 0xffff0000, v5
	v_pk_fma_f32 v[134:135], v[78:79], v[78:79], v[0:1] op_sel_hi:[1,1,0]
	v_lshlrev_b32_e32 v52, 16, v4
	v_lshlrev_b32_e32 v54, 16, v5
	v_mul_f32_e32 v2, v53, v53
	v_mul_f32_e32 v4, v55, v55
	v_and_b32_e32 v143, 0xffff0000, v106
	v_and_b32_e32 v142, s0, v106
	v_pk_add_f32 v[128:129], v[128:129], v[134:135]
	v_lshlrev_b32_e32 v134, 16, v107
	v_and_b32_e32 v135, 0xffff0000, v107
	v_pk_fma_f32 v[110:111], v[52:53], v[52:53], v[2:3] op_sel_hi:[1,1,0]
	v_pk_fma_f32 v[118:119], v[54:55], v[54:55], v[4:5] op_sel_hi:[1,1,0]
	v_lshlrev_b32_e32 v104, 16, v106
	v_mov_b32_e32 v105, v143
	v_pk_mul_f32 v[142:143], v[142:143], v[142:143]
	v_pk_mul_f32 v[106:107], v[134:135], v[134:135]
	v_and_b32_e32 v49, 0xffff0000, v7
	v_and_b32_e32 v48, 0xffff0000, v6
	v_mul_f32_e32 v129, v104, v104
	v_mov_b32_e32 v127, v143
	v_mov_b32_e32 v111, v106
	v_mov_b32_e32 v119, v107
	v_lshlrev_b32_e32 v117, 16, v7
	v_lshlrev_b32_e32 v116, 16, v6
	v_and_b32_e32 v47, 0xffff0000, v9
	v_and_b32_e32 v46, 0xffff0000, v8
	v_pk_mul_f32 v[6:7], v[48:49], v[48:49]
	v_pk_add_f32 v[126:127], v[128:129], v[126:127]
	v_pk_add_f32 v[106:107], v[110:111], v[118:119]
	v_lshlrev_b32_e32 v123, 16, v9
	v_lshlrev_b32_e32 v122, 16, v8
	v_pk_mul_f32 v[8:9], v[46:47], v[46:47]
	v_pk_fma_f32 v[2:3], v[116:117], v[116:117], v[6:7]
	v_pk_add_f32 v[106:107], v[126:127], v[106:107]
	v_pk_fma_f32 v[4:5], v[122:123], v[122:123], v[8:9]
	v_pk_add_f32 v[132:133], v[2:3], v[2:3] op_sel:[0,1] op_sel_hi:[1,0]
	v_pk_add_f32 v[170:171], v[106:107], v[106:107] op_sel:[0,1] op_sel_hi:[1,0]
	v_lshlrev_b32_e32 v106, 16, v112
	v_and_b32_e32 v107, 0xffff0000, v112
	v_pk_add_f32 v[138:139], v[4:5], v[4:5] op_sel:[0,1] op_sel_hi:[1,0]
	v_mov_b32_e32 v126, v122
	v_mov_b32_e32 v127, v46
	v_mov_b32_e32 v46, v123
	v_pk_mul_f32 v[122:123], v[106:107], v[106:107]
	v_pk_add_f32 v[132:133], v[170:171], v[132:133]
	v_and_b32_e32 v45, 0xffff0000, v10
	v_mov_b32_e32 v139, v123
	v_mov_b32_e32 v133, v122
	v_lshlrev_b32_e32 v44, 16, v10
	v_mul_f32_e32 v10, v45, v45
	v_pk_add_f32 v[138:139], v[132:133], v[138:139]
	v_lshlrev_b32_e32 v132, 16, v113
	v_and_b32_e32 v133, 0xffff0000, v113
	v_pk_fma_f32 v[124:125], v[44:45], v[44:45], v[10:11] op_sel_hi:[1,1,0]
	v_pk_mul_f32 v[112:113], v[132:133], v[132:133]
	v_lshl_add_u64 v[38:39], v[22:23], 0, s[2:3]
	v_mov_b32_e32 v125, v112
	v_mov_b32_e32 v131, v113
	v_pk_add_f32 v[112:113], v[124:125], v[130:131]
	v_lshlrev_b32_e32 v124, 16, v115
	v_pk_add_f32 v[112:113], v[138:139], v[112:113]
	v_and_b32_e32 v125, 0xffff0000, v115
	v_pk_add_f32 v[170:171], v[112:113], v[112:113] op_sel:[0,1] op_sel_hi:[1,0]
	v_lshlrev_b32_e32 v112, 16, v114
	v_and_b32_e32 v113, 0xffff0000, v114
	s_waitcnt vmcnt(1)
	v_lshlrev_b32_e32 v114, 16, v72
	v_and_b32_e32 v115, 0xffff0000, v72
	v_mov_b32_e32 v138, v136
	v_mov_b32_e32 v139, v42
	v_mov_b32_e32 v42, v137
	v_mov_b32_e32 v136, v168
	v_mov_b32_e32 v137, v40
	v_mov_b32_e32 v40, v169
	v_pk_mul_f32 v[168:169], v[114:115], v[114:115]
	v_pk_add_f32 v[140:141], v[170:171], v[140:141]
	v_mov_b32_e32 v157, v169
	v_mov_b32_e32 v141, v168
	v_pk_add_f32 v[156:157], v[140:141], v[156:157]
	v_lshlrev_b32_e32 v140, 16, v73
	v_and_b32_e32 v141, 0xffff0000, v73
	v_pk_mul_f32 v[72:73], v[140:141], v[140:141]
	ds_read_b128 v[4:7], v16
	ds_read_b128 v[0:3], v16 offset:1024
	v_mov_b32_e32 v153, v72
	v_mov_b32_e32 v155, v73
	v_pk_add_f32 v[72:73], v[152:153], v[154:155]
	s_waitcnt vmcnt(0)
	v_and_b32_e32 v155, 0xffff0000, v68
	v_pk_add_f32 v[72:73], v[156:157], v[72:73]
	v_and_b32_e32 v154, s0, v68
	v_pk_add_f32 v[152:153], v[72:73], v[72:73] op_sel:[0,1] op_sel_hi:[1,0]
	v_lshlrev_b32_e32 v72, 16, v68
	v_pk_mul_f32 v[156:157], v[154:155], v[154:155]
	v_pk_add_f32 v[146:147], v[152:153], v[146:147]
	v_mov_b32_e32 v151, v157
	v_mul_f32_e32 v147, v72, v72
	v_lshlrev_b32_e32 v68, 16, v69
	v_and_b32_e32 v69, 0xffff0000, v69
	v_pk_add_f32 v[146:147], v[146:147], v[150:151]
	v_pk_mul_f32 v[150:151], v[68:69], v[68:69]
	v_lshlrev_b32_e32 v70, 16, v76
	v_mov_b32_e32 v145, v150
	v_mov_b32_e32 v149, v151
	v_pk_add_f32 v[144:145], v[144:145], v[148:149]
	v_mov_b32_e32 v148, v84
	v_pk_add_f32 v[144:145], v[146:147], v[144:145]
	v_mov_b32_e32 v149, v30
	v_add_f32_e32 v73, v144, v145
	ds_bpermute_b32 v145, v158, v73
	v_mov_b32_e32 v30, v85
	v_lshlrev_b32_e32 v84, 16, v60
	v_and_b32_e32 v85, 0xffff0000, v60
	v_mov_b32_e32 v151, v28
	s_waitcnt lgkmcnt(0)
	v_add_f32_e32 v73, v73, v145
	ds_bpermute_b32 v147, v159, v73
	v_mov_b32_e32 v28, v83
	v_and_b32_e32 v83, 0xffff0000, v56
	v_and_b32_e32 v71, 0xffff0000, v76
	v_lshlrev_b32_e32 v76, 16, v77
	s_waitcnt lgkmcnt(0)
	v_add_f32_e32 v73, v73, v147
	ds_bpermute_b32 v150, v160, v73
	v_and_b32_e32 v77, 0xffff0000, v77
	v_mov_b32_e32 v88, v12
	v_mov_b32_e32 v89, v50
	v_lshlrev_b32_e32 v80, 16, v86
	s_waitcnt lgkmcnt(0)
	v_add_f32_e32 v73, v73, v150
	ds_bpermute_b32 v150, v161, v73
	v_and_b32_e32 v81, 0xffff0000, v86
	v_mov_b32_e32 v50, v13
	ds_read_b128 v[12:15], v16 offset:2048
	ds_read_b128 v[8:11], v16 offset:3072
	v_lshlrev_b32_e32 v86, 16, v87
	s_waitcnt lgkmcnt(2)
	v_add_f32_e32 v60, v73, v150
	ds_bpermute_b32 v73, v162, v60
	v_mov_b32_e32 v150, v82
	v_and_b32_e32 v87, 0xffff0000, v87
	v_lshlrev_b32_e32 v90, 16, v94
	v_and_b32_e32 v91, 0xffff0000, v94
	s_waitcnt lgkmcnt(0)
	v_add_f32_e32 v73, v60, v73
	ds_bpermute_b32 v82, v163, v73
	v_lshlrev_b32_e32 v94, 16, v95
	v_and_b32_e32 v95, 0xffff0000, v95
	v_lshlrev_b32_e32 v96, 16, v108
	v_and_b32_e32 v97, 0xffff0000, v108
	s_waitcnt lgkmcnt(0)
	v_add_f32_e32 v73, v73, v82
	v_fmamk_f32 v73, v73, 0x39800000, v164
	v_mul_f32_e32 v82, 0x4f800000, v73
	v_cmp_gt_f32_e32 vcc, s23, v73
	v_lshlrev_b32_e32 v128, 16, v109
	v_and_b32_e32 v129, 0xffff0000, v109
	v_cndmask_b32_e32 v73, v73, v82, vcc
	v_sqrt_f32_e32 v154, v73
	v_lshlrev_b32_e32 v82, 16, v56
	v_lshlrev_b32_e32 v110, 16, v102
	v_and_b32_e32 v111, 0xffff0000, v102
	v_add_u32_e32 v56, -1, v154
	v_fma_f32 v156, -v56, v154, v73
	v_cmp_ge_f32_e64 s[2:3], 0, v156
	v_add_u32_e32 v156, 1, v154
	v_mov_b32_e32 v142, v116
	v_cndmask_b32_e64 v56, v154, v56, s[2:3]
	v_fma_f32 v154, -v156, v154, v73
	v_cmp_lt_f32_e64 s[2:3], 0, v154
	v_mov_b32_e32 v143, v48
	v_lshlrev_b32_e32 v118, 16, v103
	v_cndmask_b32_e64 v56, v56, v156, s[2:3]
	v_mul_f32_e32 v154, 0x37800000, v56
	v_cndmask_b32_e32 v56, v56, v154, vcc
	v_cmp_class_f32_e32 vcc, v73, v165
	v_and_b32_e32 v119, 0xffff0000, v103
	v_mov_b32_e32 v48, v117
	v_cndmask_b32_e32 v154, v56, v73, vcc
	v_div_scale_f32 v156, s[2:3], v154, v154, 0.5
	v_rcp_f32_e32 v157, v156
	v_mov_b32_e32 v73, v155
	v_lshlrev_b32_e32 v116, 16, v92
	v_and_b32_e32 v117, 0xffff0000, v92
	v_fma_f32 v155, -v156, v157, 1.0
	v_fmac_f32_e32 v157, v155, v157
	v_div_scale_f32 v155, vcc, 0.5, v154, 0.5
	v_mul_f32_e32 v167, v155, v157
	v_fma_f32 v168, -v156, v167, v155
	v_fmac_f32_e32 v167, v168, v157
	v_fma_f32 v155, -v156, v167, v155
	v_div_fmas_f32 v155, v155, v157, v167
	v_div_fixup_f32 v154, v155, v154, 0.5
	v_pk_mul_f32 v[74:75], v[154:155], v[74:75] op_sel_hi:[0,1]
	v_pk_fma_f32 v[4:5], v[4:5], v[74:75], v[70:71]
	v_pk_mul_f32 v[70:71], v[154:155], v[78:79] op_sel_hi:[0,1]
	v_pk_fma_f32 v[6:7], v[6:7], v[70:71], v[76:77]
	global_store_dwordx4 v[38:39], v[4:7], off
	v_lshlrev_b32_e32 v108, 16, v93
	v_and_b32_e32 v109, 0xffff0000, v93
	v_pk_mul_f32 v[4:5], v[154:155], v[88:89] op_sel_hi:[0,1]
	v_pk_fma_f32 v[0:1], v[0:1], v[4:5], v[80:81]
	v_pk_mul_f32 v[4:5], v[154:155], v[50:51] op_sel_hi:[0,1]
	v_pk_fma_f32 v[2:3], v[2:3], v[4:5], v[86:87]
	global_store_dwordx4 v[38:39], v[0:3], off offset:1024
	v_lshlrev_b32_e32 v92, 16, v100
	v_and_b32_e32 v93, 0xffff0000, v100
	v_pk_mul_f32 v[0:1], v[154:155], v[52:53] op_sel_hi:[0,1]
	v_pk_mul_f32 v[2:3], v[154:155], v[54:55] op_sel_hi:[0,1]
	v_pk_fma_f32 v[0:1], v[12:13], v[0:1], v[90:91]
	v_pk_fma_f32 v[2:3], v[14:15], v[2:3], v[94:95]
	global_store_dwordx4 v[38:39], v[0:3], off offset:2048
	v_lshlrev_b32_e32 v100, 16, v101
	v_and_b32_e32 v101, 0xffff0000, v101
	v_pk_mul_f32 v[0:1], v[154:155], v[104:105] op_sel_hi:[0,1]
	v_pk_mul_f32 v[2:3], v[154:155], v[134:135] op_sel_hi:[0,1]
	v_pk_fma_f32 v[0:1], v[0:1], v[8:9], v[96:97]
	v_pk_fma_f32 v[2:3], v[2:3], v[10:11], v[128:129]
	v_lshlrev_b32_e32 v102, 16, v120
	v_and_b32_e32 v103, 0xffff0000, v120
	v_lshlrev_b32_e32 v122, 16, v121
	v_and_b32_e32 v123, 0xffff0000, v121
	v_lshlrev_b32_e32 v130, 16, v98
	v_and_b32_e32 v131, 0xffff0000, v98
	v_lshlrev_b32_e32 v120, 16, v99
	v_and_b32_e32 v121, 0xffff0000, v99
	v_lshlrev_b32_e32 v98, 16, v66
	v_and_b32_e32 v99, 0xffff0000, v66
	v_lshlrev_b32_e32 v66, 16, v67
	v_and_b32_e32 v67, 0xffff0000, v67
	v_lshlrev_b32_e32 v144, 16, v64
	v_and_b32_e32 v145, 0xffff0000, v64
	v_lshlrev_b32_e32 v64, 16, v65
	v_and_b32_e32 v65, 0xffff0000, v65
	v_lshlrev_b32_e32 v146, 16, v62
	v_and_b32_e32 v147, 0xffff0000, v62
	v_lshlrev_b32_e32 v62, 16, v63
	v_and_b32_e32 v63, 0xffff0000, v63
	v_lshlrev_b32_e32 v152, 16, v61
	v_and_b32_e32 v153, 0xffff0000, v61
	v_lshlrev_b32_e32 v60, 16, v58
	v_and_b32_e32 v61, 0xffff0000, v58
	v_lshlrev_b32_e32 v58, 16, v59
	v_and_b32_e32 v59, 0xffff0000, v59
	v_lshlrev_b32_e32 v56, 16, v57
	v_and_b32_e32 v57, 0xffff0000, v57
	global_store_dwordx4 v[38:39], v[0:3], off offset:3072
	ds_read_b128 v[0:3], v16 offset:4096
	ds_read_b128 v[4:7], v16 offset:5120
	v_add_co_u32_e32 v12, vcc, s22, v38
	v_pk_mul_f32 v[8:9], v[154:155], v[142:143] op_sel_hi:[0,1]
	s_nop 0
	v_addc_co_u32_e32 v13, vcc, 0, v39, vcc
	v_pk_mul_f32 v[10:11], v[154:155], v[48:49] op_sel_hi:[0,1]
	v_add_co_u32_e32 v14, vcc, s24, v38
	s_waitcnt lgkmcnt(1)
	v_pk_fma_f32 v[0:1], v[8:9], v[0:1], v[110:111]
	v_pk_fma_f32 v[2:3], v[10:11], v[2:3], v[118:119]
	v_addc_co_u32_e32 v15, vcc, 0, v39, vcc
	global_store_dwordx4 v[14:15], v[0:3], off offset:-4096
	ds_read_b128 v[8:11], v16 offset:6144
	s_nop 0
	v_pk_mul_f32 v[0:1], v[154:155], v[126:127] op_sel_hi:[0,1]
	v_pk_mul_f32 v[2:3], v[154:155], v[46:47] op_sel_hi:[0,1]
	s_waitcnt lgkmcnt(1)
	v_pk_fma_f32 v[0:1], v[0:1], v[4:5], v[116:117]
	v_pk_fma_f32 v[2:3], v[2:3], v[6:7], v[108:109]
	global_store_dwordx4 v[12:13], v[0:3], off offset:1024
	ds_read_b128 v[0:3], v16 offset:7168
	v_pk_mul_f32 v[4:5], v[154:155], v[44:45] op_sel_hi:[0,1]
	v_pk_mul_f32 v[6:7], v[154:155], v[36:37] op_sel_hi:[0,1]
	s_waitcnt lgkmcnt(1)
	v_pk_fma_f32 v[4:5], v[4:5], v[8:9], v[92:93]
	v_pk_fma_f32 v[6:7], v[6:7], v[10:11], v[100:101]
	global_store_dwordx4 v[12:13], v[4:7], off offset:2048
	s_nop 1
	v_pk_mul_f32 v[4:5], v[154:155], v[106:107] op_sel_hi:[0,1]
	s_waitcnt lgkmcnt(0)
	v_pk_fma_f32 v[0:1], v[4:5], v[0:1], v[102:103]
	v_pk_mul_f32 v[4:5], v[154:155], v[132:133] op_sel_hi:[0,1]
	v_pk_fma_f32 v[2:3], v[4:5], v[2:3], v[122:123]
	global_store_dwordx4 v[12:13], v[0:3], off offset:3072
	ds_read_b128 v[0:3], v16 offset:8192
	ds_read_b128 v[4:7], v16 offset:9216
	v_pk_mul_f32 v[8:9], v[154:155], v[138:139] op_sel_hi:[0,1]
	v_pk_mul_f32 v[10:11], v[154:155], v[42:43] op_sel_hi:[0,1]
	s_waitcnt lgkmcnt(1)
	v_pk_fma_f32 v[0:1], v[8:9], v[0:1], v[112:113]
	v_pk_fma_f32 v[2:3], v[10:11], v[2:3], v[124:125]
	global_store_dwordx4 v[14:15], v[0:3], off
	ds_read_b128 v[8:11], v16 offset:10240
	s_nop 0
	v_pk_mul_f32 v[0:1], v[154:155], v[136:137] op_sel_hi:[0,1]
	v_pk_mul_f32 v[2:3], v[154:155], v[40:41] op_sel_hi:[0,1]
	s_waitcnt lgkmcnt(1)
	v_pk_fma_f32 v[0:1], v[0:1], v[4:5], v[130:131]
	v_pk_fma_f32 v[2:3], v[2:3], v[6:7], v[120:121]
	global_store_dwordx4 v[14:15], v[0:3], off offset:1024
	ds_read_b128 v[0:3], v16 offset:11264
	v_pk_mul_f32 v[4:5], v[154:155], v[34:35] op_sel_hi:[0,1]
	v_pk_mul_f32 v[6:7], v[154:155], v[32:33] op_sel_hi:[0,1]
	s_waitcnt lgkmcnt(1)
	v_pk_fma_f32 v[4:5], v[4:5], v[8:9], v[98:99]
	v_pk_fma_f32 v[6:7], v[6:7], v[10:11], v[66:67]
	global_store_dwordx4 v[14:15], v[4:7], off offset:2048
	s_nop 1
	v_pk_mul_f32 v[4:5], v[154:155], v[114:115] op_sel_hi:[0,1]
	s_waitcnt lgkmcnt(0)
	v_pk_fma_f32 v[0:1], v[4:5], v[0:1], v[144:145]
	v_pk_mul_f32 v[4:5], v[154:155], v[140:141] op_sel_hi:[0,1]
	v_pk_fma_f32 v[2:3], v[4:5], v[2:3], v[64:65]
	global_store_dwordx4 v[14:15], v[0:3], off offset:3072
	ds_read_b128 v[0:3], v16 offset:12288
	ds_read_b128 v[4:7], v16 offset:13312
	v_pk_mul_f32 v[8:9], v[154:155], v[148:149] op_sel_hi:[0,1]
	v_pk_mul_f32 v[10:11], v[154:155], v[30:31] op_sel_hi:[0,1]
	v_add_co_u32_e32 v12, vcc, s25, v38
	s_waitcnt lgkmcnt(1)
	v_pk_fma_f32 v[0:1], v[8:9], v[0:1], v[146:147]
	v_pk_fma_f32 v[2:3], v[10:11], v[2:3], v[62:63]
	v_addc_co_u32_e32 v13, vcc, 0, v39, vcc
	global_store_dwordx4 v[12:13], v[0:3], off
	ds_read_b128 v[8:11], v16 offset:14336
	s_nop 0
	v_pk_mul_f32 v[0:1], v[154:155], v[150:151] op_sel_hi:[0,1]
	v_pk_mul_f32 v[2:3], v[154:155], v[28:29] op_sel_hi:[0,1]
	s_waitcnt lgkmcnt(1)
	v_pk_fma_f32 v[0:1], v[0:1], v[4:5], v[84:85]
	v_pk_fma_f32 v[2:3], v[2:3], v[6:7], v[152:153]
	global_store_dwordx4 v[12:13], v[0:3], off offset:1024
	ds_read_b128 v[0:3], v16 offset:15360
	v_pk_mul_f32 v[4:5], v[154:155], v[26:27] op_sel_hi:[0,1]
	v_pk_mul_f32 v[6:7], v[154:155], v[24:25] op_sel_hi:[0,1]
	s_waitcnt lgkmcnt(1)
	v_pk_fma_f32 v[4:5], v[4:5], v[8:9], v[60:61]
	v_pk_fma_f32 v[6:7], v[6:7], v[10:11], v[58:59]
	global_store_dwordx4 v[12:13], v[4:7], off offset:2048
	s_nop 1
	v_pk_mul_f32 v[4:5], v[154:155], v[72:73] op_sel_hi:[0,1]
	s_waitcnt lgkmcnt(0)
	v_pk_fma_f32 v[0:1], v[4:5], v[0:1], v[82:83]
	v_pk_mul_f32 v[4:5], v[154:155], v[68:69] op_sel_hi:[0,1]
	v_pk_fma_f32 v[2:3], v[4:5], v[2:3], v[56:57]
	global_store_dwordx4 v[12:13], v[0:3], off offset:3072
	s_mov_b64 s[2:3], -1
	s_and_b64 vcc, exec, s[6:7]
	s_cbranch_vccz .LBB0_1676
	s_andn2_b64 vcc, exec, s[10:11]
	s_mov_b32 s13, s21
	s_cbranch_vccnz .LBB0_1675
	v_readfirstlane_b32 s2, v166
	s_lshl_b32 s2, s2, 3
	s_add_i32 s13, s20, s2

	.amdhsa_kernel _Z6mk_fwd4Args
		.amdhsa_group_segment_fixed_size 0
		.amdhsa_private_segment_fixed_size 0
		.amdhsa_kernarg_size 432
		.amdhsa_user_sgpr_count 2
		.amdhsa_user_sgpr_dispatch_ptr 0
		.amdhsa_user_sgpr_queue_ptr 0
		.amdhsa_user_sgpr_kernarg_segment_ptr 1
		.amdhsa_user_sgpr_dispatch_id 0
		.amdhsa_user_sgpr_kernarg_preload_length 0
		.amdhsa_user_sgpr_kernarg_preload_offset 0
		.amdhsa_user_sgpr_private_segment_size 0
		.amdhsa_uses_dynamic_stack 0
		.amdhsa_enable_private_segment 0
		.amdhsa_system_sgpr_workgroup_id_x 1
		.amdhsa_system_sgpr_workgroup_id_y 0
		.amdhsa_system_sgpr_workgroup_id_z 0
		.amdhsa_system_sgpr_workgroup_info 0
		.amdhsa_system_vgpr_workitem_id 0
		.amdhsa_next_free_vgpr 224
		.amdhsa_next_free_sgpr 99
		.amdhsa_accum_offset 224
		.amdhsa_reserve_vcc 1
		.amdhsa_float_round_mode_32 0
		.amdhsa_float_round_mode_16_64 0
		.amdhsa_float_denorm_mode_32 3
		.amdhsa_float_denorm_mode_16_64 3
		.amdhsa_dx10_clamp 1
		.amdhsa_ieee_mode 1
		.amdhsa_fp16_overflow 0
		.amdhsa_tg_split 0
		.amdhsa_exception_fp_ieee_invalid_op 0
		.amdhsa_exception_fp_denorm_src 0
		.amdhsa_exception_fp_ieee_div_zero 0
		.amdhsa_exception_fp_ieee_overflow 0
		.amdhsa_exception_fp_ieee_underflow 0
		.amdhsa_exception_fp_ieee_inexact 0
		.amdhsa_exception_int_div_zero 0
	.end_amdhsa_kernel

amdhsa.kernels:
  - .agpr_count:     0
    .args:
      - .offset:         0
        .size:           176
        .value_kind:     by_value
      - .offset:         176
        .size:           4
        .value_kind:     hidden_block_count_x
      - .offset:         180
        .size:           4
        .value_kind:     hidden_block_count_y
      - .offset:         184
        .size:           4
        .value_kind:     hidden_block_count_z
      - .offset:         188
        .size:           2
        .value_kind:     hidden_group_size_x
      - .offset:         190
        .size:           2
        .value_kind:     hidden_group_size_y
      - .offset:         192
        .size:           2
        .value_kind:     hidden_group_size_z
      - .offset:         194
        .size:           2
        .value_kind:     hidden_remainder_x
      - .offset:         196
        .size:           2
        .value_kind:     hidden_remainder_y
      - .offset:         198
        .size:           2
        .value_kind:     hidden_remainder_z
      - .offset:         216
        .size:           8
        .value_kind:     hidden_global_offset_x
      - .offset:         224
        .size:           8
        .value_kind:     hidden_global_offset_y
      - .offset:         232
        .size:           8
        .value_kind:     hidden_global_offset_z
      - .offset:         240
        .size:           2
        .value_kind:     hidden_grid_dims
      - .offset:         296
        .size:           4
        .value_kind:     hidden_dynamic_lds_size
    .group_segment_fixed_size: 0
    .kernarg_segment_align: 8
    .kernarg_segment_size: 432
    .language:       OpenCL C
    .language_version:
      - 2
      - 0
    .max_flat_workgroup_size: 512
    .name:           _Z6mk_fwd4Args
    .private_segment_fixed_size: 0
    .sgpr_count:     105
    .sgpr_spill_count: 145
    .symbol:         _Z6mk_fwd4Args.kd
    .uniform_work_group_size: 1
    .uses_dynamic_stack: false
    .vgpr_count:     224
    .vgpr_spill_count: 0
    .wavefront_size: 64
